# L2-locality unit remap in the five static GEMM loops (MoE gate/up, down x2 layers, conv in-proj): each XCD round now covers an 8 A-tile x 4 B-tile block instead of 16x2 / 3x12; bijective index permuta
# speedup vs baseline: 1.0612x; 1.0151x over previous
.LBB0_836:
	s_cmpk_gt_i32 s47, 0x7ff
	s_cbranch_scc1 .LBB0_840
	v_writelane_b32 v196, s0, 26
	v_readlane_b32 s72, v197, 34
	s_lshl_b32 s38, s47, 7
	v_writelane_b32 v196, s1, 27
	s_lshl_b32 s39, s46, 7
	v_readlane_b32 s8, v196, 6
	v_readlane_b32 s10, v196, 8
	v_readlane_b32 s11, v196, 9
	v_readlane_b32 s12, v196, 10
	v_readlane_b32 s13, v196, 11
	v_readlane_b32 s14, v196, 12
	v_readlane_b32 s15, v196, 13
	v_readlane_b32 s16, v196, 14
	v_readlane_b32 s17, v196, 15
	v_readlane_b32 s18, v196, 16
	v_readlane_b32 s19, v196, 17
	v_readlane_b32 s20, v196, 18
	v_readlane_b32 s21, v196, 19
	s_mov_b32 s3, 0
	v_mov_b32_e32 v67, 0
	s_mov_b64 s[96:97], 0x100
	s_add_i32 s56, 0, 0xc000
	s_mov_b64 s[0:1], 0x180
	s_add_i32 s57, 0, 0x18000
	s_mov_b64 s[6:7], 0x200
	s_mov_b64 s[24:25], 0x500
	s_mov_b32 s58, s47
	s_mov_b64 s[26:27], 0x580
	s_mov_b64 s[28:29], 0x600
	s_mov_b64 s[30:31], 0x680
	s_mov_b64 s[34:35], 0x700
	s_mov_b64 s[36:37], 0x780
	v_readlane_b32 s9, v196, 7
	v_readlane_b32 s22, v196, 20
	v_readlane_b32 s23, v196, 21
	s_mov_b64 s[18:19], 0x400
	s_mov_b64 s[16:17], 0x380
	s_mov_b64 s[14:15], 0x300
	s_mov_b64 s[12:13], 0x280
	s_mov_b64 s[10:11], 0x80
	s_mov_b64 s[20:21], 0x480
	v_readlane_b32 s82, v197, 44
	v_readlane_b32 s83, v197, 45
	v_readlane_b32 s73, v197, 35
	v_readlane_b32 s74, v197, 36
	v_readlane_b32 s75, v197, 37
	v_readlane_b32 s76, v197, 38
	v_readlane_b32 s77, v197, 39
	v_readlane_b32 s78, v197, 40
	v_readlane_b32 s79, v197, 41
	v_readlane_b32 s80, v197, 42
	v_readlane_b32 s81, v197, 43
	v_readlane_b32 s84, v197, 46
	v_readlane_b32 s85, v197, 47
	v_readlane_b32 s86, v197, 48
	v_readlane_b32 s87, v197, 49
	s_mov_b32 s98, s58
.LBB0_838:
	s_mov_b32 s58, s98
	s_cmp_lg_u32 s39, 0x8000
	s_cbranch_scc1 .Lremap_done_7
	s_lshr_b32 s2, s98, 8
	s_bfe_u32 s4, s98, 0x30005
	s_and_b32 s5, s98, 31
	s_lshr_b32 s46, s2, 2
	s_lshl_b32 s46, s46, 3
	s_add_i32 s4, s4, s46
	s_and_b32 s2, s2, 3
	s_lshr_b32 s46, s2, 1
	s_xor_b32 s2, s2, s46
	s_and_b32 s2, s2, 1
	s_lshl_b32 s46, s46, 3
	s_lshr_b32 s47, s5, 2
	s_add_i32 s46, s46, s47
	s_and_b32 s5, s5, 3
	s_lshl_b32 s2, s2, 2
	s_add_i32 s2, s2, s5
	s_lshl_b32 s4, s4, 7
	s_lshl_b32 s2, s2, 4
	s_add_i32 s4, s4, s2
	s_add_i32 s58, s4, s46
.Lremap_done_7:
	s_lshl_b32 s38, s58, 7
	s_bfe_u32 s2, s58, 0x20002
	s_ashr_i32 s60, s58, 7
	s_lshl_b32 s4, s2, 4
	s_add_i32 s46, s4, s60
	v_mov_b32_e32 v1, v0
	s_lshl_b32 s5, s46, 9
	s_and_b32 s4, s38, 0x180
	s_waitcnt vmcnt(0) lgkmcnt(0)
	s_barrier
	s_or_b32 s5, s5, s4
	v_ashrrev_i32_e32 v2, 3, v1
	v_add_u32_e32 v4, s5, v2
	v_ashrrev_i32_e32 v5, 31, v4
	v_lshl_add_u64 v[4:5], v[4:5], 2, s[52:53]
	global_load_dword v6, v[4:5], off
	global_load_dword v8, v[4:5], off offset:256
	s_ashr_i32 s61, s60, 31
	v_lshrrev_b32_e32 v3, 4, v1
	s_bfe_u32 s59, s58, 0x30004
	s_lshl_b64 s[60:61], s[60:61], 22
	v_xor_b32_e32 v3, v3, v1
	s_add_u32 s5, s82, s60
	s_addc_u32 s33, s83, s61
	s_lshl_b32 s47, s59, 19
	v_lshlrev_b32_e32 v3, 4, v3
	s_add_u32 s60, s5, s47
	v_and_b32_e32 v66, 0x70, v3
	v_ashrrev_i32_e32 v3, 31, v2
	s_addc_u32 s61, s33, 0
	v_lshlrev_b64 v[2:3], 11, v[2:3]
	s_lshl_b32 s2, s2, 12
	v_lshl_add_u64 v[2:3], s[60:61], 0, v[2:3]
	v_mov_b32_e32 v14, v0
	v_lshl_add_u64 v[2:3], v[2:3], 0, v[66:67]
	s_mov_b64 s[60:61], 0x20000
	s_mov_b64 s[66:67], 0x20080
	s_mov_b64 s[68:69], 0x60080
	v_lshrrev_b32_e32 v15, 4, v14
	v_bfe_u32 v16, v14, 4, 2
	v_and_b32_e32 v17, 15, v14
	s_mov_b64 s[72:73], 0x20100
	s_mov_b64 s[74:75], 0x60100
	s_waitcnt vmcnt(1)
	v_ashrrev_i32_e32 v7, 31, v6
	s_waitcnt vmcnt(0)
	v_ashrrev_i32_e32 v9, 31, v8
	v_lshl_add_u64 v[4:5], v[6:7], 0, s[2:3]
	v_lshl_add_u64 v[6:7], v[8:9], 0, s[2:3]
	v_readfirstlane_b32 s2, v14
	v_lshl_add_u64 v[8:9], v[2:3], 0, s[60:61]
	s_mov_b64 s[60:61], 0x40000
	s_lshl_b32 s2, s2, 4
	v_lshlrev_b64 v[4:5], 11, v[4:5]
	v_lshl_add_u64 v[10:11], v[2:3], 0, s[60:61]
	s_mov_b64 s[60:61], 0x60000
	s_and_b32 s2, s2, 0xfffffc00
	v_lshl_add_u64 v[4:5], s[8:9], 0, v[4:5]
	v_lshlrev_b64 v[6:7], 11, v[6:7]
	v_lshl_add_u64 v[12:13], v[2:3], 0, s[60:61]
	s_add_i32 s61, s2, 0
	v_lshl_add_u64 v[4:5], v[4:5], 0, v[66:67]
	v_lshl_add_u64 v[6:7], s[8:9], 0, v[6:7]
	s_mov_b32 m0, s61
	s_add_i32 s47, s61, 0x2000
	v_lshl_add_u64 v[6:7], v[6:7], 0, v[66:67]
	global_load_lds_dwordx4 v[4:5], off
	s_mov_b32 m0, s47
	s_add_i32 s60, s61, 0x4000
	global_load_lds_dwordx4 v[6:7], off
	s_mov_b32 m0, s60
	s_add_i32 s33, s61, 0x6000
	global_load_lds_dwordx4 v[2:3], off
	s_mov_b32 m0, s33
	s_add_i32 s5, s61, 0x8000
	global_load_lds_dwordx4 v[8:9], off
	s_mov_b32 m0, s5
	s_add_i32 s2, s61, 0xa000
	global_load_lds_dwordx4 v[10:11], off
	s_mov_b32 m0, s2
	s_add_i32 s63, s61, 0xc000
	global_load_lds_dwordx4 v[12:13], off
	v_lshl_add_u64 v[8:9], v[4:5], 0, s[10:11]
	s_mov_b32 m0, s63
	s_add_i32 s62, s61, 0xe000
	global_load_lds_dwordx4 v[8:9], off
	v_lshl_add_u64 v[8:9], v[6:7], 0, s[10:11]
	s_mov_b32 m0, s62
	s_add_i32 s64, s61, 0x10000
	global_load_lds_dwordx4 v[8:9], off
	v_lshl_add_u64 v[8:9], v[2:3], 0, s[10:11]
	s_mov_b32 m0, s64
	s_add_i32 s65, s61, 0x12000
	global_load_lds_dwordx4 v[8:9], off
	v_lshl_add_u64 v[8:9], v[2:3], 0, s[66:67]
	s_mov_b32 m0, s65
	s_mov_b64 s[66:67], 0x40080
	global_load_lds_dwordx4 v[8:9], off
	v_lshl_add_u64 v[8:9], v[2:3], 0, s[66:67]
	s_add_i32 s66, s61, 0x14000
	s_mov_b32 m0, s66
	s_add_i32 s67, s61, 0x16000
	global_load_lds_dwordx4 v[8:9], off
	v_lshl_add_u64 v[8:9], v[2:3], 0, s[68:69]
	s_mov_b32 m0, s67
	s_mov_b32 s68, 0x1ffffc0
	global_load_lds_dwordx4 v[8:9], off
	v_bfe_u32 v8, v14, 1, 3
	v_lshrrev_b32_e32 v9, 2, v14
	v_and_or_b32 v9, v9, s68, v17
	v_lshlrev_b32_e32 v10, 7, v14
	v_bitop3_b32 v11, v15, v8, 3 bitop3:0x6c
	v_bitop3_b32 v8, v16, v8, 4 bitop3:0x36
	v_lshlrev_b32_e32 v9, 7, v9
	v_and_b32_e32 v60, 0x6780, v10
	v_lshlrev_b32_e32 v11, 4, v11
	v_lshlrev_b32_e32 v61, 4, v8
	v_add_u32_e32 v10, 0x4000, v60
	v_or_b32_e32 v64, v11, v9
	v_or_b32_e32 v66, v61, v9
	v_or_b32_e32 v9, v11, v60
	s_add_i32 s68, s61, 0x18000
	s_waitcnt vmcnt(6)
	s_barrier
	v_or_b32_e32 v65, v11, v10
	v_or_b32_e32 v152, v61, v10
	v_add_u32_e32 v8, 0, v64
	v_add_u32_e32 v9, 0, v9
	v_lshl_add_u64 v[10:11], v[4:5], 0, s[96:97]
	s_mov_b32 m0, s68
	s_add_i32 s69, s61, 0x1a000
	ds_read_b128 v[12:15], v8
	ds_read_b128 v[16:19], v8 offset:2048
	ds_read_b128 v[20:23], v8 offset:4096
	ds_read_b128 v[24:27], v8 offset:6144
	ds_read_b128 v[28:31], v9 offset:22528
	ds_read_b128 v[32:35], v9 offset:20480
	ds_read_b128 v[36:39], v9 offset:18432
	ds_read_b128 v[40:43], v9 offset:16384
	global_load_lds_dwordx4 v[10:11], off
	v_lshl_add_u64 v[10:11], v[6:7], 0, s[96:97]
	s_mov_b32 m0, s69
	s_add_i32 s70, s61, 0x1c000
	global_load_lds_dwordx4 v[10:11], off
	v_lshl_add_u64 v[10:11], v[2:3], 0, s[96:97]
	s_mov_b32 m0, s70
	s_add_i32 s71, s61, 0x1e000
	global_load_lds_dwordx4 v[10:11], off
	v_lshl_add_u64 v[10:11], v[2:3], 0, s[72:73]
	s_mov_b32 m0, s71
	s_mov_b64 s[72:73], 0x40100
	global_load_lds_dwordx4 v[10:11], off
	v_lshl_add_u64 v[10:11], v[2:3], 0, s[72:73]
	s_add_i32 s72, s61, 0x20000
	s_mov_b32 m0, s72
	s_add_i32 s73, s61, 0x22000
	global_load_lds_dwordx4 v[10:11], off
	v_lshl_add_u64 v[10:11], v[2:3], 0, s[74:75]
	s_mov_b32 m0, s73
	s_nop 0
	global_load_lds_dwordx4 v[10:11], off
	v_or_b32_e32 v11, v61, v60
	v_add_u32_e32 v10, 0, v66
	v_add_u32_e32 v11, 0, v11
	ds_read_b128 v[44:47], v10
	ds_read_b128 v[48:51], v10 offset:2048
	ds_read_b128 v[52:55], v10 offset:4096
	ds_read_b128 v[56:59], v10 offset:6144
	ds_read_b128 v[60:63], v11 offset:16384
	ds_read_b128 v[68:71], v11 offset:18432
	ds_read_b128 v[72:75], v11 offset:20480
	ds_read_b128 v[76:79], v11 offset:22528
	s_waitcnt lgkmcnt(8)
	v_mfma_f32_16x16x32_bf16 v[80:83], v[40:43], v[12:15], 0
	v_mfma_f32_16x16x32_bf16 v[84:87], v[36:39], v[12:15], 0
	v_mfma_f32_16x16x32_bf16 v[88:91], v[32:35], v[12:15], 0
	v_mfma_f32_16x16x32_bf16 v[92:95], v[28:31], v[12:15], 0
	v_mfma_f32_16x16x32_bf16 v[96:99], v[40:43], v[16:19], 0
	v_mfma_f32_16x16x32_bf16 v[100:103], v[36:39], v[16:19], 0
	v_mfma_f32_16x16x32_bf16 v[104:107], v[32:35], v[16:19], 0
	v_mfma_f32_16x16x32_bf16 v[14:17], v[28:31], v[16:19], 0
	v_mfma_f32_16x16x32_bf16 v[108:111], v[40:43], v[20:23], 0
	v_mfma_f32_16x16x32_bf16 v[112:115], v[36:39], v[20:23], 0
	v_mfma_f32_16x16x32_bf16 v[116:119], v[32:35], v[20:23], 0
	v_mfma_f32_16x16x32_bf16 v[18:21], v[28:31], v[20:23], 0
	v_mfma_f32_16x16x32_bf16 v[40:43], v[40:43], v[24:27], 0
	v_mfma_f32_16x16x32_bf16 v[36:39], v[36:39], v[24:27], 0
	v_mfma_f32_16x16x32_bf16 v[32:35], v[32:35], v[24:27], 0
	v_mfma_f32_16x16x32_bf16 v[22:25], v[28:31], v[24:27], 0
	s_waitcnt vmcnt(6) lgkmcnt(0)
	s_barrier
	v_add_u32_e32 v12, s56, v65
	ds_read_b128 v[26:29], v8 offset:49152
	ds_read_b128 v[120:123], v8 offset:51200
	ds_read_b128 v[124:127], v8 offset:53248
	ds_read_b128 v[128:131], v8 offset:55296
	ds_read_b128 v[132:135], v12
	ds_read_b128 v[136:139], v12 offset:2048
	ds_read_b128 v[140:143], v12 offset:4096
	ds_read_b128 v[144:147], v12 offset:6144
	v_mfma_f32_16x16x32_bf16 v[80:83], v[60:63], v[44:47], v[80:83]
	v_mfma_f32_16x16x32_bf16 v[84:87], v[68:71], v[44:47], v[84:87]
	v_mfma_f32_16x16x32_bf16 v[88:91], v[72:75], v[44:47], v[88:91]
	v_mfma_f32_16x16x32_bf16 v[44:47], v[76:79], v[44:47], v[92:95]
	v_mfma_f32_16x16x32_bf16 v[92:95], v[60:63], v[48:51], v[96:99]
	v_mfma_f32_16x16x32_bf16 v[96:99], v[68:71], v[48:51], v[100:103]
	v_mfma_f32_16x16x32_bf16 v[100:103], v[72:75], v[48:51], v[104:107]
	v_mfma_f32_16x16x32_bf16 v[14:17], v[76:79], v[48:51], v[14:17]
	v_mfma_f32_16x16x32_bf16 v[48:51], v[60:63], v[52:55], v[108:111]
	v_mfma_f32_16x16x32_bf16 v[104:107], v[68:71], v[52:55], v[112:115]
	v_mfma_f32_16x16x32_bf16 v[108:111], v[72:75], v[52:55], v[116:119]
	v_mfma_f32_16x16x32_bf16 v[18:21], v[76:79], v[52:55], v[18:21]
	v_mfma_f32_16x16x32_bf16 v[40:43], v[60:63], v[56:59], v[40:43]
	v_mfma_f32_16x16x32_bf16 v[36:39], v[68:71], v[56:59], v[36:39]
	v_mfma_f32_16x16x32_bf16 v[30:33], v[72:75], v[56:59], v[32:35]
	v_mfma_f32_16x16x32_bf16 v[22:25], v[76:79], v[56:59], v[22:25]
	s_mov_b32 m0, s61
	s_nop 0
	v_lshl_add_u64 v[34:35], v[4:5], 0, s[0:1]
	global_load_lds_dwordx4 v[34:35], off
	v_lshl_add_u64 v[34:35], v[6:7], 0, s[0:1]
	s_mov_b32 m0, s47
	s_mov_b64 s[74:75], 0x20180
	global_load_lds_dwordx4 v[34:35], off
	v_lshl_add_u64 v[34:35], v[2:3], 0, s[0:1]
	s_mov_b32 m0, s60
	v_add_u32_e32 v13, s56, v152
	global_load_lds_dwordx4 v[34:35], off
	v_lshl_add_u64 v[34:35], v[2:3], 0, s[74:75]
	s_mov_b32 m0, s33
	s_mov_b64 s[74:75], 0x40180
	global_load_lds_dwordx4 v[34:35], off
	v_lshl_add_u64 v[34:35], v[2:3], 0, s[74:75]
	s_mov_b32 m0, s5
	s_mov_b64 s[74:75], 0x60180
	global_load_lds_dwordx4 v[34:35], off
	v_lshl_add_u64 v[34:35], v[2:3], 0, s[74:75]
	s_mov_b32 m0, s2
	s_nop 0
	global_load_lds_dwordx4 v[34:35], off
	ds_read_b128 v[52:55], v10 offset:49152
	ds_read_b128 v[56:59], v10 offset:51200
	ds_read_b128 v[60:63], v10 offset:53248
	ds_read_b128 v[68:71], v10 offset:55296
	ds_read_b128 v[72:75], v13
	ds_read_b128 v[76:79], v13 offset:2048
	ds_read_b128 v[112:115], v13 offset:4096
	ds_read_b128 v[116:119], v13 offset:6144
	s_waitcnt lgkmcnt(8)
	v_mfma_f32_16x16x32_bf16 v[80:83], v[132:135], v[26:29], v[80:83]
	v_mfma_f32_16x16x32_bf16 v[84:87], v[136:139], v[26:29], v[84:87]
	v_mfma_f32_16x16x32_bf16 v[88:91], v[140:143], v[26:29], v[88:91]
	v_mfma_f32_16x16x32_bf16 v[26:29], v[144:147], v[26:29], v[44:47]
	v_mfma_f32_16x16x32_bf16 v[44:47], v[132:135], v[120:123], v[92:95]
	v_mfma_f32_16x16x32_bf16 v[92:95], v[136:139], v[120:123], v[96:99]
	v_mfma_f32_16x16x32_bf16 v[96:99], v[140:143], v[120:123], v[100:103]
	v_mfma_f32_16x16x32_bf16 v[100:103], v[144:147], v[120:123], v[14:17]
	v_mfma_f32_16x16x32_bf16 v[48:51], v[132:135], v[124:127], v[48:51]
	v_mfma_f32_16x16x32_bf16 v[104:107], v[136:139], v[124:127], v[104:107]
	v_mfma_f32_16x16x32_bf16 v[108:111], v[140:143], v[124:127], v[108:111]
	v_mfma_f32_16x16x32_bf16 v[16:19], v[144:147], v[124:127], v[18:21]
	v_mfma_f32_16x16x32_bf16 v[40:43], v[132:135], v[128:131], v[40:43]
	v_mfma_f32_16x16x32_bf16 v[34:37], v[136:139], v[128:131], v[36:39]
	v_mfma_f32_16x16x32_bf16 v[30:33], v[140:143], v[128:131], v[30:33]
	v_mfma_f32_16x16x32_bf16 v[20:23], v[144:147], v[128:131], v[22:25]
	s_waitcnt vmcnt(6) lgkmcnt(0)
	s_barrier
	v_add_u32_e32 v14, s57, v64
	v_add_u32_e32 v15, s57, v65
	ds_read_b128 v[120:123], v14
	ds_read_b128 v[124:127], v14 offset:2048
	ds_read_b128 v[128:131], v14 offset:4096
	ds_read_b128 v[132:135], v14 offset:6144
	ds_read_b128 v[136:139], v15
	ds_read_b128 v[140:143], v15 offset:2048
	ds_read_b128 v[144:147], v15 offset:4096
	ds_read_b128 v[148:151], v15 offset:6144
	v_mfma_f32_16x16x32_bf16 v[80:83], v[72:75], v[52:55], v[80:83]
	v_mfma_f32_16x16x32_bf16 v[84:87], v[76:79], v[52:55], v[84:87]
	v_mfma_f32_16x16x32_bf16 v[88:91], v[112:115], v[52:55], v[88:91]
	v_mfma_f32_16x16x32_bf16 v[24:27], v[116:119], v[52:55], v[26:29]
	v_mfma_f32_16x16x32_bf16 v[44:47], v[72:75], v[56:59], v[44:47]
	v_mfma_f32_16x16x32_bf16 v[52:55], v[76:79], v[56:59], v[92:95]
	v_mfma_f32_16x16x32_bf16 v[92:95], v[112:115], v[56:59], v[96:99]
	v_mfma_f32_16x16x32_bf16 v[56:59], v[116:119], v[56:59], v[100:103]
	v_mfma_f32_16x16x32_bf16 v[48:51], v[72:75], v[60:63], v[48:51]
	v_mfma_f32_16x16x32_bf16 v[96:99], v[76:79], v[60:63], v[104:107]
	v_mfma_f32_16x16x32_bf16 v[100:103], v[112:115], v[60:63], v[108:111]
	v_mfma_f32_16x16x32_bf16 v[60:63], v[116:119], v[60:63], v[16:19]
	v_mfma_f32_16x16x32_bf16 v[38:41], v[72:75], v[68:71], v[40:43]
	v_mfma_f32_16x16x32_bf16 v[34:37], v[76:79], v[68:71], v[34:37]
	v_mfma_f32_16x16x32_bf16 v[28:31], v[112:115], v[68:71], v[30:33]
	v_mfma_f32_16x16x32_bf16 v[18:21], v[116:119], v[68:71], v[20:23]
	s_mov_b32 m0, s63
	v_lshl_add_u64 v[16:17], v[4:5], 0, s[6:7]
	global_load_lds_dwordx4 v[16:17], off
	v_lshl_add_u64 v[16:17], v[6:7], 0, s[6:7]
	s_mov_b32 m0, s62
	s_mov_b64 s[74:75], 0x20200
	global_load_lds_dwordx4 v[16:17], off
	v_lshl_add_u64 v[16:17], v[2:3], 0, s[6:7]
	s_mov_b32 m0, s64
	s_nop 0
	global_load_lds_dwordx4 v[16:17], off
	v_lshl_add_u64 v[16:17], v[2:3], 0, s[74:75]
	s_mov_b32 m0, s65
	s_mov_b64 s[74:75], 0x40200
	global_load_lds_dwordx4 v[16:17], off
	v_lshl_add_u64 v[16:17], v[2:3], 0, s[74:75]
	s_mov_b32 m0, s66
	s_mov_b64 s[74:75], 0x60200
	global_load_lds_dwordx4 v[16:17], off
	v_lshl_add_u64 v[16:17], v[2:3], 0, s[74:75]
	s_mov_b32 m0, s67
	s_nop 0
	global_load_lds_dwordx4 v[16:17], off
	v_add_u32_e32 v16, s57, v66
	v_add_u32_e32 v17, s57, v152
	ds_read_b128 v[68:71], v16
	ds_read_b128 v[72:75], v16 offset:2048
	ds_read_b128 v[76:79], v16 offset:4096
	ds_read_b128 v[104:107], v16 offset:6144
	ds_read_b128 v[108:111], v17
	ds_read_b128 v[112:115], v17 offset:2048
	ds_read_b128 v[116:119], v17 offset:4096
	ds_read_b128 v[152:155], v17 offset:6144
	s_waitcnt lgkmcnt(8)
	v_mfma_f32_16x16x32_bf16 v[80:83], v[136:139], v[120:123], v[80:83]
	v_mfma_f32_16x16x32_bf16 v[84:87], v[140:143], v[120:123], v[84:87]
	v_mfma_f32_16x16x32_bf16 v[88:91], v[144:147], v[120:123], v[88:91]
	v_mfma_f32_16x16x32_bf16 v[22:25], v[148:151], v[120:123], v[24:27]
	v_mfma_f32_16x16x32_bf16 v[42:45], v[136:139], v[124:127], v[44:47]
	v_mfma_f32_16x16x32_bf16 v[52:55], v[140:143], v[124:127], v[52:55]
	v_mfma_f32_16x16x32_bf16 v[92:95], v[144:147], v[124:127], v[92:95]
	v_mfma_f32_16x16x32_bf16 v[56:59], v[148:151], v[124:127], v[56:59]
	v_mfma_f32_16x16x32_bf16 v[46:49], v[136:139], v[128:131], v[48:51]
	v_mfma_f32_16x16x32_bf16 v[96:99], v[140:143], v[128:131], v[96:99]
	v_mfma_f32_16x16x32_bf16 v[100:103], v[144:147], v[128:131], v[100:103]
	v_mfma_f32_16x16x32_bf16 v[60:63], v[148:151], v[128:131], v[60:63]
	v_mfma_f32_16x16x32_bf16 v[38:41], v[136:139], v[132:135], v[38:41]
	v_mfma_f32_16x16x32_bf16 v[32:35], v[140:143], v[132:135], v[34:37]
	v_mfma_f32_16x16x32_bf16 v[26:29], v[144:147], v[132:135], v[28:31]
	v_mfma_f32_16x16x32_bf16 v[18:21], v[148:151], v[132:135], v[18:21]
	s_waitcnt vmcnt(6) lgkmcnt(0)
	s_barrier
	ds_read_b128 v[120:123], v8
	ds_read_b128 v[124:127], v8 offset:2048
	ds_read_b128 v[128:131], v8 offset:4096
	ds_read_b128 v[132:135], v8 offset:6144
	ds_read_b128 v[136:139], v9 offset:16384
	ds_read_b128 v[140:143], v9 offset:18432
	ds_read_b128 v[144:147], v9 offset:20480
	ds_read_b128 v[148:151], v9 offset:22528
	v_mfma_f32_16x16x32_bf16 v[80:83], v[108:111], v[68:71], v[80:83]
	v_mfma_f32_16x16x32_bf16 v[84:87], v[112:115], v[68:71], v[84:87]
	v_mfma_f32_16x16x32_bf16 v[88:91], v[116:119], v[68:71], v[88:91]
	v_mfma_f32_16x16x32_bf16 v[22:25], v[152:155], v[68:71], v[22:25]
	v_mfma_f32_16x16x32_bf16 v[42:45], v[108:111], v[72:75], v[42:45]
	v_mfma_f32_16x16x32_bf16 v[50:53], v[112:115], v[72:75], v[52:55]
	v_mfma_f32_16x16x32_bf16 v[68:71], v[116:119], v[72:75], v[92:95]
	v_mfma_f32_16x16x32_bf16 v[54:57], v[152:155], v[72:75], v[56:59]
	v_mfma_f32_16x16x32_bf16 v[46:49], v[108:111], v[76:79], v[46:49]
	v_mfma_f32_16x16x32_bf16 v[72:75], v[112:115], v[76:79], v[96:99]
	v_mfma_f32_16x16x32_bf16 v[92:95], v[116:119], v[76:79], v[100:103]
	v_mfma_f32_16x16x32_bf16 v[58:61], v[152:155], v[76:79], v[60:63]
	v_mfma_f32_16x16x32_bf16 v[36:39], v[108:111], v[104:107], v[38:41]
	v_mfma_f32_16x16x32_bf16 v[30:33], v[112:115], v[104:107], v[32:35]
	v_mfma_f32_16x16x32_bf16 v[26:29], v[116:119], v[104:107], v[26:29]
	v_mfma_f32_16x16x32_bf16 v[18:21], v[152:155], v[104:107], v[18:21]
	s_mov_b32 m0, s68
	v_lshl_add_u64 v[34:35], v[4:5], 0, s[12:13]
	global_load_lds_dwordx4 v[34:35], off
	v_lshl_add_u64 v[34:35], v[6:7], 0, s[12:13]
	s_mov_b32 m0, s69
	s_mov_b64 s[74:75], 0x20280
	global_load_lds_dwordx4 v[34:35], off
	v_lshl_add_u64 v[34:35], v[2:3], 0, s[12:13]
	s_mov_b32 m0, s70
	s_nop 0
	global_load_lds_dwordx4 v[34:35], off
	v_lshl_add_u64 v[34:35], v[2:3], 0, s[74:75]
	s_mov_b32 m0, s71
	s_mov_b64 s[74:75], 0x40280
	global_load_lds_dwordx4 v[34:35], off
	v_lshl_add_u64 v[34:35], v[2:3], 0, s[74:75]
	s_mov_b32 m0, s72
	s_mov_b64 s[74:75], 0x60280
	global_load_lds_dwordx4 v[34:35], off
	v_lshl_add_u64 v[34:35], v[2:3], 0, s[74:75]
	s_mov_b32 m0, s73
	s_nop 0
	global_load_lds_dwordx4 v[34:35], off
	ds_read_b128 v[62:65], v10
	ds_read_b128 v[76:79], v10 offset:2048
	ds_read_b128 v[96:99], v10 offset:4096
	ds_read_b128 v[100:103], v10 offset:6144
	ds_read_b128 v[104:107], v11 offset:16384
	ds_read_b128 v[108:111], v11 offset:18432
	ds_read_b128 v[112:115], v11 offset:20480
	ds_read_b128 v[116:119], v11 offset:22528
	s_waitcnt lgkmcnt(8)
	v_mfma_f32_16x16x32_bf16 v[80:83], v[136:139], v[120:123], v[80:83]
	v_mfma_f32_16x16x32_bf16 v[84:87], v[140:143], v[120:123], v[84:87]
	v_mfma_f32_16x16x32_bf16 v[88:91], v[144:147], v[120:123], v[88:91]
	v_mfma_f32_16x16x32_bf16 v[22:25], v[148:151], v[120:123], v[22:25]
	v_mfma_f32_16x16x32_bf16 v[40:43], v[136:139], v[124:127], v[42:45]
	v_mfma_f32_16x16x32_bf16 v[50:53], v[140:143], v[124:127], v[50:53]
	v_mfma_f32_16x16x32_bf16 v[68:71], v[144:147], v[124:127], v[68:71]
	v_mfma_f32_16x16x32_bf16 v[54:57], v[148:151], v[124:127], v[54:57]
	v_mfma_f32_16x16x32_bf16 v[44:47], v[136:139], v[128:131], v[46:49]
	v_mfma_f32_16x16x32_bf16 v[72:75], v[140:143], v[128:131], v[72:75]
	v_mfma_f32_16x16x32_bf16 v[92:95], v[144:147], v[128:131], v[92:95]
	v_mfma_f32_16x16x32_bf16 v[58:61], v[148:151], v[128:131], v[58:61]
	v_mfma_f32_16x16x32_bf16 v[34:37], v[136:139], v[132:135], v[36:39]
	v_mfma_f32_16x16x32_bf16 v[30:33], v[140:143], v[132:135], v[30:33]
	v_mfma_f32_16x16x32_bf16 v[26:29], v[144:147], v[132:135], v[26:29]
	v_mfma_f32_16x16x32_bf16 v[18:21], v[148:151], v[132:135], v[18:21]
	s_waitcnt vmcnt(6) lgkmcnt(0)
	s_barrier
	ds_read_b128 v[120:123], v8 offset:49152
	ds_read_b128 v[124:127], v8 offset:51200
	ds_read_b128 v[128:131], v8 offset:53248
	ds_read_b128 v[132:135], v8 offset:55296
	ds_read_b128 v[136:139], v12
	ds_read_b128 v[140:143], v12 offset:2048
	ds_read_b128 v[144:147], v12 offset:4096
	ds_read_b128 v[148:151], v12 offset:6144
	v_mfma_f32_16x16x32_bf16 v[80:83], v[104:107], v[62:65], v[80:83]
	v_mfma_f32_16x16x32_bf16 v[84:87], v[108:111], v[62:65], v[84:87]
	v_mfma_f32_16x16x32_bf16 v[88:91], v[112:115], v[62:65], v[88:91]
	v_mfma_f32_16x16x32_bf16 v[22:25], v[116:119], v[62:65], v[22:25]
	v_mfma_f32_16x16x32_bf16 v[38:41], v[104:107], v[76:79], v[40:43]
	v_mfma_f32_16x16x32_bf16 v[48:51], v[108:111], v[76:79], v[50:53]
	v_mfma_f32_16x16x32_bf16 v[62:65], v[112:115], v[76:79], v[68:71]
	v_mfma_f32_16x16x32_bf16 v[52:55], v[116:119], v[76:79], v[54:57]
	v_mfma_f32_16x16x32_bf16 v[42:45], v[104:107], v[96:99], v[44:47]
	v_mfma_f32_16x16x32_bf16 v[68:71], v[108:111], v[96:99], v[72:75]
	v_mfma_f32_16x16x32_bf16 v[72:75], v[112:115], v[96:99], v[92:95]
	v_mfma_f32_16x16x32_bf16 v[56:59], v[116:119], v[96:99], v[58:61]
	v_mfma_f32_16x16x32_bf16 v[34:37], v[104:107], v[100:103], v[34:37]
	v_mfma_f32_16x16x32_bf16 v[30:33], v[108:111], v[100:103], v[30:33]
	v_mfma_f32_16x16x32_bf16 v[26:29], v[112:115], v[100:103], v[26:29]
	v_mfma_f32_16x16x32_bf16 v[18:21], v[116:119], v[100:103], v[18:21]
	s_mov_b32 m0, s61
	v_lshl_add_u64 v[46:47], v[4:5], 0, s[14:15]
	global_load_lds_dwordx4 v[46:47], off
	v_lshl_add_u64 v[46:47], v[6:7], 0, s[14:15]
	s_mov_b32 m0, s47
	s_mov_b64 s[74:75], 0x20300
	global_load_lds_dwordx4 v[46:47], off
	v_lshl_add_u64 v[46:47], v[2:3], 0, s[14:15]
	s_mov_b32 m0, s60
	s_nop 0
	global_load_lds_dwordx4 v[46:47], off
	v_lshl_add_u64 v[46:47], v[2:3], 0, s[74:75]
	s_mov_b32 m0, s33
	s_mov_b64 s[74:75], 0x40300
	global_load_lds_dwordx4 v[46:47], off
	v_lshl_add_u64 v[46:47], v[2:3], 0, s[74:75]
	s_mov_b32 m0, s5
	s_mov_b64 s[74:75], 0x60300
	global_load_lds_dwordx4 v[46:47], off
	v_lshl_add_u64 v[46:47], v[2:3], 0, s[74:75]
	s_mov_b32 m0, s2
	s_nop 0
	global_load_lds_dwordx4 v[46:47], off
	ds_read_b128 v[76:79], v10 offset:49152
	ds_read_b128 v[92:95], v10 offset:51200
	ds_read_b128 v[96:99], v10 offset:53248
	ds_read_b128 v[100:103], v10 offset:55296
	ds_read_b128 v[104:107], v13
	ds_read_b128 v[108:111], v13 offset:2048
	ds_read_b128 v[112:115], v13 offset:4096
	ds_read_b128 v[116:119], v13 offset:6144
	s_waitcnt lgkmcnt(8)
	v_mfma_f32_16x16x32_bf16 v[80:83], v[136:139], v[120:123], v[80:83]
	v_mfma_f32_16x16x32_bf16 v[84:87], v[140:143], v[120:123], v[84:87]
	v_mfma_f32_16x16x32_bf16 v[88:91], v[144:147], v[120:123], v[88:91]
	v_mfma_f32_16x16x32_bf16 v[22:25], v[148:151], v[120:123], v[22:25]
	v_mfma_f32_16x16x32_bf16 v[38:41], v[136:139], v[124:127], v[38:41]
	v_mfma_f32_16x16x32_bf16 v[46:49], v[140:143], v[124:127], v[48:51]
	v_mfma_f32_16x16x32_bf16 v[60:63], v[144:147], v[124:127], v[62:65]
	v_mfma_f32_16x16x32_bf16 v[50:53], v[148:151], v[124:127], v[52:55]
	v_mfma_f32_16x16x32_bf16 v[42:45], v[136:139], v[128:131], v[42:45]
	v_mfma_f32_16x16x32_bf16 v[68:71], v[140:143], v[128:131], v[68:71]
	v_mfma_f32_16x16x32_bf16 v[72:75], v[144:147], v[128:131], v[72:75]
	v_mfma_f32_16x16x32_bf16 v[54:57], v[148:151], v[128:131], v[56:59]
	v_mfma_f32_16x16x32_bf16 v[34:37], v[136:139], v[132:135], v[34:37]
	v_mfma_f32_16x16x32_bf16 v[30:33], v[140:143], v[132:135], v[30:33]
	v_mfma_f32_16x16x32_bf16 v[26:29], v[144:147], v[132:135], v[26:29]
	v_mfma_f32_16x16x32_bf16 v[18:21], v[148:151], v[132:135], v[18:21]
	s_waitcnt vmcnt(6) lgkmcnt(0)
	s_barrier
	ds_read_b128 v[120:123], v14
	ds_read_b128 v[124:127], v14 offset:2048
	ds_read_b128 v[128:131], v14 offset:4096
	ds_read_b128 v[132:135], v14 offset:6144
	ds_read_b128 v[136:139], v15
	ds_read_b128 v[140:143], v15 offset:2048
	ds_read_b128 v[144:147], v15 offset:4096
	ds_read_b128 v[148:151], v15 offset:6144
	v_mfma_f32_16x16x32_bf16 v[80:83], v[104:107], v[76:79], v[80:83]
	v_mfma_f32_16x16x32_bf16 v[84:87], v[108:111], v[76:79], v[84:87]
	v_mfma_f32_16x16x32_bf16 v[88:91], v[112:115], v[76:79], v[88:91]
	v_mfma_f32_16x16x32_bf16 v[22:25], v[116:119], v[76:79], v[22:25]
	v_mfma_f32_16x16x32_bf16 v[38:41], v[104:107], v[92:95], v[38:41]
	v_mfma_f32_16x16x32_bf16 v[46:49], v[108:111], v[92:95], v[46:49]
	v_mfma_f32_16x16x32_bf16 v[58:61], v[112:115], v[92:95], v[60:63]
	v_mfma_f32_16x16x32_bf16 v[50:53], v[116:119], v[92:95], v[50:53]
	v_mfma_f32_16x16x32_bf16 v[42:45], v[104:107], v[96:99], v[42:45]
	v_mfma_f32_16x16x32_bf16 v[62:65], v[108:111], v[96:99], v[68:71]
	v_mfma_f32_16x16x32_bf16 v[68:71], v[112:115], v[96:99], v[72:75]
	v_mfma_f32_16x16x32_bf16 v[54:57], v[116:119], v[96:99], v[54:57]
	v_mfma_f32_16x16x32_bf16 v[34:37], v[104:107], v[100:103], v[34:37]
	v_mfma_f32_16x16x32_bf16 v[30:33], v[108:111], v[100:103], v[30:33]
	v_mfma_f32_16x16x32_bf16 v[26:29], v[112:115], v[100:103], v[26:29]
	v_mfma_f32_16x16x32_bf16 v[18:21], v[116:119], v[100:103], v[18:21]
	s_mov_b32 m0, s63
	v_lshl_add_u64 v[72:73], v[4:5], 0, s[16:17]
	global_load_lds_dwordx4 v[72:73], off
	v_lshl_add_u64 v[72:73], v[6:7], 0, s[16:17]
	s_mov_b32 m0, s62
	s_mov_b64 s[74:75], 0x20380
	global_load_lds_dwordx4 v[72:73], off
	v_lshl_add_u64 v[72:73], v[2:3], 0, s[16:17]
	s_mov_b32 m0, s64
	s_nop 0
	global_load_lds_dwordx4 v[72:73], off
	v_lshl_add_u64 v[72:73], v[2:3], 0, s[74:75]
	s_mov_b32 m0, s65
	s_mov_b64 s[74:75], 0x40380
	global_load_lds_dwordx4 v[72:73], off
	v_lshl_add_u64 v[72:73], v[2:3], 0, s[74:75]
	s_mov_b32 m0, s66
	s_mov_b64 s[74:75], 0x60380
	global_load_lds_dwordx4 v[72:73], off
	v_lshl_add_u64 v[72:73], v[2:3], 0, s[74:75]
	s_mov_b32 m0, s67
	s_nop 0
	global_load_lds_dwordx4 v[72:73], off
	ds_read_b128 v[72:75], v16
	ds_read_b128 v[76:79], v16 offset:2048
	ds_read_b128 v[92:95], v16 offset:4096
	ds_read_b128 v[96:99], v16 offset:6144
	ds_read_b128 v[100:103], v17
	ds_read_b128 v[104:107], v17 offset:2048
	ds_read_b128 v[108:111], v17 offset:4096
	ds_read_b128 v[112:115], v17 offset:6144
	s_waitcnt lgkmcnt(8)
	v_mfma_f32_16x16x32_bf16 v[80:83], v[136:139], v[120:123], v[80:83]
	v_mfma_f32_16x16x32_bf16 v[84:87], v[140:143], v[120:123], v[84:87]
	v_mfma_f32_16x16x32_bf16 v[88:91], v[144:147], v[120:123], v[88:91]
	v_mfma_f32_16x16x32_bf16 v[22:25], v[148:151], v[120:123], v[22:25]
	v_mfma_f32_16x16x32_bf16 v[38:41], v[136:139], v[124:127], v[38:41]
	v_mfma_f32_16x16x32_bf16 v[46:49], v[140:143], v[124:127], v[46:49]
	v_mfma_f32_16x16x32_bf16 v[58:61], v[144:147], v[124:127], v[58:61]
	v_mfma_f32_16x16x32_bf16 v[50:53], v[148:151], v[124:127], v[50:53]
	v_mfma_f32_16x16x32_bf16 v[42:45], v[136:139], v[128:131], v[42:45]
	v_mfma_f32_16x16x32_bf16 v[62:65], v[140:143], v[128:131], v[62:65]
	v_mfma_f32_16x16x32_bf16 v[68:71], v[144:147], v[128:131], v[68:71]
	v_mfma_f32_16x16x32_bf16 v[54:57], v[148:151], v[128:131], v[54:57]
	v_mfma_f32_16x16x32_bf16 v[34:37], v[136:139], v[132:135], v[34:37]
	v_mfma_f32_16x16x32_bf16 v[30:33], v[140:143], v[132:135], v[30:33]
	v_mfma_f32_16x16x32_bf16 v[26:29], v[144:147], v[132:135], v[26:29]
	v_mfma_f32_16x16x32_bf16 v[18:21], v[148:151], v[132:135], v[18:21]
	s_waitcnt vmcnt(6) lgkmcnt(0)
	s_barrier
	ds_read_b128 v[116:119], v8
	ds_read_b128 v[120:123], v8 offset:2048
	ds_read_b128 v[124:127], v8 offset:4096
	ds_read_b128 v[128:131], v8 offset:6144
	ds_read_b128 v[132:135], v9 offset:16384
	ds_read_b128 v[136:139], v9 offset:18432
	ds_read_b128 v[140:143], v9 offset:20480
	ds_read_b128 v[144:147], v9 offset:22528
	v_mfma_f32_16x16x32_bf16 v[80:83], v[100:103], v[72:75], v[80:83]
	v_mfma_f32_16x16x32_bf16 v[84:87], v[104:107], v[72:75], v[84:87]
	v_mfma_f32_16x16x32_bf16 v[88:91], v[108:111], v[72:75], v[88:91]
	v_mfma_f32_16x16x32_bf16 v[22:25], v[112:115], v[72:75], v[22:25]
	v_mfma_f32_16x16x32_bf16 v[38:41], v[100:103], v[76:79], v[38:41]
	v_mfma_f32_16x16x32_bf16 v[46:49], v[104:107], v[76:79], v[46:49]
	v_mfma_f32_16x16x32_bf16 v[58:61], v[108:111], v[76:79], v[58:61]
	v_mfma_f32_16x16x32_bf16 v[50:53], v[112:115], v[76:79], v[50:53]
	v_mfma_f32_16x16x32_bf16 v[42:45], v[100:103], v[92:95], v[42:45]
	v_mfma_f32_16x16x32_bf16 v[62:65], v[104:107], v[92:95], v[62:65]
	v_mfma_f32_16x16x32_bf16 v[68:71], v[108:111], v[92:95], v[68:71]
	v_mfma_f32_16x16x32_bf16 v[54:57], v[112:115], v[92:95], v[54:57]
	v_mfma_f32_16x16x32_bf16 v[34:37], v[100:103], v[96:99], v[34:37]
	v_mfma_f32_16x16x32_bf16 v[30:33], v[104:107], v[96:99], v[30:33]
	v_mfma_f32_16x16x32_bf16 v[26:29], v[108:111], v[96:99], v[26:29]
	v_mfma_f32_16x16x32_bf16 v[18:21], v[112:115], v[96:99], v[18:21]
	s_mov_b32 m0, s68
	v_lshl_add_u64 v[72:73], v[4:5], 0, s[18:19]
	global_load_lds_dwordx4 v[72:73], off
	v_lshl_add_u64 v[72:73], v[6:7], 0, s[18:19]
	s_mov_b32 m0, s69
	s_mov_b64 s[74:75], 0x20400
	global_load_lds_dwordx4 v[72:73], off
	v_lshl_add_u64 v[72:73], v[2:3], 0, s[18:19]
	s_mov_b32 m0, s70
	s_nop 0
	global_load_lds_dwordx4 v[72:73], off
	v_lshl_add_u64 v[72:73], v[2:3], 0, s[74:75]
	s_mov_b32 m0, s71
	s_mov_b64 s[74:75], 0x40400
	global_load_lds_dwordx4 v[72:73], off
	v_lshl_add_u64 v[72:73], v[2:3], 0, s[74:75]
	s_mov_b32 m0, s72
	s_mov_b64 s[74:75], 0x60400
	global_load_lds_dwordx4 v[72:73], off
	v_lshl_add_u64 v[72:73], v[2:3], 0, s[74:75]
	s_mov_b32 m0, s73
	s_nop 0
	global_load_lds_dwordx4 v[72:73], off
	ds_read_b128 v[72:75], v10
	ds_read_b128 v[76:79], v10 offset:2048
	ds_read_b128 v[92:95], v10 offset:4096
	ds_read_b128 v[96:99], v10 offset:6144
	ds_read_b128 v[100:103], v11 offset:16384
	ds_read_b128 v[104:107], v11 offset:18432
	ds_read_b128 v[108:111], v11 offset:20480
	ds_read_b128 v[112:115], v11 offset:22528
	s_waitcnt lgkmcnt(8)
	v_mfma_f32_16x16x32_bf16 v[80:83], v[132:135], v[116:119], v[80:83]
	v_mfma_f32_16x16x32_bf16 v[84:87], v[136:139], v[116:119], v[84:87]
	v_mfma_f32_16x16x32_bf16 v[88:91], v[140:143], v[116:119], v[88:91]
	v_mfma_f32_16x16x32_bf16 v[22:25], v[144:147], v[116:119], v[22:25]
	v_mfma_f32_16x16x32_bf16 v[38:41], v[132:135], v[120:123], v[38:41]
	v_mfma_f32_16x16x32_bf16 v[46:49], v[136:139], v[120:123], v[46:49]
	v_mfma_f32_16x16x32_bf16 v[58:61], v[140:143], v[120:123], v[58:61]
	v_mfma_f32_16x16x32_bf16 v[50:53], v[144:147], v[120:123], v[50:53]
	v_mfma_f32_16x16x32_bf16 v[42:45], v[132:135], v[124:127], v[42:45]
	v_mfma_f32_16x16x32_bf16 v[62:65], v[136:139], v[124:127], v[62:65]
	v_mfma_f32_16x16x32_bf16 v[68:71], v[140:143], v[124:127], v[68:71]
	v_mfma_f32_16x16x32_bf16 v[54:57], v[144:147], v[124:127], v[54:57]
	v_mfma_f32_16x16x32_bf16 v[34:37], v[132:135], v[128:131], v[34:37]
	v_mfma_f32_16x16x32_bf16 v[30:33], v[136:139], v[128:131], v[30:33]
	v_mfma_f32_16x16x32_bf16 v[26:29], v[140:143], v[128:131], v[26:29]
	v_mfma_f32_16x16x32_bf16 v[18:21], v[144:147], v[128:131], v[18:21]
	s_waitcnt vmcnt(6) lgkmcnt(0)
	s_barrier
	ds_read_b128 v[116:119], v8 offset:49152
	ds_read_b128 v[120:123], v8 offset:51200
	ds_read_b128 v[124:127], v8 offset:53248
	ds_read_b128 v[128:131], v8 offset:55296
	ds_read_b128 v[132:135], v12
	ds_read_b128 v[136:139], v12 offset:2048
	ds_read_b128 v[140:143], v12 offset:4096
	ds_read_b128 v[144:147], v12 offset:6144
	v_mfma_f32_16x16x32_bf16 v[80:83], v[100:103], v[72:75], v[80:83]
	v_mfma_f32_16x16x32_bf16 v[84:87], v[104:107], v[72:75], v[84:87]
	v_mfma_f32_16x16x32_bf16 v[88:91], v[108:111], v[72:75], v[88:91]
	v_mfma_f32_16x16x32_bf16 v[22:25], v[112:115], v[72:75], v[22:25]
	v_mfma_f32_16x16x32_bf16 v[38:41], v[100:103], v[76:79], v[38:41]
	v_mfma_f32_16x16x32_bf16 v[46:49], v[104:107], v[76:79], v[46:49]
	v_mfma_f32_16x16x32_bf16 v[58:61], v[108:111], v[76:79], v[58:61]
	v_mfma_f32_16x16x32_bf16 v[50:53], v[112:115], v[76:79], v[50:53]
	v_mfma_f32_16x16x32_bf16 v[42:45], v[100:103], v[92:95], v[42:45]
	v_mfma_f32_16x16x32_bf16 v[62:65], v[104:107], v[92:95], v[62:65]
	v_mfma_f32_16x16x32_bf16 v[68:71], v[108:111], v[92:95], v[68:71]
	v_mfma_f32_16x16x32_bf16 v[54:57], v[112:115], v[92:95], v[54:57]
	v_mfma_f32_16x16x32_bf16 v[34:37], v[100:103], v[96:99], v[34:37]
	v_mfma_f32_16x16x32_bf16 v[30:33], v[104:107], v[96:99], v[30:33]
	v_mfma_f32_16x16x32_bf16 v[26:29], v[108:111], v[96:99], v[26:29]
	v_mfma_f32_16x16x32_bf16 v[18:21], v[112:115], v[96:99], v[18:21]
	s_mov_b32 m0, s61
	v_lshl_add_u64 v[72:73], v[4:5], 0, s[20:21]
	global_load_lds_dwordx4 v[72:73], off
	v_lshl_add_u64 v[72:73], v[6:7], 0, s[20:21]
	s_mov_b32 m0, s47
	s_mov_b64 s[74:75], 0x20480
	global_load_lds_dwordx4 v[72:73], off
	v_lshl_add_u64 v[72:73], v[2:3], 0, s[20:21]
	s_mov_b32 m0, s60
	s_nop 0
	global_load_lds_dwordx4 v[72:73], off
	v_lshl_add_u64 v[72:73], v[2:3], 0, s[74:75]
	s_mov_b32 m0, s33
	s_mov_b64 s[74:75], 0x40480
	global_load_lds_dwordx4 v[72:73], off
	v_lshl_add_u64 v[72:73], v[2:3], 0, s[74:75]
	s_mov_b32 m0, s5
	s_mov_b64 s[74:75], 0x60480
	global_load_lds_dwordx4 v[72:73], off
	v_lshl_add_u64 v[72:73], v[2:3], 0, s[74:75]
	s_mov_b32 m0, s2
	s_nop 0
	global_load_lds_dwordx4 v[72:73], off
	ds_read_b128 v[72:75], v10 offset:49152
	ds_read_b128 v[76:79], v10 offset:51200
	ds_read_b128 v[92:95], v10 offset:53248
	ds_read_b128 v[96:99], v10 offset:55296
	ds_read_b128 v[100:103], v13
	ds_read_b128 v[104:107], v13 offset:2048
	ds_read_b128 v[108:111], v13 offset:4096
	ds_read_b128 v[112:115], v13 offset:6144
	s_waitcnt lgkmcnt(8)
	v_mfma_f32_16x16x32_bf16 v[80:83], v[132:135], v[116:119], v[80:83]
	v_mfma_f32_16x16x32_bf16 v[84:87], v[136:139], v[116:119], v[84:87]
	v_mfma_f32_16x16x32_bf16 v[88:91], v[140:143], v[116:119], v[88:91]
	v_mfma_f32_16x16x32_bf16 v[22:25], v[144:147], v[116:119], v[22:25]
	v_mfma_f32_16x16x32_bf16 v[38:41], v[132:135], v[120:123], v[38:41]
	v_mfma_f32_16x16x32_bf16 v[46:49], v[136:139], v[120:123], v[46:49]
	v_mfma_f32_16x16x32_bf16 v[58:61], v[140:143], v[120:123], v[58:61]
	v_mfma_f32_16x16x32_bf16 v[50:53], v[144:147], v[120:123], v[50:53]
	v_mfma_f32_16x16x32_bf16 v[42:45], v[132:135], v[124:127], v[42:45]
	v_mfma_f32_16x16x32_bf16 v[62:65], v[136:139], v[124:127], v[62:65]
	v_mfma_f32_16x16x32_bf16 v[68:71], v[140:143], v[124:127], v[68:71]
	v_mfma_f32_16x16x32_bf16 v[54:57], v[144:147], v[124:127], v[54:57]
	v_mfma_f32_16x16x32_bf16 v[34:37], v[132:135], v[128:131], v[34:37]
	v_mfma_f32_16x16x32_bf16 v[30:33], v[136:139], v[128:131], v[30:33]
	v_mfma_f32_16x16x32_bf16 v[26:29], v[140:143], v[128:131], v[26:29]
	v_mfma_f32_16x16x32_bf16 v[18:21], v[144:147], v[128:131], v[18:21]
	s_waitcnt vmcnt(6) lgkmcnt(0)
	s_barrier
	ds_read_b128 v[116:119], v14
	ds_read_b128 v[120:123], v14 offset:2048
	ds_read_b128 v[124:127], v14 offset:4096
	ds_read_b128 v[128:131], v14 offset:6144
	ds_read_b128 v[132:135], v15
	ds_read_b128 v[136:139], v15 offset:2048
	ds_read_b128 v[140:143], v15 offset:4096
	ds_read_b128 v[144:147], v15 offset:6144
	v_mfma_f32_16x16x32_bf16 v[80:83], v[100:103], v[72:75], v[80:83]
	v_mfma_f32_16x16x32_bf16 v[84:87], v[104:107], v[72:75], v[84:87]
	v_mfma_f32_16x16x32_bf16 v[88:91], v[108:111], v[72:75], v[88:91]
	v_mfma_f32_16x16x32_bf16 v[22:25], v[112:115], v[72:75], v[22:25]
	v_mfma_f32_16x16x32_bf16 v[38:41], v[100:103], v[76:79], v[38:41]
	v_mfma_f32_16x16x32_bf16 v[46:49], v[104:107], v[76:79], v[46:49]
	v_mfma_f32_16x16x32_bf16 v[58:61], v[108:111], v[76:79], v[58:61]
	v_mfma_f32_16x16x32_bf16 v[50:53], v[112:115], v[76:79], v[50:53]
	v_mfma_f32_16x16x32_bf16 v[42:45], v[100:103], v[92:95], v[42:45]
	v_mfma_f32_16x16x32_bf16 v[62:65], v[104:107], v[92:95], v[62:65]
	v_mfma_f32_16x16x32_bf16 v[68:71], v[108:111], v[92:95], v[68:71]
	v_mfma_f32_16x16x32_bf16 v[54:57], v[112:115], v[92:95], v[54:57]
	v_mfma_f32_16x16x32_bf16 v[34:37], v[100:103], v[96:99], v[34:37]
	v_mfma_f32_16x16x32_bf16 v[30:33], v[104:107], v[96:99], v[30:33]
	v_mfma_f32_16x16x32_bf16 v[26:29], v[108:111], v[96:99], v[26:29]
	v_mfma_f32_16x16x32_bf16 v[18:21], v[112:115], v[96:99], v[18:21]
	s_mov_b32 m0, s63
	v_lshl_add_u64 v[72:73], v[4:5], 0, s[24:25]
	global_load_lds_dwordx4 v[72:73], off
	v_lshl_add_u64 v[72:73], v[6:7], 0, s[24:25]
	s_mov_b32 m0, s62
	s_mov_b64 s[74:75], 0x20500
	global_load_lds_dwordx4 v[72:73], off
	v_lshl_add_u64 v[72:73], v[2:3], 0, s[24:25]
	s_mov_b32 m0, s64
	s_nop 0
	global_load_lds_dwordx4 v[72:73], off
	v_lshl_add_u64 v[72:73], v[2:3], 0, s[74:75]
	s_mov_b32 m0, s65
	s_mov_b64 s[74:75], 0x40500
	global_load_lds_dwordx4 v[72:73], off
	v_lshl_add_u64 v[72:73], v[2:3], 0, s[74:75]
	s_mov_b32 m0, s66
	s_mov_b64 s[74:75], 0x60500
	global_load_lds_dwordx4 v[72:73], off
	v_lshl_add_u64 v[72:73], v[2:3], 0, s[74:75]
	s_mov_b32 m0, s67
	s_nop 0
	global_load_lds_dwordx4 v[72:73], off
	ds_read_b128 v[72:75], v16
	ds_read_b128 v[76:79], v16 offset:2048
	ds_read_b128 v[92:95], v16 offset:4096
	ds_read_b128 v[96:99], v16 offset:6144
	ds_read_b128 v[100:103], v17
	ds_read_b128 v[104:107], v17 offset:2048
	ds_read_b128 v[108:111], v17 offset:4096
	ds_read_b128 v[112:115], v17 offset:6144
	s_waitcnt lgkmcnt(8)
	v_mfma_f32_16x16x32_bf16 v[80:83], v[132:135], v[116:119], v[80:83]
	v_mfma_f32_16x16x32_bf16 v[84:87], v[136:139], v[116:119], v[84:87]
	v_mfma_f32_16x16x32_bf16 v[88:91], v[140:143], v[116:119], v[88:91]
	v_mfma_f32_16x16x32_bf16 v[22:25], v[144:147], v[116:119], v[22:25]
	v_mfma_f32_16x16x32_bf16 v[38:41], v[132:135], v[120:123], v[38:41]
	v_mfma_f32_16x16x32_bf16 v[46:49], v[136:139], v[120:123], v[46:49]
	v_mfma_f32_16x16x32_bf16 v[58:61], v[140:143], v[120:123], v[58:61]
	v_mfma_f32_16x16x32_bf16 v[50:53], v[144:147], v[120:123], v[50:53]
	v_mfma_f32_16x16x32_bf16 v[42:45], v[132:135], v[124:127], v[42:45]
	v_mfma_f32_16x16x32_bf16 v[62:65], v[136:139], v[124:127], v[62:65]
	v_mfma_f32_16x16x32_bf16 v[68:71], v[140:143], v[124:127], v[68:71]
	v_mfma_f32_16x16x32_bf16 v[54:57], v[144:147], v[124:127], v[54:57]
	v_mfma_f32_16x16x32_bf16 v[34:37], v[132:135], v[128:131], v[34:37]
	v_mfma_f32_16x16x32_bf16 v[30:33], v[136:139], v[128:131], v[30:33]
	v_mfma_f32_16x16x32_bf16 v[26:29], v[140:143], v[128:131], v[26:29]
	v_mfma_f32_16x16x32_bf16 v[18:21], v[144:147], v[128:131], v[18:21]
	s_waitcnt vmcnt(6) lgkmcnt(0)
	s_barrier
	ds_read_b128 v[116:119], v8
	ds_read_b128 v[120:123], v8 offset:2048
	ds_read_b128 v[124:127], v8 offset:4096
	ds_read_b128 v[128:131], v8 offset:6144
	ds_read_b128 v[132:135], v9 offset:16384
	ds_read_b128 v[136:139], v9 offset:18432
	ds_read_b128 v[140:143], v9 offset:20480
	ds_read_b128 v[144:147], v9 offset:22528
	v_mfma_f32_16x16x32_bf16 v[80:83], v[100:103], v[72:75], v[80:83]
	v_mfma_f32_16x16x32_bf16 v[84:87], v[104:107], v[72:75], v[84:87]
	v_mfma_f32_16x16x32_bf16 v[88:91], v[108:111], v[72:75], v[88:91]
	v_mfma_f32_16x16x32_bf16 v[22:25], v[112:115], v[72:75], v[22:25]
	v_mfma_f32_16x16x32_bf16 v[38:41], v[100:103], v[76:79], v[38:41]
	v_mfma_f32_16x16x32_bf16 v[46:49], v[104:107], v[76:79], v[46:49]
	v_mfma_f32_16x16x32_bf16 v[58:61], v[108:111], v[76:79], v[58:61]
	v_mfma_f32_16x16x32_bf16 v[50:53], v[112:115], v[76:79], v[50:53]
	v_mfma_f32_16x16x32_bf16 v[42:45], v[100:103], v[92:95], v[42:45]
	v_mfma_f32_16x16x32_bf16 v[62:65], v[104:107], v[92:95], v[62:65]
	v_mfma_f32_16x16x32_bf16 v[68:71], v[108:111], v[92:95], v[68:71]
	v_mfma_f32_16x16x32_bf16 v[54:57], v[112:115], v[92:95], v[54:57]
	v_mfma_f32_16x16x32_bf16 v[34:37], v[100:103], v[96:99], v[34:37]
	v_mfma_f32_16x16x32_bf16 v[30:33], v[104:107], v[96:99], v[30:33]
	v_mfma_f32_16x16x32_bf16 v[26:29], v[108:111], v[96:99], v[26:29]
	v_mfma_f32_16x16x32_bf16 v[18:21], v[112:115], v[96:99], v[18:21]
	s_mov_b32 m0, s68
	v_lshl_add_u64 v[72:73], v[4:5], 0, s[26:27]
	global_load_lds_dwordx4 v[72:73], off
	v_lshl_add_u64 v[72:73], v[6:7], 0, s[26:27]
	s_mov_b32 m0, s69
	s_mov_b64 s[74:75], 0x20580
	global_load_lds_dwordx4 v[72:73], off
	v_lshl_add_u64 v[72:73], v[2:3], 0, s[26:27]
	s_mov_b32 m0, s70
	s_nop 0
	global_load_lds_dwordx4 v[72:73], off
	v_lshl_add_u64 v[72:73], v[2:3], 0, s[74:75]
	s_mov_b32 m0, s71
	s_mov_b64 s[74:75], 0x40580
	global_load_lds_dwordx4 v[72:73], off
	v_lshl_add_u64 v[72:73], v[2:3], 0, s[74:75]
	s_mov_b32 m0, s72
	s_mov_b64 s[74:75], 0x60580
	global_load_lds_dwordx4 v[72:73], off
	v_lshl_add_u64 v[72:73], v[2:3], 0, s[74:75]
	s_mov_b32 m0, s73
	s_nop 0
	global_load_lds_dwordx4 v[72:73], off
	ds_read_b128 v[72:75], v10
	ds_read_b128 v[76:79], v10 offset:2048
	ds_read_b128 v[92:95], v10 offset:4096
	ds_read_b128 v[96:99], v10 offset:6144
	ds_read_b128 v[100:103], v11 offset:16384
	ds_read_b128 v[104:107], v11 offset:18432
	ds_read_b128 v[108:111], v11 offset:20480
	ds_read_b128 v[112:115], v11 offset:22528
	s_waitcnt lgkmcnt(8)
	v_mfma_f32_16x16x32_bf16 v[80:83], v[132:135], v[116:119], v[80:83]
	v_mfma_f32_16x16x32_bf16 v[84:87], v[136:139], v[116:119], v[84:87]
	v_mfma_f32_16x16x32_bf16 v[88:91], v[140:143], v[116:119], v[88:91]
	v_mfma_f32_16x16x32_bf16 v[22:25], v[144:147], v[116:119], v[22:25]
	v_mfma_f32_16x16x32_bf16 v[38:41], v[132:135], v[120:123], v[38:41]
	v_mfma_f32_16x16x32_bf16 v[46:49], v[136:139], v[120:123], v[46:49]
	v_mfma_f32_16x16x32_bf16 v[58:61], v[140:143], v[120:123], v[58:61]
	v_mfma_f32_16x16x32_bf16 v[50:53], v[144:147], v[120:123], v[50:53]
	v_mfma_f32_16x16x32_bf16 v[42:45], v[132:135], v[124:127], v[42:45]
	v_mfma_f32_16x16x32_bf16 v[62:65], v[136:139], v[124:127], v[62:65]
	v_mfma_f32_16x16x32_bf16 v[68:71], v[140:143], v[124:127], v[68:71]
	v_mfma_f32_16x16x32_bf16 v[54:57], v[144:147], v[124:127], v[54:57]
	v_mfma_f32_16x16x32_bf16 v[34:37], v[132:135], v[128:131], v[34:37]
	v_mfma_f32_16x16x32_bf16 v[30:33], v[136:139], v[128:131], v[30:33]
	v_mfma_f32_16x16x32_bf16 v[26:29], v[140:143], v[128:131], v[26:29]
	v_mfma_f32_16x16x32_bf16 v[18:21], v[144:147], v[128:131], v[18:21]
	s_waitcnt vmcnt(6) lgkmcnt(0)
	s_barrier
	ds_read_b128 v[116:119], v8 offset:49152
	ds_read_b128 v[120:123], v8 offset:51200
	ds_read_b128 v[124:127], v8 offset:53248
	ds_read_b128 v[128:131], v8 offset:55296
	ds_read_b128 v[132:135], v12
	ds_read_b128 v[136:139], v12 offset:2048
	ds_read_b128 v[140:143], v12 offset:4096
	ds_read_b128 v[144:147], v12 offset:6144
	v_mfma_f32_16x16x32_bf16 v[80:83], v[100:103], v[72:75], v[80:83]
	v_mfma_f32_16x16x32_bf16 v[84:87], v[104:107], v[72:75], v[84:87]
	v_mfma_f32_16x16x32_bf16 v[88:91], v[108:111], v[72:75], v[88:91]
	v_mfma_f32_16x16x32_bf16 v[22:25], v[112:115], v[72:75], v[22:25]
	v_mfma_f32_16x16x32_bf16 v[38:41], v[100:103], v[76:79], v[38:41]
	v_mfma_f32_16x16x32_bf16 v[46:49], v[104:107], v[76:79], v[46:49]
	v_mfma_f32_16x16x32_bf16 v[58:61], v[108:111], v[76:79], v[58:61]
	v_mfma_f32_16x16x32_bf16 v[50:53], v[112:115], v[76:79], v[50:53]
	v_mfma_f32_16x16x32_bf16 v[42:45], v[100:103], v[92:95], v[42:45]
	v_mfma_f32_16x16x32_bf16 v[62:65], v[104:107], v[92:95], v[62:65]
	v_mfma_f32_16x16x32_bf16 v[68:71], v[108:111], v[92:95], v[68:71]
	v_mfma_f32_16x16x32_bf16 v[54:57], v[112:115], v[92:95], v[54:57]
	v_mfma_f32_16x16x32_bf16 v[34:37], v[100:103], v[96:99], v[34:37]
	v_mfma_f32_16x16x32_bf16 v[30:33], v[104:107], v[96:99], v[30:33]
	v_mfma_f32_16x16x32_bf16 v[26:29], v[108:111], v[96:99], v[26:29]
	v_mfma_f32_16x16x32_bf16 v[18:21], v[112:115], v[96:99], v[18:21]
	s_mov_b32 m0, s61
	v_lshl_add_u64 v[72:73], v[4:5], 0, s[28:29]
	global_load_lds_dwordx4 v[72:73], off
	v_lshl_add_u64 v[72:73], v[6:7], 0, s[28:29]
	s_mov_b32 m0, s47
	s_mov_b64 s[74:75], 0x20600
	global_load_lds_dwordx4 v[72:73], off
	v_lshl_add_u64 v[72:73], v[2:3], 0, s[28:29]
	s_mov_b32 m0, s60
	s_nop 0
	global_load_lds_dwordx4 v[72:73], off
	v_lshl_add_u64 v[72:73], v[2:3], 0, s[74:75]
	s_mov_b32 m0, s33
	s_mov_b64 s[74:75], 0x40600
	global_load_lds_dwordx4 v[72:73], off
	v_lshl_add_u64 v[72:73], v[2:3], 0, s[74:75]
	s_mov_b32 m0, s5
	s_mov_b64 s[74:75], 0x60600
	global_load_lds_dwordx4 v[72:73], off
	v_lshl_add_u64 v[72:73], v[2:3], 0, s[74:75]
	s_mov_b32 m0, s2
	s_nop 0
	global_load_lds_dwordx4 v[72:73], off
	ds_read_b128 v[72:75], v10 offset:49152
	ds_read_b128 v[76:79], v10 offset:51200
	ds_read_b128 v[92:95], v10 offset:53248
	ds_read_b128 v[96:99], v10 offset:55296
	ds_read_b128 v[100:103], v13
	ds_read_b128 v[104:107], v13 offset:2048
	ds_read_b128 v[108:111], v13 offset:4096
	ds_read_b128 v[112:115], v13 offset:6144
	s_waitcnt lgkmcnt(8)
	v_mfma_f32_16x16x32_bf16 v[80:83], v[132:135], v[116:119], v[80:83]
	v_mfma_f32_16x16x32_bf16 v[84:87], v[136:139], v[116:119], v[84:87]
	v_mfma_f32_16x16x32_bf16 v[88:91], v[140:143], v[116:119], v[88:91]
	v_mfma_f32_16x16x32_bf16 v[22:25], v[144:147], v[116:119], v[22:25]
	v_mfma_f32_16x16x32_bf16 v[38:41], v[132:135], v[120:123], v[38:41]
	v_mfma_f32_16x16x32_bf16 v[46:49], v[136:139], v[120:123], v[46:49]
	v_mfma_f32_16x16x32_bf16 v[58:61], v[140:143], v[120:123], v[58:61]
	v_mfma_f32_16x16x32_bf16 v[50:53], v[144:147], v[120:123], v[50:53]
	v_mfma_f32_16x16x32_bf16 v[42:45], v[132:135], v[124:127], v[42:45]
	v_mfma_f32_16x16x32_bf16 v[62:65], v[136:139], v[124:127], v[62:65]
	v_mfma_f32_16x16x32_bf16 v[68:71], v[140:143], v[124:127], v[68:71]
	v_mfma_f32_16x16x32_bf16 v[54:57], v[144:147], v[124:127], v[54:57]
	v_mfma_f32_16x16x32_bf16 v[34:37], v[132:135], v[128:131], v[34:37]
	v_mfma_f32_16x16x32_bf16 v[30:33], v[136:139], v[128:131], v[30:33]
	v_mfma_f32_16x16x32_bf16 v[26:29], v[140:143], v[128:131], v[26:29]
	v_mfma_f32_16x16x32_bf16 v[18:21], v[144:147], v[128:131], v[18:21]
	s_waitcnt vmcnt(6) lgkmcnt(0)
	s_barrier
	ds_read_b128 v[116:119], v14
	ds_read_b128 v[120:123], v14 offset:2048
	ds_read_b128 v[124:127], v14 offset:4096
	ds_read_b128 v[128:131], v14 offset:6144
	ds_read_b128 v[132:135], v15
	ds_read_b128 v[136:139], v15 offset:2048
	ds_read_b128 v[140:143], v15 offset:4096
	ds_read_b128 v[144:147], v15 offset:6144
	v_mfma_f32_16x16x32_bf16 v[80:83], v[100:103], v[72:75], v[80:83]
	v_mfma_f32_16x16x32_bf16 v[84:87], v[104:107], v[72:75], v[84:87]
	v_mfma_f32_16x16x32_bf16 v[88:91], v[108:111], v[72:75], v[88:91]
	v_mfma_f32_16x16x32_bf16 v[22:25], v[112:115], v[72:75], v[22:25]
	v_mfma_f32_16x16x32_bf16 v[38:41], v[100:103], v[76:79], v[38:41]
	v_mfma_f32_16x16x32_bf16 v[46:49], v[104:107], v[76:79], v[46:49]
	v_mfma_f32_16x16x32_bf16 v[58:61], v[108:111], v[76:79], v[58:61]
	v_mfma_f32_16x16x32_bf16 v[50:53], v[112:115], v[76:79], v[50:53]
	v_mfma_f32_16x16x32_bf16 v[42:45], v[100:103], v[92:95], v[42:45]
	v_mfma_f32_16x16x32_bf16 v[62:65], v[104:107], v[92:95], v[62:65]
	v_mfma_f32_16x16x32_bf16 v[68:71], v[108:111], v[92:95], v[68:71]
	v_mfma_f32_16x16x32_bf16 v[54:57], v[112:115], v[92:95], v[54:57]
	v_mfma_f32_16x16x32_bf16 v[34:37], v[100:103], v[96:99], v[34:37]
	v_mfma_f32_16x16x32_bf16 v[30:33], v[104:107], v[96:99], v[30:33]
	v_mfma_f32_16x16x32_bf16 v[26:29], v[108:111], v[96:99], v[26:29]
	v_mfma_f32_16x16x32_bf16 v[18:21], v[112:115], v[96:99], v[18:21]
	s_mov_b32 m0, s63
	v_lshl_add_u64 v[72:73], v[4:5], 0, s[30:31]
	global_load_lds_dwordx4 v[72:73], off
	v_lshl_add_u64 v[72:73], v[6:7], 0, s[30:31]
	s_mov_b32 m0, s62
	s_mov_b64 s[62:63], 0x20680
	global_load_lds_dwordx4 v[72:73], off
	v_lshl_add_u64 v[72:73], v[2:3], 0, s[30:31]
	s_mov_b32 m0, s64
	s_nop 0
	global_load_lds_dwordx4 v[72:73], off
	v_lshl_add_u64 v[72:73], v[2:3], 0, s[62:63]
	s_mov_b32 m0, s65
	s_mov_b64 s[62:63], 0x40680
	global_load_lds_dwordx4 v[72:73], off
	v_lshl_add_u64 v[72:73], v[2:3], 0, s[62:63]
	s_mov_b32 m0, s66
	s_mov_b64 s[62:63], 0x60680
	global_load_lds_dwordx4 v[72:73], off
	v_lshl_add_u64 v[72:73], v[2:3], 0, s[62:63]
	s_mov_b32 m0, s67
	v_readlane_b32 s66, v196, 22
	global_load_lds_dwordx4 v[72:73], off
	ds_read_b128 v[72:75], v16
	ds_read_b128 v[76:79], v16 offset:2048
	ds_read_b128 v[92:95], v16 offset:4096
	ds_read_b128 v[96:99], v16 offset:6144
	ds_read_b128 v[100:103], v17
	ds_read_b128 v[104:107], v17 offset:2048
	ds_read_b128 v[108:111], v17 offset:4096
	ds_read_b128 v[112:115], v17 offset:6144
	v_readlane_b32 s67, v196, 23
	s_waitcnt lgkmcnt(8)
	v_mfma_f32_16x16x32_bf16 v[80:83], v[132:135], v[116:119], v[80:83]
	v_mfma_f32_16x16x32_bf16 v[84:87], v[136:139], v[116:119], v[84:87]
	v_mfma_f32_16x16x32_bf16 v[88:91], v[140:143], v[116:119], v[88:91]
	v_mfma_f32_16x16x32_bf16 v[22:25], v[144:147], v[116:119], v[22:25]
	v_mfma_f32_16x16x32_bf16 v[38:41], v[132:135], v[120:123], v[38:41]
	v_mfma_f32_16x16x32_bf16 v[46:49], v[136:139], v[120:123], v[46:49]
	v_mfma_f32_16x16x32_bf16 v[58:61], v[140:143], v[120:123], v[58:61]
	v_mfma_f32_16x16x32_bf16 v[50:53], v[144:147], v[120:123], v[50:53]
	v_mfma_f32_16x16x32_bf16 v[42:45], v[132:135], v[124:127], v[42:45]
	v_mfma_f32_16x16x32_bf16 v[62:65], v[136:139], v[124:127], v[62:65]
	v_mfma_f32_16x16x32_bf16 v[68:71], v[140:143], v[124:127], v[68:71]
	v_mfma_f32_16x16x32_bf16 v[54:57], v[144:147], v[124:127], v[54:57]
	v_mfma_f32_16x16x32_bf16 v[34:37], v[132:135], v[128:131], v[34:37]
	v_mfma_f32_16x16x32_bf16 v[30:33], v[136:139], v[128:131], v[30:33]
	v_mfma_f32_16x16x32_bf16 v[26:29], v[140:143], v[128:131], v[26:29]
	v_mfma_f32_16x16x32_bf16 v[18:21], v[144:147], v[128:131], v[18:21]
	s_waitcnt vmcnt(6) lgkmcnt(0)
	s_barrier
	ds_read_b128 v[116:119], v8
	ds_read_b128 v[120:123], v8 offset:2048
	ds_read_b128 v[124:127], v8 offset:4096
	ds_read_b128 v[128:131], v8 offset:6144
	ds_read_b128 v[132:135], v9 offset:16384
	ds_read_b128 v[136:139], v9 offset:18432
	ds_read_b128 v[140:143], v9 offset:20480
	ds_read_b128 v[144:147], v9 offset:22528
	v_mfma_f32_16x16x32_bf16 v[80:83], v[100:103], v[72:75], v[80:83]
	v_mfma_f32_16x16x32_bf16 v[84:87], v[104:107], v[72:75], v[84:87]
	v_mfma_f32_16x16x32_bf16 v[88:91], v[108:111], v[72:75], v[88:91]
	v_mfma_f32_16x16x32_bf16 v[22:25], v[112:115], v[72:75], v[22:25]
	v_mfma_f32_16x16x32_bf16 v[38:41], v[100:103], v[76:79], v[38:41]
	v_mfma_f32_16x16x32_bf16 v[46:49], v[104:107], v[76:79], v[46:49]
	v_mfma_f32_16x16x32_bf16 v[58:61], v[108:111], v[76:79], v[58:61]
	v_mfma_f32_16x16x32_bf16 v[50:53], v[112:115], v[76:79], v[50:53]
	v_mfma_f32_16x16x32_bf16 v[42:45], v[100:103], v[92:95], v[42:45]
	v_mfma_f32_16x16x32_bf16 v[62:65], v[104:107], v[92:95], v[62:65]
	v_mfma_f32_16x16x32_bf16 v[68:71], v[108:111], v[92:95], v[68:71]
	v_mfma_f32_16x16x32_bf16 v[54:57], v[112:115], v[92:95], v[54:57]
	v_mfma_f32_16x16x32_bf16 v[34:37], v[100:103], v[96:99], v[34:37]
	v_mfma_f32_16x16x32_bf16 v[30:33], v[104:107], v[96:99], v[30:33]
	v_mfma_f32_16x16x32_bf16 v[26:29], v[108:111], v[96:99], v[26:29]
	v_mfma_f32_16x16x32_bf16 v[18:21], v[112:115], v[96:99], v[18:21]
	s_mov_b32 m0, s68
	v_lshl_add_u64 v[72:73], v[4:5], 0, s[34:35]
	global_load_lds_dwordx4 v[72:73], off
	v_lshl_add_u64 v[72:73], v[6:7], 0, s[34:35]
	s_mov_b32 m0, s69
	s_mov_b64 s[62:63], 0x20700
	global_load_lds_dwordx4 v[72:73], off
	v_lshl_add_u64 v[72:73], v[2:3], 0, s[34:35]
	s_mov_b32 m0, s70
	s_nop 0
	global_load_lds_dwordx4 v[72:73], off
	v_lshl_add_u64 v[72:73], v[2:3], 0, s[62:63]
	s_mov_b32 m0, s71
	s_mov_b64 s[62:63], 0x40700
	global_load_lds_dwordx4 v[72:73], off
	v_lshl_add_u64 v[72:73], v[2:3], 0, s[62:63]
	s_mov_b32 m0, s72
	s_mov_b64 s[62:63], 0x60700
	global_load_lds_dwordx4 v[72:73], off
	v_lshl_add_u64 v[72:73], v[2:3], 0, s[62:63]
	s_mov_b32 m0, s73
	v_readlane_b32 s72, v197, 34
	global_load_lds_dwordx4 v[72:73], off
	ds_read_b128 v[72:75], v10
	ds_read_b128 v[76:79], v10 offset:2048
	ds_read_b128 v[92:95], v10 offset:4096
	ds_read_b128 v[96:99], v10 offset:6144
	ds_read_b128 v[100:103], v11 offset:16384
	ds_read_b128 v[104:107], v11 offset:18432
	ds_read_b128 v[108:111], v11 offset:20480
	ds_read_b128 v[112:115], v11 offset:22528
	v_readlane_b32 s73, v197, 35
	v_readlane_b32 s74, v197, 36
	v_readlane_b32 s75, v197, 37
	v_readlane_b32 s76, v197, 38
	v_readlane_b32 s77, v197, 39
	v_readlane_b32 s78, v197, 40
	v_readlane_b32 s79, v197, 41
	v_readlane_b32 s80, v197, 42
	v_readlane_b32 s81, v197, 43
	v_readlane_b32 s82, v197, 44
	v_readlane_b32 s83, v197, 45
	v_readlane_b32 s84, v197, 46
	v_readlane_b32 s85, v197, 47
	v_readlane_b32 s86, v197, 48
	v_readlane_b32 s87, v197, 49
	s_waitcnt lgkmcnt(8)
	v_mfma_f32_16x16x32_bf16 v[80:83], v[132:135], v[116:119], v[80:83]
	v_mfma_f32_16x16x32_bf16 v[84:87], v[136:139], v[116:119], v[84:87]
	v_mfma_f32_16x16x32_bf16 v[88:91], v[140:143], v[116:119], v[88:91]
	v_mfma_f32_16x16x32_bf16 v[22:25], v[144:147], v[116:119], v[22:25]
	v_mfma_f32_16x16x32_bf16 v[38:41], v[132:135], v[120:123], v[38:41]
	v_mfma_f32_16x16x32_bf16 v[46:49], v[136:139], v[120:123], v[46:49]
	v_mfma_f32_16x16x32_bf16 v[58:61], v[140:143], v[120:123], v[58:61]
	v_mfma_f32_16x16x32_bf16 v[50:53], v[144:147], v[120:123], v[50:53]
	v_mfma_f32_16x16x32_bf16 v[42:45], v[132:135], v[124:127], v[42:45]
	v_mfma_f32_16x16x32_bf16 v[62:65], v[136:139], v[124:127], v[62:65]
	v_mfma_f32_16x16x32_bf16 v[68:71], v[140:143], v[124:127], v[68:71]
	v_mfma_f32_16x16x32_bf16 v[54:57], v[144:147], v[124:127], v[54:57]
	v_mfma_f32_16x16x32_bf16 v[34:37], v[132:135], v[128:131], v[34:37]
	v_mfma_f32_16x16x32_bf16 v[30:33], v[136:139], v[128:131], v[30:33]
	v_mfma_f32_16x16x32_bf16 v[26:29], v[140:143], v[128:131], v[26:29]
	v_mfma_f32_16x16x32_bf16 v[18:21], v[144:147], v[128:131], v[18:21]
	s_waitcnt vmcnt(6) lgkmcnt(0)
	s_barrier
	ds_read_b128 v[116:119], v8 offset:49152
	ds_read_b128 v[120:123], v8 offset:51200
	ds_read_b128 v[124:127], v8 offset:53248
	ds_read_b128 v[128:131], v8 offset:55296
	ds_read_b128 v[132:135], v12
	ds_read_b128 v[136:139], v12 offset:2048
	ds_read_b128 v[140:143], v12 offset:4096
	ds_read_b128 v[144:147], v12 offset:6144
	v_mfma_f32_16x16x32_bf16 v[80:83], v[100:103], v[72:75], v[80:83]
	v_mfma_f32_16x16x32_bf16 v[84:87], v[104:107], v[72:75], v[84:87]
	v_mfma_f32_16x16x32_bf16 v[88:91], v[108:111], v[72:75], v[88:91]
	v_mfma_f32_16x16x32_bf16 v[22:25], v[112:115], v[72:75], v[22:25]
	v_mfma_f32_16x16x32_bf16 v[38:41], v[100:103], v[76:79], v[38:41]
	v_mfma_f32_16x16x32_bf16 v[46:49], v[104:107], v[76:79], v[46:49]
	v_mfma_f32_16x16x32_bf16 v[58:61], v[108:111], v[76:79], v[58:61]
	v_mfma_f32_16x16x32_bf16 v[50:53], v[112:115], v[76:79], v[50:53]
	v_mfma_f32_16x16x32_bf16 v[42:45], v[100:103], v[92:95], v[42:45]
	v_mfma_f32_16x16x32_bf16 v[62:65], v[104:107], v[92:95], v[62:65]
	v_mfma_f32_16x16x32_bf16 v[68:71], v[108:111], v[92:95], v[68:71]
	v_mfma_f32_16x16x32_bf16 v[54:57], v[112:115], v[92:95], v[54:57]
	v_mfma_f32_16x16x32_bf16 v[34:37], v[100:103], v[96:99], v[34:37]
	v_mfma_f32_16x16x32_bf16 v[30:33], v[104:107], v[96:99], v[30:33]
	v_mfma_f32_16x16x32_bf16 v[26:29], v[108:111], v[96:99], v[26:29]
	v_mfma_f32_16x16x32_bf16 v[18:21], v[112:115], v[96:99], v[18:21]
	s_mov_b32 m0, s61
	v_lshl_add_u64 v[4:5], v[4:5], 0, s[36:37]
	global_load_lds_dwordx4 v[4:5], off
	v_lshl_add_u64 v[4:5], v[6:7], 0, s[36:37]
	s_mov_b32 m0, s47
	s_nop 0
	global_load_lds_dwordx4 v[4:5], off
	v_lshl_add_u64 v[4:5], v[2:3], 0, s[36:37]
	s_mov_b32 m0, s60
	s_mov_b64 s[60:61], 0x20780
	global_load_lds_dwordx4 v[4:5], off
	v_lshl_add_u64 v[4:5], v[2:3], 0, s[60:61]
	s_mov_b32 m0, s33
	s_mov_b64 s[60:61], 0x40780
	global_load_lds_dwordx4 v[4:5], off
	v_lshl_add_u64 v[4:5], v[2:3], 0, s[60:61]
	s_mov_b32 m0, s5
	s_mov_b64 s[60:61], 0x60780
	global_load_lds_dwordx4 v[4:5], off
	v_lshl_add_u64 v[2:3], v[2:3], 0, s[60:61]
	s_mov_b32 m0, s2
	s_nop 0
	global_load_lds_dwordx4 v[2:3], off
	ds_read_b128 v[2:5], v10 offset:49152
	ds_read_b128 v[72:75], v10 offset:51200
	ds_read_b128 v[76:79], v10 offset:53248
	ds_read_b128 v[92:95], v10 offset:55296
	ds_read_b128 v[96:99], v13
	ds_read_b128 v[100:103], v13 offset:2048
	ds_read_b128 v[104:107], v13 offset:4096
	ds_read_b128 v[108:111], v13 offset:6144
	s_waitcnt lgkmcnt(8)
	v_mfma_f32_16x16x32_bf16 v[80:83], v[132:135], v[116:119], v[80:83]
	v_mfma_f32_16x16x32_bf16 v[84:87], v[136:139], v[116:119], v[84:87]
	v_mfma_f32_16x16x32_bf16 v[88:91], v[140:143], v[116:119], v[88:91]
	v_mfma_f32_16x16x32_bf16 v[22:25], v[144:147], v[116:119], v[22:25]
	v_mfma_f32_16x16x32_bf16 v[38:41], v[132:135], v[120:123], v[38:41]
	v_mfma_f32_16x16x32_bf16 v[46:49], v[136:139], v[120:123], v[46:49]
	v_mfma_f32_16x16x32_bf16 v[58:61], v[140:143], v[120:123], v[58:61]
	v_mfma_f32_16x16x32_bf16 v[50:53], v[144:147], v[120:123], v[50:53]
	v_mfma_f32_16x16x32_bf16 v[42:45], v[132:135], v[124:127], v[42:45]
	v_mfma_f32_16x16x32_bf16 v[62:65], v[136:139], v[124:127], v[62:65]
	v_mfma_f32_16x16x32_bf16 v[68:71], v[140:143], v[124:127], v[68:71]
	v_mfma_f32_16x16x32_bf16 v[54:57], v[144:147], v[124:127], v[54:57]
	v_mfma_f32_16x16x32_bf16 v[34:37], v[132:135], v[128:131], v[34:37]
	v_mfma_f32_16x16x32_bf16 v[30:33], v[136:139], v[128:131], v[30:33]
	v_mfma_f32_16x16x32_bf16 v[26:29], v[140:143], v[128:131], v[26:29]
	v_mfma_f32_16x16x32_bf16 v[18:21], v[144:147], v[128:131], v[18:21]
	s_waitcnt vmcnt(6) lgkmcnt(0)
	s_barrier
	ds_read_b128 v[112:115], v14
	ds_read_b128 v[116:119], v14 offset:2048
	ds_read_b128 v[120:123], v14 offset:4096
	ds_read_b128 v[124:127], v14 offset:6144
	ds_read_b128 v[128:131], v15
	ds_read_b128 v[132:135], v15 offset:2048
	ds_read_b128 v[136:139], v15 offset:4096
	ds_read_b128 v[12:15], v15 offset:6144
	v_mfma_f32_16x16x32_bf16 v[80:83], v[96:99], v[2:5], v[80:83]
	v_mfma_f32_16x16x32_bf16 v[84:87], v[100:103], v[2:5], v[84:87]
	v_mfma_f32_16x16x32_bf16 v[88:91], v[104:107], v[2:5], v[88:91]
	v_mfma_f32_16x16x32_bf16 v[2:5], v[108:111], v[2:5], v[22:25]
	v_mfma_f32_16x16x32_bf16 v[22:25], v[96:99], v[72:75], v[38:41]
	v_mfma_f32_16x16x32_bf16 v[38:41], v[100:103], v[72:75], v[46:49]
	v_mfma_f32_16x16x32_bf16 v[46:49], v[104:107], v[72:75], v[58:61]
	v_mfma_f32_16x16x32_bf16 v[50:53], v[108:111], v[72:75], v[50:53]
	v_mfma_f32_16x16x32_bf16 v[42:45], v[96:99], v[76:79], v[42:45]
	v_mfma_f32_16x16x32_bf16 v[58:61], v[100:103], v[76:79], v[62:65]
	v_mfma_f32_16x16x32_bf16 v[62:65], v[104:107], v[76:79], v[68:71]
	v_mfma_f32_16x16x32_bf16 v[54:57], v[108:111], v[76:79], v[54:57]
	v_mfma_f32_16x16x32_bf16 v[34:37], v[96:99], v[92:95], v[34:37]
	v_mfma_f32_16x16x32_bf16 v[30:33], v[100:103], v[92:95], v[30:33]
	v_mfma_f32_16x16x32_bf16 v[26:29], v[104:107], v[92:95], v[26:29]
	v_mfma_f32_16x16x32_bf16 v[18:21], v[108:111], v[92:95], v[18:21]
	ds_read_b128 v[68:71], v16
	ds_read_b128 v[72:75], v16 offset:2048
	ds_read_b128 v[76:79], v16 offset:4096
	ds_read_b128 v[92:95], v16 offset:6144
	ds_read_b128 v[96:99], v17
	ds_read_b128 v[100:103], v17 offset:2048
	ds_read_b128 v[104:107], v17 offset:4096
	ds_read_b128 v[108:111], v17 offset:6144
	s_waitcnt lgkmcnt(8)
	v_mfma_f32_16x16x32_bf16 v[80:83], v[128:131], v[112:115], v[80:83]
	v_mfma_f32_16x16x32_bf16 v[84:87], v[132:135], v[112:115], v[84:87]
	v_mfma_f32_16x16x32_bf16 v[88:91], v[136:139], v[112:115], v[88:91]
	v_mfma_f32_16x16x32_bf16 v[2:5], v[12:15], v[112:115], v[2:5]
	v_mfma_f32_16x16x32_bf16 v[22:25], v[128:131], v[116:119], v[22:25]
	v_mfma_f32_16x16x32_bf16 v[38:41], v[132:135], v[116:119], v[38:41]
	v_mfma_f32_16x16x32_bf16 v[46:49], v[136:139], v[116:119], v[46:49]
	v_mfma_f32_16x16x32_bf16 v[50:53], v[12:15], v[116:119], v[50:53]
	v_mfma_f32_16x16x32_bf16 v[42:45], v[128:131], v[120:123], v[42:45]
	v_mfma_f32_16x16x32_bf16 v[58:61], v[132:135], v[120:123], v[58:61]
	v_mfma_f32_16x16x32_bf16 v[62:65], v[136:139], v[120:123], v[62:65]
	v_mfma_f32_16x16x32_bf16 v[54:57], v[12:15], v[120:123], v[54:57]
	v_mfma_f32_16x16x32_bf16 v[34:37], v[128:131], v[124:127], v[34:37]
	v_mfma_f32_16x16x32_bf16 v[30:33], v[132:135], v[124:127], v[30:33]
	v_mfma_f32_16x16x32_bf16 v[26:29], v[136:139], v[124:127], v[26:29]
	v_mfma_f32_16x16x32_bf16 v[12:15], v[12:15], v[124:127], v[18:21]
	s_waitcnt vmcnt(0) lgkmcnt(0)
	s_barrier
	s_nop 1
	ds_read_b128 v[16:19], v8
	ds_read_b128 v[112:115], v8 offset:2048
	ds_read_b128 v[116:119], v8 offset:4096
	ds_read_b128 v[120:123], v8 offset:6144
	ds_read_b128 v[124:127], v9 offset:16384
	ds_read_b128 v[128:131], v9 offset:18432
	ds_read_b128 v[132:135], v9 offset:20480
	ds_read_b128 v[6:9], v9 offset:22528
	v_mfma_f32_16x16x32_bf16 v[80:83], v[96:99], v[68:71], v[80:83]
	v_mfma_f32_16x16x32_bf16 v[84:87], v[100:103], v[68:71], v[84:87]
	v_mfma_f32_16x16x32_bf16 v[88:91], v[104:107], v[68:71], v[88:91]
	v_mfma_f32_16x16x32_bf16 v[2:5], v[108:111], v[68:71], v[2:5]
	v_mfma_f32_16x16x32_bf16 v[20:23], v[96:99], v[72:75], v[22:25]
	v_mfma_f32_16x16x32_bf16 v[38:41], v[100:103], v[72:75], v[38:41]
	v_mfma_f32_16x16x32_bf16 v[46:49], v[104:107], v[72:75], v[46:49]
	v_mfma_f32_16x16x32_bf16 v[50:53], v[108:111], v[72:75], v[50:53]
	v_mfma_f32_16x16x32_bf16 v[42:45], v[96:99], v[76:79], v[42:45]
	v_mfma_f32_16x16x32_bf16 v[58:61], v[100:103], v[76:79], v[58:61]
	v_mfma_f32_16x16x32_bf16 v[62:65], v[104:107], v[76:79], v[62:65]
	v_mfma_f32_16x16x32_bf16 v[54:57], v[108:111], v[76:79], v[54:57]
	v_mfma_f32_16x16x32_bf16 v[34:37], v[96:99], v[92:95], v[34:37]
	v_mfma_f32_16x16x32_bf16 v[30:33], v[100:103], v[92:95], v[30:33]
	v_mfma_f32_16x16x32_bf16 v[24:27], v[104:107], v[92:95], v[26:29]
	v_mfma_f32_16x16x32_bf16 v[12:15], v[108:111], v[92:95], v[12:15]
	ds_read_b128 v[68:71], v10
	ds_read_b128 v[72:75], v10 offset:2048
	ds_read_b128 v[76:79], v10 offset:4096
	ds_read_b128 v[92:95], v10 offset:6144
	ds_read_b128 v[96:99], v11 offset:16384
	ds_read_b128 v[100:103], v11 offset:18432
	ds_read_b128 v[104:107], v11 offset:20480
	ds_read_b128 v[108:111], v11 offset:22528
	s_waitcnt lgkmcnt(8)
	v_mfma_f32_16x16x32_bf16 v[80:83], v[124:127], v[16:19], v[80:83]
	v_mfma_f32_16x16x32_bf16 v[84:87], v[128:131], v[16:19], v[84:87]
	v_mfma_f32_16x16x32_bf16 v[88:91], v[132:135], v[16:19], v[88:91]
	v_mfma_f32_16x16x32_bf16 v[2:5], v[6:9], v[16:19], v[2:5]
	v_mfma_f32_16x16x32_bf16 v[16:19], v[124:127], v[112:115], v[20:23]
	v_mfma_f32_16x16x32_bf16 v[20:23], v[128:131], v[112:115], v[38:41]
	v_mfma_f32_16x16x32_bf16 v[38:41], v[132:135], v[112:115], v[46:49]
	v_mfma_f32_16x16x32_bf16 v[112:115], v[6:9], v[112:115], v[50:53]
	v_mfma_f32_16x16x32_bf16 v[136:139], v[124:127], v[116:119], v[42:45]
	v_mfma_f32_16x16x32_bf16 v[140:143], v[128:131], v[116:119], v[58:61]
	v_mfma_f32_16x16x32_bf16 v[144:147], v[132:135], v[116:119], v[62:65]
	v_mfma_f32_16x16x32_bf16 v[116:119], v[6:9], v[116:119], v[54:57]
	v_mfma_f32_16x16x32_bf16 v[124:127], v[124:127], v[120:123], v[34:37]
	v_mfma_f32_16x16x32_bf16 v[128:131], v[128:131], v[120:123], v[30:33]
	v_mfma_f32_16x16x32_bf16 v[132:135], v[132:135], v[120:123], v[24:27]
	v_mfma_f32_16x16x32_bf16 v[120:123], v[6:9], v[120:123], v[12:15]
	s_waitcnt vmcnt(0) lgkmcnt(0)
	s_barrier
	v_mfma_f32_16x16x32_bf16 v[58:61], v[96:99], v[68:71], v[80:83]
	v_mfma_f32_16x16x32_bf16 v[62:65], v[100:103], v[68:71], v[84:87]
	v_mfma_f32_16x16x32_bf16 v[54:57], v[104:107], v[68:71], v[88:91]
	v_mfma_f32_16x16x32_bf16 v[50:53], v[108:111], v[68:71], v[2:5]
	v_mfma_f32_16x16x32_bf16 v[42:45], v[96:99], v[72:75], v[16:19]
	v_mfma_f32_16x16x32_bf16 v[46:49], v[100:103], v[72:75], v[20:23]
	v_mfma_f32_16x16x32_bf16 v[38:41], v[104:107], v[72:75], v[38:41]
	v_mfma_f32_16x16x32_bf16 v[34:37], v[108:111], v[72:75], v[112:115]
	v_mfma_f32_16x16x32_bf16 v[26:29], v[96:99], v[76:79], v[136:139]
	v_mfma_f32_16x16x32_bf16 v[30:33], v[100:103], v[76:79], v[140:143]
	v_mfma_f32_16x16x32_bf16 v[22:25], v[104:107], v[76:79], v[144:147]
	v_mfma_f32_16x16x32_bf16 v[18:21], v[108:111], v[76:79], v[116:119]
	v_mfma_f32_16x16x32_bf16 v[10:13], v[96:99], v[92:95], v[124:127]
	v_mfma_f32_16x16x32_bf16 v[14:17], v[100:103], v[92:95], v[128:131]
	v_mfma_f32_16x16x32_bf16 v[6:9], v[104:107], v[92:95], v[132:135]
	v_mfma_f32_16x16x32_bf16 v[2:5], v[108:111], v[92:95], v[120:123]
	v_ashrrev_i32_e32 v66, 2, v1
	v_and_b32_e32 v66, 0xffffffc0, v66
	v_add_u32_e32 v66, s4, v66
	s_ashr_i32 s47, s46, 31
	v_and_or_b32 v68, v1, 15, v66
	s_lshl_b64 s[4:5], s[46:47], 20
	v_ashrrev_i32_e32 v69, 31, v68
	s_add_u32 s4, s22, s4
	s_addc_u32 s5, s23, s5
	v_lshlrev_b64 v[70:71], 11, v[68:69]
	v_lshl_add_u64 v[70:71], s[4:5], 0, v[70:71]
	s_lshl_b32 s2, s59, 8
	v_lshrrev_b32_e32 v74, 1, v1
	v_lshl_add_u64 v[70:71], v[70:71], 0, s[2:3]
	v_and_b32_e32 v66, 0xc0, v1
	v_mul_f32_e32 v1, 0xbfb8aa3b, v58
	v_lshl_add_u64 v[72:73], v[70:71], 0, v[66:67]
	v_and_b32_e32 v70, 24, v74
	v_exp_f32_e32 v74, v1
	v_mul_f32_e32 v1, 0xbfb8aa3b, v59
	v_exp_f32_e32 v75, v1
	v_mov_b32_e32 v71, v67
	v_lshl_add_u64 v[72:73], v[72:73], 0, v[70:71]
	s_waitcnt lgkmcnt(0)
	v_pk_add_f32 v[74:75], v[74:75], 1.0 op_sel_hi:[1,0]
	s_barrier
	v_div_scale_f32 v1, s[46:47], v75, v75, v59
	v_rcp_f32_e32 v69, v1
	s_add_i32 s98, s98, s66
	s_add_i32 s38, s38, s39
	v_fma_f32 v76, -v1, v69, 1.0
	v_fmac_f32_e32 v69, v76, v69
	v_div_scale_f32 v76, vcc, v59, v75, v59
	v_mul_f32_e32 v77, v76, v69
	v_fma_f32 v78, -v1, v77, v76
	v_fmac_f32_e32 v77, v78, v69
	v_fma_f32 v1, -v1, v77, v76
	v_div_fmas_f32 v1, v1, v69, v77
	v_div_fixup_f32 v59, v1, v75, v59
	v_div_scale_f32 v1, s[46:47], v74, v74, v58
	v_rcp_f32_e32 v69, v1
	s_cmpk_lt_i32 s98, 0x800
	v_fma_f32 v75, -v1, v69, 1.0
	v_fmac_f32_e32 v69, v75, v69
	v_div_scale_f32 v75, vcc, v58, v74, v58
	v_mul_f32_e32 v76, v75, v69
	v_fma_f32 v77, -v1, v76, v75
	v_fmac_f32_e32 v76, v77, v69
	v_fma_f32 v1, -v1, v76, v75
	v_div_fmas_f32 v1, v1, v69, v76
	v_div_fixup_f32 v58, v1, v74, v58
	v_mul_f32_e32 v1, 0xbfb8aa3b, v60
	v_pk_mul_f32 v[58:59], v[62:63], v[58:59]
	v_exp_f32_e32 v62, v1
	v_mul_f32_e32 v1, 0xbfb8aa3b, v61
	v_exp_f32_e32 v63, v1
	v_cvt_pk_bf16_f32 v58, v58, v59
	v_pk_add_f32 v[62:63], v[62:63], 1.0 op_sel_hi:[1,0]
	s_nop 0
	v_div_scale_f32 v1, s[46:47], v63, v63, v61
	v_rcp_f32_e32 v69, v1
	s_nop 0
	v_fma_f32 v74, -v1, v69, 1.0
	v_fmac_f32_e32 v69, v74, v69
	v_div_scale_f32 v74, vcc, v61, v63, v61
	v_mul_f32_e32 v75, v74, v69
	v_fma_f32 v76, -v1, v75, v74
	v_fmac_f32_e32 v75, v76, v69
	v_fma_f32 v1, -v1, v75, v74
	v_div_fmas_f32 v1, v1, v69, v75
	v_div_fixup_f32 v61, v1, v63, v61
	v_div_scale_f32 v1, s[46:47], v62, v62, v60
	v_rcp_f32_e32 v63, v1
	s_nop 0
	v_fma_f32 v69, -v1, v63, 1.0
	v_fmac_f32_e32 v63, v69, v63
	v_div_scale_f32 v69, vcc, v60, v62, v60
	v_mul_f32_e32 v74, v69, v63
	v_fma_f32 v75, -v1, v74, v69
	v_fmac_f32_e32 v74, v75, v63
	v_fma_f32 v1, -v1, v74, v69
	v_div_fmas_f32 v1, v1, v63, v74
	v_div_fixup_f32 v60, v1, v62, v60
	v_pk_mul_f32 v[60:61], v[64:65], v[60:61]
	v_mul_f32_e32 v1, 0xbfb8aa3b, v54
	v_cvt_pk_bf16_f32 v59, v60, v61
	global_store_dwordx2 v[72:73], v[58:59], off
	v_exp_f32_e32 v58, v1
	v_mul_f32_e32 v1, 0xbfb8aa3b, v55
	v_exp_f32_e32 v59, v1
	s_nop 0
	v_pk_add_f32 v[58:59], v[58:59], 1.0 op_sel_hi:[1,0]
	s_nop 0
	v_div_scale_f32 v1, s[46:47], v59, v59, v55
	v_rcp_f32_e32 v60, v1
	s_nop 0
	v_fma_f32 v61, -v1, v60, 1.0
	v_fmac_f32_e32 v60, v61, v60
	v_div_scale_f32 v61, vcc, v55, v59, v55
	v_mul_f32_e32 v62, v61, v60
	v_fma_f32 v63, -v1, v62, v61
	v_fmac_f32_e32 v62, v63, v60
	v_fma_f32 v1, -v1, v62, v61
	v_div_fmas_f32 v1, v1, v60, v62
	v_div_fixup_f32 v55, v1, v59, v55
	v_div_scale_f32 v1, s[46:47], v58, v58, v54
	v_rcp_f32_e32 v59, v1
	s_nop 0
	v_fma_f32 v60, -v1, v59, 1.0
	v_fmac_f32_e32 v59, v60, v59
	v_div_scale_f32 v60, vcc, v54, v58, v54
	v_mul_f32_e32 v61, v60, v59
	v_fma_f32 v62, -v1, v61, v60
	v_fmac_f32_e32 v61, v62, v59
	v_fma_f32 v1, -v1, v61, v60
	v_div_fmas_f32 v1, v1, v59, v61
	v_div_fixup_f32 v54, v1, v58, v54
	v_mul_f32_e32 v1, 0xbfb8aa3b, v56
	v_pk_mul_f32 v[50:51], v[50:51], v[54:55]
	v_exp_f32_e32 v54, v1
	v_mul_f32_e32 v1, 0xbfb8aa3b, v57
	v_exp_f32_e32 v55, v1
	v_cvt_pk_bf16_f32 v50, v50, v51
	v_pk_add_f32 v[54:55], v[54:55], 1.0 op_sel_hi:[1,0]
	s_nop 0
	v_div_scale_f32 v1, s[46:47], v55, v55, v57
	v_rcp_f32_e32 v58, v1
	s_nop 0
	v_fma_f32 v59, -v1, v58, 1.0
	v_fmac_f32_e32 v58, v59, v58
	v_div_scale_f32 v59, vcc, v57, v55, v57
	v_mul_f32_e32 v60, v59, v58
	v_fma_f32 v61, -v1, v60, v59
	v_fmac_f32_e32 v60, v61, v58
	v_fma_f32 v1, -v1, v60, v59
	v_div_fmas_f32 v1, v1, v58, v60
	v_div_fixup_f32 v55, v1, v55, v57
	v_div_scale_f32 v1, s[46:47], v54, v54, v56
	v_rcp_f32_e32 v57, v1
	s_nop 0
	v_fma_f32 v58, -v1, v57, 1.0
	v_fmac_f32_e32 v57, v58, v57
	v_div_scale_f32 v58, vcc, v56, v54, v56
	v_mul_f32_e32 v59, v58, v57
	v_fma_f32 v60, -v1, v59, v58
	v_fmac_f32_e32 v59, v60, v57
	v_fma_f32 v1, -v1, v59, v58
	v_div_fmas_f32 v1, v1, v57, v59
	v_div_fixup_f32 v54, v1, v54, v56
	v_pk_mul_f32 v[52:53], v[52:53], v[54:55]
	v_mul_f32_e32 v1, 0xbfb8aa3b, v42
	v_cvt_pk_bf16_f32 v51, v52, v53
	v_exp_f32_e32 v52, v1
	v_mul_f32_e32 v1, 0xbfb8aa3b, v43
	v_exp_f32_e32 v53, v1
	global_store_dwordx2 v[72:73], v[50:51], off offset:32
	v_or_b32_e32 v50, 16, v68
	v_ashrrev_i32_e32 v51, 31, v50
	v_pk_add_f32 v[52:53], v[52:53], 1.0 op_sel_hi:[1,0]
	v_lshlrev_b64 v[50:51], 11, v[50:51]
	v_div_scale_f32 v1, s[46:47], v53, v53, v43
	v_rcp_f32_e32 v54, v1
	v_lshl_add_u64 v[50:51], s[4:5], 0, v[50:51]
	v_lshl_add_u64 v[50:51], v[50:51], 0, s[2:3]
	v_lshl_add_u64 v[50:51], v[50:51], 0, v[66:67]
	v_fma_f32 v55, -v1, v54, 1.0
	v_fmac_f32_e32 v54, v55, v54
	v_div_scale_f32 v55, vcc, v43, v53, v43
	v_mul_f32_e32 v56, v55, v54
	v_fma_f32 v57, -v1, v56, v55
	v_fmac_f32_e32 v56, v57, v54
	v_fma_f32 v1, -v1, v56, v55
	v_div_fmas_f32 v1, v1, v54, v56
	v_div_fixup_f32 v43, v1, v53, v43
	v_div_scale_f32 v1, s[46:47], v52, v52, v42
	v_rcp_f32_e32 v53, v1
	v_lshl_add_u64 v[50:51], v[50:51], 0, v[70:71]
	v_fma_f32 v54, -v1, v53, 1.0
	v_fmac_f32_e32 v53, v54, v53
	v_div_scale_f32 v54, vcc, v42, v52, v42
	v_mul_f32_e32 v55, v54, v53
	v_fma_f32 v56, -v1, v55, v54
	v_fmac_f32_e32 v55, v56, v53
	v_fma_f32 v1, -v1, v55, v54
	v_div_fmas_f32 v1, v1, v53, v55
	v_div_fixup_f32 v42, v1, v52, v42
	v_mul_f32_e32 v1, 0xbfb8aa3b, v44
	v_pk_mul_f32 v[42:43], v[46:47], v[42:43]
	v_exp_f32_e32 v46, v1
	v_mul_f32_e32 v1, 0xbfb8aa3b, v45
	v_exp_f32_e32 v47, v1
	v_cvt_pk_bf16_f32 v42, v42, v43
	v_pk_add_f32 v[46:47], v[46:47], 1.0 op_sel_hi:[1,0]
	s_nop 0
	v_div_scale_f32 v1, s[46:47], v47, v47, v45
	v_rcp_f32_e32 v52, v1
	s_nop 0
	v_fma_f32 v53, -v1, v52, 1.0
	v_fmac_f32_e32 v52, v53, v52
	v_div_scale_f32 v53, vcc, v45, v47, v45
	v_mul_f32_e32 v54, v53, v52
	v_fma_f32 v55, -v1, v54, v53
	v_fmac_f32_e32 v54, v55, v52
	v_fma_f32 v1, -v1, v54, v53
	v_div_fmas_f32 v1, v1, v52, v54
	v_div_fixup_f32 v45, v1, v47, v45
	v_div_scale_f32 v1, s[46:47], v46, v46, v44
	v_rcp_f32_e32 v47, v1
	s_nop 0
	v_fma_f32 v52, -v1, v47, 1.0
	v_fmac_f32_e32 v47, v52, v47
	v_div_scale_f32 v52, vcc, v44, v46, v44
	v_mul_f32_e32 v53, v52, v47
	v_fma_f32 v54, -v1, v53, v52
	v_fmac_f32_e32 v53, v54, v47
	v_fma_f32 v1, -v1, v53, v52
	v_div_fmas_f32 v1, v1, v47, v53
	v_div_fixup_f32 v44, v1, v46, v44
	v_pk_mul_f32 v[44:45], v[48:49], v[44:45]
	v_mul_f32_e32 v1, 0xbfb8aa3b, v38
	v_cvt_pk_bf16_f32 v43, v44, v45
	global_store_dwordx2 v[50:51], v[42:43], off
	v_exp_f32_e32 v42, v1
	v_mul_f32_e32 v1, 0xbfb8aa3b, v39
	v_exp_f32_e32 v43, v1
	s_nop 0
	v_pk_add_f32 v[42:43], v[42:43], 1.0 op_sel_hi:[1,0]
	s_nop 0
	v_div_scale_f32 v1, s[46:47], v43, v43, v39
	v_rcp_f32_e32 v44, v1
	s_nop 0
	v_fma_f32 v45, -v1, v44, 1.0
	v_fmac_f32_e32 v44, v45, v44
	v_div_scale_f32 v45, vcc, v39, v43, v39
	v_mul_f32_e32 v46, v45, v44
	v_fma_f32 v47, -v1, v46, v45
	v_fmac_f32_e32 v46, v47, v44
	v_fma_f32 v1, -v1, v46, v45
	v_div_fmas_f32 v1, v1, v44, v46
	v_div_fixup_f32 v39, v1, v43, v39
	v_div_scale_f32 v1, s[46:47], v42, v42, v38
	v_rcp_f32_e32 v43, v1
	s_nop 0
	v_fma_f32 v44, -v1, v43, 1.0
	v_fmac_f32_e32 v43, v44, v43
	v_div_scale_f32 v44, vcc, v38, v42, v38
	v_mul_f32_e32 v45, v44, v43
	v_fma_f32 v46, -v1, v45, v44
	v_fmac_f32_e32 v45, v46, v43
	v_fma_f32 v1, -v1, v45, v44
	v_div_fmas_f32 v1, v1, v43, v45
	v_div_fixup_f32 v38, v1, v42, v38
	v_mul_f32_e32 v1, 0xbfb8aa3b, v40
	v_pk_mul_f32 v[34:35], v[34:35], v[38:39]
	v_exp_f32_e32 v38, v1
	v_mul_f32_e32 v1, 0xbfb8aa3b, v41
	v_exp_f32_e32 v39, v1
	v_cvt_pk_bf16_f32 v34, v34, v35
	v_pk_add_f32 v[38:39], v[38:39], 1.0 op_sel_hi:[1,0]
	s_nop 0
	v_div_scale_f32 v1, s[46:47], v39, v39, v41
	v_rcp_f32_e32 v42, v1
	s_nop 0
	v_fma_f32 v43, -v1, v42, 1.0
	v_fmac_f32_e32 v42, v43, v42
	v_div_scale_f32 v43, vcc, v41, v39, v41
	v_mul_f32_e32 v44, v43, v42
	v_fma_f32 v45, -v1, v44, v43
	v_fmac_f32_e32 v44, v45, v42
	v_fma_f32 v1, -v1, v44, v43
	v_div_fmas_f32 v1, v1, v42, v44
	v_div_fixup_f32 v39, v1, v39, v41
	v_div_scale_f32 v1, s[46:47], v38, v38, v40
	v_rcp_f32_e32 v41, v1
	s_nop 0
	v_fma_f32 v42, -v1, v41, 1.0
	v_fmac_f32_e32 v41, v42, v41
	v_div_scale_f32 v42, vcc, v40, v38, v40
	v_mul_f32_e32 v43, v42, v41
	v_fma_f32 v44, -v1, v43, v42
	v_fmac_f32_e32 v43, v44, v41
	v_fma_f32 v1, -v1, v43, v42
	v_div_fmas_f32 v1, v1, v41, v43
	v_div_fixup_f32 v38, v1, v38, v40
	v_pk_mul_f32 v[36:37], v[36:37], v[38:39]
	v_mul_f32_e32 v1, 0xbfb8aa3b, v26
	v_cvt_pk_bf16_f32 v35, v36, v37
	v_exp_f32_e32 v36, v1
	v_mul_f32_e32 v1, 0xbfb8aa3b, v27
	v_exp_f32_e32 v37, v1
	global_store_dwordx2 v[50:51], v[34:35], off offset:32
	v_or_b32_e32 v34, 32, v68
	v_ashrrev_i32_e32 v35, 31, v34
	v_pk_add_f32 v[36:37], v[36:37], 1.0 op_sel_hi:[1,0]
	v_lshlrev_b64 v[34:35], 11, v[34:35]
	v_div_scale_f32 v1, s[46:47], v37, v37, v27
	v_rcp_f32_e32 v38, v1
	v_lshl_add_u64 v[34:35], s[4:5], 0, v[34:35]
	v_lshl_add_u64 v[34:35], v[34:35], 0, s[2:3]
	v_lshl_add_u64 v[34:35], v[34:35], 0, v[66:67]
	v_fma_f32 v39, -v1, v38, 1.0
	v_fmac_f32_e32 v38, v39, v38
	v_div_scale_f32 v39, vcc, v27, v37, v27
	v_mul_f32_e32 v40, v39, v38
	v_fma_f32 v41, -v1, v40, v39
	v_fmac_f32_e32 v40, v41, v38
	v_fma_f32 v1, -v1, v40, v39
	v_div_fmas_f32 v1, v1, v38, v40
	v_div_fixup_f32 v27, v1, v37, v27
	v_div_scale_f32 v1, s[46:47], v36, v36, v26
	v_rcp_f32_e32 v37, v1
	v_lshl_add_u64 v[34:35], v[34:35], 0, v[70:71]
	v_fma_f32 v38, -v1, v37, 1.0
	v_fmac_f32_e32 v37, v38, v37
	v_div_scale_f32 v38, vcc, v26, v36, v26
	v_mul_f32_e32 v39, v38, v37
	v_fma_f32 v40, -v1, v39, v38
	v_fmac_f32_e32 v39, v40, v37
	v_fma_f32 v1, -v1, v39, v38
	v_div_fmas_f32 v1, v1, v37, v39
	v_div_fixup_f32 v26, v1, v36, v26
	v_mul_f32_e32 v1, 0xbfb8aa3b, v28
	v_pk_mul_f32 v[26:27], v[30:31], v[26:27]
	v_exp_f32_e32 v30, v1
	v_mul_f32_e32 v1, 0xbfb8aa3b, v29
	v_exp_f32_e32 v31, v1
	v_cvt_pk_bf16_f32 v26, v26, v27
	v_pk_add_f32 v[30:31], v[30:31], 1.0 op_sel_hi:[1,0]
	s_nop 0
	v_div_scale_f32 v1, s[46:47], v31, v31, v29
	v_rcp_f32_e32 v36, v1
	s_nop 0
	v_fma_f32 v37, -v1, v36, 1.0
	v_fmac_f32_e32 v36, v37, v36
	v_div_scale_f32 v37, vcc, v29, v31, v29
	v_mul_f32_e32 v38, v37, v36
	v_fma_f32 v39, -v1, v38, v37
	v_fmac_f32_e32 v38, v39, v36
	v_fma_f32 v1, -v1, v38, v37
	v_div_fmas_f32 v1, v1, v36, v38
	v_div_fixup_f32 v29, v1, v31, v29
	v_div_scale_f32 v1, s[46:47], v30, v30, v28
	v_rcp_f32_e32 v31, v1
	s_nop 0
	v_fma_f32 v36, -v1, v31, 1.0
	v_fmac_f32_e32 v31, v36, v31
	v_div_scale_f32 v36, vcc, v28, v30, v28
	v_mul_f32_e32 v37, v36, v31
	v_fma_f32 v38, -v1, v37, v36
	v_fmac_f32_e32 v37, v38, v31
	v_fma_f32 v1, -v1, v37, v36
	v_div_fmas_f32 v1, v1, v31, v37
	v_div_fixup_f32 v28, v1, v30, v28
	v_pk_mul_f32 v[28:29], v[32:33], v[28:29]
	v_mul_f32_e32 v1, 0xbfb8aa3b, v22
	v_cvt_pk_bf16_f32 v27, v28, v29
	global_store_dwordx2 v[34:35], v[26:27], off
	v_exp_f32_e32 v26, v1
	v_mul_f32_e32 v1, 0xbfb8aa3b, v23
	v_exp_f32_e32 v27, v1
	s_nop 0
	v_pk_add_f32 v[26:27], v[26:27], 1.0 op_sel_hi:[1,0]
	s_nop 0
	v_div_scale_f32 v1, s[46:47], v27, v27, v23
	v_rcp_f32_e32 v28, v1
	s_nop 0
	v_fma_f32 v29, -v1, v28, 1.0
	v_fmac_f32_e32 v28, v29, v28
	v_div_scale_f32 v29, vcc, v23, v27, v23
	v_mul_f32_e32 v30, v29, v28
	v_fma_f32 v31, -v1, v30, v29
	v_fmac_f32_e32 v30, v31, v28
	v_fma_f32 v1, -v1, v30, v29
	v_div_fmas_f32 v1, v1, v28, v30
	v_div_fixup_f32 v23, v1, v27, v23
	v_div_scale_f32 v1, s[46:47], v26, v26, v22
	v_rcp_f32_e32 v27, v1
	s_nop 0
	v_fma_f32 v28, -v1, v27, 1.0
	v_fmac_f32_e32 v27, v28, v27
	v_div_scale_f32 v28, vcc, v22, v26, v22
	v_mul_f32_e32 v29, v28, v27
	v_fma_f32 v30, -v1, v29, v28
	v_fmac_f32_e32 v29, v30, v27
	v_fma_f32 v1, -v1, v29, v28
	v_div_fmas_f32 v1, v1, v27, v29
	v_div_fixup_f32 v22, v1, v26, v22
	v_mul_f32_e32 v1, 0xbfb8aa3b, v24
	v_pk_mul_f32 v[18:19], v[18:19], v[22:23]
	v_exp_f32_e32 v22, v1
	v_mul_f32_e32 v1, 0xbfb8aa3b, v25
	v_exp_f32_e32 v23, v1
	v_cvt_pk_bf16_f32 v18, v18, v19
	v_pk_add_f32 v[22:23], v[22:23], 1.0 op_sel_hi:[1,0]
	s_nop 0
	v_div_scale_f32 v1, s[46:47], v23, v23, v25
	v_rcp_f32_e32 v26, v1
	s_nop 0
	v_fma_f32 v27, -v1, v26, 1.0
	v_fmac_f32_e32 v26, v27, v26
	v_div_scale_f32 v27, vcc, v25, v23, v25
	v_mul_f32_e32 v28, v27, v26
	v_fma_f32 v29, -v1, v28, v27
	v_fmac_f32_e32 v28, v29, v26
	v_fma_f32 v1, -v1, v28, v27
	v_div_fmas_f32 v1, v1, v26, v28
	v_div_fixup_f32 v23, v1, v23, v25
	v_div_scale_f32 v1, s[46:47], v22, v22, v24
	v_rcp_f32_e32 v25, v1
	s_nop 0
	v_fma_f32 v26, -v1, v25, 1.0
	v_fmac_f32_e32 v25, v26, v25
	v_div_scale_f32 v26, vcc, v24, v22, v24
	v_mul_f32_e32 v27, v26, v25
	v_fma_f32 v28, -v1, v27, v26
	v_fmac_f32_e32 v27, v28, v25
	v_fma_f32 v1, -v1, v27, v26
	v_div_fmas_f32 v1, v1, v25, v27
	v_div_fixup_f32 v22, v1, v22, v24
	v_pk_mul_f32 v[20:21], v[20:21], v[22:23]
	v_mul_f32_e32 v1, 0xbfb8aa3b, v10
	v_cvt_pk_bf16_f32 v19, v20, v21
	v_exp_f32_e32 v20, v1
	v_mul_f32_e32 v1, 0xbfb8aa3b, v11
	v_exp_f32_e32 v21, v1
	global_store_dwordx2 v[34:35], v[18:19], off offset:32
	v_or_b32_e32 v18, 48, v68
	v_ashrrev_i32_e32 v19, 31, v18
	v_lshlrev_b64 v[18:19], 11, v[18:19]
	v_pk_add_f32 v[20:21], v[20:21], 1.0 op_sel_hi:[1,0]
	v_lshl_add_u64 v[18:19], s[4:5], 0, v[18:19]
	v_div_scale_f32 v1, s[4:5], v21, v21, v11
	v_rcp_f32_e32 v22, v1
	v_lshl_add_u64 v[18:19], v[18:19], 0, s[2:3]
	v_lshl_add_u64 v[18:19], v[18:19], 0, v[66:67]
	v_lshl_add_u64 v[18:19], v[18:19], 0, v[70:71]
	v_fma_f32 v23, -v1, v22, 1.0
	v_fmac_f32_e32 v22, v23, v22
	v_div_scale_f32 v23, vcc, v11, v21, v11
	v_mul_f32_e32 v24, v23, v22
	v_fma_f32 v25, -v1, v24, v23
	v_fmac_f32_e32 v24, v25, v22
	v_fma_f32 v1, -v1, v24, v23
	v_div_fmas_f32 v1, v1, v22, v24
	v_div_fixup_f32 v11, v1, v21, v11
	v_div_scale_f32 v1, s[4:5], v20, v20, v10
	v_rcp_f32_e32 v21, v1
	s_nop 0
	v_fma_f32 v22, -v1, v21, 1.0
	v_fmac_f32_e32 v21, v22, v21
	v_div_scale_f32 v22, vcc, v10, v20, v10
	v_mul_f32_e32 v23, v22, v21
	v_fma_f32 v24, -v1, v23, v22
	v_fmac_f32_e32 v23, v24, v21
	v_fma_f32 v1, -v1, v23, v22
	v_div_fmas_f32 v1, v1, v21, v23
	v_div_fixup_f32 v10, v1, v20, v10
	v_mul_f32_e32 v1, 0xbfb8aa3b, v12
	v_pk_mul_f32 v[10:11], v[14:15], v[10:11]
	v_exp_f32_e32 v14, v1
	v_mul_f32_e32 v1, 0xbfb8aa3b, v13
	v_exp_f32_e32 v15, v1
	v_cvt_pk_bf16_f32 v10, v10, v11
	v_pk_add_f32 v[14:15], v[14:15], 1.0 op_sel_hi:[1,0]
	s_nop 0
	v_div_scale_f32 v1, s[4:5], v15, v15, v13
	v_rcp_f32_e32 v20, v1
	s_nop 0
	v_fma_f32 v21, -v1, v20, 1.0
	v_fmac_f32_e32 v20, v21, v20
	v_div_scale_f32 v21, vcc, v13, v15, v13
	v_mul_f32_e32 v22, v21, v20
	v_fma_f32 v23, -v1, v22, v21
	v_fmac_f32_e32 v22, v23, v20
	v_fma_f32 v1, -v1, v22, v21
	v_div_fmas_f32 v1, v1, v20, v22
	v_div_fixup_f32 v13, v1, v15, v13
	v_div_scale_f32 v1, s[4:5], v14, v14, v12
	v_rcp_f32_e32 v15, v1
	s_nop 0
	v_fma_f32 v20, -v1, v15, 1.0
	v_fmac_f32_e32 v15, v20, v15
	v_div_scale_f32 v20, vcc, v12, v14, v12
	v_mul_f32_e32 v21, v20, v15
	v_fma_f32 v22, -v1, v21, v20
	v_fmac_f32_e32 v21, v22, v15
	v_fma_f32 v1, -v1, v21, v20
	v_div_fmas_f32 v1, v1, v15, v21
	v_div_fixup_f32 v12, v1, v14, v12
	v_pk_mul_f32 v[12:13], v[16:17], v[12:13]
	v_mul_f32_e32 v1, 0xbfb8aa3b, v6
	v_cvt_pk_bf16_f32 v11, v12, v13
	global_store_dwordx2 v[18:19], v[10:11], off
	v_exp_f32_e32 v10, v1
	v_mul_f32_e32 v1, 0xbfb8aa3b, v7
	v_exp_f32_e32 v11, v1
	s_nop 0
	v_pk_add_f32 v[10:11], v[10:11], 1.0 op_sel_hi:[1,0]
	s_nop 0
	v_div_scale_f32 v1, s[4:5], v11, v11, v7
	v_rcp_f32_e32 v12, v1
	s_nop 0
	v_fma_f32 v13, -v1, v12, 1.0
	v_fmac_f32_e32 v12, v13, v12
	v_div_scale_f32 v13, vcc, v7, v11, v7
	v_mul_f32_e32 v14, v13, v12
	v_fma_f32 v15, -v1, v14, v13
	v_fmac_f32_e32 v14, v15, v12
	v_fma_f32 v1, -v1, v14, v13
	v_div_fmas_f32 v1, v1, v12, v14
	v_div_fixup_f32 v7, v1, v11, v7
	v_div_scale_f32 v1, s[4:5], v10, v10, v6
	v_rcp_f32_e32 v11, v1
	s_nop 0
	v_fma_f32 v12, -v1, v11, 1.0
	v_fmac_f32_e32 v11, v12, v11
	v_div_scale_f32 v12, vcc, v6, v10, v6
	v_mul_f32_e32 v13, v12, v11
	v_fma_f32 v14, -v1, v13, v12
	v_fmac_f32_e32 v13, v14, v11
	v_fma_f32 v1, -v1, v13, v12
	v_div_fmas_f32 v1, v1, v11, v13
	v_div_fixup_f32 v6, v1, v10, v6
	v_mul_f32_e32 v1, 0xbfb8aa3b, v8
	v_pk_mul_f32 v[2:3], v[2:3], v[6:7]
	v_exp_f32_e32 v6, v1
	v_mul_f32_e32 v1, 0xbfb8aa3b, v9
	v_exp_f32_e32 v7, v1
	v_cvt_pk_bf16_f32 v2, v2, v3
	v_pk_add_f32 v[6:7], v[6:7], 1.0 op_sel_hi:[1,0]
	s_nop 0
	v_div_scale_f32 v1, s[4:5], v7, v7, v9
	v_rcp_f32_e32 v10, v1
	s_nop 0
	v_fma_f32 v11, -v1, v10, 1.0
	v_fmac_f32_e32 v10, v11, v10
	v_div_scale_f32 v11, vcc, v9, v7, v9
	v_mul_f32_e32 v12, v11, v10
	v_fma_f32 v13, -v1, v12, v11
	v_fmac_f32_e32 v12, v13, v10
	v_fma_f32 v1, -v1, v12, v11
	v_div_fmas_f32 v1, v1, v10, v12
	v_div_fixup_f32 v7, v1, v7, v9
	v_div_scale_f32 v1, s[4:5], v6, v6, v8
	v_rcp_f32_e32 v9, v1
	s_nop 0
	v_fma_f32 v10, -v1, v9, 1.0
	v_fmac_f32_e32 v9, v10, v9
	v_div_scale_f32 v10, vcc, v8, v6, v8
	v_mul_f32_e32 v11, v10, v9
	v_fma_f32 v12, -v1, v11, v10
	v_fmac_f32_e32 v11, v12, v9
	v_fma_f32 v1, -v1, v11, v10
	v_div_fmas_f32 v1, v1, v9, v11
	v_div_fixup_f32 v6, v1, v6, v8
	v_pk_mul_f32 v[4:5], v[4:5], v[6:7]
	s_nop 0
	v_cvt_pk_bf16_f32 v3, v4, v5
	global_store_dwordx2 v[18:19], v[2:3], off offset:32
	s_cbranch_scc1 .LBB0_838
	v_readlane_b32 s0, v196, 26
	v_readlane_b32 s47, v196, 5
	v_readlane_b32 s96, v196, 24
	v_readlane_b32 s1, v196, 27
	s_mov_b32 s46, s66
	v_readlane_b32 s97, v196, 25

.LBB0_895:
	s_cmpk_gt_i32 s47, 0x3ff
	s_cbranch_scc1 .LBB0_899
	v_writelane_b32 v196, s24, 26
	v_readlane_b32 s4, v197, 34
	v_readlane_b32 s5, v197, 35
	v_writelane_b32 v196, s25, 27
	v_readlane_b32 s6, v197, 36
	v_readlane_b32 s7, v197, 37
	v_readlane_b32 s8, v197, 38
	v_readlane_b32 s9, v197, 39
	v_readlane_b32 s10, v197, 40
	v_readlane_b32 s11, v197, 41
	v_readlane_b32 s12, v197, 42
	v_readlane_b32 s13, v197, 43
	v_readlane_b32 s14, v197, 44
	v_readlane_b32 s15, v197, 45
	v_readlane_b32 s16, v197, 46
	v_readlane_b32 s17, v197, 47
	v_readlane_b32 s18, v197, 48
	v_readlane_b32 s19, v197, 49
	v_readlane_b32 s4, v196, 6
	v_readlane_b32 s5, v196, 7
	s_lshl_b32 s65, s47, 2
	s_mov_b32 s28, s46
	s_lshl_b32 s66, s46, 2
	s_lshl_b32 s67, s47, 4
	s_lshl_b32 s68, s46, 4
	s_lshl_b32 s69, s47, 7
	s_lshl_b32 s33, s46, 7
	v_mov_b32_e32 v3, 0
	s_add_i32 s64, 0, 0xc000
	s_mov_b64 s[30:31], 0x380
	s_mov_b64 s[34:35], 0x20380
	s_mov_b64 s[36:37], 0x400
	s_mov_b32 s72, s47
	s_mov_b64 s[46:47], 0x20400
	s_mov_b64 s[70:71], 0x480
	s_mov_b64 s[74:75], 0x20480
	s_mov_b64 s[76:77], 0x500
	s_mov_b64 s[78:79], 0x20500
	s_mov_b64 s[80:81], 0x580
	s_mov_b64 s[82:83], 0x20580
	s_mov_b64 s[96:97], 0x600
	s_mov_b64 vcc, 0x20600
	s_mov_b64 s[24:25], 0x680
	s_mov_b64 s[2:3], 0x20680
	s_mov_b64 s[38:39], 0x700
	s_mov_b64 s[56:57], 0x20700
	s_mov_b64 s[58:59], 0x780
	s_mov_b64 s[60:61], 0x20780
	s_mov_b64 s[4:5], 0x20000
	v_readlane_b32 s6, v196, 8
	v_readlane_b32 s7, v196, 9
	v_readlane_b32 s8, v196, 10
	v_readlane_b32 s9, v196, 11
	v_readlane_b32 s10, v196, 12
	v_readlane_b32 s11, v196, 13
	v_readlane_b32 s12, v196, 14
	v_readlane_b32 s13, v196, 15
	v_readlane_b32 s14, v196, 16
	v_readlane_b32 s15, v196, 17
	v_readlane_b32 s16, v196, 18
	v_readlane_b32 s17, v196, 19
	v_readlane_b32 s18, v196, 20
	v_readlane_b32 s19, v196, 21
	s_mov_b32 s98, s72
.LBB0_897:
	s_mov_b32 s72, s98
	s_cmp_lg_u32 s66, 0x400
	s_cbranch_scc1 .Lremap_done_8
	s_lshr_b32 s0, s98, 8
	s_bfe_u32 s1, s98, 0x30005
	s_and_b32 s6, s98, 31
	s_lshr_b32 s7, s0, 1
	s_lshl_b32 s7, s7, 3
	s_add_i32 s1, s1, s7
	s_and_b32 s0, s0, 1
	s_lshl_b32 s0, s0, 3
	s_lshr_b32 s8, s6, 2
	s_add_i32 s0, s0, s8
	s_and_b32 s6, s6, 3
	s_lshl_b32 s6, s6, 4
	s_lshl_b32 s1, s1, 6
	s_add_i32 s1, s1, s6
	s_add_i32 s72, s1, s0
.Lremap_done_8:
	s_lshl_b32 s65, s72, 2
	s_lshl_b32 s67, s72, 4
	s_lshl_b32 s69, s72, 7
	s_ashr_i32 s0, s72, 6
	s_and_b32 s1, s65, 48
	s_add_i32 s6, s1, s0
	s_ashr_i32 s1, s0, 31
	v_readlane_b32 s8, v197, 34
	s_and_b32 s73, s67, 0x300
	s_lshl_b64 s[0:1], s[0:1], 21
	v_readlane_b32 s20, v197, 46
	v_readlane_b32 s21, v197, 47
	s_add_u32 s0, s20, s0
	s_addc_u32 s1, s21, s1
	s_lshl_b32 s7, s73, 11
	s_add_u32 s0, s0, s7
	v_mov_b32_e32 v1, v0
	s_addc_u32 s1, s1, 0
	s_ashr_i32 s7, s6, 31
	s_waitcnt vmcnt(0) lgkmcnt(0)
	s_barrier
	s_lshl_b64 s[62:63], s[6:7], 9
	v_ashrrev_i32_e32 v4, 3, v1
	s_and_b32 s84, s69, 0x180
	v_lshrrev_b32_e32 v2, 4, v1
	v_readlane_b32 s9, v197, 35
	v_readlane_b32 s10, v197, 36
	v_readlane_b32 s11, v197, 37
	v_readlane_b32 s12, v197, 38
	v_readlane_b32 s13, v197, 39
	v_readlane_b32 s14, v197, 40
	v_readlane_b32 s15, v197, 41
	v_readlane_b32 s16, v197, 42
	v_readlane_b32 s17, v197, 43
	v_readlane_b32 s18, v197, 44
	v_readlane_b32 s19, v197, 45
	v_readlane_b32 s22, v197, 48
	v_readlane_b32 s23, v197, 49
	s_or_b32 s6, s62, s84
	s_mov_b32 s7, s63
	v_ashrrev_i32_e32 v5, 31, v4
	v_xor_b32_e32 v2, v2, v1
	v_lshl_add_u64 v[6:7], s[6:7], 0, v[4:5]
	v_readlane_b32 s8, v196, 6
	v_lshlrev_b64 v[6:7], 11, v[6:7]
	v_readlane_b32 s22, v196, 20
	v_readlane_b32 s23, v196, 21
	v_lshlrev_b32_e32 v2, 4, v2
	v_lshlrev_b64 v[4:5], 11, v[4:5]
	v_lshl_add_u64 v[6:7], s[22:23], 0, v[6:7]
	v_and_b32_e32 v2, 0x70, v2
	v_lshl_add_u64 v[4:5], s[0:1], 0, v[4:5]
	v_lshl_add_u64 v[6:7], v[6:7], 0, v[2:3]
	v_lshl_add_u64 v[4:5], v[4:5], 0, v[2:3]
	v_mov_b32_e32 v2, v0
	s_mov_b64 s[0:1], 0x40000
	v_lshl_add_u64 v[12:13], v[4:5], 0, s[0:1]
	v_readfirstlane_b32 s6, v2
	s_mov_b64 s[0:1], 0x60000
	v_lshl_add_u64 v[14:15], v[4:5], 0, s[0:1]
	s_lshl_b32 s0, s6, 4
	s_and_b32 s0, s0, 0xfffffc00
	s_add_i32 s6, s0, 0
	s_mov_b32 m0, s6
	s_add_i32 s87, s6, 0x2000
	v_lshl_add_u64 v[8:9], v[6:7], 0, s[4:5]
	global_load_lds_dwordx4 v[6:7], off
	s_mov_b32 m0, s87
	s_add_i32 s0, s6, 0x4000
	global_load_lds_dwordx4 v[8:9], off
	s_mov_b32 m0, s0
	s_add_i32 s1, s6, 0x6000
	v_lshl_add_u64 v[10:11], v[4:5], 0, s[4:5]
	global_load_lds_dwordx4 v[4:5], off
	s_mov_b32 m0, s1
	s_add_i32 s86, s6, 0x8000
	v_readlane_b32 s10, v196, 8
	v_readlane_b32 s11, v196, 9
	global_load_lds_dwordx4 v[10:11], off
	s_mov_b32 m0, s86
	s_add_i32 s85, s6, 0xa000
	v_readlane_b32 s12, v196, 10
	v_readlane_b32 s13, v196, 11
	global_load_lds_dwordx4 v[12:13], off
	s_mov_b32 m0, s85
	s_mov_b64 s[10:11], 0x80
	s_add_i32 s8, s6, 0xc000
	v_readlane_b32 s9, v196, 7
	global_load_lds_dwordx4 v[14:15], off
	v_lshl_add_u64 v[8:9], v[6:7], 0, s[10:11]
	s_mov_b32 m0, s8
	s_mov_b64 s[12:13], 0x20080
	s_add_i32 s7, s6, 0xe000
	global_load_lds_dwordx4 v[8:9], off
	v_lshl_add_u64 v[8:9], v[6:7], 0, s[12:13]
	s_mov_b32 m0, s7
	s_add_i32 s9, s6, 0x10000
	global_load_lds_dwordx4 v[8:9], off
	v_lshl_add_u64 v[8:9], v[4:5], 0, s[10:11]
	s_mov_b32 m0, s9
	s_add_i32 s10, s6, 0x12000
	global_load_lds_dwordx4 v[8:9], off
	v_lshl_add_u64 v[8:9], v[4:5], 0, s[12:13]
	s_mov_b32 m0, s10
	s_mov_b64 s[12:13], 0x40080
	s_add_i32 s11, s6, 0x14000
	global_load_lds_dwordx4 v[8:9], off
	v_lshl_add_u64 v[8:9], v[4:5], 0, s[12:13]
	s_mov_b32 m0, s11
	s_mov_b64 s[12:13], 0x60080
	global_load_lds_dwordx4 v[8:9], off
	v_lshl_add_u64 v[8:9], v[4:5], 0, s[12:13]
	s_add_i32 s12, s6, 0x16000
	s_mov_b32 m0, s12
	v_lshrrev_b32_e32 v16, 4, v2
	v_and_b32_e32 v18, 15, v2
	global_load_lds_dwordx4 v[8:9], off
	v_bfe_u32 v8, v2, 1, 3
	v_lshrrev_b32_e32 v9, 2, v2
	s_mov_b32 s13, 0x1ffffc0
	v_bfe_u32 v17, v2, 4, 2
	v_and_or_b32 v9, v9, s13, v18
	v_lshlrev_b32_e32 v2, 7, v2
	v_bitop3_b32 v10, v16, v8, 3 bitop3:0x6c
	v_readlane_b32 s16, v196, 14
	v_readlane_b32 s17, v196, 15
	v_lshlrev_b32_e32 v9, 7, v9
	v_and_b32_e32 v60, 0x6780, v2
	v_lshlrev_b32_e32 v10, 4, v10
	v_bitop3_b32 v8, v17, v8, 4 bitop3:0x36
	v_readlane_b32 s14, v196, 12
	v_readlane_b32 s18, v196, 16
	v_readlane_b32 s19, v196, 17
	v_add_u32_e32 v2, 0x4000, v60
	v_or_b32_e32 v144, v10, v9
	v_lshlrev_b32_e32 v61, 4, v8
	v_or_b32_e32 v8, v10, v60
	s_add_i32 s13, s6, 0x18000
	s_mov_b64 s[16:17], 0x100
	v_readlane_b32 s15, v196, 13
	s_waitcnt vmcnt(6)
	s_barrier
	v_or_b32_e32 v145, v10, v2
	v_or_b32_e32 v149, v61, v2
	v_add_u32_e32 v2, 0, v144
	v_add_u32_e32 v8, 0, v8
	v_lshl_add_u64 v[10:11], v[6:7], 0, s[16:17]
	s_mov_b32 m0, s13
	s_mov_b64 s[18:19], 0x20100
	s_add_i32 s14, s6, 0x1a000
	ds_read_b128 v[12:15], v2
	ds_read_b128 v[16:19], v2 offset:2048
	ds_read_b128 v[20:23], v2 offset:4096
	ds_read_b128 v[24:27], v2 offset:6144
	ds_read_b128 v[28:31], v8 offset:22528
	ds_read_b128 v[32:35], v8 offset:20480
	ds_read_b128 v[36:39], v8 offset:18432
	ds_read_b128 v[40:43], v8 offset:16384
	global_load_lds_dwordx4 v[10:11], off
	v_lshl_add_u64 v[10:11], v[6:7], 0, s[18:19]
	s_mov_b32 m0, s14
	s_add_i32 s15, s6, 0x1c000
	global_load_lds_dwordx4 v[10:11], off
	v_lshl_add_u64 v[10:11], v[4:5], 0, s[16:17]
	s_mov_b32 m0, s15
	s_add_i32 s16, s6, 0x1e000
	global_load_lds_dwordx4 v[10:11], off
	v_lshl_add_u64 v[10:11], v[4:5], 0, s[18:19]
	s_mov_b32 m0, s16
	s_mov_b64 s[18:19], 0x40100
	s_add_i32 s17, s6, 0x20000
	global_load_lds_dwordx4 v[10:11], off
	v_lshl_add_u64 v[10:11], v[4:5], 0, s[18:19]
	s_mov_b32 m0, s17
	s_mov_b64 s[18:19], 0x60100
	global_load_lds_dwordx4 v[10:11], off
	v_lshl_add_u64 v[10:11], v[4:5], 0, s[18:19]
	s_add_i32 s18, s6, 0x22000
	s_mov_b32 m0, s18
	v_or_b32_e32 v148, v61, v9
	global_load_lds_dwordx4 v[10:11], off
	v_or_b32_e32 v10, v61, v60
	v_add_u32_e32 v9, 0, v148
	v_add_u32_e32 v10, 0, v10
	ds_read_b128 v[44:47], v9
	ds_read_b128 v[48:51], v9 offset:2048
	ds_read_b128 v[52:55], v9 offset:4096
	ds_read_b128 v[56:59], v9 offset:6144
	ds_read_b128 v[60:63], v10 offset:16384
	ds_read_b128 v[64:67], v10 offset:18432
	ds_read_b128 v[68:71], v10 offset:20480
	ds_read_b128 v[72:75], v10 offset:22528
	v_readlane_b32 s20, v196, 18
	v_readlane_b32 s21, v196, 19
	s_waitcnt lgkmcnt(8)
	v_mfma_f32_16x16x32_bf16 v[76:79], v[40:43], v[12:15], 0
	v_mfma_f32_16x16x32_bf16 v[80:83], v[36:39], v[12:15], 0
	v_mfma_f32_16x16x32_bf16 v[84:87], v[32:35], v[12:15], 0
	v_mfma_f32_16x16x32_bf16 v[12:15], v[28:31], v[12:15], 0
	v_mfma_f32_16x16x32_bf16 v[88:91], v[40:43], v[16:19], 0
	v_mfma_f32_16x16x32_bf16 v[92:95], v[36:39], v[16:19], 0
	v_mfma_f32_16x16x32_bf16 v[96:99], v[32:35], v[16:19], 0
	v_mfma_f32_16x16x32_bf16 v[16:19], v[28:31], v[16:19], 0
	v_mfma_f32_16x16x32_bf16 v[100:103], v[40:43], v[20:23], 0
	v_mfma_f32_16x16x32_bf16 v[104:107], v[36:39], v[20:23], 0
	v_mfma_f32_16x16x32_bf16 v[108:111], v[32:35], v[20:23], 0
	v_mfma_f32_16x16x32_bf16 v[20:23], v[28:31], v[20:23], 0
	v_mfma_f32_16x16x32_bf16 v[40:43], v[40:43], v[24:27], 0
	v_mfma_f32_16x16x32_bf16 v[36:39], v[36:39], v[24:27], 0
	v_mfma_f32_16x16x32_bf16 v[32:35], v[32:35], v[24:27], 0
	v_mfma_f32_16x16x32_bf16 v[24:27], v[28:31], v[24:27], 0
	s_waitcnt vmcnt(6) lgkmcnt(0)
	s_barrier
	v_add_u32_e32 v11, s64, v145
	ds_read_b128 v[28:31], v2 offset:49152
	ds_read_b128 v[112:115], v2 offset:51200
	ds_read_b128 v[116:119], v2 offset:53248
	ds_read_b128 v[120:123], v2 offset:55296
	ds_read_b128 v[124:127], v11
	ds_read_b128 v[128:131], v11 offset:2048
	ds_read_b128 v[132:135], v11 offset:4096
	ds_read_b128 v[136:139], v11 offset:6144
	v_mfma_f32_16x16x32_bf16 v[76:79], v[60:63], v[44:47], v[76:79]
	v_mfma_f32_16x16x32_bf16 v[80:83], v[64:67], v[44:47], v[80:83]
	v_mfma_f32_16x16x32_bf16 v[84:87], v[68:71], v[44:47], v[84:87]
	v_mfma_f32_16x16x32_bf16 v[44:47], v[72:75], v[44:47], v[12:15]
	v_mfma_f32_16x16x32_bf16 v[88:91], v[60:63], v[48:51], v[88:91]
	v_mfma_f32_16x16x32_bf16 v[92:95], v[64:67], v[48:51], v[92:95]
	v_mfma_f32_16x16x32_bf16 v[96:99], v[68:71], v[48:51], v[96:99]
	v_mfma_f32_16x16x32_bf16 v[14:17], v[72:75], v[48:51], v[16:19]
	v_mfma_f32_16x16x32_bf16 v[48:51], v[60:63], v[52:55], v[100:103]
	v_mfma_f32_16x16x32_bf16 v[100:103], v[64:67], v[52:55], v[104:107]
	v_mfma_f32_16x16x32_bf16 v[104:107], v[68:71], v[52:55], v[108:111]
	v_mfma_f32_16x16x32_bf16 v[18:21], v[72:75], v[52:55], v[20:23]
	v_mfma_f32_16x16x32_bf16 v[40:43], v[60:63], v[56:59], v[40:43]
	v_mfma_f32_16x16x32_bf16 v[36:39], v[64:67], v[56:59], v[36:39]
	v_mfma_f32_16x16x32_bf16 v[32:35], v[68:71], v[56:59], v[32:35]
	v_mfma_f32_16x16x32_bf16 v[22:25], v[72:75], v[56:59], v[24:27]
	s_mov_b64 s[20:21], 0x180
	s_mov_b32 m0, s6
	v_lshl_add_u64 v[12:13], v[6:7], 0, s[20:21]
	s_mov_b64 s[26:27], 0x20180
	global_load_lds_dwordx4 v[12:13], off
	v_lshl_add_u64 v[12:13], v[6:7], 0, s[26:27]
	s_mov_b32 m0, s87
	s_nop 0
	global_load_lds_dwordx4 v[12:13], off
	v_lshl_add_u64 v[12:13], v[4:5], 0, s[20:21]
	s_mov_b32 m0, s0
	s_mov_b64 s[20:21], 0x40180
	global_load_lds_dwordx4 v[12:13], off
	v_lshl_add_u64 v[12:13], v[4:5], 0, s[26:27]
	s_mov_b32 m0, s1
	s_nop 0
	global_load_lds_dwordx4 v[12:13], off
	v_lshl_add_u64 v[12:13], v[4:5], 0, s[20:21]
	s_mov_b32 m0, s86
	s_mov_b64 s[20:21], 0x60180
	global_load_lds_dwordx4 v[12:13], off
	v_lshl_add_u64 v[12:13], v[4:5], 0, s[20:21]
	s_mov_b32 m0, s85
	s_nop 0
	global_load_lds_dwordx4 v[12:13], off
	v_add_u32_e32 v12, s64, v149
	ds_read_b128 v[52:55], v9 offset:49152
	ds_read_b128 v[56:59], v9 offset:51200
	ds_read_b128 v[60:63], v9 offset:53248
	ds_read_b128 v[64:67], v9 offset:55296
	ds_read_b128 v[68:71], v12
	ds_read_b128 v[72:75], v12 offset:2048
	ds_read_b128 v[108:111], v12 offset:4096
	ds_read_b128 v[140:143], v12 offset:6144
	s_waitcnt lgkmcnt(8)
	v_mfma_f32_16x16x32_bf16 v[76:79], v[124:127], v[28:31], v[76:79]
	v_mfma_f32_16x16x32_bf16 v[80:83], v[128:131], v[28:31], v[80:83]
	v_mfma_f32_16x16x32_bf16 v[84:87], v[132:135], v[28:31], v[84:87]
	v_mfma_f32_16x16x32_bf16 v[26:29], v[136:139], v[28:31], v[44:47]
	v_mfma_f32_16x16x32_bf16 v[44:47], v[124:127], v[112:115], v[88:91]
	v_mfma_f32_16x16x32_bf16 v[88:91], v[128:131], v[112:115], v[92:95]
	v_mfma_f32_16x16x32_bf16 v[92:95], v[132:135], v[112:115], v[96:99]
	v_mfma_f32_16x16x32_bf16 v[96:99], v[136:139], v[112:115], v[14:17]
	v_mfma_f32_16x16x32_bf16 v[48:51], v[124:127], v[116:119], v[48:51]
	v_mfma_f32_16x16x32_bf16 v[100:103], v[128:131], v[116:119], v[100:103]
	v_mfma_f32_16x16x32_bf16 v[104:107], v[132:135], v[116:119], v[104:107]
	v_mfma_f32_16x16x32_bf16 v[16:19], v[136:139], v[116:119], v[18:21]
	v_mfma_f32_16x16x32_bf16 v[40:43], v[124:127], v[120:123], v[40:43]
	v_mfma_f32_16x16x32_bf16 v[36:39], v[128:131], v[120:123], v[36:39]
	v_mfma_f32_16x16x32_bf16 v[30:33], v[132:135], v[120:123], v[32:35]
	v_mfma_f32_16x16x32_bf16 v[20:23], v[136:139], v[120:123], v[22:25]
	s_add_i32 s19, 0, 0x18000
	s_waitcnt vmcnt(6) lgkmcnt(0)
	s_barrier
	v_add_u32_e32 v13, s19, v144
	v_add_u32_e32 v14, s19, v145
	ds_read_b128 v[112:115], v13
	ds_read_b128 v[116:119], v13 offset:2048
	ds_read_b128 v[120:123], v13 offset:4096
	ds_read_b128 v[124:127], v13 offset:6144
	ds_read_b128 v[128:131], v14
	ds_read_b128 v[132:135], v14 offset:2048
	ds_read_b128 v[136:139], v14 offset:4096
	ds_read_b128 v[144:147], v14 offset:6144
	v_mfma_f32_16x16x32_bf16 v[76:79], v[68:71], v[52:55], v[76:79]
	v_mfma_f32_16x16x32_bf16 v[80:83], v[72:75], v[52:55], v[80:83]
	v_mfma_f32_16x16x32_bf16 v[84:87], v[108:111], v[52:55], v[84:87]
	v_mfma_f32_16x16x32_bf16 v[24:27], v[140:143], v[52:55], v[26:29]
	v_mfma_f32_16x16x32_bf16 v[44:47], v[68:71], v[56:59], v[44:47]
	v_mfma_f32_16x16x32_bf16 v[52:55], v[72:75], v[56:59], v[88:91]
	v_mfma_f32_16x16x32_bf16 v[88:91], v[108:111], v[56:59], v[92:95]
	v_mfma_f32_16x16x32_bf16 v[56:59], v[140:143], v[56:59], v[96:99]
	v_mfma_f32_16x16x32_bf16 v[48:51], v[68:71], v[60:63], v[48:51]
	v_mfma_f32_16x16x32_bf16 v[92:95], v[72:75], v[60:63], v[100:103]
	v_mfma_f32_16x16x32_bf16 v[96:99], v[108:111], v[60:63], v[104:107]
	v_mfma_f32_16x16x32_bf16 v[60:63], v[140:143], v[60:63], v[16:19]
	v_mfma_f32_16x16x32_bf16 v[40:43], v[68:71], v[64:67], v[40:43]
	v_mfma_f32_16x16x32_bf16 v[34:37], v[72:75], v[64:67], v[36:39]
	v_mfma_f32_16x16x32_bf16 v[28:31], v[108:111], v[64:67], v[30:33]
	v_mfma_f32_16x16x32_bf16 v[18:21], v[140:143], v[64:67], v[20:23]
	s_mov_b64 s[20:21], 0x200
	s_mov_b32 m0, s8
	v_lshl_add_u64 v[16:17], v[6:7], 0, s[20:21]
	s_mov_b64 s[26:27], 0x20200
	global_load_lds_dwordx4 v[16:17], off
	v_lshl_add_u64 v[16:17], v[6:7], 0, s[26:27]
	s_mov_b32 m0, s7
	v_add_u32_e32 v15, s19, v148
	global_load_lds_dwordx4 v[16:17], off
	v_lshl_add_u64 v[16:17], v[4:5], 0, s[20:21]
	s_mov_b32 m0, s9
	s_mov_b64 s[20:21], 0x40200
	global_load_lds_dwordx4 v[16:17], off
	v_lshl_add_u64 v[16:17], v[4:5], 0, s[26:27]
	s_mov_b32 m0, s10
	s_nop 0
	global_load_lds_dwordx4 v[16:17], off
	v_lshl_add_u64 v[16:17], v[4:5], 0, s[20:21]
	s_mov_b32 m0, s11
	s_mov_b64 s[20:21], 0x60200
	global_load_lds_dwordx4 v[16:17], off
	v_lshl_add_u64 v[16:17], v[4:5], 0, s[20:21]
	s_mov_b32 m0, s12
	s_nop 0
	global_load_lds_dwordx4 v[16:17], off
	v_add_u32_e32 v16, s19, v149
	ds_read_b128 v[64:67], v15
	ds_read_b128 v[68:71], v15 offset:2048
	ds_read_b128 v[72:75], v15 offset:4096
	ds_read_b128 v[100:103], v15 offset:6144
	ds_read_b128 v[104:107], v16
	ds_read_b128 v[108:111], v16 offset:2048
	ds_read_b128 v[140:143], v16 offset:4096
	ds_read_b128 v[148:151], v16 offset:6144
	s_waitcnt lgkmcnt(8)
	v_mfma_f32_16x16x32_bf16 v[76:79], v[128:131], v[112:115], v[76:79]
	v_mfma_f32_16x16x32_bf16 v[80:83], v[132:135], v[112:115], v[80:83]
	v_mfma_f32_16x16x32_bf16 v[84:87], v[136:139], v[112:115], v[84:87]
	v_mfma_f32_16x16x32_bf16 v[22:25], v[144:147], v[112:115], v[24:27]
	v_mfma_f32_16x16x32_bf16 v[44:47], v[128:131], v[116:119], v[44:47]
	v_mfma_f32_16x16x32_bf16 v[52:55], v[132:135], v[116:119], v[52:55]
	v_mfma_f32_16x16x32_bf16 v[88:91], v[136:139], v[116:119], v[88:91]
	v_mfma_f32_16x16x32_bf16 v[56:59], v[144:147], v[116:119], v[56:59]
	v_mfma_f32_16x16x32_bf16 v[48:51], v[128:131], v[120:123], v[48:51]
	v_mfma_f32_16x16x32_bf16 v[92:95], v[132:135], v[120:123], v[92:95]
	v_mfma_f32_16x16x32_bf16 v[96:99], v[136:139], v[120:123], v[96:99]
	v_mfma_f32_16x16x32_bf16 v[60:63], v[144:147], v[120:123], v[60:63]
	v_mfma_f32_16x16x32_bf16 v[38:41], v[128:131], v[124:127], v[40:43]
	v_mfma_f32_16x16x32_bf16 v[32:35], v[132:135], v[124:127], v[34:37]
	v_mfma_f32_16x16x32_bf16 v[26:29], v[136:139], v[124:127], v[28:31]
	v_mfma_f32_16x16x32_bf16 v[18:21], v[144:147], v[124:127], v[18:21]
	s_waitcnt vmcnt(6) lgkmcnt(0)
	s_barrier
	ds_read_b128 v[112:115], v2
	ds_read_b128 v[116:119], v2 offset:2048
	ds_read_b128 v[120:123], v2 offset:4096
	ds_read_b128 v[124:127], v2 offset:6144
	ds_read_b128 v[128:131], v8 offset:16384
	ds_read_b128 v[132:135], v8 offset:18432
	ds_read_b128 v[136:139], v8 offset:20480
	ds_read_b128 v[144:147], v8 offset:22528
	v_mfma_f32_16x16x32_bf16 v[76:79], v[104:107], v[64:67], v[76:79]
	v_mfma_f32_16x16x32_bf16 v[80:83], v[108:111], v[64:67], v[80:83]
	v_mfma_f32_16x16x32_bf16 v[84:87], v[140:143], v[64:67], v[84:87]
	v_mfma_f32_16x16x32_bf16 v[22:25], v[148:151], v[64:67], v[22:25]
	v_mfma_f32_16x16x32_bf16 v[42:45], v[104:107], v[68:71], v[44:47]
	v_mfma_f32_16x16x32_bf16 v[52:55], v[108:111], v[68:71], v[52:55]
	v_mfma_f32_16x16x32_bf16 v[64:67], v[140:143], v[68:71], v[88:91]
	v_mfma_f32_16x16x32_bf16 v[56:59], v[148:151], v[68:71], v[56:59]
	v_mfma_f32_16x16x32_bf16 v[46:49], v[104:107], v[72:75], v[48:51]
	v_mfma_f32_16x16x32_bf16 v[68:71], v[108:111], v[72:75], v[92:95]
	v_mfma_f32_16x16x32_bf16 v[88:91], v[140:143], v[72:75], v[96:99]
	v_mfma_f32_16x16x32_bf16 v[60:63], v[148:151], v[72:75], v[60:63]
	v_mfma_f32_16x16x32_bf16 v[36:39], v[104:107], v[100:103], v[38:41]
	v_mfma_f32_16x16x32_bf16 v[30:33], v[108:111], v[100:103], v[32:35]
	v_mfma_f32_16x16x32_bf16 v[26:29], v[140:143], v[100:103], v[26:29]
	v_mfma_f32_16x16x32_bf16 v[18:21], v[148:151], v[100:103], v[18:21]
	s_mov_b64 s[20:21], 0x280
	s_mov_b32 m0, s13
	v_lshl_add_u64 v[34:35], v[6:7], 0, s[20:21]
	s_mov_b64 s[26:27], 0x20280
	global_load_lds_dwordx4 v[34:35], off
	v_lshl_add_u64 v[34:35], v[6:7], 0, s[26:27]
	s_mov_b32 m0, s14
	s_nop 0
	global_load_lds_dwordx4 v[34:35], off
	v_lshl_add_u64 v[34:35], v[4:5], 0, s[20:21]
	s_mov_b32 m0, s15
	s_mov_b64 s[20:21], 0x40280
	global_load_lds_dwordx4 v[34:35], off
	v_lshl_add_u64 v[34:35], v[4:5], 0, s[26:27]
	s_mov_b32 m0, s16
	s_nop 0
	global_load_lds_dwordx4 v[34:35], off
	v_lshl_add_u64 v[34:35], v[4:5], 0, s[20:21]
	s_mov_b32 m0, s17
	s_mov_b64 s[20:21], 0x60280
	global_load_lds_dwordx4 v[34:35], off
	v_lshl_add_u64 v[34:35], v[4:5], 0, s[20:21]
	s_mov_b32 m0, s18
	s_nop 0
	global_load_lds_dwordx4 v[34:35], off
	ds_read_b128 v[72:75], v9
	ds_read_b128 v[92:95], v9 offset:2048
	ds_read_b128 v[96:99], v9 offset:4096
	ds_read_b128 v[100:103], v9 offset:6144
	ds_read_b128 v[104:107], v10 offset:16384
	ds_read_b128 v[108:111], v10 offset:18432
	ds_read_b128 v[140:143], v10 offset:20480
	ds_read_b128 v[148:151], v10 offset:22528
	s_waitcnt lgkmcnt(8)
	v_mfma_f32_16x16x32_bf16 v[76:79], v[128:131], v[112:115], v[76:79]
	v_mfma_f32_16x16x32_bf16 v[80:83], v[132:135], v[112:115], v[80:83]
	v_mfma_f32_16x16x32_bf16 v[84:87], v[136:139], v[112:115], v[84:87]
	v_mfma_f32_16x16x32_bf16 v[22:25], v[144:147], v[112:115], v[22:25]
	v_mfma_f32_16x16x32_bf16 v[40:43], v[128:131], v[116:119], v[42:45]
	v_mfma_f32_16x16x32_bf16 v[50:53], v[132:135], v[116:119], v[52:55]
	v_mfma_f32_16x16x32_bf16 v[64:67], v[136:139], v[116:119], v[64:67]
	v_mfma_f32_16x16x32_bf16 v[54:57], v[144:147], v[116:119], v[56:59]
	v_mfma_f32_16x16x32_bf16 v[44:47], v[128:131], v[120:123], v[46:49]
	v_mfma_f32_16x16x32_bf16 v[68:71], v[132:135], v[120:123], v[68:71]
	v_mfma_f32_16x16x32_bf16 v[88:91], v[136:139], v[120:123], v[88:91]
	v_mfma_f32_16x16x32_bf16 v[58:61], v[144:147], v[120:123], v[60:63]
	v_mfma_f32_16x16x32_bf16 v[34:37], v[128:131], v[124:127], v[36:39]
	v_mfma_f32_16x16x32_bf16 v[30:33], v[132:135], v[124:127], v[30:33]
	v_mfma_f32_16x16x32_bf16 v[26:29], v[136:139], v[124:127], v[26:29]
	v_mfma_f32_16x16x32_bf16 v[18:21], v[144:147], v[124:127], v[18:21]
	s_waitcnt vmcnt(6) lgkmcnt(0)
	s_barrier
	ds_read_b128 v[112:115], v2 offset:49152
	ds_read_b128 v[116:119], v2 offset:51200
	ds_read_b128 v[120:123], v2 offset:53248
	ds_read_b128 v[124:127], v2 offset:55296
	ds_read_b128 v[128:131], v11
	ds_read_b128 v[132:135], v11 offset:2048
	ds_read_b128 v[136:139], v11 offset:4096
	ds_read_b128 v[144:147], v11 offset:6144
	v_mfma_f32_16x16x32_bf16 v[76:79], v[104:107], v[72:75], v[76:79]
	v_mfma_f32_16x16x32_bf16 v[80:83], v[108:111], v[72:75], v[80:83]
	v_mfma_f32_16x16x32_bf16 v[84:87], v[140:143], v[72:75], v[84:87]
	v_mfma_f32_16x16x32_bf16 v[22:25], v[148:151], v[72:75], v[22:25]
	v_mfma_f32_16x16x32_bf16 v[38:41], v[104:107], v[92:95], v[40:43]
	v_mfma_f32_16x16x32_bf16 v[48:51], v[108:111], v[92:95], v[50:53]
	v_mfma_f32_16x16x32_bf16 v[62:65], v[140:143], v[92:95], v[64:67]
	v_mfma_f32_16x16x32_bf16 v[52:55], v[148:151], v[92:95], v[54:57]
	v_mfma_f32_16x16x32_bf16 v[42:45], v[104:107], v[96:99], v[44:47]
	v_mfma_f32_16x16x32_bf16 v[66:69], v[108:111], v[96:99], v[68:71]
	v_mfma_f32_16x16x32_bf16 v[70:73], v[140:143], v[96:99], v[88:91]
	v_mfma_f32_16x16x32_bf16 v[56:59], v[148:151], v[96:99], v[58:61]
	v_mfma_f32_16x16x32_bf16 v[34:37], v[104:107], v[100:103], v[34:37]
	v_mfma_f32_16x16x32_bf16 v[30:33], v[108:111], v[100:103], v[30:33]
	v_mfma_f32_16x16x32_bf16 v[26:29], v[140:143], v[100:103], v[26:29]
	v_mfma_f32_16x16x32_bf16 v[18:21], v[148:151], v[100:103], v[18:21]
	s_mov_b64 s[20:21], 0x300
	s_mov_b32 m0, s6
	v_lshl_add_u64 v[46:47], v[6:7], 0, s[20:21]
	s_mov_b64 s[22:23], 0x20300
	global_load_lds_dwordx4 v[46:47], off
	v_lshl_add_u64 v[46:47], v[6:7], 0, s[22:23]
	s_mov_b32 m0, s87
	s_nop 0
	global_load_lds_dwordx4 v[46:47], off
	v_lshl_add_u64 v[46:47], v[4:5], 0, s[20:21]
	s_mov_b32 m0, s0
	s_mov_b64 s[20:21], 0x40300
	global_load_lds_dwordx4 v[46:47], off
	v_lshl_add_u64 v[46:47], v[4:5], 0, s[22:23]
	s_mov_b32 m0, s1
	s_nop 0
	global_load_lds_dwordx4 v[46:47], off
	v_lshl_add_u64 v[46:47], v[4:5], 0, s[20:21]
	s_mov_b32 m0, s86
	s_mov_b64 s[20:21], 0x60300
	global_load_lds_dwordx4 v[46:47], off
	v_lshl_add_u64 v[46:47], v[4:5], 0, s[20:21]
	s_mov_b32 m0, s85
	s_nop 0
	global_load_lds_dwordx4 v[46:47], off
	ds_read_b128 v[88:91], v9 offset:49152
	ds_read_b128 v[92:95], v9 offset:51200
	ds_read_b128 v[96:99], v9 offset:53248
	ds_read_b128 v[100:103], v9 offset:55296
	ds_read_b128 v[104:107], v12
	ds_read_b128 v[108:111], v12 offset:2048
	ds_read_b128 v[140:143], v12 offset:4096
	ds_read_b128 v[148:151], v12 offset:6144
	s_waitcnt lgkmcnt(8)
	v_mfma_f32_16x16x32_bf16 v[74:77], v[128:131], v[112:115], v[76:79]
	v_mfma_f32_16x16x32_bf16 v[78:81], v[132:135], v[112:115], v[80:83]
	v_mfma_f32_16x16x32_bf16 v[82:85], v[136:139], v[112:115], v[84:87]
	v_mfma_f32_16x16x32_bf16 v[22:25], v[144:147], v[112:115], v[22:25]
	v_mfma_f32_16x16x32_bf16 v[38:41], v[128:131], v[116:119], v[38:41]
	v_mfma_f32_16x16x32_bf16 v[46:49], v[132:135], v[116:119], v[48:51]
	v_mfma_f32_16x16x32_bf16 v[60:63], v[136:139], v[116:119], v[62:65]
	v_mfma_f32_16x16x32_bf16 v[50:53], v[144:147], v[116:119], v[52:55]
	v_mfma_f32_16x16x32_bf16 v[42:45], v[128:131], v[120:123], v[42:45]
	v_mfma_f32_16x16x32_bf16 v[64:67], v[132:135], v[120:123], v[66:69]
	v_mfma_f32_16x16x32_bf16 v[68:71], v[136:139], v[120:123], v[70:73]
	v_mfma_f32_16x16x32_bf16 v[54:57], v[144:147], v[120:123], v[56:59]
	v_mfma_f32_16x16x32_bf16 v[34:37], v[128:131], v[124:127], v[34:37]
	v_mfma_f32_16x16x32_bf16 v[30:33], v[132:135], v[124:127], v[30:33]
	v_mfma_f32_16x16x32_bf16 v[26:29], v[136:139], v[124:127], v[26:29]
	v_mfma_f32_16x16x32_bf16 v[18:21], v[144:147], v[124:127], v[18:21]
	s_waitcnt vmcnt(6) lgkmcnt(0)
	s_barrier
	ds_read_b128 v[112:115], v13
	ds_read_b128 v[116:119], v13 offset:2048
	ds_read_b128 v[120:123], v13 offset:4096
	ds_read_b128 v[124:127], v13 offset:6144
	ds_read_b128 v[128:131], v14
	ds_read_b128 v[132:135], v14 offset:2048
	ds_read_b128 v[136:139], v14 offset:4096
	ds_read_b128 v[144:147], v14 offset:6144
	v_mfma_f32_16x16x32_bf16 v[72:75], v[104:107], v[88:91], v[74:77]
	v_mfma_f32_16x16x32_bf16 v[76:79], v[108:111], v[88:91], v[78:81]
	v_mfma_f32_16x16x32_bf16 v[80:83], v[140:143], v[88:91], v[82:85]
	v_mfma_f32_16x16x32_bf16 v[22:25], v[148:151], v[88:91], v[22:25]
	v_mfma_f32_16x16x32_bf16 v[38:41], v[104:107], v[92:95], v[38:41]
	v_mfma_f32_16x16x32_bf16 v[46:49], v[108:111], v[92:95], v[46:49]
	v_mfma_f32_16x16x32_bf16 v[58:61], v[140:143], v[92:95], v[60:63]
	v_mfma_f32_16x16x32_bf16 v[50:53], v[148:151], v[92:95], v[50:53]
	v_mfma_f32_16x16x32_bf16 v[42:45], v[104:107], v[96:99], v[42:45]
	v_mfma_f32_16x16x32_bf16 v[62:65], v[108:111], v[96:99], v[64:67]
	v_mfma_f32_16x16x32_bf16 v[66:69], v[140:143], v[96:99], v[68:71]
	v_mfma_f32_16x16x32_bf16 v[54:57], v[148:151], v[96:99], v[54:57]
	v_mfma_f32_16x16x32_bf16 v[34:37], v[104:107], v[100:103], v[34:37]
	v_mfma_f32_16x16x32_bf16 v[30:33], v[108:111], v[100:103], v[30:33]
	v_mfma_f32_16x16x32_bf16 v[26:29], v[140:143], v[100:103], v[26:29]
	v_mfma_f32_16x16x32_bf16 v[18:21], v[148:151], v[100:103], v[18:21]
	s_mov_b32 m0, s8
	v_lshl_add_u64 v[70:71], v[6:7], 0, s[30:31]
	global_load_lds_dwordx4 v[70:71], off
	v_lshl_add_u64 v[70:71], v[6:7], 0, s[34:35]
	s_mov_b32 m0, s7
	s_mov_b64 s[20:21], 0x40380
	global_load_lds_dwordx4 v[70:71], off
	v_lshl_add_u64 v[70:71], v[4:5], 0, s[30:31]
	s_mov_b32 m0, s9
	s_nop 0
	global_load_lds_dwordx4 v[70:71], off
	v_lshl_add_u64 v[70:71], v[4:5], 0, s[34:35]
	s_mov_b32 m0, s10
	s_nop 0
	global_load_lds_dwordx4 v[70:71], off
	v_lshl_add_u64 v[70:71], v[4:5], 0, s[20:21]
	s_mov_b32 m0, s11
	s_mov_b64 s[20:21], 0x60380
	global_load_lds_dwordx4 v[70:71], off
	v_lshl_add_u64 v[70:71], v[4:5], 0, s[20:21]
	s_mov_b32 m0, s12
	s_nop 0
	global_load_lds_dwordx4 v[70:71], off
	ds_read_b128 v[84:87], v15
	ds_read_b128 v[88:91], v15 offset:2048
	ds_read_b128 v[92:95], v15 offset:4096
	ds_read_b128 v[96:99], v15 offset:6144
	ds_read_b128 v[100:103], v16
	ds_read_b128 v[104:107], v16 offset:2048
	ds_read_b128 v[108:111], v16 offset:4096
	ds_read_b128 v[140:143], v16 offset:6144
	s_waitcnt lgkmcnt(8)
	v_mfma_f32_16x16x32_bf16 v[70:73], v[128:131], v[112:115], v[72:75]
	v_mfma_f32_16x16x32_bf16 v[74:77], v[132:135], v[112:115], v[76:79]
	v_mfma_f32_16x16x32_bf16 v[78:81], v[136:139], v[112:115], v[80:83]
	v_mfma_f32_16x16x32_bf16 v[22:25], v[144:147], v[112:115], v[22:25]
	v_mfma_f32_16x16x32_bf16 v[38:41], v[128:131], v[116:119], v[38:41]
	v_mfma_f32_16x16x32_bf16 v[46:49], v[132:135], v[116:119], v[46:49]
	v_mfma_f32_16x16x32_bf16 v[58:61], v[136:139], v[116:119], v[58:61]
	v_mfma_f32_16x16x32_bf16 v[50:53], v[144:147], v[116:119], v[50:53]
	v_mfma_f32_16x16x32_bf16 v[42:45], v[128:131], v[120:123], v[42:45]
	v_mfma_f32_16x16x32_bf16 v[62:65], v[132:135], v[120:123], v[62:65]
	v_mfma_f32_16x16x32_bf16 v[66:69], v[136:139], v[120:123], v[66:69]
	v_mfma_f32_16x16x32_bf16 v[54:57], v[144:147], v[120:123], v[54:57]
	v_mfma_f32_16x16x32_bf16 v[34:37], v[128:131], v[124:127], v[34:37]
	v_mfma_f32_16x16x32_bf16 v[30:33], v[132:135], v[124:127], v[30:33]
	v_mfma_f32_16x16x32_bf16 v[26:29], v[136:139], v[124:127], v[26:29]
	v_mfma_f32_16x16x32_bf16 v[18:21], v[144:147], v[124:127], v[18:21]
	s_waitcnt vmcnt(6) lgkmcnt(0)
	s_barrier
	ds_read_b128 v[112:115], v2
	ds_read_b128 v[116:119], v2 offset:2048
	ds_read_b128 v[120:123], v2 offset:4096
	ds_read_b128 v[124:127], v2 offset:6144
	ds_read_b128 v[128:131], v8 offset:16384
	ds_read_b128 v[132:135], v8 offset:18432
	ds_read_b128 v[136:139], v8 offset:20480
	ds_read_b128 v[144:147], v8 offset:22528
	v_mfma_f32_16x16x32_bf16 v[70:73], v[100:103], v[84:87], v[70:73]
	v_mfma_f32_16x16x32_bf16 v[74:77], v[104:107], v[84:87], v[74:77]
	v_mfma_f32_16x16x32_bf16 v[78:81], v[108:111], v[84:87], v[78:81]
	v_mfma_f32_16x16x32_bf16 v[22:25], v[140:143], v[84:87], v[22:25]
	v_mfma_f32_16x16x32_bf16 v[38:41], v[100:103], v[88:91], v[38:41]
	v_mfma_f32_16x16x32_bf16 v[46:49], v[104:107], v[88:91], v[46:49]
	v_mfma_f32_16x16x32_bf16 v[58:61], v[108:111], v[88:91], v[58:61]
	v_mfma_f32_16x16x32_bf16 v[50:53], v[140:143], v[88:91], v[50:53]
	v_mfma_f32_16x16x32_bf16 v[42:45], v[100:103], v[92:95], v[42:45]
	v_mfma_f32_16x16x32_bf16 v[62:65], v[104:107], v[92:95], v[62:65]
	v_mfma_f32_16x16x32_bf16 v[66:69], v[108:111], v[92:95], v[66:69]
	v_mfma_f32_16x16x32_bf16 v[54:57], v[140:143], v[92:95], v[54:57]
	v_mfma_f32_16x16x32_bf16 v[34:37], v[100:103], v[96:99], v[34:37]
	v_mfma_f32_16x16x32_bf16 v[30:33], v[104:107], v[96:99], v[30:33]
	v_mfma_f32_16x16x32_bf16 v[26:29], v[108:111], v[96:99], v[26:29]
	v_mfma_f32_16x16x32_bf16 v[18:21], v[140:143], v[96:99], v[18:21]
	s_mov_b32 m0, s13
	v_lshl_add_u64 v[82:83], v[6:7], 0, s[36:37]
	global_load_lds_dwordx4 v[82:83], off
	v_lshl_add_u64 v[82:83], v[6:7], 0, s[46:47]
	s_mov_b32 m0, s14
	s_mov_b64 s[20:21], 0x40400
	global_load_lds_dwordx4 v[82:83], off
	v_lshl_add_u64 v[82:83], v[4:5], 0, s[36:37]
	s_mov_b32 m0, s15
	s_nop 0
	global_load_lds_dwordx4 v[82:83], off
	v_lshl_add_u64 v[82:83], v[4:5], 0, s[46:47]
	s_mov_b32 m0, s16
	s_nop 0
	global_load_lds_dwordx4 v[82:83], off
	v_lshl_add_u64 v[82:83], v[4:5], 0, s[20:21]
	s_mov_b32 m0, s17
	s_mov_b64 s[20:21], 0x60400
	global_load_lds_dwordx4 v[82:83], off
	v_lshl_add_u64 v[82:83], v[4:5], 0, s[20:21]
	s_mov_b32 m0, s18
	s_nop 0
	global_load_lds_dwordx4 v[82:83], off
	ds_read_b128 v[82:85], v9
	ds_read_b128 v[86:89], v9 offset:2048
	ds_read_b128 v[90:93], v9 offset:4096
	ds_read_b128 v[94:97], v9 offset:6144
	ds_read_b128 v[98:101], v10 offset:16384
	ds_read_b128 v[102:105], v10 offset:18432
	ds_read_b128 v[106:109], v10 offset:20480
	ds_read_b128 v[140:143], v10 offset:22528
	s_waitcnt lgkmcnt(8)
	v_mfma_f32_16x16x32_bf16 v[70:73], v[128:131], v[112:115], v[70:73]
	v_mfma_f32_16x16x32_bf16 v[74:77], v[132:135], v[112:115], v[74:77]
	v_mfma_f32_16x16x32_bf16 v[78:81], v[136:139], v[112:115], v[78:81]
	v_mfma_f32_16x16x32_bf16 v[22:25], v[144:147], v[112:115], v[22:25]
	v_mfma_f32_16x16x32_bf16 v[38:41], v[128:131], v[116:119], v[38:41]
	v_mfma_f32_16x16x32_bf16 v[46:49], v[132:135], v[116:119], v[46:49]
	v_mfma_f32_16x16x32_bf16 v[58:61], v[136:139], v[116:119], v[58:61]
	v_mfma_f32_16x16x32_bf16 v[50:53], v[144:147], v[116:119], v[50:53]
	v_mfma_f32_16x16x32_bf16 v[42:45], v[128:131], v[120:123], v[42:45]
	v_mfma_f32_16x16x32_bf16 v[62:65], v[132:135], v[120:123], v[62:65]
	v_mfma_f32_16x16x32_bf16 v[66:69], v[136:139], v[120:123], v[66:69]
	v_mfma_f32_16x16x32_bf16 v[54:57], v[144:147], v[120:123], v[54:57]
	v_mfma_f32_16x16x32_bf16 v[34:37], v[128:131], v[124:127], v[34:37]
	v_mfma_f32_16x16x32_bf16 v[30:33], v[132:135], v[124:127], v[30:33]
	v_mfma_f32_16x16x32_bf16 v[26:29], v[136:139], v[124:127], v[26:29]
	v_mfma_f32_16x16x32_bf16 v[18:21], v[144:147], v[124:127], v[18:21]
	s_waitcnt vmcnt(6) lgkmcnt(0)
	s_barrier
	ds_read_b128 v[110:113], v2 offset:49152
	ds_read_b128 v[114:117], v2 offset:51200
	ds_read_b128 v[118:121], v2 offset:53248
	ds_read_b128 v[122:125], v2 offset:55296
	ds_read_b128 v[126:129], v11
	ds_read_b128 v[130:133], v11 offset:2048
	ds_read_b128 v[134:137], v11 offset:4096
	ds_read_b128 v[144:147], v11 offset:6144
	v_mfma_f32_16x16x32_bf16 v[70:73], v[98:101], v[82:85], v[70:73]
	v_mfma_f32_16x16x32_bf16 v[74:77], v[102:105], v[82:85], v[74:77]
	v_mfma_f32_16x16x32_bf16 v[78:81], v[106:109], v[82:85], v[78:81]
	v_mfma_f32_16x16x32_bf16 v[22:25], v[140:143], v[82:85], v[22:25]
	v_mfma_f32_16x16x32_bf16 v[38:41], v[98:101], v[86:89], v[38:41]
	v_mfma_f32_16x16x32_bf16 v[46:49], v[102:105], v[86:89], v[46:49]
	v_mfma_f32_16x16x32_bf16 v[58:61], v[106:109], v[86:89], v[58:61]
	v_mfma_f32_16x16x32_bf16 v[50:53], v[140:143], v[86:89], v[50:53]
	v_mfma_f32_16x16x32_bf16 v[42:45], v[98:101], v[90:93], v[42:45]
	v_mfma_f32_16x16x32_bf16 v[62:65], v[102:105], v[90:93], v[62:65]
	v_mfma_f32_16x16x32_bf16 v[66:69], v[106:109], v[90:93], v[66:69]
	v_mfma_f32_16x16x32_bf16 v[54:57], v[140:143], v[90:93], v[54:57]
	v_mfma_f32_16x16x32_bf16 v[34:37], v[98:101], v[94:97], v[34:37]
	v_mfma_f32_16x16x32_bf16 v[30:33], v[102:105], v[94:97], v[30:33]
	v_mfma_f32_16x16x32_bf16 v[26:29], v[106:109], v[94:97], v[26:29]
	v_mfma_f32_16x16x32_bf16 v[18:21], v[140:143], v[94:97], v[18:21]
	s_mov_b32 m0, s6
	v_lshl_add_u64 v[82:83], v[6:7], 0, s[70:71]
	global_load_lds_dwordx4 v[82:83], off
	v_lshl_add_u64 v[82:83], v[6:7], 0, s[74:75]
	s_mov_b32 m0, s87
	s_mov_b64 s[20:21], 0x40480
	global_load_lds_dwordx4 v[82:83], off
	v_lshl_add_u64 v[82:83], v[4:5], 0, s[70:71]
	s_mov_b32 m0, s0
	s_nop 0
	global_load_lds_dwordx4 v[82:83], off
	v_lshl_add_u64 v[82:83], v[4:5], 0, s[74:75]
	s_mov_b32 m0, s1
	s_nop 0
	global_load_lds_dwordx4 v[82:83], off
	v_lshl_add_u64 v[82:83], v[4:5], 0, s[20:21]
	s_mov_b32 m0, s86
	s_mov_b64 s[20:21], 0x60480
	global_load_lds_dwordx4 v[82:83], off
	v_lshl_add_u64 v[82:83], v[4:5], 0, s[20:21]
	s_mov_b32 m0, s85
	s_nop 0
	global_load_lds_dwordx4 v[82:83], off
	ds_read_b128 v[82:85], v9 offset:49152
	ds_read_b128 v[86:89], v9 offset:51200
	ds_read_b128 v[90:93], v9 offset:53248
	ds_read_b128 v[94:97], v9 offset:55296
	ds_read_b128 v[98:101], v12
	ds_read_b128 v[102:105], v12 offset:2048
	ds_read_b128 v[106:109], v12 offset:4096
	ds_read_b128 v[138:141], v12 offset:6144
	s_waitcnt lgkmcnt(8)
	v_mfma_f32_16x16x32_bf16 v[70:73], v[126:129], v[110:113], v[70:73]
	v_mfma_f32_16x16x32_bf16 v[74:77], v[130:133], v[110:113], v[74:77]
	v_mfma_f32_16x16x32_bf16 v[78:81], v[134:137], v[110:113], v[78:81]
	v_mfma_f32_16x16x32_bf16 v[22:25], v[144:147], v[110:113], v[22:25]
	v_mfma_f32_16x16x32_bf16 v[38:41], v[126:129], v[114:117], v[38:41]
	v_mfma_f32_16x16x32_bf16 v[46:49], v[130:133], v[114:117], v[46:49]
	v_mfma_f32_16x16x32_bf16 v[58:61], v[134:137], v[114:117], v[58:61]
	v_mfma_f32_16x16x32_bf16 v[50:53], v[144:147], v[114:117], v[50:53]
	v_mfma_f32_16x16x32_bf16 v[42:45], v[126:129], v[118:121], v[42:45]
	v_mfma_f32_16x16x32_bf16 v[62:65], v[130:133], v[118:121], v[62:65]
	v_mfma_f32_16x16x32_bf16 v[66:69], v[134:137], v[118:121], v[66:69]
	v_mfma_f32_16x16x32_bf16 v[54:57], v[144:147], v[118:121], v[54:57]
	v_mfma_f32_16x16x32_bf16 v[34:37], v[126:129], v[122:125], v[34:37]
	v_mfma_f32_16x16x32_bf16 v[30:33], v[130:133], v[122:125], v[30:33]
	v_mfma_f32_16x16x32_bf16 v[26:29], v[134:137], v[122:125], v[26:29]
	v_mfma_f32_16x16x32_bf16 v[18:21], v[144:147], v[122:125], v[18:21]
	s_waitcnt vmcnt(6) lgkmcnt(0)
	s_barrier
	ds_read_b128 v[110:113], v13
	ds_read_b128 v[114:117], v13 offset:2048
	ds_read_b128 v[118:121], v13 offset:4096
	ds_read_b128 v[122:125], v13 offset:6144
	ds_read_b128 v[126:129], v14
	ds_read_b128 v[130:133], v14 offset:2048
	ds_read_b128 v[134:137], v14 offset:4096
	ds_read_b128 v[142:145], v14 offset:6144
	v_mfma_f32_16x16x32_bf16 v[70:73], v[98:101], v[82:85], v[70:73]
	v_mfma_f32_16x16x32_bf16 v[74:77], v[102:105], v[82:85], v[74:77]
	v_mfma_f32_16x16x32_bf16 v[78:81], v[106:109], v[82:85], v[78:81]
	v_mfma_f32_16x16x32_bf16 v[22:25], v[138:141], v[82:85], v[22:25]
	v_mfma_f32_16x16x32_bf16 v[38:41], v[98:101], v[86:89], v[38:41]
	v_mfma_f32_16x16x32_bf16 v[46:49], v[102:105], v[86:89], v[46:49]
	v_mfma_f32_16x16x32_bf16 v[58:61], v[106:109], v[86:89], v[58:61]
	v_mfma_f32_16x16x32_bf16 v[50:53], v[138:141], v[86:89], v[50:53]
	v_mfma_f32_16x16x32_bf16 v[42:45], v[98:101], v[90:93], v[42:45]
	v_mfma_f32_16x16x32_bf16 v[62:65], v[102:105], v[90:93], v[62:65]
	v_mfma_f32_16x16x32_bf16 v[66:69], v[106:109], v[90:93], v[66:69]
	v_mfma_f32_16x16x32_bf16 v[54:57], v[138:141], v[90:93], v[54:57]
	v_mfma_f32_16x16x32_bf16 v[34:37], v[98:101], v[94:97], v[34:37]
	v_mfma_f32_16x16x32_bf16 v[30:33], v[102:105], v[94:97], v[30:33]
	v_mfma_f32_16x16x32_bf16 v[26:29], v[106:109], v[94:97], v[26:29]
	v_mfma_f32_16x16x32_bf16 v[18:21], v[138:141], v[94:97], v[18:21]
	s_mov_b32 m0, s8
	v_lshl_add_u64 v[82:83], v[6:7], 0, s[76:77]
	global_load_lds_dwordx4 v[82:83], off
	v_lshl_add_u64 v[82:83], v[6:7], 0, s[78:79]
	s_mov_b32 m0, s7
	s_mov_b64 s[20:21], 0x40500
	global_load_lds_dwordx4 v[82:83], off
	v_lshl_add_u64 v[82:83], v[4:5], 0, s[76:77]
	s_mov_b32 m0, s9
	s_nop 0
	global_load_lds_dwordx4 v[82:83], off
	v_lshl_add_u64 v[82:83], v[4:5], 0, s[78:79]
	s_mov_b32 m0, s10
	s_nop 0
	global_load_lds_dwordx4 v[82:83], off
	v_lshl_add_u64 v[82:83], v[4:5], 0, s[20:21]
	s_mov_b32 m0, s11
	s_mov_b64 s[20:21], 0x60500
	global_load_lds_dwordx4 v[82:83], off
	v_lshl_add_u64 v[82:83], v[4:5], 0, s[20:21]
	s_mov_b32 m0, s12
	s_nop 0
	global_load_lds_dwordx4 v[82:83], off
	ds_read_b128 v[82:85], v15
	ds_read_b128 v[86:89], v15 offset:2048
	ds_read_b128 v[90:93], v15 offset:4096
	ds_read_b128 v[94:97], v15 offset:6144
	ds_read_b128 v[98:101], v16
	ds_read_b128 v[102:105], v16 offset:2048
	ds_read_b128 v[106:109], v16 offset:4096
	ds_read_b128 v[138:141], v16 offset:6144
	s_waitcnt lgkmcnt(8)
	v_mfma_f32_16x16x32_bf16 v[70:73], v[126:129], v[110:113], v[70:73]
	v_mfma_f32_16x16x32_bf16 v[74:77], v[130:133], v[110:113], v[74:77]
	v_mfma_f32_16x16x32_bf16 v[78:81], v[134:137], v[110:113], v[78:81]
	v_mfma_f32_16x16x32_bf16 v[22:25], v[142:145], v[110:113], v[22:25]
	v_mfma_f32_16x16x32_bf16 v[38:41], v[126:129], v[114:117], v[38:41]
	v_mfma_f32_16x16x32_bf16 v[46:49], v[130:133], v[114:117], v[46:49]
	v_mfma_f32_16x16x32_bf16 v[58:61], v[134:137], v[114:117], v[58:61]
	v_mfma_f32_16x16x32_bf16 v[50:53], v[142:145], v[114:117], v[50:53]
	v_mfma_f32_16x16x32_bf16 v[42:45], v[126:129], v[118:121], v[42:45]
	v_mfma_f32_16x16x32_bf16 v[62:65], v[130:133], v[118:121], v[62:65]
	v_mfma_f32_16x16x32_bf16 v[66:69], v[134:137], v[118:121], v[66:69]
	v_mfma_f32_16x16x32_bf16 v[54:57], v[142:145], v[118:121], v[54:57]
	v_mfma_f32_16x16x32_bf16 v[34:37], v[126:129], v[122:125], v[34:37]
	v_mfma_f32_16x16x32_bf16 v[30:33], v[130:133], v[122:125], v[30:33]
	v_mfma_f32_16x16x32_bf16 v[26:29], v[134:137], v[122:125], v[26:29]
	v_mfma_f32_16x16x32_bf16 v[18:21], v[142:145], v[122:125], v[18:21]
	s_waitcnt vmcnt(6) lgkmcnt(0)
	s_barrier
	ds_read_b128 v[110:113], v2
	ds_read_b128 v[114:117], v2 offset:2048
	ds_read_b128 v[118:121], v2 offset:4096
	ds_read_b128 v[122:125], v2 offset:6144
	ds_read_b128 v[126:129], v8 offset:16384
	ds_read_b128 v[130:133], v8 offset:18432
	ds_read_b128 v[134:137], v8 offset:20480
	ds_read_b128 v[142:145], v8 offset:22528
	v_mfma_f32_16x16x32_bf16 v[70:73], v[98:101], v[82:85], v[70:73]
	v_mfma_f32_16x16x32_bf16 v[74:77], v[102:105], v[82:85], v[74:77]
	v_mfma_f32_16x16x32_bf16 v[78:81], v[106:109], v[82:85], v[78:81]
	v_mfma_f32_16x16x32_bf16 v[22:25], v[138:141], v[82:85], v[22:25]
	v_mfma_f32_16x16x32_bf16 v[38:41], v[98:101], v[86:89], v[38:41]
	v_mfma_f32_16x16x32_bf16 v[46:49], v[102:105], v[86:89], v[46:49]
	v_mfma_f32_16x16x32_bf16 v[58:61], v[106:109], v[86:89], v[58:61]
	v_mfma_f32_16x16x32_bf16 v[50:53], v[138:141], v[86:89], v[50:53]
	v_mfma_f32_16x16x32_bf16 v[42:45], v[98:101], v[90:93], v[42:45]
	v_mfma_f32_16x16x32_bf16 v[62:65], v[102:105], v[90:93], v[62:65]
	v_mfma_f32_16x16x32_bf16 v[66:69], v[106:109], v[90:93], v[66:69]
	v_mfma_f32_16x16x32_bf16 v[54:57], v[138:141], v[90:93], v[54:57]
	v_mfma_f32_16x16x32_bf16 v[34:37], v[98:101], v[94:97], v[34:37]
	v_mfma_f32_16x16x32_bf16 v[30:33], v[102:105], v[94:97], v[30:33]
	v_mfma_f32_16x16x32_bf16 v[26:29], v[106:109], v[94:97], v[26:29]
	v_mfma_f32_16x16x32_bf16 v[18:21], v[138:141], v[94:97], v[18:21]
	s_mov_b32 m0, s13
	v_lshl_add_u64 v[82:83], v[6:7], 0, s[80:81]
	global_load_lds_dwordx4 v[82:83], off
	v_lshl_add_u64 v[82:83], v[6:7], 0, s[82:83]
	s_mov_b32 m0, s14
	s_mov_b64 s[20:21], 0x40580
	global_load_lds_dwordx4 v[82:83], off
	v_lshl_add_u64 v[82:83], v[4:5], 0, s[80:81]
	s_mov_b32 m0, s15
	s_nop 0
	global_load_lds_dwordx4 v[82:83], off
	v_lshl_add_u64 v[82:83], v[4:5], 0, s[82:83]
	s_mov_b32 m0, s16
	s_nop 0
	global_load_lds_dwordx4 v[82:83], off
	v_lshl_add_u64 v[82:83], v[4:5], 0, s[20:21]
	s_mov_b32 m0, s17
	s_mov_b64 s[20:21], 0x60580
	global_load_lds_dwordx4 v[82:83], off
	v_lshl_add_u64 v[82:83], v[4:5], 0, s[20:21]
	s_mov_b32 m0, s18
	s_nop 0
	global_load_lds_dwordx4 v[82:83], off
	ds_read_b128 v[82:85], v9
	ds_read_b128 v[86:89], v9 offset:2048
	ds_read_b128 v[90:93], v9 offset:4096
	ds_read_b128 v[94:97], v9 offset:6144
	ds_read_b128 v[98:101], v10 offset:16384
	ds_read_b128 v[102:105], v10 offset:18432
	ds_read_b128 v[106:109], v10 offset:20480
	ds_read_b128 v[138:141], v10 offset:22528
	s_waitcnt lgkmcnt(8)
	v_mfma_f32_16x16x32_bf16 v[70:73], v[126:129], v[110:113], v[70:73]
	v_mfma_f32_16x16x32_bf16 v[74:77], v[130:133], v[110:113], v[74:77]
	v_mfma_f32_16x16x32_bf16 v[78:81], v[134:137], v[110:113], v[78:81]
	v_mfma_f32_16x16x32_bf16 v[22:25], v[142:145], v[110:113], v[22:25]
	v_mfma_f32_16x16x32_bf16 v[38:41], v[126:129], v[114:117], v[38:41]
	v_mfma_f32_16x16x32_bf16 v[46:49], v[130:133], v[114:117], v[46:49]
	v_mfma_f32_16x16x32_bf16 v[58:61], v[134:137], v[114:117], v[58:61]
	v_mfma_f32_16x16x32_bf16 v[50:53], v[142:145], v[114:117], v[50:53]
	v_mfma_f32_16x16x32_bf16 v[42:45], v[126:129], v[118:121], v[42:45]
	v_mfma_f32_16x16x32_bf16 v[62:65], v[130:133], v[118:121], v[62:65]
	v_mfma_f32_16x16x32_bf16 v[66:69], v[134:137], v[118:121], v[66:69]
	v_mfma_f32_16x16x32_bf16 v[54:57], v[142:145], v[118:121], v[54:57]
	v_mfma_f32_16x16x32_bf16 v[34:37], v[126:129], v[122:125], v[34:37]
	v_mfma_f32_16x16x32_bf16 v[30:33], v[130:133], v[122:125], v[30:33]
	v_mfma_f32_16x16x32_bf16 v[26:29], v[134:137], v[122:125], v[26:29]
	v_mfma_f32_16x16x32_bf16 v[18:21], v[142:145], v[122:125], v[18:21]
	s_waitcnt vmcnt(6) lgkmcnt(0)
	s_barrier
	ds_read_b128 v[110:113], v2 offset:49152
	ds_read_b128 v[114:117], v2 offset:51200
	ds_read_b128 v[118:121], v2 offset:53248
	ds_read_b128 v[122:125], v2 offset:55296
	ds_read_b128 v[126:129], v11
	ds_read_b128 v[130:133], v11 offset:2048
	ds_read_b128 v[134:137], v11 offset:4096
	ds_read_b128 v[142:145], v11 offset:6144
	v_mfma_f32_16x16x32_bf16 v[70:73], v[98:101], v[82:85], v[70:73]
	v_mfma_f32_16x16x32_bf16 v[74:77], v[102:105], v[82:85], v[74:77]
	v_mfma_f32_16x16x32_bf16 v[78:81], v[106:109], v[82:85], v[78:81]
	v_mfma_f32_16x16x32_bf16 v[22:25], v[138:141], v[82:85], v[22:25]
	v_mfma_f32_16x16x32_bf16 v[38:41], v[98:101], v[86:89], v[38:41]
	v_mfma_f32_16x16x32_bf16 v[46:49], v[102:105], v[86:89], v[46:49]
	v_mfma_f32_16x16x32_bf16 v[58:61], v[106:109], v[86:89], v[58:61]
	v_mfma_f32_16x16x32_bf16 v[50:53], v[138:141], v[86:89], v[50:53]
	v_mfma_f32_16x16x32_bf16 v[42:45], v[98:101], v[90:93], v[42:45]
	v_mfma_f32_16x16x32_bf16 v[62:65], v[102:105], v[90:93], v[62:65]
	v_mfma_f32_16x16x32_bf16 v[66:69], v[106:109], v[90:93], v[66:69]
	v_mfma_f32_16x16x32_bf16 v[54:57], v[138:141], v[90:93], v[54:57]
	v_mfma_f32_16x16x32_bf16 v[34:37], v[98:101], v[94:97], v[34:37]
	v_mfma_f32_16x16x32_bf16 v[30:33], v[102:105], v[94:97], v[30:33]
	v_mfma_f32_16x16x32_bf16 v[26:29], v[106:109], v[94:97], v[26:29]
	v_mfma_f32_16x16x32_bf16 v[18:21], v[138:141], v[94:97], v[18:21]
	s_mov_b32 m0, s6
	v_lshl_add_u64 v[82:83], v[6:7], 0, s[96:97]
	global_load_lds_dwordx4 v[82:83], off
	v_lshl_add_u64 v[82:83], v[6:7], 0, vcc
	s_mov_b32 m0, s87
	s_mov_b64 s[20:21], 0x40600
	global_load_lds_dwordx4 v[82:83], off
	v_lshl_add_u64 v[82:83], v[4:5], 0, s[96:97]
	s_mov_b32 m0, s0
	s_nop 0
	global_load_lds_dwordx4 v[82:83], off
	v_lshl_add_u64 v[82:83], v[4:5], 0, vcc
	s_mov_b32 m0, s1
	s_nop 0
	global_load_lds_dwordx4 v[82:83], off
	v_lshl_add_u64 v[82:83], v[4:5], 0, s[20:21]
	s_mov_b32 m0, s86
	s_mov_b64 s[20:21], 0x60600
	global_load_lds_dwordx4 v[82:83], off
	v_lshl_add_u64 v[82:83], v[4:5], 0, s[20:21]
	s_mov_b32 m0, s85
	s_nop 0
	global_load_lds_dwordx4 v[82:83], off
	ds_read_b128 v[82:85], v9 offset:49152
	ds_read_b128 v[86:89], v9 offset:51200
	ds_read_b128 v[90:93], v9 offset:53248
	ds_read_b128 v[94:97], v9 offset:55296
	ds_read_b128 v[98:101], v12
	ds_read_b128 v[102:105], v12 offset:2048
	ds_read_b128 v[106:109], v12 offset:4096
	ds_read_b128 v[138:141], v12 offset:6144
	s_waitcnt lgkmcnt(8)
	v_mfma_f32_16x16x32_bf16 v[70:73], v[126:129], v[110:113], v[70:73]
	v_mfma_f32_16x16x32_bf16 v[74:77], v[130:133], v[110:113], v[74:77]
	v_mfma_f32_16x16x32_bf16 v[78:81], v[134:137], v[110:113], v[78:81]
	v_mfma_f32_16x16x32_bf16 v[22:25], v[142:145], v[110:113], v[22:25]
	v_mfma_f32_16x16x32_bf16 v[38:41], v[126:129], v[114:117], v[38:41]
	v_mfma_f32_16x16x32_bf16 v[46:49], v[130:133], v[114:117], v[46:49]
	v_mfma_f32_16x16x32_bf16 v[58:61], v[134:137], v[114:117], v[58:61]
	v_mfma_f32_16x16x32_bf16 v[50:53], v[142:145], v[114:117], v[50:53]
	v_mfma_f32_16x16x32_bf16 v[42:45], v[126:129], v[118:121], v[42:45]
	v_mfma_f32_16x16x32_bf16 v[62:65], v[130:133], v[118:121], v[62:65]
	v_mfma_f32_16x16x32_bf16 v[66:69], v[134:137], v[118:121], v[66:69]
	v_mfma_f32_16x16x32_bf16 v[54:57], v[142:145], v[118:121], v[54:57]
	v_mfma_f32_16x16x32_bf16 v[34:37], v[126:129], v[122:125], v[34:37]
	v_mfma_f32_16x16x32_bf16 v[30:33], v[130:133], v[122:125], v[30:33]
	v_mfma_f32_16x16x32_bf16 v[26:29], v[134:137], v[122:125], v[26:29]
	v_mfma_f32_16x16x32_bf16 v[18:21], v[142:145], v[122:125], v[18:21]
	s_waitcnt vmcnt(6) lgkmcnt(0)
	s_barrier
	ds_read_b128 v[110:113], v13
	ds_read_b128 v[114:117], v13 offset:2048
	ds_read_b128 v[118:121], v13 offset:4096
	ds_read_b128 v[122:125], v13 offset:6144
	ds_read_b128 v[126:129], v14
	ds_read_b128 v[130:133], v14 offset:2048
	ds_read_b128 v[134:137], v14 offset:4096
	ds_read_b128 v[142:145], v14 offset:6144
	v_mfma_f32_16x16x32_bf16 v[70:73], v[98:101], v[82:85], v[70:73]
	v_mfma_f32_16x16x32_bf16 v[74:77], v[102:105], v[82:85], v[74:77]
	v_mfma_f32_16x16x32_bf16 v[78:81], v[106:109], v[82:85], v[78:81]
	v_mfma_f32_16x16x32_bf16 v[22:25], v[138:141], v[82:85], v[22:25]
	v_mfma_f32_16x16x32_bf16 v[38:41], v[98:101], v[86:89], v[38:41]
	v_mfma_f32_16x16x32_bf16 v[46:49], v[102:105], v[86:89], v[46:49]
	v_mfma_f32_16x16x32_bf16 v[58:61], v[106:109], v[86:89], v[58:61]
	v_mfma_f32_16x16x32_bf16 v[50:53], v[138:141], v[86:89], v[50:53]
	v_mfma_f32_16x16x32_bf16 v[42:45], v[98:101], v[90:93], v[42:45]
	v_mfma_f32_16x16x32_bf16 v[62:65], v[102:105], v[90:93], v[62:65]
	v_mfma_f32_16x16x32_bf16 v[66:69], v[106:109], v[90:93], v[66:69]
	v_mfma_f32_16x16x32_bf16 v[54:57], v[138:141], v[90:93], v[54:57]
	v_mfma_f32_16x16x32_bf16 v[34:37], v[98:101], v[94:97], v[34:37]
	v_mfma_f32_16x16x32_bf16 v[30:33], v[102:105], v[94:97], v[30:33]
	v_mfma_f32_16x16x32_bf16 v[26:29], v[106:109], v[94:97], v[26:29]
	v_mfma_f32_16x16x32_bf16 v[18:21], v[138:141], v[94:97], v[18:21]
	s_mov_b32 m0, s8
	v_lshl_add_u64 v[82:83], v[6:7], 0, s[24:25]
	global_load_lds_dwordx4 v[82:83], off
	v_lshl_add_u64 v[82:83], v[6:7], 0, s[2:3]
	s_mov_b32 m0, s7
	s_nop 0
	global_load_lds_dwordx4 v[82:83], off
	v_lshl_add_u64 v[82:83], v[4:5], 0, s[24:25]
	s_mov_b32 m0, s9
	s_mov_b64 s[8:9], 0x40680
	global_load_lds_dwordx4 v[82:83], off
	v_lshl_add_u64 v[82:83], v[4:5], 0, s[2:3]
	s_mov_b32 m0, s10
	s_nop 0
	global_load_lds_dwordx4 v[82:83], off
	v_lshl_add_u64 v[82:83], v[4:5], 0, s[8:9]
	s_mov_b32 m0, s11
	s_mov_b64 s[8:9], 0x60680
	global_load_lds_dwordx4 v[82:83], off
	v_lshl_add_u64 v[82:83], v[4:5], 0, s[8:9]
	s_mov_b32 m0, s12
	s_nop 0
	global_load_lds_dwordx4 v[82:83], off
	ds_read_b128 v[82:85], v15
	ds_read_b128 v[86:89], v15 offset:2048
	ds_read_b128 v[90:93], v15 offset:4096
	ds_read_b128 v[94:97], v15 offset:6144
	ds_read_b128 v[98:101], v16
	ds_read_b128 v[102:105], v16 offset:2048
	ds_read_b128 v[106:109], v16 offset:4096
	ds_read_b128 v[138:141], v16 offset:6144
	s_waitcnt lgkmcnt(8)
	v_mfma_f32_16x16x32_bf16 v[70:73], v[126:129], v[110:113], v[70:73]
	v_mfma_f32_16x16x32_bf16 v[74:77], v[130:133], v[110:113], v[74:77]
	v_mfma_f32_16x16x32_bf16 v[78:81], v[134:137], v[110:113], v[78:81]
	v_mfma_f32_16x16x32_bf16 v[22:25], v[142:145], v[110:113], v[22:25]
	v_mfma_f32_16x16x32_bf16 v[38:41], v[126:129], v[114:117], v[38:41]
	v_mfma_f32_16x16x32_bf16 v[46:49], v[130:133], v[114:117], v[46:49]
	v_mfma_f32_16x16x32_bf16 v[58:61], v[134:137], v[114:117], v[58:61]
	v_mfma_f32_16x16x32_bf16 v[50:53], v[142:145], v[114:117], v[50:53]
	v_mfma_f32_16x16x32_bf16 v[42:45], v[126:129], v[118:121], v[42:45]
	v_mfma_f32_16x16x32_bf16 v[62:65], v[130:133], v[118:121], v[62:65]
	v_mfma_f32_16x16x32_bf16 v[66:69], v[134:137], v[118:121], v[66:69]
	v_mfma_f32_16x16x32_bf16 v[54:57], v[142:145], v[118:121], v[54:57]
	v_mfma_f32_16x16x32_bf16 v[34:37], v[126:129], v[122:125], v[34:37]
	v_mfma_f32_16x16x32_bf16 v[30:33], v[130:133], v[122:125], v[30:33]
	v_mfma_f32_16x16x32_bf16 v[26:29], v[134:137], v[122:125], v[26:29]
	v_mfma_f32_16x16x32_bf16 v[18:21], v[142:145], v[122:125], v[18:21]
	s_waitcnt vmcnt(6) lgkmcnt(0)
	s_barrier
	ds_read_b128 v[110:113], v2
	ds_read_b128 v[114:117], v2 offset:2048
	ds_read_b128 v[118:121], v2 offset:4096
	ds_read_b128 v[122:125], v2 offset:6144
	ds_read_b128 v[126:129], v8 offset:16384
	ds_read_b128 v[130:133], v8 offset:18432
	ds_read_b128 v[134:137], v8 offset:20480
	ds_read_b128 v[142:145], v8 offset:22528
	v_mfma_f32_16x16x32_bf16 v[70:73], v[98:101], v[82:85], v[70:73]
	v_mfma_f32_16x16x32_bf16 v[74:77], v[102:105], v[82:85], v[74:77]
	v_mfma_f32_16x16x32_bf16 v[78:81], v[106:109], v[82:85], v[78:81]
	v_mfma_f32_16x16x32_bf16 v[22:25], v[138:141], v[82:85], v[22:25]
	v_mfma_f32_16x16x32_bf16 v[38:41], v[98:101], v[86:89], v[38:41]
	v_mfma_f32_16x16x32_bf16 v[46:49], v[102:105], v[86:89], v[46:49]
	v_mfma_f32_16x16x32_bf16 v[58:61], v[106:109], v[86:89], v[58:61]
	v_mfma_f32_16x16x32_bf16 v[50:53], v[138:141], v[86:89], v[50:53]
	v_mfma_f32_16x16x32_bf16 v[42:45], v[98:101], v[90:93], v[42:45]
	v_mfma_f32_16x16x32_bf16 v[62:65], v[102:105], v[90:93], v[62:65]
	v_mfma_f32_16x16x32_bf16 v[66:69], v[106:109], v[90:93], v[66:69]
	v_mfma_f32_16x16x32_bf16 v[54:57], v[138:141], v[90:93], v[54:57]
	v_mfma_f32_16x16x32_bf16 v[34:37], v[98:101], v[94:97], v[34:37]
	v_mfma_f32_16x16x32_bf16 v[30:33], v[102:105], v[94:97], v[30:33]
	v_mfma_f32_16x16x32_bf16 v[26:29], v[106:109], v[94:97], v[26:29]
	v_mfma_f32_16x16x32_bf16 v[18:21], v[138:141], v[94:97], v[18:21]
	s_mov_b32 m0, s13
	v_lshl_add_u64 v[82:83], v[6:7], 0, s[38:39]
	global_load_lds_dwordx4 v[82:83], off
	v_lshl_add_u64 v[82:83], v[6:7], 0, s[56:57]
	s_mov_b32 m0, s14
	s_mov_b64 s[8:9], 0x40700
	global_load_lds_dwordx4 v[82:83], off
	v_lshl_add_u64 v[82:83], v[4:5], 0, s[38:39]
	s_mov_b32 m0, s15
	s_nop 0
	global_load_lds_dwordx4 v[82:83], off
	v_lshl_add_u64 v[82:83], v[4:5], 0, s[56:57]
	s_mov_b32 m0, s16
	s_nop 0
	global_load_lds_dwordx4 v[82:83], off
	v_lshl_add_u64 v[82:83], v[4:5], 0, s[8:9]
	s_mov_b32 m0, s17
	s_mov_b64 s[8:9], 0x60700
	global_load_lds_dwordx4 v[82:83], off
	v_lshl_add_u64 v[82:83], v[4:5], 0, s[8:9]
	s_mov_b32 m0, s18
	s_nop 0
	global_load_lds_dwordx4 v[82:83], off
	ds_read_b128 v[82:85], v9
	ds_read_b128 v[86:89], v9 offset:2048
	ds_read_b128 v[90:93], v9 offset:4096
	ds_read_b128 v[94:97], v9 offset:6144
	ds_read_b128 v[98:101], v10 offset:16384
	ds_read_b128 v[102:105], v10 offset:18432
	ds_read_b128 v[106:109], v10 offset:20480
	ds_read_b128 v[138:141], v10 offset:22528
	s_waitcnt lgkmcnt(8)
	v_mfma_f32_16x16x32_bf16 v[70:73], v[126:129], v[110:113], v[70:73]
	v_mfma_f32_16x16x32_bf16 v[74:77], v[130:133], v[110:113], v[74:77]
	v_mfma_f32_16x16x32_bf16 v[78:81], v[134:137], v[110:113], v[78:81]
	v_mfma_f32_16x16x32_bf16 v[22:25], v[142:145], v[110:113], v[22:25]
	v_mfma_f32_16x16x32_bf16 v[38:41], v[126:129], v[114:117], v[38:41]
	v_mfma_f32_16x16x32_bf16 v[46:49], v[130:133], v[114:117], v[46:49]
	v_mfma_f32_16x16x32_bf16 v[58:61], v[134:137], v[114:117], v[58:61]
	v_mfma_f32_16x16x32_bf16 v[50:53], v[142:145], v[114:117], v[50:53]
	v_mfma_f32_16x16x32_bf16 v[42:45], v[126:129], v[118:121], v[42:45]
	v_mfma_f32_16x16x32_bf16 v[62:65], v[130:133], v[118:121], v[62:65]
	v_mfma_f32_16x16x32_bf16 v[66:69], v[134:137], v[118:121], v[66:69]
	v_mfma_f32_16x16x32_bf16 v[54:57], v[142:145], v[118:121], v[54:57]
	v_mfma_f32_16x16x32_bf16 v[34:37], v[126:129], v[122:125], v[34:37]
	v_mfma_f32_16x16x32_bf16 v[30:33], v[130:133], v[122:125], v[30:33]
	v_mfma_f32_16x16x32_bf16 v[26:29], v[134:137], v[122:125], v[26:29]
	v_mfma_f32_16x16x32_bf16 v[18:21], v[142:145], v[122:125], v[18:21]
	s_waitcnt vmcnt(6) lgkmcnt(0)
	s_barrier
	ds_read_b128 v[110:113], v2 offset:49152
	ds_read_b128 v[114:117], v2 offset:51200
	ds_read_b128 v[118:121], v2 offset:53248
	ds_read_b128 v[122:125], v2 offset:55296
	ds_read_b128 v[126:129], v11
	ds_read_b128 v[130:133], v11 offset:2048
	ds_read_b128 v[134:137], v11 offset:4096
	ds_read_b128 v[142:145], v11 offset:6144
	v_mfma_f32_16x16x32_bf16 v[70:73], v[98:101], v[82:85], v[70:73]
	v_mfma_f32_16x16x32_bf16 v[74:77], v[102:105], v[82:85], v[74:77]
	v_mfma_f32_16x16x32_bf16 v[78:81], v[106:109], v[82:85], v[78:81]
	v_mfma_f32_16x16x32_bf16 v[22:25], v[138:141], v[82:85], v[22:25]
	v_mfma_f32_16x16x32_bf16 v[38:41], v[98:101], v[86:89], v[38:41]
	v_mfma_f32_16x16x32_bf16 v[46:49], v[102:105], v[86:89], v[46:49]
	v_mfma_f32_16x16x32_bf16 v[58:61], v[106:109], v[86:89], v[58:61]
	v_mfma_f32_16x16x32_bf16 v[50:53], v[138:141], v[86:89], v[50:53]
	v_mfma_f32_16x16x32_bf16 v[42:45], v[98:101], v[90:93], v[42:45]
	v_mfma_f32_16x16x32_bf16 v[62:65], v[102:105], v[90:93], v[62:65]
	v_mfma_f32_16x16x32_bf16 v[66:69], v[106:109], v[90:93], v[66:69]
	v_mfma_f32_16x16x32_bf16 v[54:57], v[138:141], v[90:93], v[54:57]
	v_mfma_f32_16x16x32_bf16 v[34:37], v[98:101], v[94:97], v[34:37]
	v_mfma_f32_16x16x32_bf16 v[30:33], v[102:105], v[94:97], v[30:33]
	v_mfma_f32_16x16x32_bf16 v[26:29], v[106:109], v[94:97], v[26:29]
	v_mfma_f32_16x16x32_bf16 v[18:21], v[138:141], v[94:97], v[18:21]
	s_mov_b32 m0, s6
	v_lshl_add_u64 v[82:83], v[6:7], 0, s[58:59]
	global_load_lds_dwordx4 v[82:83], off
	v_lshl_add_u64 v[6:7], v[6:7], 0, s[60:61]
	s_mov_b32 m0, s87
	s_nop 0
	global_load_lds_dwordx4 v[6:7], off
	v_lshl_add_u64 v[6:7], v[4:5], 0, s[58:59]
	s_mov_b32 m0, s0
	s_nop 0
	global_load_lds_dwordx4 v[6:7], off
	v_lshl_add_u64 v[6:7], v[4:5], 0, s[60:61]
	s_mov_b32 m0, s1
	s_mov_b64 s[0:1], 0x40780
	global_load_lds_dwordx4 v[6:7], off
	v_lshl_add_u64 v[6:7], v[4:5], 0, s[0:1]
	s_mov_b32 m0, s86
	s_mov_b64 s[0:1], 0x60780
	global_load_lds_dwordx4 v[6:7], off
	v_lshl_add_u64 v[4:5], v[4:5], 0, s[0:1]
	s_mov_b32 m0, s85
	s_nop 0
	global_load_lds_dwordx4 v[4:5], off
	ds_read_b128 v[4:7], v9 offset:49152
	ds_read_b128 v[82:85], v9 offset:51200
	ds_read_b128 v[86:89], v9 offset:53248
	ds_read_b128 v[90:93], v9 offset:55296
	ds_read_b128 v[94:97], v12
	ds_read_b128 v[98:101], v12 offset:2048
	ds_read_b128 v[102:105], v12 offset:4096
	ds_read_b128 v[106:109], v12 offset:6144
	s_waitcnt lgkmcnt(8)
	v_mfma_f32_16x16x32_bf16 v[70:73], v[126:129], v[110:113], v[70:73]
	v_mfma_f32_16x16x32_bf16 v[74:77], v[130:133], v[110:113], v[74:77]
	v_mfma_f32_16x16x32_bf16 v[78:81], v[134:137], v[110:113], v[78:81]
	v_mfma_f32_16x16x32_bf16 v[22:25], v[142:145], v[110:113], v[22:25]
	v_mfma_f32_16x16x32_bf16 v[38:41], v[126:129], v[114:117], v[38:41]
	v_mfma_f32_16x16x32_bf16 v[46:49], v[130:133], v[114:117], v[46:49]
	v_mfma_f32_16x16x32_bf16 v[58:61], v[134:137], v[114:117], v[58:61]
	v_mfma_f32_16x16x32_bf16 v[50:53], v[142:145], v[114:117], v[50:53]
	v_mfma_f32_16x16x32_bf16 v[42:45], v[126:129], v[118:121], v[42:45]
	v_mfma_f32_16x16x32_bf16 v[62:65], v[130:133], v[118:121], v[62:65]
	v_mfma_f32_16x16x32_bf16 v[66:69], v[134:137], v[118:121], v[66:69]
	v_mfma_f32_16x16x32_bf16 v[54:57], v[142:145], v[118:121], v[54:57]
	v_mfma_f32_16x16x32_bf16 v[34:37], v[126:129], v[122:125], v[34:37]
	v_mfma_f32_16x16x32_bf16 v[30:33], v[130:133], v[122:125], v[30:33]
	v_mfma_f32_16x16x32_bf16 v[26:29], v[134:137], v[122:125], v[26:29]
	v_mfma_f32_16x16x32_bf16 v[18:21], v[142:145], v[122:125], v[18:21]
	s_waitcnt vmcnt(6) lgkmcnt(0)
	s_barrier
	ds_read_b128 v[110:113], v13
	ds_read_b128 v[114:117], v13 offset:2048
	ds_read_b128 v[118:121], v13 offset:4096
	ds_read_b128 v[122:125], v13 offset:6144
	ds_read_b128 v[126:129], v14
	ds_read_b128 v[130:133], v14 offset:2048
	ds_read_b128 v[134:137], v14 offset:4096
	ds_read_b128 v[138:141], v14 offset:6144
	v_mfma_f32_16x16x32_bf16 v[70:73], v[94:97], v[4:7], v[70:73]
	v_mfma_f32_16x16x32_bf16 v[74:77], v[98:101], v[4:7], v[74:77]
	v_mfma_f32_16x16x32_bf16 v[78:81], v[102:105], v[4:7], v[78:81]
	v_mfma_f32_16x16x32_bf16 v[4:7], v[106:109], v[4:7], v[22:25]
	v_mfma_f32_16x16x32_bf16 v[22:25], v[94:97], v[82:85], v[38:41]
	v_mfma_f32_16x16x32_bf16 v[38:41], v[98:101], v[82:85], v[46:49]
	v_mfma_f32_16x16x32_bf16 v[46:49], v[102:105], v[82:85], v[58:61]
	v_mfma_f32_16x16x32_bf16 v[50:53], v[106:109], v[82:85], v[50:53]
	v_mfma_f32_16x16x32_bf16 v[42:45], v[94:97], v[86:89], v[42:45]
	v_mfma_f32_16x16x32_bf16 v[58:61], v[98:101], v[86:89], v[62:65]
	v_mfma_f32_16x16x32_bf16 v[62:65], v[102:105], v[86:89], v[66:69]
	v_mfma_f32_16x16x32_bf16 v[54:57], v[106:109], v[86:89], v[54:57]
	v_mfma_f32_16x16x32_bf16 v[34:37], v[94:97], v[90:93], v[34:37]
	v_mfma_f32_16x16x32_bf16 v[30:33], v[98:101], v[90:93], v[30:33]
	v_mfma_f32_16x16x32_bf16 v[26:29], v[102:105], v[90:93], v[26:29]
	v_mfma_f32_16x16x32_bf16 v[18:21], v[106:109], v[90:93], v[18:21]
	ds_read_b128 v[66:69], v15
	ds_read_b128 v[82:85], v15 offset:2048
	ds_read_b128 v[86:89], v15 offset:4096
	ds_read_b128 v[12:15], v15 offset:6144
	ds_read_b128 v[90:93], v16
	ds_read_b128 v[94:97], v16 offset:2048
	ds_read_b128 v[98:101], v16 offset:4096
	ds_read_b128 v[102:105], v16 offset:6144
	s_waitcnt lgkmcnt(8)
	v_mfma_f32_16x16x32_bf16 v[70:73], v[126:129], v[110:113], v[70:73]
	v_mfma_f32_16x16x32_bf16 v[74:77], v[130:133], v[110:113], v[74:77]
	v_mfma_f32_16x16x32_bf16 v[78:81], v[134:137], v[110:113], v[78:81]
	v_mfma_f32_16x16x32_bf16 v[4:7], v[138:141], v[110:113], v[4:7]
	v_mfma_f32_16x16x32_bf16 v[22:25], v[126:129], v[114:117], v[22:25]
	v_mfma_f32_16x16x32_bf16 v[38:41], v[130:133], v[114:117], v[38:41]
	v_mfma_f32_16x16x32_bf16 v[46:49], v[134:137], v[114:117], v[46:49]
	v_mfma_f32_16x16x32_bf16 v[50:53], v[138:141], v[114:117], v[50:53]
	v_mfma_f32_16x16x32_bf16 v[42:45], v[126:129], v[118:121], v[42:45]
	v_mfma_f32_16x16x32_bf16 v[58:61], v[130:133], v[118:121], v[58:61]
	v_mfma_f32_16x16x32_bf16 v[62:65], v[134:137], v[118:121], v[62:65]
	v_mfma_f32_16x16x32_bf16 v[54:57], v[138:141], v[118:121], v[54:57]
	v_mfma_f32_16x16x32_bf16 v[34:37], v[126:129], v[122:125], v[34:37]
	v_mfma_f32_16x16x32_bf16 v[30:33], v[130:133], v[122:125], v[30:33]
	v_mfma_f32_16x16x32_bf16 v[26:29], v[134:137], v[122:125], v[26:29]
	v_mfma_f32_16x16x32_bf16 v[16:19], v[138:141], v[122:125], v[18:21]
	s_waitcnt vmcnt(0) lgkmcnt(0)
	s_barrier
	ds_read_b128 v[106:109], v2
	ds_read_b128 v[110:113], v2 offset:2048
	ds_read_b128 v[114:117], v2 offset:4096
	ds_read_b128 v[118:121], v2 offset:6144
	ds_read_b128 v[122:125], v8 offset:16384
	ds_read_b128 v[126:129], v8 offset:18432
	ds_read_b128 v[130:133], v8 offset:20480
	ds_read_b128 v[134:137], v8 offset:22528
	v_and_b32_e32 v2, 0xc0, v1
	v_mfma_f32_16x16x32_bf16 v[70:73], v[90:93], v[66:69], v[70:73]
	v_mfma_f32_16x16x32_bf16 v[74:77], v[94:97], v[66:69], v[74:77]
	v_mfma_f32_16x16x32_bf16 v[78:81], v[98:101], v[66:69], v[78:81]
	v_mfma_f32_16x16x32_bf16 v[4:7], v[102:105], v[66:69], v[4:7]
	v_mfma_f32_16x16x32_bf16 v[20:23], v[90:93], v[82:85], v[22:25]
	v_mfma_f32_16x16x32_bf16 v[38:41], v[94:97], v[82:85], v[38:41]
	v_mfma_f32_16x16x32_bf16 v[46:49], v[98:101], v[82:85], v[46:49]
	v_mfma_f32_16x16x32_bf16 v[50:53], v[102:105], v[82:85], v[50:53]
	v_mfma_f32_16x16x32_bf16 v[42:45], v[90:93], v[86:89], v[42:45]
	v_mfma_f32_16x16x32_bf16 v[58:61], v[94:97], v[86:89], v[58:61]
	v_mfma_f32_16x16x32_bf16 v[62:65], v[98:101], v[86:89], v[62:65]
	v_mfma_f32_16x16x32_bf16 v[54:57], v[102:105], v[86:89], v[54:57]
	v_mfma_f32_16x16x32_bf16 v[34:37], v[90:93], v[12:15], v[34:37]
	v_mfma_f32_16x16x32_bf16 v[30:33], v[94:97], v[12:15], v[30:33]
	v_mfma_f32_16x16x32_bf16 v[24:27], v[98:101], v[12:15], v[26:29]
	v_mfma_f32_16x16x32_bf16 v[12:15], v[102:105], v[12:15], v[16:19]
	s_nop 2
	ds_read_b128 v[16:19], v9
	ds_read_b128 v[66:69], v9 offset:2048
	ds_read_b128 v[82:85], v9 offset:4096
	ds_read_b128 v[86:89], v9 offset:6144
	ds_read_b128 v[90:93], v10 offset:16384
	ds_read_b128 v[94:97], v10 offset:18432
	ds_read_b128 v[98:101], v10 offset:20480
	ds_read_b128 v[8:11], v10 offset:22528
	s_waitcnt lgkmcnt(8)
	v_mfma_f32_16x16x32_bf16 v[70:73], v[122:125], v[106:109], v[70:73]
	v_mfma_f32_16x16x32_bf16 v[74:77], v[126:129], v[106:109], v[74:77]
	v_mfma_f32_16x16x32_bf16 v[78:81], v[130:133], v[106:109], v[78:81]
	v_mfma_f32_16x16x32_bf16 v[4:7], v[134:137], v[106:109], v[4:7]
	v_mfma_f32_16x16x32_bf16 v[20:23], v[122:125], v[110:113], v[20:23]
	v_mfma_f32_16x16x32_bf16 v[38:41], v[126:129], v[110:113], v[38:41]
	v_mfma_f32_16x16x32_bf16 v[46:49], v[130:133], v[110:113], v[46:49]
	v_mfma_f32_16x16x32_bf16 v[50:53], v[134:137], v[110:113], v[50:53]
	v_mfma_f32_16x16x32_bf16 v[42:45], v[122:125], v[114:117], v[42:45]
	v_mfma_f32_16x16x32_bf16 v[58:61], v[126:129], v[114:117], v[58:61]
	v_mfma_f32_16x16x32_bf16 v[62:65], v[130:133], v[114:117], v[62:65]
	v_mfma_f32_16x16x32_bf16 v[54:57], v[134:137], v[114:117], v[54:57]
	v_mfma_f32_16x16x32_bf16 v[34:37], v[122:125], v[118:121], v[34:37]
	v_mfma_f32_16x16x32_bf16 v[28:31], v[126:129], v[118:121], v[30:33]
	v_mfma_f32_16x16x32_bf16 v[24:27], v[130:133], v[118:121], v[24:27]
	v_mfma_f32_16x16x32_bf16 v[12:15], v[134:137], v[118:121], v[12:15]
	s_waitcnt vmcnt(0) lgkmcnt(0)
	s_barrier
	v_mfma_f32_16x16x32_bf16 v[70:73], v[90:93], v[16:19], v[70:73]
	v_mfma_f32_16x16x32_bf16 v[74:77], v[94:97], v[16:19], v[74:77]
	v_mfma_f32_16x16x32_bf16 v[78:81], v[98:101], v[16:19], v[78:81]
	v_mfma_f32_16x16x32_bf16 v[4:7], v[8:11], v[16:19], v[4:7]
	v_mfma_f32_16x16x32_bf16 v[16:19], v[90:93], v[66:69], v[20:23]
	v_mfma_f32_16x16x32_bf16 v[20:23], v[94:97], v[66:69], v[38:41]
	v_mfma_f32_16x16x32_bf16 v[38:41], v[98:101], v[66:69], v[46:49]
	v_mfma_f32_16x16x32_bf16 v[46:49], v[8:11], v[66:69], v[50:53]
	v_mfma_f32_16x16x32_bf16 v[42:45], v[90:93], v[82:85], v[42:45]
	v_mfma_f32_16x16x32_bf16 v[50:53], v[94:97], v[82:85], v[58:61]
	v_mfma_f32_16x16x32_bf16 v[58:61], v[98:101], v[82:85], v[62:65]
	v_mfma_f32_16x16x32_bf16 v[54:57], v[8:11], v[82:85], v[54:57]
	v_mfma_f32_16x16x32_bf16 v[32:35], v[90:93], v[86:89], v[34:37]
	v_mfma_f32_16x16x32_bf16 v[28:31], v[94:97], v[86:89], v[28:31]
	v_mfma_f32_16x16x32_bf16 v[24:27], v[98:101], v[86:89], v[24:27]
	v_mfma_f32_16x16x32_bf16 v[8:11], v[8:11], v[86:89], v[12:15]
	s_nop 2
	v_ashrrev_i32_e32 v12, 2, v1
	v_and_b32_e32 v12, 0xffffffc0, v12
	v_add_u32_e32 v12, s84, v12
	s_add_u32 s0, s88, s73
	v_and_or_b32 v12, v1, 15, v12
	s_addc_u32 s1, s89, 0
	v_lshrrev_b32_e32 v1, 2, v1
	v_lshl_add_u64 v[14:15], s[0:1], 0, v[2:3]
	v_and_b32_e32 v2, 12, v1
	v_mov_b32_e32 v1, v3
	v_lshl_add_u64 v[14:15], v[14:15], 0, v[2:3]
	v_ashrrev_i32_e32 v13, 31, v12
	v_cvt_pk_fp8_f32 v1, v70, v71
	v_mov_b32_e32 v2, v3
	v_lshl_add_u64 v[36:37], s[62:63], 0, v[12:13]
	v_cvt_pk_fp8_f32 v2, v74, v75
	v_mov_b32_e32 v13, v3
	v_cvt_pk_fp8_f32 v13, v78, v79
	v_mov_b32_e32 v62, v3
	v_cvt_pk_fp8_f32 v62, v4, v5
	v_cvt_pk_fp8_f32 v1, v72, v73 op_sel:[0,0,1]
	v_cvt_pk_fp8_f32 v2, v76, v77 op_sel:[0,0,1]
	v_lshlrev_b64 v[36:37], 10, v[36:37]
	v_cvt_pk_fp8_f32 v13, v80, v81 op_sel:[0,0,1]
	v_lshl_add_u64 v[36:37], v[14:15], 0, v[36:37]
	v_cvt_pk_fp8_f32 v62, v6, v7 op_sel:[0,0,1]
	s_waitcnt lgkmcnt(0)
	s_barrier
	global_store_dword v[36:37], v1, off
	global_store_dword v[36:37], v2, off offset:16
	global_store_dword v[36:37], v13, off offset:32
	global_store_dword v[36:37], v62, off offset:48
	v_mov_b32_e32 v1, v3
	v_cvt_pk_fp8_f32 v1, v16, v17
	v_mov_b32_e32 v2, v3
	v_cvt_pk_fp8_f32 v2, v20, v21
	v_mov_b32_e32 v6, v3
	v_cvt_pk_fp8_f32 v6, v38, v39
	v_mov_b32_e32 v7, v3
	v_or_b32_e32 v4, 16, v12
	v_cvt_pk_fp8_f32 v7, v46, v47
	v_ashrrev_i32_e32 v5, 31, v4
	v_cvt_pk_fp8_f32 v1, v18, v19 op_sel:[0,0,1]
	v_lshl_add_u64 v[4:5], s[62:63], 0, v[4:5]
	v_cvt_pk_fp8_f32 v2, v22, v23 op_sel:[0,0,1]
	v_lshlrev_b64 v[4:5], 10, v[4:5]
	v_cvt_pk_fp8_f32 v6, v40, v41 op_sel:[0,0,1]
	v_lshl_add_u64 v[4:5], v[14:15], 0, v[4:5]
	v_cvt_pk_fp8_f32 v7, v48, v49 op_sel:[0,0,1]
	global_store_dword v[4:5], v1, off
	global_store_dword v[4:5], v2, off offset:16
	global_store_dword v[4:5], v6, off offset:32
	global_store_dword v[4:5], v7, off offset:48
	v_mov_b32_e32 v1, v3
	v_cvt_pk_fp8_f32 v1, v42, v43
	v_mov_b32_e32 v2, v3
	v_cvt_pk_fp8_f32 v2, v50, v51
	v_mov_b32_e32 v6, v3
	v_cvt_pk_fp8_f32 v6, v58, v59
	v_mov_b32_e32 v7, v3
	v_or_b32_e32 v4, 32, v12
	v_cvt_pk_fp8_f32 v7, v54, v55
	v_ashrrev_i32_e32 v5, 31, v4
	v_cvt_pk_fp8_f32 v1, v44, v45 op_sel:[0,0,1]
	v_lshl_add_u64 v[4:5], s[62:63], 0, v[4:5]
	v_cvt_pk_fp8_f32 v2, v52, v53 op_sel:[0,0,1]
	v_lshlrev_b64 v[4:5], 10, v[4:5]
	v_cvt_pk_fp8_f32 v6, v60, v61 op_sel:[0,0,1]
	v_lshl_add_u64 v[4:5], v[14:15], 0, v[4:5]
	v_cvt_pk_fp8_f32 v7, v56, v57 op_sel:[0,0,1]
	global_store_dword v[4:5], v1, off
	global_store_dword v[4:5], v2, off offset:16
	global_store_dword v[4:5], v6, off offset:32
	global_store_dword v[4:5], v7, off offset:48
	v_mov_b32_e32 v1, v3
	v_mov_b32_e32 v7, v3
	v_cvt_pk_fp8_f32 v1, v32, v33
	v_mov_b32_e32 v2, v3
	v_cvt_pk_fp8_f32 v7, v8, v9
	v_cvt_pk_fp8_f32 v2, v28, v29
	v_mov_b32_e32 v6, v3
	v_cvt_pk_fp8_f32 v6, v24, v25
	v_or_b32_e32 v4, 48, v12
	v_ashrrev_i32_e32 v5, 31, v4
	v_cvt_pk_fp8_f32 v1, v34, v35 op_sel:[0,0,1]
	v_cvt_pk_fp8_f32 v7, v10, v11 op_sel:[0,0,1]
	v_lshl_add_u64 v[4:5], s[62:63], 0, v[4:5]
	v_cvt_pk_fp8_f32 v2, v30, v31 op_sel:[0,0,1]
	v_lshlrev_b64 v[4:5], 10, v[4:5]
	v_cvt_pk_fp8_f32 v6, v26, v27 op_sel:[0,0,1]
	s_add_i32 s98, s98, s28
	s_add_i32 s65, s65, s66
	s_add_i32 s67, s67, s68
	s_add_i32 s69, s69, s33
	v_lshl_add_u64 v[4:5], v[14:15], 0, v[4:5]
	s_cmpk_lt_i32 s98, 0x400
	global_store_dword v[4:5], v1, off
	global_store_dword v[4:5], v2, off offset:16
	global_store_dword v[4:5], v6, off offset:32
	global_store_dword v[4:5], v7, off offset:48
	s_cbranch_scc1 .LBB0_897
	v_readlane_b32 s24, v196, 26
	v_readlane_b32 s0, v197, 34
	v_readlane_b32 s96, v196, 24
	s_mov_b32 s46, s28
	v_readlane_b32 s47, v196, 5
	v_readlane_b32 s25, v196, 27
	v_readlane_b32 s1, v197, 35
	v_readlane_b32 s2, v197, 36
	v_readlane_b32 s3, v197, 37
	v_readlane_b32 s4, v197, 38
	v_readlane_b32 s5, v197, 39
	v_readlane_b32 s6, v197, 40
	v_readlane_b32 s7, v197, 41
	v_readlane_b32 s8, v197, 42
	v_readlane_b32 s9, v197, 43
	v_readlane_b32 s10, v197, 44
	v_readlane_b32 s11, v197, 45
	v_readlane_b32 s12, v197, 46
	v_readlane_b32 s13, v197, 47
	v_readlane_b32 s14, v197, 48
	v_readlane_b32 s15, v197, 49
	v_readlane_b32 s97, v196, 25

.LBB0_1025:
	s_cmpk_gt_i32 s47, 0x5ff
	s_cbranch_scc1 .LBB0_1045
	s_lshl_b32 s56, s47, 8
	s_lshl_b32 s57, s46, 8
	s_lshl_b32 s58, s47, 7
	s_lshl_b32 s59, s46, 7
	s_mov_b32 s7, 0
	v_mov_b32_e32 v67, 0
	s_mov_b64 s[8:9], 0x80
	s_mov_b64 s[10:11], 0x100
	s_add_i32 s60, 0, 0xc000
	s_mov_b64 s[12:13], 0x180
	s_mov_b64 s[14:15], 0x200
	s_mov_b64 s[16:17], 0x280
	s_mov_b64 s[18:19], 0x300
	s_mov_b64 s[20:21], 0x380
	s_mov_b64 s[22:23], 0x400
	s_mov_b64 s[24:25], 0x480
	s_mov_b64 s[26:27], 0x500
	s_mov_b32 s61, s47
	s_mov_b64 s[28:29], 0x580
	s_mov_b64 s[30:31], 0x600
	s_mov_b64 s[34:35], 0x680
	s_mov_b64 s[36:37], 0x700
	s_mov_b64 s[46:47], 0x780
	s_mov_b32 s98, s61
	s_branch .LBB0_1028
.LBB0_1027:
	s_add_i32 s98, s98, s66
	s_add_i32 s56, s56, s57
	s_add_i32 s58, s58, s59
	s_cmpk_lt_i32 s98, 0x600
	s_cbranch_scc0 .LBB0_1044
.LBB0_1028:
	s_mov_b32 s61, s98
	s_cmp_lg_u32 s57, 0x10000
	s_cbranch_scc1 .Lremap_done_10
	s_lshr_b32 s0, s98, 8
	s_bfe_u32 s1, s98, 0x30005
	s_and_b32 s4, s98, 31
	s_sub_i32 s5, 5, s0
	s_cmp_ge_u32 s0, 3
	s_cselect_b32 s6, 1, 0
	s_cselect_b32 s0, s5, s0
	s_lshl_b32 s1, s1, 4
	s_lshl_b32 s6, s6, 3
	s_add_i32 s1, s1, s6
	s_lshr_b32 s6, s4, 2
	s_add_i32 s1, s1, s6
	s_and_b32 s4, s4, 3
	s_lshl_b32 s0, s0, 2
	s_add_i32 s0, s0, s4
	s_mul_i32 s1, s1, 12
	s_add_i32 s61, s1, s0
.Lremap_done_10:
	s_lshl_b32 s56, s61, 8
	s_lshl_b32 s58, s61, 7
	s_mul_hi_i32 s0, s61, 0x2aaaaaab
	s_lshr_b32 s1, s0, 31
	s_ashr_i32 s4, s0, 1
	s_add_i32 s4, s4, s1
	s_mul_i32 s0, s4, -12
	v_mov_b32_e32 v68, v0
	s_add_i32 s0, s61, s0
	s_waitcnt vmcnt(0) lgkmcnt(0)
	s_barrier
	s_ashr_i32 s1, s0, 31
	v_lshrrev_b32_e32 v3, 4, v68
	v_readlane_b32 s64, v197, 34
	v_xor_b32_e32 v3, v3, v68
	s_lshl_b64 s[38:39], s[0:1], 19
	v_readlane_b32 s70, v197, 40
	v_ashrrev_i32_e32 v2, 3, v68
	v_readlane_b32 s71, v197, 41
	s_add_u32 s38, s70, s38
	v_lshlrev_b32_e32 v3, 4, v3
	s_addc_u32 s39, s71, s39
	s_lshl_b32 s1, s4, 7
	v_and_b32_e32 v66, 0x70, v3
	v_ashrrev_i32_e32 v3, 31, v2
	v_add_u32_e32 v6, s1, v2
	v_lshlrev_b64 v[2:3], 11, v[2:3]
	v_mov_b32_e32 v14, v0
	v_readlane_b32 s65, v197, 35
	v_readlane_b32 s66, v197, 36
	v_readlane_b32 s67, v197, 37
	v_readlane_b32 s68, v197, 38
	v_readlane_b32 s69, v197, 39
	v_readlane_b32 s72, v197, 42
	v_readlane_b32 s73, v197, 43
	v_readlane_b32 s74, v197, 44
	v_readlane_b32 s75, v197, 45
	v_readlane_b32 s76, v197, 46
	v_readlane_b32 s77, v197, 47
	v_readlane_b32 s78, v197, 48
	v_readlane_b32 s79, v197, 49
	v_ashrrev_i32_e32 v7, 31, v6
	v_lshl_add_u64 v[2:3], s[38:39], 0, v[2:3]
	v_lshlrev_b64 v[4:5], 11, v[6:7]
	v_readfirstlane_b32 s5, v14
	v_readlane_b32 s64, v196, 6
	v_add_u32_e32 v6, 64, v6
	v_lshl_add_u64 v[2:3], v[2:3], 0, v[66:67]
	s_mov_b64 s[38:39], 0x20000
	s_lshl_b32 s5, s5, 4
	v_readlane_b32 s65, v196, 7
	v_ashrrev_i32_e32 v7, 31, v6
	v_lshl_add_u64 v[8:9], v[2:3], 0, s[38:39]
	s_mov_b64 s[38:39], 0x40000
	s_and_b32 s5, s5, 0xfffffc00
	v_lshl_add_u64 v[4:5], s[64:65], 0, v[4:5]
	v_lshlrev_b64 v[6:7], 11, v[6:7]
	v_lshl_add_u64 v[10:11], v[2:3], 0, s[38:39]
	s_mov_b64 s[38:39], 0x60000
	s_add_i32 s62, s5, 0
	v_lshl_add_u64 v[4:5], v[4:5], 0, v[66:67]
	v_lshl_add_u64 v[6:7], s[64:65], 0, v[6:7]
	v_lshl_add_u64 v[12:13], v[2:3], 0, s[38:39]
	s_mov_b32 m0, s62
	s_add_i32 s38, s62, 0x2000
	v_lshl_add_u64 v[6:7], v[6:7], 0, v[66:67]
	global_load_lds_dwordx4 v[4:5], off
	s_mov_b32 m0, s38
	s_add_i32 s39, s62, 0x4000
	global_load_lds_dwordx4 v[6:7], off
	s_mov_b32 m0, s39
	s_add_i32 s33, s62, 0x6000
	global_load_lds_dwordx4 v[2:3], off
	s_mov_b32 m0, s33
	s_add_i32 s6, s62, 0x8000
	global_load_lds_dwordx4 v[8:9], off
	s_mov_b32 m0, s6
	s_add_i32 s5, s62, 0xa000
	global_load_lds_dwordx4 v[10:11], off
	s_mov_b32 m0, s5
	s_add_i32 s64, s62, 0xc000
	global_load_lds_dwordx4 v[12:13], off
	v_lshl_add_u64 v[8:9], v[4:5], 0, s[8:9]
	s_mov_b32 m0, s64
	s_add_i32 s63, s62, 0xe000
	v_readlane_b32 s66, v196, 8
	v_readlane_b32 s67, v196, 9
	global_load_lds_dwordx4 v[8:9], off
	v_lshl_add_u64 v[8:9], v[6:7], 0, s[8:9]
	s_mov_b32 m0, s63
	s_add_i32 s65, s62, 0x10000
	global_load_lds_dwordx4 v[8:9], off
	v_lshl_add_u64 v[8:9], v[2:3], 0, s[8:9]
	s_mov_b32 m0, s65
	s_mov_b64 s[66:67], 0x20080
	v_readlane_b32 s68, v196, 10
	v_readlane_b32 s69, v196, 11
	global_load_lds_dwordx4 v[8:9], off
	v_lshl_add_u64 v[8:9], v[2:3], 0, s[66:67]
	s_add_i32 s66, s62, 0x12000
	s_mov_b32 m0, s66
	s_mov_b64 s[68:69], 0x40080
	s_add_i32 s67, s62, 0x14000
	global_load_lds_dwordx4 v[8:9], off
	v_lshl_add_u64 v[8:9], v[2:3], 0, s[68:69]
	s_mov_b32 m0, s67
	s_mov_b64 s[68:69], 0x60080
	global_load_lds_dwordx4 v[8:9], off
	v_lshl_add_u64 v[8:9], v[2:3], 0, s[68:69]
	s_add_i32 s68, s62, 0x16000
	s_mov_b32 m0, s68
	v_lshrrev_b32_e32 v15, 4, v14
	v_bfe_u32 v16, v14, 4, 2
	v_and_b32_e32 v17, 15, v14
	global_load_lds_dwordx4 v[8:9], off
	v_bfe_u32 v8, v14, 1, 3
	v_lshrrev_b32_e32 v9, 2, v14
	s_mov_b32 s69, 0x1ffffc0
	v_and_or_b32 v9, v9, s69, v17
	v_lshlrev_b32_e32 v10, 7, v14
	v_bitop3_b32 v11, v15, v8, 3 bitop3:0x6c
	v_bitop3_b32 v8, v16, v8, 4 bitop3:0x36
	v_lshlrev_b32_e32 v9, 7, v9
	v_and_b32_e32 v60, 0x6780, v10
	v_lshlrev_b32_e32 v11, 4, v11
	v_lshlrev_b32_e32 v61, 4, v8
	v_readlane_b32 s70, v196, 12
	v_add_u32_e32 v10, 0x4000, v60
	v_or_b32_e32 v64, v11, v9
	v_or_b32_e32 v66, v61, v9
	v_or_b32_e32 v9, v11, v60
	s_add_i32 s69, s62, 0x18000
	v_readlane_b32 s71, v196, 13
	s_waitcnt vmcnt(6)
	s_barrier
	v_or_b32_e32 v65, v11, v10
	v_or_b32_e32 v69, v61, v10
	v_add_u32_e32 v8, 0, v64
	v_add_u32_e32 v9, 0, v9
	v_lshl_add_u64 v[10:11], v[4:5], 0, s[10:11]
	s_mov_b32 m0, s69
	s_add_i32 s70, s62, 0x1a000
	v_readlane_b32 s72, v196, 14
	v_readlane_b32 s73, v196, 15
	ds_read_b128 v[12:15], v8
	ds_read_b128 v[16:19], v8 offset:2048
	ds_read_b128 v[20:23], v8 offset:4096
	ds_read_b128 v[24:27], v8 offset:6144
	ds_read_b128 v[28:31], v9 offset:22528
	ds_read_b128 v[32:35], v9 offset:20480
	ds_read_b128 v[36:39], v9 offset:18432
	ds_read_b128 v[40:43], v9 offset:16384
	global_load_lds_dwordx4 v[10:11], off
	v_lshl_add_u64 v[10:11], v[6:7], 0, s[10:11]
	s_mov_b32 m0, s70
	s_add_i32 s71, s62, 0x1c000
	global_load_lds_dwordx4 v[10:11], off
	v_lshl_add_u64 v[10:11], v[2:3], 0, s[10:11]
	s_mov_b32 m0, s71
	s_mov_b64 s[72:73], 0x20100
	v_readlane_b32 s74, v196, 16
	v_readlane_b32 s75, v196, 17
	global_load_lds_dwordx4 v[10:11], off
	v_lshl_add_u64 v[10:11], v[2:3], 0, s[72:73]
	s_add_i32 s72, s62, 0x1e000
	s_mov_b32 m0, s72
	s_mov_b64 s[74:75], 0x40100
	s_add_i32 s73, s62, 0x20000
	global_load_lds_dwordx4 v[10:11], off
	v_lshl_add_u64 v[10:11], v[2:3], 0, s[74:75]
	s_mov_b32 m0, s73
	s_mov_b64 s[74:75], 0x60100
	global_load_lds_dwordx4 v[10:11], off
	v_lshl_add_u64 v[10:11], v[2:3], 0, s[74:75]
	s_add_i32 s74, s62, 0x22000
	s_mov_b32 m0, s74
	v_bfe_u32 v1, v68, 6, 2
	global_load_lds_dwordx4 v[10:11], off
	v_or_b32_e32 v11, v61, v60
	v_add_u32_e32 v10, 0, v66
	v_add_u32_e32 v11, 0, v11
	ds_read_b128 v[44:47], v10
	ds_read_b128 v[48:51], v10 offset:2048
	ds_read_b128 v[52:55], v10 offset:4096
	ds_read_b128 v[56:59], v10 offset:6144
	ds_read_b128 v[60:63], v11 offset:16384
	ds_read_b128 v[70:73], v11 offset:18432
	ds_read_b128 v[74:77], v11 offset:20480
	ds_read_b128 v[78:81], v11 offset:22528
	v_readlane_b32 s76, v196, 18
	v_readlane_b32 s77, v196, 19
	v_readlane_b32 s78, v196, 20
	v_readlane_b32 s79, v196, 21
	s_waitcnt lgkmcnt(8)
	v_mfma_f32_16x16x32_bf16 v[82:85], v[40:43], v[12:15], 0
	v_mfma_f32_16x16x32_bf16 v[86:89], v[36:39], v[12:15], 0
	v_mfma_f32_16x16x32_bf16 v[90:93], v[32:35], v[12:15], 0
	v_mfma_f32_16x16x32_bf16 v[94:97], v[28:31], v[12:15], 0
	v_mfma_f32_16x16x32_bf16 v[98:101], v[40:43], v[16:19], 0
	v_mfma_f32_16x16x32_bf16 v[102:105], v[36:39], v[16:19], 0
	v_mfma_f32_16x16x32_bf16 v[106:109], v[32:35], v[16:19], 0
	v_mfma_f32_16x16x32_bf16 v[14:17], v[28:31], v[16:19], 0
	v_mfma_f32_16x16x32_bf16 v[110:113], v[40:43], v[20:23], 0
	v_mfma_f32_16x16x32_bf16 v[114:117], v[36:39], v[20:23], 0
	v_mfma_f32_16x16x32_bf16 v[118:121], v[32:35], v[20:23], 0
	v_mfma_f32_16x16x32_bf16 v[18:21], v[28:31], v[20:23], 0
	v_mfma_f32_16x16x32_bf16 v[40:43], v[40:43], v[24:27], 0
	v_mfma_f32_16x16x32_bf16 v[36:39], v[36:39], v[24:27], 0
	v_mfma_f32_16x16x32_bf16 v[32:35], v[32:35], v[24:27], 0
	v_mfma_f32_16x16x32_bf16 v[22:25], v[28:31], v[24:27], 0
	s_waitcnt vmcnt(6) lgkmcnt(0)
	s_barrier
	v_add_u32_e32 v12, s60, v65
	ds_read_b128 v[26:29], v8 offset:49152
	ds_read_b128 v[122:125], v8 offset:51200
	ds_read_b128 v[126:129], v8 offset:53248
	ds_read_b128 v[130:133], v8 offset:55296
	ds_read_b128 v[134:137], v12
	ds_read_b128 v[138:141], v12 offset:2048
	ds_read_b128 v[142:145], v12 offset:4096
	ds_read_b128 v[146:149], v12 offset:6144
	v_mfma_f32_16x16x32_bf16 v[82:85], v[60:63], v[44:47], v[82:85]
	v_mfma_f32_16x16x32_bf16 v[86:89], v[70:73], v[44:47], v[86:89]
	v_mfma_f32_16x16x32_bf16 v[90:93], v[74:77], v[44:47], v[90:93]
	v_mfma_f32_16x16x32_bf16 v[44:47], v[78:81], v[44:47], v[94:97]
	v_mfma_f32_16x16x32_bf16 v[94:97], v[60:63], v[48:51], v[98:101]
	v_mfma_f32_16x16x32_bf16 v[98:101], v[70:73], v[48:51], v[102:105]
	v_mfma_f32_16x16x32_bf16 v[102:105], v[74:77], v[48:51], v[106:109]
	v_mfma_f32_16x16x32_bf16 v[14:17], v[78:81], v[48:51], v[14:17]
	v_mfma_f32_16x16x32_bf16 v[48:51], v[60:63], v[52:55], v[110:113]
	v_mfma_f32_16x16x32_bf16 v[18:21], v[78:81], v[52:55], v[18:21]
	v_mfma_f32_16x16x32_bf16 v[40:43], v[60:63], v[56:59], v[40:43]
	v_mfma_f32_16x16x32_bf16 v[36:39], v[70:73], v[56:59], v[36:39]
	v_mfma_f32_16x16x32_bf16 v[30:33], v[74:77], v[56:59], v[32:35]
	v_mfma_f32_16x16x32_bf16 v[22:25], v[78:81], v[56:59], v[22:25]
	v_mfma_f32_16x16x32_bf16 v[106:109], v[70:73], v[52:55], v[114:117]
	v_mfma_f32_16x16x32_bf16 v[110:113], v[74:77], v[52:55], v[118:121]
	s_mov_b32 m0, s62
	v_lshl_add_u64 v[34:35], v[4:5], 0, s[12:13]
	global_load_lds_dwordx4 v[34:35], off
	v_lshl_add_u64 v[34:35], v[6:7], 0, s[12:13]
	s_mov_b32 m0, s38
	s_mov_b64 s[76:77], 0x20180
	global_load_lds_dwordx4 v[34:35], off
	v_lshl_add_u64 v[34:35], v[2:3], 0, s[12:13]
	s_mov_b32 m0, s39
	v_add_u32_e32 v13, s60, v69
	global_load_lds_dwordx4 v[34:35], off
	v_lshl_add_u64 v[34:35], v[2:3], 0, s[76:77]
	s_mov_b32 m0, s33
	s_mov_b64 s[76:77], 0x40180
	global_load_lds_dwordx4 v[34:35], off
	v_lshl_add_u64 v[34:35], v[2:3], 0, s[76:77]
	s_mov_b32 m0, s6
	s_mov_b64 s[76:77], 0x60180
	global_load_lds_dwordx4 v[34:35], off
	v_lshl_add_u64 v[34:35], v[2:3], 0, s[76:77]
	s_mov_b32 m0, s5
	s_nop 0
	global_load_lds_dwordx4 v[34:35], off
	ds_read_b128 v[52:55], v10 offset:49152
	ds_read_b128 v[56:59], v10 offset:51200
	ds_read_b128 v[60:63], v10 offset:53248
	ds_read_b128 v[70:73], v10 offset:55296
	ds_read_b128 v[74:77], v13
	ds_read_b128 v[78:81], v13 offset:2048
	ds_read_b128 v[114:117], v13 offset:4096
	ds_read_b128 v[118:121], v13 offset:6144
	s_waitcnt lgkmcnt(8)
	v_mfma_f32_16x16x32_bf16 v[82:85], v[134:137], v[26:29], v[82:85]
	v_mfma_f32_16x16x32_bf16 v[86:89], v[138:141], v[26:29], v[86:89]
	v_mfma_f32_16x16x32_bf16 v[90:93], v[142:145], v[26:29], v[90:93]
	v_mfma_f32_16x16x32_bf16 v[26:29], v[146:149], v[26:29], v[44:47]
	v_mfma_f32_16x16x32_bf16 v[44:47], v[134:137], v[122:125], v[94:97]
	v_mfma_f32_16x16x32_bf16 v[94:97], v[138:141], v[122:125], v[98:101]
	v_mfma_f32_16x16x32_bf16 v[98:101], v[142:145], v[122:125], v[102:105]
	v_mfma_f32_16x16x32_bf16 v[102:105], v[146:149], v[122:125], v[14:17]
	v_mfma_f32_16x16x32_bf16 v[48:51], v[134:137], v[126:129], v[48:51]
	v_mfma_f32_16x16x32_bf16 v[16:19], v[146:149], v[126:129], v[18:21]
	v_mfma_f32_16x16x32_bf16 v[40:43], v[134:137], v[130:133], v[40:43]
	v_mfma_f32_16x16x32_bf16 v[34:37], v[138:141], v[130:133], v[36:39]
	v_mfma_f32_16x16x32_bf16 v[30:33], v[142:145], v[130:133], v[30:33]
	v_mfma_f32_16x16x32_bf16 v[20:23], v[146:149], v[130:133], v[22:25]
	v_mfma_f32_16x16x32_bf16 v[106:109], v[138:141], v[126:129], v[106:109]
	v_mfma_f32_16x16x32_bf16 v[110:113], v[142:145], v[126:129], v[110:113]
	s_add_i32 s75, 0, 0x18000
	s_waitcnt vmcnt(6) lgkmcnt(0)
	s_barrier
	v_add_u32_e32 v14, s75, v64
	v_add_u32_e32 v15, s75, v65
	ds_read_b128 v[122:125], v14
	ds_read_b128 v[126:129], v14 offset:2048
	ds_read_b128 v[130:133], v14 offset:4096
	ds_read_b128 v[134:137], v14 offset:6144
	ds_read_b128 v[138:141], v15
	ds_read_b128 v[142:145], v15 offset:2048
	ds_read_b128 v[146:149], v15 offset:4096
	ds_read_b128 v[150:153], v15 offset:6144
	v_mfma_f32_16x16x32_bf16 v[82:85], v[74:77], v[52:55], v[82:85]
	v_mfma_f32_16x16x32_bf16 v[86:89], v[78:81], v[52:55], v[86:89]
	v_mfma_f32_16x16x32_bf16 v[90:93], v[114:117], v[52:55], v[90:93]
	v_mfma_f32_16x16x32_bf16 v[24:27], v[118:121], v[52:55], v[26:29]
	v_mfma_f32_16x16x32_bf16 v[44:47], v[74:77], v[56:59], v[44:47]
	v_mfma_f32_16x16x32_bf16 v[52:55], v[78:81], v[56:59], v[94:97]
	v_mfma_f32_16x16x32_bf16 v[94:97], v[114:117], v[56:59], v[98:101]
	v_mfma_f32_16x16x32_bf16 v[56:59], v[118:121], v[56:59], v[102:105]
	v_mfma_f32_16x16x32_bf16 v[48:51], v[74:77], v[60:63], v[48:51]
	v_mfma_f32_16x16x32_bf16 v[98:101], v[78:81], v[60:63], v[106:109]
	v_mfma_f32_16x16x32_bf16 v[102:105], v[114:117], v[60:63], v[110:113]
	v_mfma_f32_16x16x32_bf16 v[60:63], v[118:121], v[60:63], v[16:19]
	v_mfma_f32_16x16x32_bf16 v[38:41], v[74:77], v[70:73], v[40:43]
	v_mfma_f32_16x16x32_bf16 v[34:37], v[78:81], v[70:73], v[34:37]
	v_mfma_f32_16x16x32_bf16 v[28:31], v[114:117], v[70:73], v[30:33]
	v_mfma_f32_16x16x32_bf16 v[18:21], v[118:121], v[70:73], v[20:23]
	s_mov_b32 m0, s64
	v_lshl_add_u64 v[16:17], v[4:5], 0, s[14:15]
	global_load_lds_dwordx4 v[16:17], off
	v_lshl_add_u64 v[16:17], v[6:7], 0, s[14:15]
	s_mov_b32 m0, s63
	s_mov_b64 s[76:77], 0x20200
	global_load_lds_dwordx4 v[16:17], off
	v_lshl_add_u64 v[16:17], v[2:3], 0, s[14:15]
	s_mov_b32 m0, s65
	s_nop 0
	global_load_lds_dwordx4 v[16:17], off
	v_lshl_add_u64 v[16:17], v[2:3], 0, s[76:77]
	s_mov_b32 m0, s66
	s_mov_b64 s[76:77], 0x40200
	global_load_lds_dwordx4 v[16:17], off
	v_lshl_add_u64 v[16:17], v[2:3], 0, s[76:77]
	s_mov_b32 m0, s67
	s_mov_b64 s[76:77], 0x60200
	global_load_lds_dwordx4 v[16:17], off
	v_lshl_add_u64 v[16:17], v[2:3], 0, s[76:77]
	s_mov_b32 m0, s68
	s_nop 0
	global_load_lds_dwordx4 v[16:17], off
	v_add_u32_e32 v16, s75, v66
	v_add_u32_e32 v17, s75, v69
	ds_read_b128 v[70:73], v16
	ds_read_b128 v[74:77], v16 offset:2048
	ds_read_b128 v[78:81], v16 offset:4096
	ds_read_b128 v[106:109], v16 offset:6144
	ds_read_b128 v[110:113], v17
	ds_read_b128 v[114:117], v17 offset:2048
	ds_read_b128 v[118:121], v17 offset:4096
	ds_read_b128 v[154:157], v17 offset:6144
	s_waitcnt lgkmcnt(8)
	v_mfma_f32_16x16x32_bf16 v[22:25], v[150:153], v[122:125], v[24:27]
	v_mfma_f32_16x16x32_bf16 v[42:45], v[138:141], v[126:129], v[44:47]
	v_mfma_f32_16x16x32_bf16 v[52:55], v[142:145], v[126:129], v[52:55]
	v_mfma_f32_16x16x32_bf16 v[56:59], v[150:153], v[126:129], v[56:59]
	v_mfma_f32_16x16x32_bf16 v[46:49], v[138:141], v[130:133], v[48:51]
	v_mfma_f32_16x16x32_bf16 v[60:63], v[150:153], v[130:133], v[60:63]
	v_mfma_f32_16x16x32_bf16 v[38:41], v[138:141], v[134:137], v[38:41]
	v_mfma_f32_16x16x32_bf16 v[32:35], v[142:145], v[134:137], v[34:37]
	v_mfma_f32_16x16x32_bf16 v[26:29], v[146:149], v[134:137], v[28:31]
	v_mfma_f32_16x16x32_bf16 v[18:21], v[150:153], v[134:137], v[18:21]
	v_mfma_f32_16x16x32_bf16 v[82:85], v[138:141], v[122:125], v[82:85]
	v_mfma_f32_16x16x32_bf16 v[86:89], v[142:145], v[122:125], v[86:89]
	v_mfma_f32_16x16x32_bf16 v[90:93], v[146:149], v[122:125], v[90:93]
	v_mfma_f32_16x16x32_bf16 v[94:97], v[146:149], v[126:129], v[94:97]
	v_mfma_f32_16x16x32_bf16 v[98:101], v[142:145], v[130:133], v[98:101]
	v_mfma_f32_16x16x32_bf16 v[102:105], v[146:149], v[130:133], v[102:105]
	s_waitcnt vmcnt(6) lgkmcnt(0)
	s_barrier
	ds_read_b128 v[122:125], v8
	ds_read_b128 v[126:129], v8 offset:2048
	ds_read_b128 v[130:133], v8 offset:4096
	ds_read_b128 v[134:137], v8 offset:6144
	ds_read_b128 v[138:141], v9 offset:16384
	ds_read_b128 v[142:145], v9 offset:18432
	ds_read_b128 v[146:149], v9 offset:20480
	ds_read_b128 v[150:153], v9 offset:22528
	v_mfma_f32_16x16x32_bf16 v[82:85], v[110:113], v[70:73], v[82:85]
	v_mfma_f32_16x16x32_bf16 v[86:89], v[114:117], v[70:73], v[86:89]
	v_mfma_f32_16x16x32_bf16 v[90:93], v[118:121], v[70:73], v[90:93]
	v_mfma_f32_16x16x32_bf16 v[22:25], v[154:157], v[70:73], v[22:25]
	v_mfma_f32_16x16x32_bf16 v[42:45], v[110:113], v[74:77], v[42:45]
	v_mfma_f32_16x16x32_bf16 v[50:53], v[114:117], v[74:77], v[52:55]
	v_mfma_f32_16x16x32_bf16 v[70:73], v[118:121], v[74:77], v[94:97]
	v_mfma_f32_16x16x32_bf16 v[54:57], v[154:157], v[74:77], v[56:59]
	v_mfma_f32_16x16x32_bf16 v[46:49], v[110:113], v[78:81], v[46:49]
	v_mfma_f32_16x16x32_bf16 v[74:77], v[114:117], v[78:81], v[98:101]
	v_mfma_f32_16x16x32_bf16 v[58:61], v[154:157], v[78:81], v[60:63]
	v_mfma_f32_16x16x32_bf16 v[36:39], v[110:113], v[106:109], v[38:41]
	v_mfma_f32_16x16x32_bf16 v[30:33], v[114:117], v[106:109], v[32:35]
	v_mfma_f32_16x16x32_bf16 v[26:29], v[118:121], v[106:109], v[26:29]
	v_mfma_f32_16x16x32_bf16 v[18:21], v[154:157], v[106:109], v[18:21]
	v_mfma_f32_16x16x32_bf16 v[94:97], v[118:121], v[78:81], v[102:105]
	s_mov_b32 m0, s69
	v_lshl_add_u64 v[34:35], v[4:5], 0, s[16:17]
	global_load_lds_dwordx4 v[34:35], off
	v_lshl_add_u64 v[34:35], v[6:7], 0, s[16:17]
	s_mov_b32 m0, s70
	s_mov_b64 s[76:77], 0x20280
	global_load_lds_dwordx4 v[34:35], off
	v_lshl_add_u64 v[34:35], v[2:3], 0, s[16:17]
	s_mov_b32 m0, s71
	s_nop 0
	global_load_lds_dwordx4 v[34:35], off
	v_lshl_add_u64 v[34:35], v[2:3], 0, s[76:77]
	s_mov_b32 m0, s72
	s_mov_b64 s[76:77], 0x40280
	global_load_lds_dwordx4 v[34:35], off
	v_lshl_add_u64 v[34:35], v[2:3], 0, s[76:77]
	s_mov_b32 m0, s73
	s_mov_b64 s[76:77], 0x60280
	global_load_lds_dwordx4 v[34:35], off
	v_lshl_add_u64 v[34:35], v[2:3], 0, s[76:77]
	s_mov_b32 m0, s74
	s_nop 0
	global_load_lds_dwordx4 v[34:35], off
	ds_read_b128 v[62:65], v10
	ds_read_b128 v[78:81], v10 offset:2048
	ds_read_b128 v[98:101], v10 offset:4096
	ds_read_b128 v[102:105], v10 offset:6144
	ds_read_b128 v[106:109], v11 offset:16384
	ds_read_b128 v[110:113], v11 offset:18432
	ds_read_b128 v[114:117], v11 offset:20480
	ds_read_b128 v[118:121], v11 offset:22528
	s_waitcnt lgkmcnt(8)
	v_mfma_f32_16x16x32_bf16 v[22:25], v[150:153], v[122:125], v[22:25]
	v_mfma_f32_16x16x32_bf16 v[40:43], v[138:141], v[126:129], v[42:45]
	v_mfma_f32_16x16x32_bf16 v[50:53], v[142:145], v[126:129], v[50:53]
	v_mfma_f32_16x16x32_bf16 v[70:73], v[146:149], v[126:129], v[70:73]
	v_mfma_f32_16x16x32_bf16 v[54:57], v[150:153], v[126:129], v[54:57]
	v_mfma_f32_16x16x32_bf16 v[44:47], v[138:141], v[130:133], v[46:49]
	v_mfma_f32_16x16x32_bf16 v[74:77], v[142:145], v[130:133], v[74:77]
	v_mfma_f32_16x16x32_bf16 v[58:61], v[150:153], v[130:133], v[58:61]
	v_mfma_f32_16x16x32_bf16 v[34:37], v[138:141], v[134:137], v[36:39]
	v_mfma_f32_16x16x32_bf16 v[30:33], v[142:145], v[134:137], v[30:33]
	v_mfma_f32_16x16x32_bf16 v[26:29], v[146:149], v[134:137], v[26:29]
	v_mfma_f32_16x16x32_bf16 v[18:21], v[150:153], v[134:137], v[18:21]
	v_mfma_f32_16x16x32_bf16 v[82:85], v[138:141], v[122:125], v[82:85]
	v_mfma_f32_16x16x32_bf16 v[86:89], v[142:145], v[122:125], v[86:89]
	v_mfma_f32_16x16x32_bf16 v[90:93], v[146:149], v[122:125], v[90:93]
	v_mfma_f32_16x16x32_bf16 v[94:97], v[146:149], v[130:133], v[94:97]
	s_waitcnt vmcnt(6) lgkmcnt(0)
	s_barrier
	ds_read_b128 v[122:125], v8 offset:49152
	ds_read_b128 v[126:129], v8 offset:51200
	ds_read_b128 v[130:133], v8 offset:53248
	ds_read_b128 v[134:137], v8 offset:55296
	ds_read_b128 v[138:141], v12
	ds_read_b128 v[142:145], v12 offset:2048
	ds_read_b128 v[146:149], v12 offset:4096
	ds_read_b128 v[150:153], v12 offset:6144
	v_mfma_f32_16x16x32_bf16 v[82:85], v[106:109], v[62:65], v[82:85]
	v_mfma_f32_16x16x32_bf16 v[86:89], v[110:113], v[62:65], v[86:89]
	v_mfma_f32_16x16x32_bf16 v[90:93], v[114:117], v[62:65], v[90:93]
	v_mfma_f32_16x16x32_bf16 v[22:25], v[118:121], v[62:65], v[22:25]
	v_mfma_f32_16x16x32_bf16 v[38:41], v[106:109], v[78:81], v[40:43]
	v_mfma_f32_16x16x32_bf16 v[48:51], v[110:113], v[78:81], v[50:53]
	v_mfma_f32_16x16x32_bf16 v[62:65], v[114:117], v[78:81], v[70:73]
	v_mfma_f32_16x16x32_bf16 v[52:55], v[118:121], v[78:81], v[54:57]
	v_mfma_f32_16x16x32_bf16 v[42:45], v[106:109], v[98:101], v[44:47]
	v_mfma_f32_16x16x32_bf16 v[70:73], v[110:113], v[98:101], v[74:77]
	v_mfma_f32_16x16x32_bf16 v[74:77], v[114:117], v[98:101], v[94:97]
	v_mfma_f32_16x16x32_bf16 v[56:59], v[118:121], v[98:101], v[58:61]
	v_mfma_f32_16x16x32_bf16 v[34:37], v[106:109], v[102:105], v[34:37]
	v_mfma_f32_16x16x32_bf16 v[30:33], v[110:113], v[102:105], v[30:33]
	v_mfma_f32_16x16x32_bf16 v[26:29], v[114:117], v[102:105], v[26:29]
	v_mfma_f32_16x16x32_bf16 v[18:21], v[118:121], v[102:105], v[18:21]
	s_mov_b32 m0, s62
	v_lshl_add_u64 v[46:47], v[4:5], 0, s[18:19]
	global_load_lds_dwordx4 v[46:47], off
	v_lshl_add_u64 v[46:47], v[6:7], 0, s[18:19]
	s_mov_b32 m0, s38
	s_mov_b64 s[76:77], 0x20300
	global_load_lds_dwordx4 v[46:47], off
	v_lshl_add_u64 v[46:47], v[2:3], 0, s[18:19]
	s_mov_b32 m0, s39
	s_nop 0
	global_load_lds_dwordx4 v[46:47], off
	v_lshl_add_u64 v[46:47], v[2:3], 0, s[76:77]
	s_mov_b32 m0, s33
	s_mov_b64 s[76:77], 0x40300
	global_load_lds_dwordx4 v[46:47], off
	v_lshl_add_u64 v[46:47], v[2:3], 0, s[76:77]
	s_mov_b32 m0, s6
	s_mov_b64 s[76:77], 0x60300
	global_load_lds_dwordx4 v[46:47], off
	v_lshl_add_u64 v[46:47], v[2:3], 0, s[76:77]
	s_mov_b32 m0, s5
	s_nop 0
	global_load_lds_dwordx4 v[46:47], off
	ds_read_b128 v[78:81], v10 offset:49152
	ds_read_b128 v[94:97], v10 offset:51200
	ds_read_b128 v[98:101], v10 offset:53248
	ds_read_b128 v[102:105], v10 offset:55296
	ds_read_b128 v[106:109], v13
	ds_read_b128 v[110:113], v13 offset:2048
	ds_read_b128 v[114:117], v13 offset:4096
	ds_read_b128 v[118:121], v13 offset:6144
	s_waitcnt lgkmcnt(8)
	v_mfma_f32_16x16x32_bf16 v[22:25], v[150:153], v[122:125], v[22:25]
	v_mfma_f32_16x16x32_bf16 v[38:41], v[138:141], v[126:129], v[38:41]
	v_mfma_f32_16x16x32_bf16 v[46:49], v[142:145], v[126:129], v[48:51]
	v_mfma_f32_16x16x32_bf16 v[60:63], v[146:149], v[126:129], v[62:65]
	v_mfma_f32_16x16x32_bf16 v[50:53], v[150:153], v[126:129], v[52:55]
	v_mfma_f32_16x16x32_bf16 v[42:45], v[138:141], v[130:133], v[42:45]
	v_mfma_f32_16x16x32_bf16 v[70:73], v[142:145], v[130:133], v[70:73]
	v_mfma_f32_16x16x32_bf16 v[74:77], v[146:149], v[130:133], v[74:77]
	v_mfma_f32_16x16x32_bf16 v[54:57], v[150:153], v[130:133], v[56:59]
	v_mfma_f32_16x16x32_bf16 v[34:37], v[138:141], v[134:137], v[34:37]
	v_mfma_f32_16x16x32_bf16 v[30:33], v[142:145], v[134:137], v[30:33]
	v_mfma_f32_16x16x32_bf16 v[26:29], v[146:149], v[134:137], v[26:29]
	v_mfma_f32_16x16x32_bf16 v[18:21], v[150:153], v[134:137], v[18:21]
	v_mfma_f32_16x16x32_bf16 v[82:85], v[138:141], v[122:125], v[82:85]
	v_mfma_f32_16x16x32_bf16 v[86:89], v[142:145], v[122:125], v[86:89]
	v_mfma_f32_16x16x32_bf16 v[90:93], v[146:149], v[122:125], v[90:93]
	s_waitcnt vmcnt(6) lgkmcnt(0)
	s_barrier
	ds_read_b128 v[122:125], v14
	ds_read_b128 v[126:129], v14 offset:2048
	ds_read_b128 v[130:133], v14 offset:4096
	ds_read_b128 v[134:137], v14 offset:6144
	ds_read_b128 v[138:141], v15
	ds_read_b128 v[142:145], v15 offset:2048
	ds_read_b128 v[146:149], v15 offset:4096
	ds_read_b128 v[150:153], v15 offset:6144
	v_mfma_f32_16x16x32_bf16 v[22:25], v[118:121], v[78:81], v[22:25]
	v_mfma_f32_16x16x32_bf16 v[38:41], v[106:109], v[94:97], v[38:41]
	v_mfma_f32_16x16x32_bf16 v[46:49], v[110:113], v[94:97], v[46:49]
	v_mfma_f32_16x16x32_bf16 v[58:61], v[114:117], v[94:97], v[60:63]
	v_mfma_f32_16x16x32_bf16 v[50:53], v[118:121], v[94:97], v[50:53]
	v_mfma_f32_16x16x32_bf16 v[42:45], v[106:109], v[98:101], v[42:45]
	v_mfma_f32_16x16x32_bf16 v[62:65], v[110:113], v[98:101], v[70:73]
	v_mfma_f32_16x16x32_bf16 v[70:73], v[114:117], v[98:101], v[74:77]
	v_mfma_f32_16x16x32_bf16 v[54:57], v[118:121], v[98:101], v[54:57]
	v_mfma_f32_16x16x32_bf16 v[34:37], v[106:109], v[102:105], v[34:37]
	v_mfma_f32_16x16x32_bf16 v[30:33], v[110:113], v[102:105], v[30:33]
	v_mfma_f32_16x16x32_bf16 v[26:29], v[114:117], v[102:105], v[26:29]
	v_mfma_f32_16x16x32_bf16 v[18:21], v[118:121], v[102:105], v[18:21]
	v_mfma_f32_16x16x32_bf16 v[82:85], v[106:109], v[78:81], v[82:85]
	v_mfma_f32_16x16x32_bf16 v[86:89], v[110:113], v[78:81], v[86:89]
	v_mfma_f32_16x16x32_bf16 v[90:93], v[114:117], v[78:81], v[90:93]
	s_mov_b32 m0, s64
	v_lshl_add_u64 v[74:75], v[4:5], 0, s[20:21]
	global_load_lds_dwordx4 v[74:75], off
	v_lshl_add_u64 v[74:75], v[6:7], 0, s[20:21]
	s_mov_b32 m0, s63
	s_mov_b64 s[76:77], 0x20380
	global_load_lds_dwordx4 v[74:75], off
	v_lshl_add_u64 v[74:75], v[2:3], 0, s[20:21]
	s_mov_b32 m0, s65
	s_nop 0
	global_load_lds_dwordx4 v[74:75], off
	v_lshl_add_u64 v[74:75], v[2:3], 0, s[76:77]
	s_mov_b32 m0, s66
	s_mov_b64 s[76:77], 0x40380
	global_load_lds_dwordx4 v[74:75], off
	v_lshl_add_u64 v[74:75], v[2:3], 0, s[76:77]
	s_mov_b32 m0, s67
	s_mov_b64 s[76:77], 0x60380
	global_load_lds_dwordx4 v[74:75], off
	v_lshl_add_u64 v[74:75], v[2:3], 0, s[76:77]
	s_mov_b32 m0, s68
	s_nop 0
	global_load_lds_dwordx4 v[74:75], off
	ds_read_b128 v[74:77], v16
	ds_read_b128 v[78:81], v16 offset:2048
	ds_read_b128 v[94:97], v16 offset:4096
	ds_read_b128 v[98:101], v16 offset:6144
	ds_read_b128 v[102:105], v17
	ds_read_b128 v[106:109], v17 offset:2048
	ds_read_b128 v[110:113], v17 offset:4096
	ds_read_b128 v[114:117], v17 offset:6144
	s_waitcnt lgkmcnt(8)
	v_mfma_f32_16x16x32_bf16 v[22:25], v[150:153], v[122:125], v[22:25]
	v_mfma_f32_16x16x32_bf16 v[38:41], v[138:141], v[126:129], v[38:41]
	v_mfma_f32_16x16x32_bf16 v[46:49], v[142:145], v[126:129], v[46:49]
	v_mfma_f32_16x16x32_bf16 v[58:61], v[146:149], v[126:129], v[58:61]
	v_mfma_f32_16x16x32_bf16 v[50:53], v[150:153], v[126:129], v[50:53]
	v_mfma_f32_16x16x32_bf16 v[42:45], v[138:141], v[130:133], v[42:45]
	v_mfma_f32_16x16x32_bf16 v[62:65], v[142:145], v[130:133], v[62:65]
	v_mfma_f32_16x16x32_bf16 v[70:73], v[146:149], v[130:133], v[70:73]
	v_mfma_f32_16x16x32_bf16 v[54:57], v[150:153], v[130:133], v[54:57]
	v_mfma_f32_16x16x32_bf16 v[34:37], v[138:141], v[134:137], v[34:37]
	v_mfma_f32_16x16x32_bf16 v[30:33], v[142:145], v[134:137], v[30:33]
	v_mfma_f32_16x16x32_bf16 v[26:29], v[146:149], v[134:137], v[26:29]
	v_mfma_f32_16x16x32_bf16 v[18:21], v[150:153], v[134:137], v[18:21]
	v_mfma_f32_16x16x32_bf16 v[82:85], v[138:141], v[122:125], v[82:85]
	v_mfma_f32_16x16x32_bf16 v[86:89], v[142:145], v[122:125], v[86:89]
	v_mfma_f32_16x16x32_bf16 v[90:93], v[146:149], v[122:125], v[90:93]
	s_waitcnt vmcnt(6) lgkmcnt(0)
	s_barrier
	ds_read_b128 v[118:121], v8
	ds_read_b128 v[122:125], v8 offset:2048
	ds_read_b128 v[126:129], v8 offset:4096
	ds_read_b128 v[130:133], v8 offset:6144
	ds_read_b128 v[134:137], v9 offset:16384
	ds_read_b128 v[138:141], v9 offset:18432
	ds_read_b128 v[142:145], v9 offset:20480
	ds_read_b128 v[146:149], v9 offset:22528
	v_mfma_f32_16x16x32_bf16 v[22:25], v[114:117], v[74:77], v[22:25]
	v_mfma_f32_16x16x32_bf16 v[38:41], v[102:105], v[78:81], v[38:41]
	v_mfma_f32_16x16x32_bf16 v[46:49], v[106:109], v[78:81], v[46:49]
	v_mfma_f32_16x16x32_bf16 v[58:61], v[110:113], v[78:81], v[58:61]
	v_mfma_f32_16x16x32_bf16 v[50:53], v[114:117], v[78:81], v[50:53]
	v_mfma_f32_16x16x32_bf16 v[42:45], v[102:105], v[94:97], v[42:45]
	v_mfma_f32_16x16x32_bf16 v[62:65], v[106:109], v[94:97], v[62:65]
	v_mfma_f32_16x16x32_bf16 v[70:73], v[110:113], v[94:97], v[70:73]
	v_mfma_f32_16x16x32_bf16 v[54:57], v[114:117], v[94:97], v[54:57]
	v_mfma_f32_16x16x32_bf16 v[34:37], v[102:105], v[98:101], v[34:37]
	v_mfma_f32_16x16x32_bf16 v[30:33], v[106:109], v[98:101], v[30:33]
	v_mfma_f32_16x16x32_bf16 v[26:29], v[110:113], v[98:101], v[26:29]
	v_mfma_f32_16x16x32_bf16 v[18:21], v[114:117], v[98:101], v[18:21]
	v_mfma_f32_16x16x32_bf16 v[82:85], v[102:105], v[74:77], v[82:85]
	v_mfma_f32_16x16x32_bf16 v[86:89], v[106:109], v[74:77], v[86:89]
	v_mfma_f32_16x16x32_bf16 v[90:93], v[110:113], v[74:77], v[90:93]
	s_mov_b32 m0, s69
	v_lshl_add_u64 v[74:75], v[4:5], 0, s[22:23]
	global_load_lds_dwordx4 v[74:75], off
	v_lshl_add_u64 v[74:75], v[6:7], 0, s[22:23]
	s_mov_b32 m0, s70
	s_mov_b64 s[76:77], 0x20400
	global_load_lds_dwordx4 v[74:75], off
	v_lshl_add_u64 v[74:75], v[2:3], 0, s[22:23]
	s_mov_b32 m0, s71
	s_nop 0
	global_load_lds_dwordx4 v[74:75], off
	v_lshl_add_u64 v[74:75], v[2:3], 0, s[76:77]
	s_mov_b32 m0, s72
	s_mov_b64 s[76:77], 0x40400
	global_load_lds_dwordx4 v[74:75], off
	v_lshl_add_u64 v[74:75], v[2:3], 0, s[76:77]
	s_mov_b32 m0, s73
	s_mov_b64 s[76:77], 0x60400
	global_load_lds_dwordx4 v[74:75], off
	v_lshl_add_u64 v[74:75], v[2:3], 0, s[76:77]
	s_mov_b32 m0, s74
	s_nop 0
	global_load_lds_dwordx4 v[74:75], off
	ds_read_b128 v[74:77], v10
	ds_read_b128 v[78:81], v10 offset:2048
	ds_read_b128 v[94:97], v10 offset:4096
	ds_read_b128 v[98:101], v10 offset:6144
	ds_read_b128 v[102:105], v11 offset:16384
	ds_read_b128 v[106:109], v11 offset:18432
	ds_read_b128 v[110:113], v11 offset:20480
	ds_read_b128 v[114:117], v11 offset:22528
	s_waitcnt lgkmcnt(8)
	v_mfma_f32_16x16x32_bf16 v[22:25], v[146:149], v[118:121], v[22:25]
	v_mfma_f32_16x16x32_bf16 v[38:41], v[134:137], v[122:125], v[38:41]
	v_mfma_f32_16x16x32_bf16 v[46:49], v[138:141], v[122:125], v[46:49]
	v_mfma_f32_16x16x32_bf16 v[58:61], v[142:145], v[122:125], v[58:61]
	v_mfma_f32_16x16x32_bf16 v[50:53], v[146:149], v[122:125], v[50:53]
	v_mfma_f32_16x16x32_bf16 v[42:45], v[134:137], v[126:129], v[42:45]
	v_mfma_f32_16x16x32_bf16 v[62:65], v[138:141], v[126:129], v[62:65]
	v_mfma_f32_16x16x32_bf16 v[70:73], v[142:145], v[126:129], v[70:73]
	v_mfma_f32_16x16x32_bf16 v[54:57], v[146:149], v[126:129], v[54:57]
	v_mfma_f32_16x16x32_bf16 v[34:37], v[134:137], v[130:133], v[34:37]
	v_mfma_f32_16x16x32_bf16 v[30:33], v[138:141], v[130:133], v[30:33]
	v_mfma_f32_16x16x32_bf16 v[26:29], v[142:145], v[130:133], v[26:29]
	v_mfma_f32_16x16x32_bf16 v[18:21], v[146:149], v[130:133], v[18:21]
	v_mfma_f32_16x16x32_bf16 v[82:85], v[134:137], v[118:121], v[82:85]
	v_mfma_f32_16x16x32_bf16 v[86:89], v[138:141], v[118:121], v[86:89]
	v_mfma_f32_16x16x32_bf16 v[90:93], v[142:145], v[118:121], v[90:93]
	s_waitcnt vmcnt(6) lgkmcnt(0)
	s_barrier
	ds_read_b128 v[118:121], v8 offset:49152
	ds_read_b128 v[122:125], v8 offset:51200
	ds_read_b128 v[126:129], v8 offset:53248
	ds_read_b128 v[130:133], v8 offset:55296
	ds_read_b128 v[134:137], v12
	ds_read_b128 v[138:141], v12 offset:2048
	ds_read_b128 v[142:145], v12 offset:4096
	ds_read_b128 v[146:149], v12 offset:6144
	v_mfma_f32_16x16x32_bf16 v[22:25], v[114:117], v[74:77], v[22:25]
	v_mfma_f32_16x16x32_bf16 v[38:41], v[102:105], v[78:81], v[38:41]
	v_mfma_f32_16x16x32_bf16 v[46:49], v[106:109], v[78:81], v[46:49]
	v_mfma_f32_16x16x32_bf16 v[58:61], v[110:113], v[78:81], v[58:61]
	v_mfma_f32_16x16x32_bf16 v[50:53], v[114:117], v[78:81], v[50:53]
	v_mfma_f32_16x16x32_bf16 v[42:45], v[102:105], v[94:97], v[42:45]
	v_mfma_f32_16x16x32_bf16 v[62:65], v[106:109], v[94:97], v[62:65]
	v_mfma_f32_16x16x32_bf16 v[70:73], v[110:113], v[94:97], v[70:73]
	v_mfma_f32_16x16x32_bf16 v[54:57], v[114:117], v[94:97], v[54:57]
	v_mfma_f32_16x16x32_bf16 v[34:37], v[102:105], v[98:101], v[34:37]
	v_mfma_f32_16x16x32_bf16 v[30:33], v[106:109], v[98:101], v[30:33]
	v_mfma_f32_16x16x32_bf16 v[26:29], v[110:113], v[98:101], v[26:29]
	v_mfma_f32_16x16x32_bf16 v[18:21], v[114:117], v[98:101], v[18:21]
	v_mfma_f32_16x16x32_bf16 v[82:85], v[102:105], v[74:77], v[82:85]
	v_mfma_f32_16x16x32_bf16 v[86:89], v[106:109], v[74:77], v[86:89]
	v_mfma_f32_16x16x32_bf16 v[90:93], v[110:113], v[74:77], v[90:93]
	s_mov_b32 m0, s62
	v_lshl_add_u64 v[74:75], v[4:5], 0, s[24:25]
	global_load_lds_dwordx4 v[74:75], off
	v_lshl_add_u64 v[74:75], v[6:7], 0, s[24:25]
	s_mov_b32 m0, s38
	s_mov_b64 s[76:77], 0x20480
	global_load_lds_dwordx4 v[74:75], off
	v_lshl_add_u64 v[74:75], v[2:3], 0, s[24:25]
	s_mov_b32 m0, s39
	s_nop 0
	global_load_lds_dwordx4 v[74:75], off
	v_lshl_add_u64 v[74:75], v[2:3], 0, s[76:77]
	s_mov_b32 m0, s33
	s_mov_b64 s[76:77], 0x40480
	global_load_lds_dwordx4 v[74:75], off
	v_lshl_add_u64 v[74:75], v[2:3], 0, s[76:77]
	s_mov_b32 m0, s6
	s_mov_b64 s[76:77], 0x60480
	global_load_lds_dwordx4 v[74:75], off
	v_lshl_add_u64 v[74:75], v[2:3], 0, s[76:77]
	s_mov_b32 m0, s5
	s_nop 0
	global_load_lds_dwordx4 v[74:75], off
	ds_read_b128 v[74:77], v10 offset:49152
	ds_read_b128 v[78:81], v10 offset:51200
	ds_read_b128 v[94:97], v10 offset:53248
	ds_read_b128 v[98:101], v10 offset:55296
	ds_read_b128 v[102:105], v13
	ds_read_b128 v[106:109], v13 offset:2048
	ds_read_b128 v[110:113], v13 offset:4096
	ds_read_b128 v[114:117], v13 offset:6144
	s_waitcnt lgkmcnt(8)
	v_mfma_f32_16x16x32_bf16 v[22:25], v[146:149], v[118:121], v[22:25]
	v_mfma_f32_16x16x32_bf16 v[38:41], v[134:137], v[122:125], v[38:41]
	v_mfma_f32_16x16x32_bf16 v[46:49], v[138:141], v[122:125], v[46:49]
	v_mfma_f32_16x16x32_bf16 v[58:61], v[142:145], v[122:125], v[58:61]
	v_mfma_f32_16x16x32_bf16 v[50:53], v[146:149], v[122:125], v[50:53]
	v_mfma_f32_16x16x32_bf16 v[42:45], v[134:137], v[126:129], v[42:45]
	v_mfma_f32_16x16x32_bf16 v[62:65], v[138:141], v[126:129], v[62:65]
	v_mfma_f32_16x16x32_bf16 v[70:73], v[142:145], v[126:129], v[70:73]
	v_mfma_f32_16x16x32_bf16 v[54:57], v[146:149], v[126:129], v[54:57]
	v_mfma_f32_16x16x32_bf16 v[34:37], v[134:137], v[130:133], v[34:37]
	v_mfma_f32_16x16x32_bf16 v[30:33], v[138:141], v[130:133], v[30:33]
	v_mfma_f32_16x16x32_bf16 v[26:29], v[142:145], v[130:133], v[26:29]
	v_mfma_f32_16x16x32_bf16 v[18:21], v[146:149], v[130:133], v[18:21]
	v_mfma_f32_16x16x32_bf16 v[82:85], v[134:137], v[118:121], v[82:85]
	v_mfma_f32_16x16x32_bf16 v[86:89], v[138:141], v[118:121], v[86:89]
	v_mfma_f32_16x16x32_bf16 v[90:93], v[142:145], v[118:121], v[90:93]
	s_waitcnt vmcnt(6) lgkmcnt(0)
	s_barrier
	ds_read_b128 v[118:121], v14
	ds_read_b128 v[122:125], v14 offset:2048
	ds_read_b128 v[126:129], v14 offset:4096
	ds_read_b128 v[130:133], v14 offset:6144
	ds_read_b128 v[134:137], v15
	ds_read_b128 v[138:141], v15 offset:2048
	ds_read_b128 v[142:145], v15 offset:4096
	ds_read_b128 v[146:149], v15 offset:6144
	v_mfma_f32_16x16x32_bf16 v[22:25], v[114:117], v[74:77], v[22:25]
	v_mfma_f32_16x16x32_bf16 v[38:41], v[102:105], v[78:81], v[38:41]
	v_mfma_f32_16x16x32_bf16 v[46:49], v[106:109], v[78:81], v[46:49]
	v_mfma_f32_16x16x32_bf16 v[58:61], v[110:113], v[78:81], v[58:61]
	v_mfma_f32_16x16x32_bf16 v[50:53], v[114:117], v[78:81], v[50:53]
	v_mfma_f32_16x16x32_bf16 v[42:45], v[102:105], v[94:97], v[42:45]
	v_mfma_f32_16x16x32_bf16 v[62:65], v[106:109], v[94:97], v[62:65]
	v_mfma_f32_16x16x32_bf16 v[70:73], v[110:113], v[94:97], v[70:73]
	v_mfma_f32_16x16x32_bf16 v[54:57], v[114:117], v[94:97], v[54:57]
	v_mfma_f32_16x16x32_bf16 v[34:37], v[102:105], v[98:101], v[34:37]
	v_mfma_f32_16x16x32_bf16 v[30:33], v[106:109], v[98:101], v[30:33]
	v_mfma_f32_16x16x32_bf16 v[26:29], v[110:113], v[98:101], v[26:29]
	v_mfma_f32_16x16x32_bf16 v[18:21], v[114:117], v[98:101], v[18:21]
	v_mfma_f32_16x16x32_bf16 v[82:85], v[102:105], v[74:77], v[82:85]
	v_mfma_f32_16x16x32_bf16 v[86:89], v[106:109], v[74:77], v[86:89]
	v_mfma_f32_16x16x32_bf16 v[90:93], v[110:113], v[74:77], v[90:93]
	s_mov_b32 m0, s64
	v_lshl_add_u64 v[74:75], v[4:5], 0, s[26:27]
	global_load_lds_dwordx4 v[74:75], off
	v_lshl_add_u64 v[74:75], v[6:7], 0, s[26:27]
	s_mov_b32 m0, s63
	s_mov_b64 s[76:77], 0x20500
	global_load_lds_dwordx4 v[74:75], off
	v_lshl_add_u64 v[74:75], v[2:3], 0, s[26:27]
	s_mov_b32 m0, s65
	s_nop 0
	global_load_lds_dwordx4 v[74:75], off
	v_lshl_add_u64 v[74:75], v[2:3], 0, s[76:77]
	s_mov_b32 m0, s66
	s_mov_b64 s[76:77], 0x40500
	global_load_lds_dwordx4 v[74:75], off
	v_lshl_add_u64 v[74:75], v[2:3], 0, s[76:77]
	s_mov_b32 m0, s67
	s_mov_b64 s[76:77], 0x60500
	global_load_lds_dwordx4 v[74:75], off
	v_lshl_add_u64 v[74:75], v[2:3], 0, s[76:77]
	s_mov_b32 m0, s68
	s_nop 0
	global_load_lds_dwordx4 v[74:75], off
	ds_read_b128 v[74:77], v16
	ds_read_b128 v[78:81], v16 offset:2048
	ds_read_b128 v[94:97], v16 offset:4096
	ds_read_b128 v[98:101], v16 offset:6144
	ds_read_b128 v[102:105], v17
	ds_read_b128 v[106:109], v17 offset:2048
	ds_read_b128 v[110:113], v17 offset:4096
	ds_read_b128 v[114:117], v17 offset:6144
	s_waitcnt lgkmcnt(8)
	v_mfma_f32_16x16x32_bf16 v[22:25], v[146:149], v[118:121], v[22:25]
	v_mfma_f32_16x16x32_bf16 v[38:41], v[134:137], v[122:125], v[38:41]
	v_mfma_f32_16x16x32_bf16 v[46:49], v[138:141], v[122:125], v[46:49]
	v_mfma_f32_16x16x32_bf16 v[58:61], v[142:145], v[122:125], v[58:61]
	v_mfma_f32_16x16x32_bf16 v[50:53], v[146:149], v[122:125], v[50:53]
	v_mfma_f32_16x16x32_bf16 v[42:45], v[134:137], v[126:129], v[42:45]
	v_mfma_f32_16x16x32_bf16 v[62:65], v[138:141], v[126:129], v[62:65]
	v_mfma_f32_16x16x32_bf16 v[70:73], v[142:145], v[126:129], v[70:73]
	v_mfma_f32_16x16x32_bf16 v[54:57], v[146:149], v[126:129], v[54:57]
	v_mfma_f32_16x16x32_bf16 v[34:37], v[134:137], v[130:133], v[34:37]
	v_mfma_f32_16x16x32_bf16 v[30:33], v[138:141], v[130:133], v[30:33]
	v_mfma_f32_16x16x32_bf16 v[26:29], v[142:145], v[130:133], v[26:29]
	v_mfma_f32_16x16x32_bf16 v[18:21], v[146:149], v[130:133], v[18:21]
	v_mfma_f32_16x16x32_bf16 v[82:85], v[134:137], v[118:121], v[82:85]
	v_mfma_f32_16x16x32_bf16 v[86:89], v[138:141], v[118:121], v[86:89]
	v_mfma_f32_16x16x32_bf16 v[90:93], v[142:145], v[118:121], v[90:93]
	s_waitcnt vmcnt(6) lgkmcnt(0)
	s_barrier
	ds_read_b128 v[118:121], v8
	ds_read_b128 v[122:125], v8 offset:2048
	ds_read_b128 v[126:129], v8 offset:4096
	ds_read_b128 v[130:133], v8 offset:6144
	ds_read_b128 v[134:137], v9 offset:16384
	ds_read_b128 v[138:141], v9 offset:18432
	ds_read_b128 v[142:145], v9 offset:20480
	ds_read_b128 v[146:149], v9 offset:22528
	v_mfma_f32_16x16x32_bf16 v[22:25], v[114:117], v[74:77], v[22:25]
	v_mfma_f32_16x16x32_bf16 v[38:41], v[102:105], v[78:81], v[38:41]
	v_mfma_f32_16x16x32_bf16 v[46:49], v[106:109], v[78:81], v[46:49]
	v_mfma_f32_16x16x32_bf16 v[58:61], v[110:113], v[78:81], v[58:61]
	v_mfma_f32_16x16x32_bf16 v[50:53], v[114:117], v[78:81], v[50:53]
	v_mfma_f32_16x16x32_bf16 v[42:45], v[102:105], v[94:97], v[42:45]
	v_mfma_f32_16x16x32_bf16 v[62:65], v[106:109], v[94:97], v[62:65]
	v_mfma_f32_16x16x32_bf16 v[70:73], v[110:113], v[94:97], v[70:73]
	v_mfma_f32_16x16x32_bf16 v[54:57], v[114:117], v[94:97], v[54:57]
	v_mfma_f32_16x16x32_bf16 v[34:37], v[102:105], v[98:101], v[34:37]
	v_mfma_f32_16x16x32_bf16 v[30:33], v[106:109], v[98:101], v[30:33]
	v_mfma_f32_16x16x32_bf16 v[26:29], v[110:113], v[98:101], v[26:29]
	v_mfma_f32_16x16x32_bf16 v[18:21], v[114:117], v[98:101], v[18:21]
	v_mfma_f32_16x16x32_bf16 v[82:85], v[102:105], v[74:77], v[82:85]
	v_mfma_f32_16x16x32_bf16 v[86:89], v[106:109], v[74:77], v[86:89]
	v_mfma_f32_16x16x32_bf16 v[90:93], v[110:113], v[74:77], v[90:93]
	s_mov_b32 m0, s69
	v_lshl_add_u64 v[74:75], v[4:5], 0, s[28:29]
	global_load_lds_dwordx4 v[74:75], off
	v_lshl_add_u64 v[74:75], v[6:7], 0, s[28:29]
	s_mov_b32 m0, s70
	s_mov_b64 s[76:77], 0x20580
	global_load_lds_dwordx4 v[74:75], off
	v_lshl_add_u64 v[74:75], v[2:3], 0, s[28:29]
	s_mov_b32 m0, s71
	s_nop 0
	global_load_lds_dwordx4 v[74:75], off
	v_lshl_add_u64 v[74:75], v[2:3], 0, s[76:77]
	s_mov_b32 m0, s72
	s_mov_b64 s[76:77], 0x40580
	global_load_lds_dwordx4 v[74:75], off
	v_lshl_add_u64 v[74:75], v[2:3], 0, s[76:77]
	s_mov_b32 m0, s73
	s_mov_b64 s[76:77], 0x60580
	global_load_lds_dwordx4 v[74:75], off
	v_lshl_add_u64 v[74:75], v[2:3], 0, s[76:77]
	s_mov_b32 m0, s74
	s_nop 0
	global_load_lds_dwordx4 v[74:75], off
	ds_read_b128 v[74:77], v10
	ds_read_b128 v[78:81], v10 offset:2048
	ds_read_b128 v[94:97], v10 offset:4096
	ds_read_b128 v[98:101], v10 offset:6144
	ds_read_b128 v[102:105], v11 offset:16384
	ds_read_b128 v[106:109], v11 offset:18432
	ds_read_b128 v[110:113], v11 offset:20480
	ds_read_b128 v[114:117], v11 offset:22528
	s_waitcnt lgkmcnt(8)
	v_mfma_f32_16x16x32_bf16 v[22:25], v[146:149], v[118:121], v[22:25]
	v_mfma_f32_16x16x32_bf16 v[38:41], v[134:137], v[122:125], v[38:41]
	v_mfma_f32_16x16x32_bf16 v[46:49], v[138:141], v[122:125], v[46:49]
	v_mfma_f32_16x16x32_bf16 v[58:61], v[142:145], v[122:125], v[58:61]
	v_mfma_f32_16x16x32_bf16 v[50:53], v[146:149], v[122:125], v[50:53]
	v_mfma_f32_16x16x32_bf16 v[42:45], v[134:137], v[126:129], v[42:45]
	v_mfma_f32_16x16x32_bf16 v[62:65], v[138:141], v[126:129], v[62:65]
	v_mfma_f32_16x16x32_bf16 v[70:73], v[142:145], v[126:129], v[70:73]
	v_mfma_f32_16x16x32_bf16 v[54:57], v[146:149], v[126:129], v[54:57]
	v_mfma_f32_16x16x32_bf16 v[34:37], v[134:137], v[130:133], v[34:37]
	v_mfma_f32_16x16x32_bf16 v[30:33], v[138:141], v[130:133], v[30:33]
	v_mfma_f32_16x16x32_bf16 v[26:29], v[142:145], v[130:133], v[26:29]
	v_mfma_f32_16x16x32_bf16 v[18:21], v[146:149], v[130:133], v[18:21]
	v_mfma_f32_16x16x32_bf16 v[82:85], v[134:137], v[118:121], v[82:85]
	v_mfma_f32_16x16x32_bf16 v[86:89], v[138:141], v[118:121], v[86:89]
	v_mfma_f32_16x16x32_bf16 v[90:93], v[142:145], v[118:121], v[90:93]
	s_waitcnt vmcnt(6) lgkmcnt(0)
	s_barrier
	ds_read_b128 v[118:121], v8 offset:49152
	ds_read_b128 v[122:125], v8 offset:51200
	ds_read_b128 v[126:129], v8 offset:53248
	ds_read_b128 v[130:133], v8 offset:55296
	ds_read_b128 v[134:137], v12
	ds_read_b128 v[138:141], v12 offset:2048
	ds_read_b128 v[142:145], v12 offset:4096
	ds_read_b128 v[146:149], v12 offset:6144
	v_mfma_f32_16x16x32_bf16 v[22:25], v[114:117], v[74:77], v[22:25]
	v_mfma_f32_16x16x32_bf16 v[38:41], v[102:105], v[78:81], v[38:41]
	v_mfma_f32_16x16x32_bf16 v[46:49], v[106:109], v[78:81], v[46:49]
	v_mfma_f32_16x16x32_bf16 v[58:61], v[110:113], v[78:81], v[58:61]
	v_mfma_f32_16x16x32_bf16 v[50:53], v[114:117], v[78:81], v[50:53]
	v_mfma_f32_16x16x32_bf16 v[42:45], v[102:105], v[94:97], v[42:45]
	v_mfma_f32_16x16x32_bf16 v[62:65], v[106:109], v[94:97], v[62:65]
	v_mfma_f32_16x16x32_bf16 v[70:73], v[110:113], v[94:97], v[70:73]
	v_mfma_f32_16x16x32_bf16 v[54:57], v[114:117], v[94:97], v[54:57]
	v_mfma_f32_16x16x32_bf16 v[34:37], v[102:105], v[98:101], v[34:37]
	v_mfma_f32_16x16x32_bf16 v[30:33], v[106:109], v[98:101], v[30:33]
	v_mfma_f32_16x16x32_bf16 v[26:29], v[110:113], v[98:101], v[26:29]
	v_mfma_f32_16x16x32_bf16 v[18:21], v[114:117], v[98:101], v[18:21]
	v_mfma_f32_16x16x32_bf16 v[82:85], v[102:105], v[74:77], v[82:85]
	v_mfma_f32_16x16x32_bf16 v[86:89], v[106:109], v[74:77], v[86:89]
	v_mfma_f32_16x16x32_bf16 v[90:93], v[110:113], v[74:77], v[90:93]
	s_mov_b32 m0, s62
	v_lshl_add_u64 v[74:75], v[4:5], 0, s[30:31]
	global_load_lds_dwordx4 v[74:75], off
	v_lshl_add_u64 v[74:75], v[6:7], 0, s[30:31]
	s_mov_b32 m0, s38
	s_mov_b64 s[76:77], 0x20600
	global_load_lds_dwordx4 v[74:75], off
	v_lshl_add_u64 v[74:75], v[2:3], 0, s[30:31]
	s_mov_b32 m0, s39
	s_nop 0
	global_load_lds_dwordx4 v[74:75], off
	v_lshl_add_u64 v[74:75], v[2:3], 0, s[76:77]
	s_mov_b32 m0, s33
	s_mov_b64 s[76:77], 0x40600
	global_load_lds_dwordx4 v[74:75], off
	v_lshl_add_u64 v[74:75], v[2:3], 0, s[76:77]
	s_mov_b32 m0, s6
	s_mov_b64 s[76:77], 0x60600
	global_load_lds_dwordx4 v[74:75], off
	v_lshl_add_u64 v[74:75], v[2:3], 0, s[76:77]
	s_mov_b32 m0, s5
	s_nop 0
	global_load_lds_dwordx4 v[74:75], off
	ds_read_b128 v[74:77], v10 offset:49152
	ds_read_b128 v[78:81], v10 offset:51200
	ds_read_b128 v[94:97], v10 offset:53248
	ds_read_b128 v[98:101], v10 offset:55296
	ds_read_b128 v[102:105], v13
	ds_read_b128 v[106:109], v13 offset:2048
	ds_read_b128 v[110:113], v13 offset:4096
	ds_read_b128 v[114:117], v13 offset:6144
	s_waitcnt lgkmcnt(8)
	v_mfma_f32_16x16x32_bf16 v[22:25], v[146:149], v[118:121], v[22:25]
	v_mfma_f32_16x16x32_bf16 v[38:41], v[134:137], v[122:125], v[38:41]
	v_mfma_f32_16x16x32_bf16 v[46:49], v[138:141], v[122:125], v[46:49]
	v_mfma_f32_16x16x32_bf16 v[58:61], v[142:145], v[122:125], v[58:61]
	v_mfma_f32_16x16x32_bf16 v[50:53], v[146:149], v[122:125], v[50:53]
	v_mfma_f32_16x16x32_bf16 v[42:45], v[134:137], v[126:129], v[42:45]
	v_mfma_f32_16x16x32_bf16 v[62:65], v[138:141], v[126:129], v[62:65]
	v_mfma_f32_16x16x32_bf16 v[70:73], v[142:145], v[126:129], v[70:73]
	v_mfma_f32_16x16x32_bf16 v[54:57], v[146:149], v[126:129], v[54:57]
	v_mfma_f32_16x16x32_bf16 v[34:37], v[134:137], v[130:133], v[34:37]
	v_mfma_f32_16x16x32_bf16 v[30:33], v[138:141], v[130:133], v[30:33]
	v_mfma_f32_16x16x32_bf16 v[26:29], v[142:145], v[130:133], v[26:29]
	v_mfma_f32_16x16x32_bf16 v[18:21], v[146:149], v[130:133], v[18:21]
	v_mfma_f32_16x16x32_bf16 v[82:85], v[134:137], v[118:121], v[82:85]
	v_mfma_f32_16x16x32_bf16 v[86:89], v[138:141], v[118:121], v[86:89]
	v_mfma_f32_16x16x32_bf16 v[90:93], v[142:145], v[118:121], v[90:93]
	s_waitcnt vmcnt(6) lgkmcnt(0)
	s_barrier
	ds_read_b128 v[118:121], v14
	ds_read_b128 v[122:125], v14 offset:2048
	ds_read_b128 v[126:129], v14 offset:4096
	ds_read_b128 v[130:133], v14 offset:6144
	ds_read_b128 v[134:137], v15
	ds_read_b128 v[138:141], v15 offset:2048
	ds_read_b128 v[142:145], v15 offset:4096
	ds_read_b128 v[146:149], v15 offset:6144
	v_mfma_f32_16x16x32_bf16 v[22:25], v[114:117], v[74:77], v[22:25]
	v_mfma_f32_16x16x32_bf16 v[38:41], v[102:105], v[78:81], v[38:41]
	v_mfma_f32_16x16x32_bf16 v[46:49], v[106:109], v[78:81], v[46:49]
	v_mfma_f32_16x16x32_bf16 v[58:61], v[110:113], v[78:81], v[58:61]
	v_mfma_f32_16x16x32_bf16 v[50:53], v[114:117], v[78:81], v[50:53]
	v_mfma_f32_16x16x32_bf16 v[42:45], v[102:105], v[94:97], v[42:45]
	v_mfma_f32_16x16x32_bf16 v[62:65], v[106:109], v[94:97], v[62:65]
	v_mfma_f32_16x16x32_bf16 v[70:73], v[110:113], v[94:97], v[70:73]
	v_mfma_f32_16x16x32_bf16 v[54:57], v[114:117], v[94:97], v[54:57]
	v_mfma_f32_16x16x32_bf16 v[34:37], v[102:105], v[98:101], v[34:37]
	v_mfma_f32_16x16x32_bf16 v[30:33], v[106:109], v[98:101], v[30:33]
	v_mfma_f32_16x16x32_bf16 v[26:29], v[110:113], v[98:101], v[26:29]
	v_mfma_f32_16x16x32_bf16 v[18:21], v[114:117], v[98:101], v[18:21]
	v_mfma_f32_16x16x32_bf16 v[82:85], v[102:105], v[74:77], v[82:85]
	v_mfma_f32_16x16x32_bf16 v[86:89], v[106:109], v[74:77], v[86:89]
	v_mfma_f32_16x16x32_bf16 v[90:93], v[110:113], v[74:77], v[90:93]
	s_mov_b32 m0, s64
	v_lshl_add_u64 v[74:75], v[4:5], 0, s[34:35]
	global_load_lds_dwordx4 v[74:75], off
	v_lshl_add_u64 v[74:75], v[6:7], 0, s[34:35]
	s_mov_b32 m0, s63
	s_nop 0
	global_load_lds_dwordx4 v[74:75], off
	v_lshl_add_u64 v[74:75], v[2:3], 0, s[34:35]
	s_mov_b32 m0, s65
	s_mov_b64 s[64:65], 0x20680
	global_load_lds_dwordx4 v[74:75], off
	v_lshl_add_u64 v[74:75], v[2:3], 0, s[64:65]
	s_mov_b32 m0, s66
	s_mov_b64 s[64:65], 0x40680
	global_load_lds_dwordx4 v[74:75], off
	v_lshl_add_u64 v[74:75], v[2:3], 0, s[64:65]
	s_mov_b32 m0, s67
	s_mov_b64 s[64:65], 0x60680
	global_load_lds_dwordx4 v[74:75], off
	v_lshl_add_u64 v[74:75], v[2:3], 0, s[64:65]
	s_mov_b32 m0, s68
	s_nop 0
	global_load_lds_dwordx4 v[74:75], off
	ds_read_b128 v[74:77], v16
	ds_read_b128 v[78:81], v16 offset:2048
	ds_read_b128 v[94:97], v16 offset:4096
	ds_read_b128 v[98:101], v16 offset:6144
	ds_read_b128 v[102:105], v17
	ds_read_b128 v[106:109], v17 offset:2048
	ds_read_b128 v[110:113], v17 offset:4096
	ds_read_b128 v[114:117], v17 offset:6144
	s_waitcnt lgkmcnt(8)
	v_mfma_f32_16x16x32_bf16 v[22:25], v[146:149], v[118:121], v[22:25]
	v_mfma_f32_16x16x32_bf16 v[38:41], v[134:137], v[122:125], v[38:41]
	v_mfma_f32_16x16x32_bf16 v[46:49], v[138:141], v[122:125], v[46:49]
	v_mfma_f32_16x16x32_bf16 v[58:61], v[142:145], v[122:125], v[58:61]
	v_mfma_f32_16x16x32_bf16 v[50:53], v[146:149], v[122:125], v[50:53]
	v_mfma_f32_16x16x32_bf16 v[42:45], v[134:137], v[126:129], v[42:45]
	v_mfma_f32_16x16x32_bf16 v[62:65], v[138:141], v[126:129], v[62:65]
	v_mfma_f32_16x16x32_bf16 v[70:73], v[142:145], v[126:129], v[70:73]
	v_mfma_f32_16x16x32_bf16 v[54:57], v[146:149], v[126:129], v[54:57]
	v_mfma_f32_16x16x32_bf16 v[34:37], v[134:137], v[130:133], v[34:37]
	v_mfma_f32_16x16x32_bf16 v[30:33], v[138:141], v[130:133], v[30:33]
	v_mfma_f32_16x16x32_bf16 v[26:29], v[142:145], v[130:133], v[26:29]
	v_mfma_f32_16x16x32_bf16 v[18:21], v[146:149], v[130:133], v[18:21]
	v_mfma_f32_16x16x32_bf16 v[82:85], v[134:137], v[118:121], v[82:85]
	v_mfma_f32_16x16x32_bf16 v[86:89], v[138:141], v[118:121], v[86:89]
	v_mfma_f32_16x16x32_bf16 v[90:93], v[142:145], v[118:121], v[90:93]
	s_waitcnt vmcnt(6) lgkmcnt(0)
	s_barrier
	ds_read_b128 v[118:121], v8
	ds_read_b128 v[122:125], v8 offset:2048
	ds_read_b128 v[126:129], v8 offset:4096
	ds_read_b128 v[130:133], v8 offset:6144
	ds_read_b128 v[134:137], v9 offset:16384
	ds_read_b128 v[138:141], v9 offset:18432
	ds_read_b128 v[142:145], v9 offset:20480
	ds_read_b128 v[146:149], v9 offset:22528
	v_mfma_f32_16x16x32_bf16 v[22:25], v[114:117], v[74:77], v[22:25]
	v_mfma_f32_16x16x32_bf16 v[38:41], v[102:105], v[78:81], v[38:41]
	v_mfma_f32_16x16x32_bf16 v[46:49], v[106:109], v[78:81], v[46:49]
	v_mfma_f32_16x16x32_bf16 v[58:61], v[110:113], v[78:81], v[58:61]
	v_mfma_f32_16x16x32_bf16 v[50:53], v[114:117], v[78:81], v[50:53]
	v_mfma_f32_16x16x32_bf16 v[42:45], v[102:105], v[94:97], v[42:45]
	v_mfma_f32_16x16x32_bf16 v[62:65], v[106:109], v[94:97], v[62:65]
	v_mfma_f32_16x16x32_bf16 v[70:73], v[110:113], v[94:97], v[70:73]
	v_mfma_f32_16x16x32_bf16 v[54:57], v[114:117], v[94:97], v[54:57]
	v_mfma_f32_16x16x32_bf16 v[34:37], v[102:105], v[98:101], v[34:37]
	v_mfma_f32_16x16x32_bf16 v[30:33], v[106:109], v[98:101], v[30:33]
	v_mfma_f32_16x16x32_bf16 v[26:29], v[110:113], v[98:101], v[26:29]
	v_mfma_f32_16x16x32_bf16 v[18:21], v[114:117], v[98:101], v[18:21]
	v_mfma_f32_16x16x32_bf16 v[82:85], v[102:105], v[74:77], v[82:85]
	v_mfma_f32_16x16x32_bf16 v[86:89], v[106:109], v[74:77], v[86:89]
	v_mfma_f32_16x16x32_bf16 v[90:93], v[110:113], v[74:77], v[90:93]
	s_mov_b32 m0, s69
	v_lshl_add_u64 v[74:75], v[4:5], 0, s[36:37]
	global_load_lds_dwordx4 v[74:75], off
	v_lshl_add_u64 v[74:75], v[6:7], 0, s[36:37]
	s_mov_b32 m0, s70
	s_mov_b64 s[64:65], 0x20700
	global_load_lds_dwordx4 v[74:75], off
	v_lshl_add_u64 v[74:75], v[2:3], 0, s[36:37]
	s_mov_b32 m0, s71
	s_nop 0
	global_load_lds_dwordx4 v[74:75], off
	v_lshl_add_u64 v[74:75], v[2:3], 0, s[64:65]
	s_mov_b32 m0, s72
	s_mov_b64 s[64:65], 0x40700
	global_load_lds_dwordx4 v[74:75], off
	v_lshl_add_u64 v[74:75], v[2:3], 0, s[64:65]
	s_mov_b32 m0, s73
	s_mov_b64 s[64:65], 0x60700
	global_load_lds_dwordx4 v[74:75], off
	v_lshl_add_u64 v[74:75], v[2:3], 0, s[64:65]
	s_mov_b32 m0, s74
	s_nop 0
	global_load_lds_dwordx4 v[74:75], off
	ds_read_b128 v[74:77], v10
	ds_read_b128 v[78:81], v10 offset:2048
	ds_read_b128 v[94:97], v10 offset:4096
	ds_read_b128 v[98:101], v10 offset:6144
	ds_read_b128 v[102:105], v11 offset:16384
	ds_read_b128 v[106:109], v11 offset:18432
	ds_read_b128 v[110:113], v11 offset:20480
	ds_read_b128 v[114:117], v11 offset:22528
	s_waitcnt lgkmcnt(8)
	v_mfma_f32_16x16x32_bf16 v[22:25], v[146:149], v[118:121], v[22:25]
	v_mfma_f32_16x16x32_bf16 v[38:41], v[134:137], v[122:125], v[38:41]
	v_mfma_f32_16x16x32_bf16 v[46:49], v[138:141], v[122:125], v[46:49]
	v_mfma_f32_16x16x32_bf16 v[58:61], v[142:145], v[122:125], v[58:61]
	v_mfma_f32_16x16x32_bf16 v[50:53], v[146:149], v[122:125], v[50:53]
	v_mfma_f32_16x16x32_bf16 v[42:45], v[134:137], v[126:129], v[42:45]
	v_mfma_f32_16x16x32_bf16 v[62:65], v[138:141], v[126:129], v[62:65]
	v_mfma_f32_16x16x32_bf16 v[70:73], v[142:145], v[126:129], v[70:73]
	v_mfma_f32_16x16x32_bf16 v[54:57], v[146:149], v[126:129], v[54:57]
	v_mfma_f32_16x16x32_bf16 v[34:37], v[134:137], v[130:133], v[34:37]
	v_mfma_f32_16x16x32_bf16 v[30:33], v[138:141], v[130:133], v[30:33]
	v_mfma_f32_16x16x32_bf16 v[26:29], v[142:145], v[130:133], v[26:29]
	v_mfma_f32_16x16x32_bf16 v[18:21], v[146:149], v[130:133], v[18:21]
	v_mfma_f32_16x16x32_bf16 v[82:85], v[134:137], v[118:121], v[82:85]
	v_mfma_f32_16x16x32_bf16 v[86:89], v[138:141], v[118:121], v[86:89]
	v_mfma_f32_16x16x32_bf16 v[90:93], v[142:145], v[118:121], v[90:93]
	s_waitcnt vmcnt(6) lgkmcnt(0)
	s_barrier
	ds_read_b128 v[118:121], v8 offset:49152
	ds_read_b128 v[122:125], v8 offset:51200
	ds_read_b128 v[126:129], v8 offset:53248
	ds_read_b128 v[130:133], v8 offset:55296
	ds_read_b128 v[134:137], v12
	ds_read_b128 v[138:141], v12 offset:2048
	ds_read_b128 v[142:145], v12 offset:4096
	ds_read_b128 v[146:149], v12 offset:6144
	v_mfma_f32_16x16x32_bf16 v[22:25], v[114:117], v[74:77], v[22:25]
	v_mfma_f32_16x16x32_bf16 v[38:41], v[102:105], v[78:81], v[38:41]
	v_mfma_f32_16x16x32_bf16 v[46:49], v[106:109], v[78:81], v[46:49]
	v_mfma_f32_16x16x32_bf16 v[58:61], v[110:113], v[78:81], v[58:61]
	v_mfma_f32_16x16x32_bf16 v[50:53], v[114:117], v[78:81], v[50:53]
	v_mfma_f32_16x16x32_bf16 v[42:45], v[102:105], v[94:97], v[42:45]
	v_mfma_f32_16x16x32_bf16 v[62:65], v[106:109], v[94:97], v[62:65]
	v_mfma_f32_16x16x32_bf16 v[70:73], v[110:113], v[94:97], v[70:73]
	v_mfma_f32_16x16x32_bf16 v[54:57], v[114:117], v[94:97], v[54:57]
	v_mfma_f32_16x16x32_bf16 v[34:37], v[102:105], v[98:101], v[34:37]
	v_mfma_f32_16x16x32_bf16 v[30:33], v[106:109], v[98:101], v[30:33]
	v_mfma_f32_16x16x32_bf16 v[26:29], v[110:113], v[98:101], v[26:29]
	v_mfma_f32_16x16x32_bf16 v[18:21], v[114:117], v[98:101], v[18:21]
	v_mfma_f32_16x16x32_bf16 v[82:85], v[102:105], v[74:77], v[82:85]
	v_mfma_f32_16x16x32_bf16 v[86:89], v[106:109], v[74:77], v[86:89]
	v_mfma_f32_16x16x32_bf16 v[90:93], v[110:113], v[74:77], v[90:93]
	s_mov_b32 m0, s62
	v_lshl_add_u64 v[4:5], v[4:5], 0, s[46:47]
	global_load_lds_dwordx4 v[4:5], off
	v_lshl_add_u64 v[4:5], v[6:7], 0, s[46:47]
	s_mov_b32 m0, s38
	s_nop 0
	global_load_lds_dwordx4 v[4:5], off
	v_lshl_add_u64 v[4:5], v[2:3], 0, s[46:47]
	s_mov_b32 m0, s39
	s_mov_b64 s[38:39], 0x20780
	global_load_lds_dwordx4 v[4:5], off
	v_lshl_add_u64 v[4:5], v[2:3], 0, s[38:39]
	s_mov_b32 m0, s33
	s_mov_b64 s[38:39], 0x40780
	global_load_lds_dwordx4 v[4:5], off
	v_lshl_add_u64 v[4:5], v[2:3], 0, s[38:39]
	s_mov_b32 m0, s6
	s_mov_b64 s[38:39], 0x60780
	global_load_lds_dwordx4 v[4:5], off
	v_lshl_add_u64 v[2:3], v[2:3], 0, s[38:39]
	s_mov_b32 m0, s5
	s_nop 0
	global_load_lds_dwordx4 v[2:3], off
	ds_read_b128 v[2:5], v10 offset:49152
	ds_read_b128 v[74:77], v10 offset:51200
	ds_read_b128 v[78:81], v10 offset:53248
	ds_read_b128 v[94:97], v10 offset:55296
	ds_read_b128 v[98:101], v13
	ds_read_b128 v[102:105], v13 offset:2048
	ds_read_b128 v[106:109], v13 offset:4096
	ds_read_b128 v[110:113], v13 offset:6144
	s_waitcnt lgkmcnt(8)
	v_mfma_f32_16x16x32_bf16 v[22:25], v[146:149], v[118:121], v[22:25]
	v_mfma_f32_16x16x32_bf16 v[38:41], v[134:137], v[122:125], v[38:41]
	v_mfma_f32_16x16x32_bf16 v[46:49], v[138:141], v[122:125], v[46:49]
	v_mfma_f32_16x16x32_bf16 v[58:61], v[142:145], v[122:125], v[58:61]
	v_mfma_f32_16x16x32_bf16 v[50:53], v[146:149], v[122:125], v[50:53]
	v_mfma_f32_16x16x32_bf16 v[42:45], v[134:137], v[126:129], v[42:45]
	v_mfma_f32_16x16x32_bf16 v[62:65], v[138:141], v[126:129], v[62:65]
	v_mfma_f32_16x16x32_bf16 v[70:73], v[142:145], v[126:129], v[70:73]
	v_mfma_f32_16x16x32_bf16 v[54:57], v[146:149], v[126:129], v[54:57]
	v_mfma_f32_16x16x32_bf16 v[34:37], v[134:137], v[130:133], v[34:37]
	v_mfma_f32_16x16x32_bf16 v[30:33], v[138:141], v[130:133], v[30:33]
	v_mfma_f32_16x16x32_bf16 v[26:29], v[142:145], v[130:133], v[26:29]
	v_mfma_f32_16x16x32_bf16 v[18:21], v[146:149], v[130:133], v[18:21]
	v_mfma_f32_16x16x32_bf16 v[82:85], v[134:137], v[118:121], v[82:85]
	v_mfma_f32_16x16x32_bf16 v[86:89], v[138:141], v[118:121], v[86:89]
	v_mfma_f32_16x16x32_bf16 v[90:93], v[142:145], v[118:121], v[90:93]
	s_waitcnt vmcnt(6) lgkmcnt(0)
	s_barrier
	ds_read_b128 v[114:117], v14
	ds_read_b128 v[118:121], v14 offset:2048
	ds_read_b128 v[122:125], v14 offset:4096
	ds_read_b128 v[126:129], v14 offset:6144
	ds_read_b128 v[130:133], v15
	ds_read_b128 v[134:137], v15 offset:2048
	ds_read_b128 v[138:141], v15 offset:4096
	ds_read_b128 v[12:15], v15 offset:6144
	v_mfma_f32_16x16x32_bf16 v[82:85], v[98:101], v[2:5], v[82:85]
	v_mfma_f32_16x16x32_bf16 v[86:89], v[102:105], v[2:5], v[86:89]
	v_mfma_f32_16x16x32_bf16 v[90:93], v[106:109], v[2:5], v[90:93]
	v_mfma_f32_16x16x32_bf16 v[2:5], v[110:113], v[2:5], v[22:25]
	v_mfma_f32_16x16x32_bf16 v[22:25], v[98:101], v[74:77], v[38:41]
	v_mfma_f32_16x16x32_bf16 v[38:41], v[102:105], v[74:77], v[46:49]
	v_mfma_f32_16x16x32_bf16 v[46:49], v[106:109], v[74:77], v[58:61]
	v_mfma_f32_16x16x32_bf16 v[50:53], v[110:113], v[74:77], v[50:53]
	v_mfma_f32_16x16x32_bf16 v[42:45], v[98:101], v[78:81], v[42:45]
	v_mfma_f32_16x16x32_bf16 v[58:61], v[102:105], v[78:81], v[62:65]
	v_mfma_f32_16x16x32_bf16 v[62:65], v[106:109], v[78:81], v[70:73]
	v_mfma_f32_16x16x32_bf16 v[54:57], v[110:113], v[78:81], v[54:57]
	v_mfma_f32_16x16x32_bf16 v[34:37], v[98:101], v[94:97], v[34:37]
	v_mfma_f32_16x16x32_bf16 v[30:33], v[102:105], v[94:97], v[30:33]
	v_mfma_f32_16x16x32_bf16 v[26:29], v[106:109], v[94:97], v[26:29]
	v_mfma_f32_16x16x32_bf16 v[18:21], v[110:113], v[94:97], v[18:21]
	ds_read_b128 v[70:73], v16
	ds_read_b128 v[74:77], v16 offset:2048
	ds_read_b128 v[78:81], v16 offset:4096
	ds_read_b128 v[94:97], v16 offset:6144
	ds_read_b128 v[98:101], v17
	ds_read_b128 v[102:105], v17 offset:2048
	ds_read_b128 v[106:109], v17 offset:4096
	ds_read_b128 v[110:113], v17 offset:6144
	s_waitcnt lgkmcnt(8)
	v_mfma_f32_16x16x32_bf16 v[2:5], v[12:15], v[114:117], v[2:5]
	v_mfma_f32_16x16x32_bf16 v[22:25], v[130:133], v[118:121], v[22:25]
	v_mfma_f32_16x16x32_bf16 v[38:41], v[134:137], v[118:121], v[38:41]
	v_mfma_f32_16x16x32_bf16 v[46:49], v[138:141], v[118:121], v[46:49]
	v_mfma_f32_16x16x32_bf16 v[50:53], v[12:15], v[118:121], v[50:53]
	v_mfma_f32_16x16x32_bf16 v[42:45], v[130:133], v[122:125], v[42:45]
	v_mfma_f32_16x16x32_bf16 v[58:61], v[134:137], v[122:125], v[58:61]
	v_mfma_f32_16x16x32_bf16 v[62:65], v[138:141], v[122:125], v[62:65]
	v_mfma_f32_16x16x32_bf16 v[54:57], v[12:15], v[122:125], v[54:57]
	v_mfma_f32_16x16x32_bf16 v[34:37], v[130:133], v[126:129], v[34:37]
	v_mfma_f32_16x16x32_bf16 v[30:33], v[134:137], v[126:129], v[30:33]
	v_mfma_f32_16x16x32_bf16 v[26:29], v[138:141], v[126:129], v[26:29]
	v_mfma_f32_16x16x32_bf16 v[12:15], v[12:15], v[126:129], v[18:21]
	v_mfma_f32_16x16x32_bf16 v[82:85], v[130:133], v[114:117], v[82:85]
	v_mfma_f32_16x16x32_bf16 v[86:89], v[134:137], v[114:117], v[86:89]
	v_mfma_f32_16x16x32_bf16 v[90:93], v[138:141], v[114:117], v[90:93]
	s_waitcnt vmcnt(0) lgkmcnt(0)
	s_barrier
	ds_read_b128 v[16:19], v8
	ds_read_b128 v[114:117], v8 offset:2048
	ds_read_b128 v[118:121], v8 offset:4096
	ds_read_b128 v[122:125], v8 offset:6144
	ds_read_b128 v[126:129], v9 offset:16384
	ds_read_b128 v[130:133], v9 offset:18432
	ds_read_b128 v[134:137], v9 offset:20480
	ds_read_b128 v[6:9], v9 offset:22528
	v_mfma_f32_16x16x32_bf16 v[2:5], v[110:113], v[70:73], v[2:5]
	v_mfma_f32_16x16x32_bf16 v[20:23], v[98:101], v[74:77], v[22:25]
	v_mfma_f32_16x16x32_bf16 v[38:41], v[102:105], v[74:77], v[38:41]
	v_mfma_f32_16x16x32_bf16 v[46:49], v[106:109], v[74:77], v[46:49]
	v_mfma_f32_16x16x32_bf16 v[50:53], v[110:113], v[74:77], v[50:53]
	v_mfma_f32_16x16x32_bf16 v[42:45], v[98:101], v[78:81], v[42:45]
	v_mfma_f32_16x16x32_bf16 v[58:61], v[102:105], v[78:81], v[58:61]
	v_mfma_f32_16x16x32_bf16 v[62:65], v[106:109], v[78:81], v[62:65]
	v_mfma_f32_16x16x32_bf16 v[54:57], v[110:113], v[78:81], v[54:57]
	v_mfma_f32_16x16x32_bf16 v[34:37], v[98:101], v[94:97], v[34:37]
	v_mfma_f32_16x16x32_bf16 v[30:33], v[102:105], v[94:97], v[30:33]
	v_mfma_f32_16x16x32_bf16 v[24:27], v[106:109], v[94:97], v[26:29]
	v_mfma_f32_16x16x32_bf16 v[12:15], v[110:113], v[94:97], v[12:15]
	v_mfma_f32_16x16x32_bf16 v[82:85], v[98:101], v[70:73], v[82:85]
	v_mfma_f32_16x16x32_bf16 v[86:89], v[102:105], v[70:73], v[86:89]
	v_mfma_f32_16x16x32_bf16 v[90:93], v[106:109], v[70:73], v[90:93]
	ds_read_b128 v[70:73], v10
	ds_read_b128 v[74:77], v10 offset:2048
	ds_read_b128 v[78:81], v10 offset:4096
	ds_read_b128 v[94:97], v10 offset:6144
	ds_read_b128 v[98:101], v11 offset:16384
	ds_read_b128 v[102:105], v11 offset:18432
	ds_read_b128 v[106:109], v11 offset:20480
	ds_read_b128 v[110:113], v11 offset:22528
	s_waitcnt lgkmcnt(8)
	v_mfma_f32_16x16x32_bf16 v[82:85], v[126:129], v[16:19], v[82:85]
	v_mfma_f32_16x16x32_bf16 v[86:89], v[130:133], v[16:19], v[86:89]
	v_mfma_f32_16x16x32_bf16 v[90:93], v[134:137], v[16:19], v[90:93]
	v_mfma_f32_16x16x32_bf16 v[2:5], v[6:9], v[16:19], v[2:5]
	v_mfma_f32_16x16x32_bf16 v[16:19], v[126:129], v[114:117], v[20:23]
	v_mfma_f32_16x16x32_bf16 v[20:23], v[130:133], v[114:117], v[38:41]
	v_mfma_f32_16x16x32_bf16 v[38:41], v[134:137], v[114:117], v[46:49]
	v_mfma_f32_16x16x32_bf16 v[114:117], v[6:9], v[114:117], v[50:53]
	v_mfma_f32_16x16x32_bf16 v[138:141], v[126:129], v[118:121], v[42:45]
	v_mfma_f32_16x16x32_bf16 v[142:145], v[130:133], v[118:121], v[58:61]
	v_mfma_f32_16x16x32_bf16 v[146:149], v[134:137], v[118:121], v[62:65]
	v_mfma_f32_16x16x32_bf16 v[118:121], v[6:9], v[118:121], v[54:57]
	v_mfma_f32_16x16x32_bf16 v[6:9], v[6:9], v[122:125], v[12:15]
	v_mfma_f32_16x16x32_bf16 v[126:129], v[126:129], v[122:125], v[34:37]
	v_mfma_f32_16x16x32_bf16 v[130:133], v[130:133], v[122:125], v[30:33]
	v_mfma_f32_16x16x32_bf16 v[134:137], v[134:137], v[122:125], v[24:27]
	s_waitcnt vmcnt(0) lgkmcnt(0)
	s_barrier
	v_mfma_f32_16x16x32_bf16 v[58:61], v[98:101], v[70:73], v[82:85]
	v_mfma_f32_16x16x32_bf16 v[62:65], v[102:105], v[70:73], v[86:89]
	v_mfma_f32_16x16x32_bf16 v[50:53], v[106:109], v[70:73], v[90:93]
	v_mfma_f32_16x16x32_bf16 v[54:57], v[110:113], v[70:73], v[2:5]
	v_mfma_f32_16x16x32_bf16 v[42:45], v[98:101], v[74:77], v[16:19]
	v_mfma_f32_16x16x32_bf16 v[46:49], v[102:105], v[74:77], v[20:23]
	v_mfma_f32_16x16x32_bf16 v[34:37], v[106:109], v[74:77], v[38:41]
	v_mfma_f32_16x16x32_bf16 v[38:41], v[110:113], v[74:77], v[114:117]
	v_mfma_f32_16x16x32_bf16 v[26:29], v[98:101], v[78:81], v[138:141]
	v_mfma_f32_16x16x32_bf16 v[30:33], v[102:105], v[78:81], v[142:145]
	v_mfma_f32_16x16x32_bf16 v[18:21], v[106:109], v[78:81], v[146:149]
	v_mfma_f32_16x16x32_bf16 v[22:25], v[110:113], v[78:81], v[118:121]
	v_mfma_f32_16x16x32_bf16 v[10:13], v[98:101], v[94:97], v[126:129]
	v_mfma_f32_16x16x32_bf16 v[14:17], v[102:105], v[94:97], v[130:133]
	v_mfma_f32_16x16x32_bf16 v[2:5], v[106:109], v[94:97], v[134:137]
	v_mfma_f32_16x16x32_bf16 v[6:9], v[110:113], v[94:97], v[6:9]
	v_ashrrev_i32_e32 v66, 2, v68
	v_and_b32_e32 v66, 0xffffffc0, v66
	v_add_u32_e32 v66, s1, v66
	s_waitcnt lgkmcnt(0)
	s_barrier
	v_and_or_b32 v70, v68, 15, v66
	s_cmp_gt_i32 s0, 7
	v_lshrrev_b32_e32 v68, 2, v68
	s_cselect_b64 s[38:39], -1, 0
	s_mul_i32 s0, s4, 0xfffff400
	v_lshlrev_b32_e32 v66, 6, v1
	v_and_b32_e32 v68, 12, v68
	v_ashrrev_i32_e32 v71, 31, v70
	s_add_i32 s6, s56, s0
	v_lshlrev_b64 v[74:75], 11, v[70:71]
	s_mov_b64 s[0:1], -1
	s_and_b64 vcc, exec, s[38:39]
	v_lshlrev_b32_e32 v72, 1, v66
	v_lshlrev_b32_e32 v68, 1, v68
	s_cbranch_vccz .LBB0_1030
	v_lshl_add_u64 v[76:77], s[42:43], 0, v[74:75]
	v_lshl_add_u64 v[76:77], s[6:7], 1, v[76:77]
	v_mov_b32_e32 v73, v67
	v_lshl_add_u64 v[76:77], v[76:77], 0, v[72:73]
	v_mov_b32_e32 v69, v67
	v_lshl_add_u64 v[76:77], v[76:77], 0, v[68:69]
	v_cvt_pk_bf16_f32 v78, v58, v59
	v_cvt_pk_bf16_f32 v79, v60, v61
	global_store_dwordx2 v[76:77], v[78:79], off offset:-4096
	v_cvt_pk_bf16_f32 v78, v62, v63
	v_cvt_pk_bf16_f32 v79, v64, v65
	global_store_dwordx2 v[76:77], v[78:79], off offset:-4064
	v_cvt_pk_bf16_f32 v78, v50, v51
	v_cvt_pk_bf16_f32 v79, v52, v53
	global_store_dwordx2 v[76:77], v[78:79], off offset:-4032
	v_cvt_pk_bf16_f32 v78, v54, v55
	v_cvt_pk_bf16_f32 v79, v56, v57
	global_store_dwordx2 v[76:77], v[78:79], off offset:-4000
	s_mov_b64 s[0:1], 0

.LBB0_1433:
	s_cmpk_gt_i32 s47, 0x7ff
	s_cbranch_scc1 .LBB0_1437
	v_writelane_b32 v196, s96, 24
	v_writelane_b32 v197, s0, 18
	s_lshl_b32 s38, s47, 7
	v_writelane_b32 v196, s97, 25
	v_writelane_b32 v197, s1, 19
	v_readlane_b32 s8, v196, 6
	v_readlane_b32 s12, v196, 10
	v_readlane_b32 s13, v196, 11
	v_readlane_b32 s14, v196, 12
	v_readlane_b32 s15, v196, 13
	v_readlane_b32 s16, v196, 14
	v_readlane_b32 s17, v196, 15
	v_readlane_b32 s18, v196, 16
	v_readlane_b32 s19, v196, 17
	v_readlane_b32 s20, v196, 18
	v_readlane_b32 s21, v196, 19
	v_readlane_b32 s72, v197, 34
	s_lshl_b32 s39, s46, 7
	s_mov_b32 s3, 0
	v_mov_b32_e32 v67, 0
	s_mov_b64 s[0:1], 0x100
	s_add_i32 s56, 0, 0xc000
	s_mov_b64 s[40:41], 0x180
	s_mov_b64 s[42:43], 0x200
	s_mov_b32 s57, s47
	s_mov_b64 s[46:47], 0x280
	s_mov_b64 s[48:49], 0x300
	s_mov_b64 s[96:97], 0x380
	s_mov_b64 s[6:7], 0x400
	s_mov_b64 s[24:25], 0x500
	s_mov_b64 s[26:27], 0x580
	s_mov_b64 s[28:29], 0x600
	s_mov_b64 s[30:31], 0x680
	s_mov_b64 s[34:35], 0x700
	s_mov_b64 s[36:37], 0x780
	v_readlane_b32 s9, v196, 7
	v_readlane_b32 s22, v196, 20
	v_readlane_b32 s23, v196, 21
	s_mov_b64 s[20:21], 0x4040780
	s_mov_b64 s[18:19], 0x4020780
	s_mov_b64 s[16:17], 0x4000780
	s_mov_b64 s[14:15], 0x480
	s_mov_b64 s[12:13], 0x80
	v_readlane_b32 s82, v197, 44
	v_readlane_b32 s83, v197, 45
	v_readlane_b32 s10, v196, 8
	v_readlane_b32 s11, v196, 9
	v_readlane_b32 s73, v197, 35
	v_readlane_b32 s74, v197, 36
	v_readlane_b32 s75, v197, 37
	v_readlane_b32 s76, v197, 38
	v_readlane_b32 s77, v197, 39
	v_readlane_b32 s78, v197, 40
	v_readlane_b32 s79, v197, 41
	v_readlane_b32 s80, v197, 42
	v_readlane_b32 s81, v197, 43
	v_readlane_b32 s84, v197, 46
	v_readlane_b32 s85, v197, 47
	v_readlane_b32 s86, v197, 48
	v_readlane_b32 s87, v197, 49
	s_mov_b32 s98, s57
.LBB0_1435:
	s_mov_b32 s57, s98
	s_cmp_lg_u32 s39, 0x8000
	s_cbranch_scc1 .Lremap_done_15
	s_lshr_b32 s2, s98, 8
	s_bfe_u32 s4, s98, 0x30005
	s_and_b32 s5, s98, 31
	s_lshr_b32 s10, s2, 2
	s_lshl_b32 s10, s10, 3
	s_add_i32 s4, s4, s10
	s_and_b32 s2, s2, 3
	s_lshr_b32 s10, s2, 1
	s_xor_b32 s2, s2, s10
	s_and_b32 s2, s2, 1
	s_lshl_b32 s10, s10, 3
	s_lshr_b32 s11, s5, 2
	s_add_i32 s10, s10, s11
	s_and_b32 s5, s5, 3
	s_lshl_b32 s2, s2, 2
	s_add_i32 s2, s2, s5
	s_lshl_b32 s4, s4, 7
	s_lshl_b32 s2, s2, 4
	s_add_i32 s4, s4, s2
	s_add_i32 s57, s4, s10
.Lremap_done_15:
	s_lshl_b32 s38, s57, 7
	s_bfe_u32 s2, s57, 0x20002
	s_ashr_i32 s4, s57, 7
	s_lshl_b32 s5, s2, 4
	s_add_i32 s58, s5, s4
	v_mov_b32_e32 v1, v0
	s_lshl_b32 s5, s58, 9
	s_and_b32 s59, s38, 0x180
	s_waitcnt vmcnt(0) lgkmcnt(0)
	s_barrier
	s_or_b32 s5, s5, s59
	v_ashrrev_i32_e32 v2, 3, v1
	v_add_u32_e32 v4, s5, v2
	v_ashrrev_i32_e32 v5, 31, v4
	v_lshl_add_u64 v[4:5], v[4:5], 2, s[52:53]
	global_load_dword v6, v[4:5], off
	global_load_dword v8, v[4:5], off offset:256
	s_ashr_i32 s5, s4, 31
	s_bfe_u32 s60, s57, 0x30004
	s_lshl_b64 s[4:5], s[4:5], 22
	s_add_u32 s4, s82, s4
	s_addc_u32 s5, s83, s5
	s_lshl_b32 s33, s60, 19
	s_add_u32 s4, s4, s33
	v_lshrrev_b32_e32 v3, 4, v1
	s_addc_u32 s5, s5, 0
	s_lshl_b32 s2, s2, 12
	v_mov_b32_e32 v16, v0
	v_xor_b32_e32 v3, v3, v1
	v_lshlrev_b32_e32 v3, 4, v3
	v_and_b32_e32 v66, 0x70, v3
	v_ashrrev_i32_e32 v3, 31, v2
	v_lshlrev_b64 v[2:3], 11, v[2:3]
	v_lshl_add_u64 v[2:3], s[4:5], 0, v[2:3]
	v_lshl_add_u64 v[2:3], v[2:3], 0, v[66:67]
	s_mov_b64 s[4:5], 0x4000000
	s_mov_b64 s[68:69], 0x4020080
	v_lshrrev_b32_e32 v17, 4, v16
	v_bfe_u32 v18, v16, 4, 2
	v_and_b32_e32 v19, 15, v16
	s_mov_b64 s[72:73], 0x4000100
	s_mov_b64 s[74:75], 0x4040100
	s_waitcnt vmcnt(1)
	v_ashrrev_i32_e32 v7, 31, v6
	s_waitcnt vmcnt(0)
	v_ashrrev_i32_e32 v9, 31, v8
	v_lshl_add_u64 v[4:5], v[6:7], 0, s[2:3]
	v_lshl_add_u64 v[6:7], v[8:9], 0, s[2:3]
	v_readfirstlane_b32 s2, v16
	s_lshl_b32 s2, s2, 4
	v_lshlrev_b64 v[4:5], 11, v[4:5]
	s_and_b32 s2, s2, 0xfffffc00
	v_lshl_add_u64 v[4:5], s[8:9], 0, v[4:5]
	v_lshlrev_b64 v[6:7], 11, v[6:7]
	s_add_i32 s64, s2, 0
	v_lshl_add_u64 v[4:5], v[4:5], 0, v[66:67]
	v_lshl_add_u64 v[6:7], s[8:9], 0, v[6:7]
	s_mov_b32 m0, s64
	s_add_i32 s2, s64, 0x2000
	v_lshl_add_u64 v[6:7], v[6:7], 0, v[66:67]
	global_load_lds_dwordx4 v[4:5], off
	s_mov_b32 m0, s2
	s_add_i32 s33, s64, 0x4000
	v_lshl_add_u64 v[8:9], v[2:3], 0, s[4:5]
	s_mov_b64 s[4:5], 0x4020000
	global_load_lds_dwordx4 v[6:7], off
	s_mov_b32 m0, s33
	s_add_i32 s61, s64, 0x6000
	v_lshl_add_u64 v[10:11], v[2:3], 0, s[4:5]
	s_mov_b64 s[4:5], 0x4040000
	global_load_lds_dwordx4 v[8:9], off
	s_mov_b32 m0, s61
	s_add_i32 s62, s64, 0x8000
	v_lshl_add_u64 v[12:13], v[2:3], 0, s[4:5]
	s_mov_b64 s[4:5], 0x4060000
	global_load_lds_dwordx4 v[10:11], off
	s_mov_b32 m0, s62
	s_add_i32 s63, s64, 0xa000
	v_lshl_add_u64 v[14:15], v[2:3], 0, s[4:5]
	global_load_lds_dwordx4 v[12:13], off
	s_mov_b32 m0, s63
	s_add_i32 s66, s64, 0xc000
	global_load_lds_dwordx4 v[14:15], off
	v_lshl_add_u64 v[8:9], v[4:5], 0, s[12:13]
	s_mov_b32 m0, s66
	s_add_i32 s65, s64, 0xe000
	global_load_lds_dwordx4 v[8:9], off
	v_lshl_add_u64 v[8:9], v[6:7], 0, s[12:13]
	s_mov_b32 m0, s65
	s_mov_b64 s[4:5], 0x4000080
	global_load_lds_dwordx4 v[8:9], off
	v_lshl_add_u64 v[8:9], v[2:3], 0, s[4:5]
	s_add_i32 s4, s64, 0x10000
	s_mov_b32 m0, s4
	s_add_i32 s5, s64, 0x12000
	global_load_lds_dwordx4 v[8:9], off
	v_lshl_add_u64 v[8:9], v[2:3], 0, s[68:69]
	s_mov_b32 m0, s5
	s_mov_b64 s[68:69], 0x4040080
	s_add_i32 s67, s64, 0x14000
	global_load_lds_dwordx4 v[8:9], off
	v_lshl_add_u64 v[8:9], v[2:3], 0, s[68:69]
	s_mov_b32 m0, s67
	s_mov_b64 s[68:69], 0x4060080
	global_load_lds_dwordx4 v[8:9], off
	v_lshl_add_u64 v[8:9], v[2:3], 0, s[68:69]
	s_add_i32 s68, s64, 0x16000
	s_mov_b32 m0, s68
	s_mov_b32 s69, 0x1ffffc0
	global_load_lds_dwordx4 v[8:9], off
	v_bfe_u32 v8, v16, 1, 3
	v_lshrrev_b32_e32 v9, 2, v16
	v_and_or_b32 v9, v9, s69, v19
	v_lshlrev_b32_e32 v10, 7, v16
	v_bitop3_b32 v11, v17, v8, 3 bitop3:0x6c
	v_bitop3_b32 v8, v18, v8, 4 bitop3:0x36
	v_lshlrev_b32_e32 v9, 7, v9
	v_and_b32_e32 v60, 0x6780, v10
	v_lshlrev_b32_e32 v11, 4, v11
	v_lshlrev_b32_e32 v61, 4, v8
	v_add_u32_e32 v10, 0x4000, v60
	v_or_b32_e32 v64, v11, v9
	v_or_b32_e32 v66, v61, v9
	v_or_b32_e32 v9, v11, v60
	s_add_i32 s69, s64, 0x18000
	s_waitcnt vmcnt(6)
	s_barrier
	v_or_b32_e32 v65, v11, v10
	v_or_b32_e32 v152, v61, v10
	v_add_u32_e32 v8, 0, v64
	v_add_u32_e32 v9, 0, v9
	v_lshl_add_u64 v[10:11], v[4:5], 0, s[0:1]
	s_mov_b32 m0, s69
	s_add_i32 s70, s64, 0x1a000
	ds_read_b128 v[12:15], v8
	ds_read_b128 v[16:19], v8 offset:2048
	ds_read_b128 v[20:23], v8 offset:4096
	ds_read_b128 v[24:27], v8 offset:6144
	ds_read_b128 v[28:31], v9 offset:22528
	ds_read_b128 v[32:35], v9 offset:20480
	ds_read_b128 v[36:39], v9 offset:18432
	ds_read_b128 v[40:43], v9 offset:16384
	global_load_lds_dwordx4 v[10:11], off
	v_lshl_add_u64 v[10:11], v[6:7], 0, s[0:1]
	s_mov_b32 m0, s70
	s_add_i32 s71, s64, 0x1c000
	global_load_lds_dwordx4 v[10:11], off
	v_lshl_add_u64 v[10:11], v[2:3], 0, s[72:73]
	s_mov_b32 m0, s71
	s_mov_b64 s[72:73], 0x4020100
	global_load_lds_dwordx4 v[10:11], off
	v_lshl_add_u64 v[10:11], v[2:3], 0, s[72:73]
	s_add_i32 s72, s64, 0x1e000
	s_mov_b32 m0, s72
	s_add_i32 s73, s64, 0x20000
	global_load_lds_dwordx4 v[10:11], off
	v_lshl_add_u64 v[10:11], v[2:3], 0, s[74:75]
	s_mov_b32 m0, s73
	s_mov_b64 s[74:75], 0x4060100
	global_load_lds_dwordx4 v[10:11], off
	v_lshl_add_u64 v[10:11], v[2:3], 0, s[74:75]
	s_add_i32 s74, s64, 0x22000
	s_mov_b32 m0, s74
	s_nop 0
	global_load_lds_dwordx4 v[10:11], off
	v_or_b32_e32 v11, v61, v60
	v_add_u32_e32 v10, 0, v66
	v_add_u32_e32 v11, 0, v11
	ds_read_b128 v[44:47], v10
	ds_read_b128 v[48:51], v10 offset:2048
	ds_read_b128 v[52:55], v10 offset:4096
	ds_read_b128 v[56:59], v10 offset:6144
	ds_read_b128 v[60:63], v11 offset:16384
	ds_read_b128 v[68:71], v11 offset:18432
	ds_read_b128 v[72:75], v11 offset:20480
	ds_read_b128 v[76:79], v11 offset:22528
	s_waitcnt lgkmcnt(8)
	v_mfma_f32_16x16x32_bf16 v[80:83], v[40:43], v[12:15], 0
	v_mfma_f32_16x16x32_bf16 v[84:87], v[36:39], v[12:15], 0
	v_mfma_f32_16x16x32_bf16 v[88:91], v[32:35], v[12:15], 0
	v_mfma_f32_16x16x32_bf16 v[92:95], v[28:31], v[12:15], 0
	v_mfma_f32_16x16x32_bf16 v[96:99], v[40:43], v[16:19], 0
	v_mfma_f32_16x16x32_bf16 v[100:103], v[36:39], v[16:19], 0
	v_mfma_f32_16x16x32_bf16 v[104:107], v[32:35], v[16:19], 0
	v_mfma_f32_16x16x32_bf16 v[14:17], v[28:31], v[16:19], 0
	v_mfma_f32_16x16x32_bf16 v[108:111], v[40:43], v[20:23], 0
	v_mfma_f32_16x16x32_bf16 v[112:115], v[36:39], v[20:23], 0
	v_mfma_f32_16x16x32_bf16 v[116:119], v[32:35], v[20:23], 0
	v_mfma_f32_16x16x32_bf16 v[18:21], v[28:31], v[20:23], 0
	v_mfma_f32_16x16x32_bf16 v[40:43], v[40:43], v[24:27], 0
	v_mfma_f32_16x16x32_bf16 v[36:39], v[36:39], v[24:27], 0
	v_mfma_f32_16x16x32_bf16 v[32:35], v[32:35], v[24:27], 0
	v_mfma_f32_16x16x32_bf16 v[22:25], v[28:31], v[24:27], 0
	s_waitcnt vmcnt(6) lgkmcnt(0)
	s_barrier
	v_add_u32_e32 v12, s56, v65
	ds_read_b128 v[26:29], v8 offset:49152
	ds_read_b128 v[120:123], v8 offset:51200
	ds_read_b128 v[124:127], v8 offset:53248
	ds_read_b128 v[128:131], v8 offset:55296
	ds_read_b128 v[132:135], v12
	ds_read_b128 v[136:139], v12 offset:2048
	ds_read_b128 v[140:143], v12 offset:4096
	ds_read_b128 v[144:147], v12 offset:6144
	v_mfma_f32_16x16x32_bf16 v[80:83], v[60:63], v[44:47], v[80:83]
	v_mfma_f32_16x16x32_bf16 v[84:87], v[68:71], v[44:47], v[84:87]
	v_mfma_f32_16x16x32_bf16 v[88:91], v[72:75], v[44:47], v[88:91]
	v_mfma_f32_16x16x32_bf16 v[44:47], v[76:79], v[44:47], v[92:95]
	v_mfma_f32_16x16x32_bf16 v[92:95], v[60:63], v[48:51], v[96:99]
	v_mfma_f32_16x16x32_bf16 v[96:99], v[68:71], v[48:51], v[100:103]
	v_mfma_f32_16x16x32_bf16 v[100:103], v[72:75], v[48:51], v[104:107]
	v_mfma_f32_16x16x32_bf16 v[14:17], v[76:79], v[48:51], v[14:17]
	v_mfma_f32_16x16x32_bf16 v[48:51], v[60:63], v[52:55], v[108:111]
	v_mfma_f32_16x16x32_bf16 v[104:107], v[68:71], v[52:55], v[112:115]
	v_mfma_f32_16x16x32_bf16 v[108:111], v[72:75], v[52:55], v[116:119]
	v_mfma_f32_16x16x32_bf16 v[18:21], v[76:79], v[52:55], v[18:21]
	v_mfma_f32_16x16x32_bf16 v[40:43], v[60:63], v[56:59], v[40:43]
	v_mfma_f32_16x16x32_bf16 v[36:39], v[68:71], v[56:59], v[36:39]
	v_mfma_f32_16x16x32_bf16 v[30:33], v[72:75], v[56:59], v[32:35]
	v_mfma_f32_16x16x32_bf16 v[22:25], v[76:79], v[56:59], v[22:25]
	s_mov_b32 m0, s64
	s_nop 0
	v_lshl_add_u64 v[34:35], v[4:5], 0, s[40:41]
	global_load_lds_dwordx4 v[34:35], off
	v_lshl_add_u64 v[34:35], v[6:7], 0, s[40:41]
	s_mov_b32 m0, s2
	s_mov_b64 s[76:77], 0x4000180
	global_load_lds_dwordx4 v[34:35], off
	v_lshl_add_u64 v[34:35], v[2:3], 0, s[76:77]
	s_mov_b32 m0, s33
	s_mov_b64 s[76:77], 0x4020180
	global_load_lds_dwordx4 v[34:35], off
	v_lshl_add_u64 v[34:35], v[2:3], 0, s[76:77]
	s_mov_b32 m0, s61
	s_mov_b64 s[76:77], 0x4040180
	global_load_lds_dwordx4 v[34:35], off
	v_lshl_add_u64 v[34:35], v[2:3], 0, s[76:77]
	s_mov_b32 m0, s62
	s_mov_b64 s[76:77], 0x4060180
	global_load_lds_dwordx4 v[34:35], off
	v_lshl_add_u64 v[34:35], v[2:3], 0, s[76:77]
	s_mov_b32 m0, s63
	v_add_u32_e32 v13, s56, v152
	global_load_lds_dwordx4 v[34:35], off
	ds_read_b128 v[52:55], v10 offset:49152
	ds_read_b128 v[56:59], v10 offset:51200
	ds_read_b128 v[60:63], v10 offset:53248
	ds_read_b128 v[68:71], v10 offset:55296
	ds_read_b128 v[72:75], v13
	ds_read_b128 v[76:79], v13 offset:2048
	ds_read_b128 v[112:115], v13 offset:4096
	ds_read_b128 v[116:119], v13 offset:6144
	s_waitcnt lgkmcnt(8)
	v_mfma_f32_16x16x32_bf16 v[80:83], v[132:135], v[26:29], v[80:83]
	v_mfma_f32_16x16x32_bf16 v[84:87], v[136:139], v[26:29], v[84:87]
	v_mfma_f32_16x16x32_bf16 v[88:91], v[140:143], v[26:29], v[88:91]
	v_mfma_f32_16x16x32_bf16 v[26:29], v[144:147], v[26:29], v[44:47]
	v_mfma_f32_16x16x32_bf16 v[44:47], v[132:135], v[120:123], v[92:95]
	v_mfma_f32_16x16x32_bf16 v[92:95], v[136:139], v[120:123], v[96:99]
	v_mfma_f32_16x16x32_bf16 v[96:99], v[140:143], v[120:123], v[100:103]
	v_mfma_f32_16x16x32_bf16 v[100:103], v[144:147], v[120:123], v[14:17]
	v_mfma_f32_16x16x32_bf16 v[48:51], v[132:135], v[124:127], v[48:51]
	v_mfma_f32_16x16x32_bf16 v[104:107], v[136:139], v[124:127], v[104:107]
	v_mfma_f32_16x16x32_bf16 v[108:111], v[140:143], v[124:127], v[108:111]
	v_mfma_f32_16x16x32_bf16 v[16:19], v[144:147], v[124:127], v[18:21]
	v_mfma_f32_16x16x32_bf16 v[40:43], v[132:135], v[128:131], v[40:43]
	v_mfma_f32_16x16x32_bf16 v[34:37], v[136:139], v[128:131], v[36:39]
	v_mfma_f32_16x16x32_bf16 v[30:33], v[140:143], v[128:131], v[30:33]
	v_mfma_f32_16x16x32_bf16 v[20:23], v[144:147], v[128:131], v[22:25]
	s_add_i32 s75, 0, 0x18000
	s_waitcnt vmcnt(6) lgkmcnt(0)
	s_barrier
	v_add_u32_e32 v14, s75, v64
	v_add_u32_e32 v15, s75, v65
	ds_read_b128 v[120:123], v14
	ds_read_b128 v[124:127], v14 offset:2048
	ds_read_b128 v[128:131], v14 offset:4096
	ds_read_b128 v[132:135], v14 offset:6144
	ds_read_b128 v[136:139], v15
	ds_read_b128 v[140:143], v15 offset:2048
	ds_read_b128 v[144:147], v15 offset:4096
	ds_read_b128 v[148:151], v15 offset:6144
	v_mfma_f32_16x16x32_bf16 v[80:83], v[72:75], v[52:55], v[80:83]
	v_mfma_f32_16x16x32_bf16 v[84:87], v[76:79], v[52:55], v[84:87]
	v_mfma_f32_16x16x32_bf16 v[88:91], v[112:115], v[52:55], v[88:91]
	v_mfma_f32_16x16x32_bf16 v[24:27], v[116:119], v[52:55], v[26:29]
	v_mfma_f32_16x16x32_bf16 v[44:47], v[72:75], v[56:59], v[44:47]
	v_mfma_f32_16x16x32_bf16 v[52:55], v[76:79], v[56:59], v[92:95]
	v_mfma_f32_16x16x32_bf16 v[92:95], v[112:115], v[56:59], v[96:99]
	v_mfma_f32_16x16x32_bf16 v[56:59], v[116:119], v[56:59], v[100:103]
	v_mfma_f32_16x16x32_bf16 v[48:51], v[72:75], v[60:63], v[48:51]
	v_mfma_f32_16x16x32_bf16 v[96:99], v[76:79], v[60:63], v[104:107]
	v_mfma_f32_16x16x32_bf16 v[100:103], v[112:115], v[60:63], v[108:111]
	v_mfma_f32_16x16x32_bf16 v[60:63], v[116:119], v[60:63], v[16:19]
	v_mfma_f32_16x16x32_bf16 v[38:41], v[72:75], v[68:71], v[40:43]
	v_mfma_f32_16x16x32_bf16 v[34:37], v[76:79], v[68:71], v[34:37]
	v_mfma_f32_16x16x32_bf16 v[28:31], v[112:115], v[68:71], v[30:33]
	v_mfma_f32_16x16x32_bf16 v[18:21], v[116:119], v[68:71], v[20:23]
	s_mov_b32 m0, s66
	v_lshl_add_u64 v[16:17], v[4:5], 0, s[42:43]
	global_load_lds_dwordx4 v[16:17], off
	v_lshl_add_u64 v[16:17], v[6:7], 0, s[42:43]
	s_mov_b32 m0, s65
	s_mov_b64 s[76:77], 0x4000200
	global_load_lds_dwordx4 v[16:17], off
	v_lshl_add_u64 v[16:17], v[2:3], 0, s[76:77]
	s_mov_b32 m0, s4
	s_mov_b64 s[76:77], 0x4020200
	global_load_lds_dwordx4 v[16:17], off
	v_lshl_add_u64 v[16:17], v[2:3], 0, s[76:77]
	s_mov_b32 m0, s5
	s_mov_b64 s[76:77], 0x4040200
	global_load_lds_dwordx4 v[16:17], off
	v_lshl_add_u64 v[16:17], v[2:3], 0, s[76:77]
	s_mov_b32 m0, s67
	s_mov_b64 s[76:77], 0x4060200
	global_load_lds_dwordx4 v[16:17], off
	v_lshl_add_u64 v[16:17], v[2:3], 0, s[76:77]
	s_mov_b32 m0, s68
	s_nop 0
	global_load_lds_dwordx4 v[16:17], off
	v_add_u32_e32 v16, s75, v66
	v_add_u32_e32 v17, s75, v152
	ds_read_b128 v[68:71], v16
	ds_read_b128 v[72:75], v16 offset:2048
	ds_read_b128 v[76:79], v16 offset:4096
	ds_read_b128 v[104:107], v16 offset:6144
	ds_read_b128 v[108:111], v17
	ds_read_b128 v[112:115], v17 offset:2048
	ds_read_b128 v[116:119], v17 offset:4096
	ds_read_b128 v[152:155], v17 offset:6144
	s_waitcnt lgkmcnt(8)
	v_mfma_f32_16x16x32_bf16 v[80:83], v[136:139], v[120:123], v[80:83]
	v_mfma_f32_16x16x32_bf16 v[84:87], v[140:143], v[120:123], v[84:87]
	v_mfma_f32_16x16x32_bf16 v[88:91], v[144:147], v[120:123], v[88:91]
	v_mfma_f32_16x16x32_bf16 v[22:25], v[148:151], v[120:123], v[24:27]
	v_mfma_f32_16x16x32_bf16 v[42:45], v[136:139], v[124:127], v[44:47]
	v_mfma_f32_16x16x32_bf16 v[52:55], v[140:143], v[124:127], v[52:55]
	v_mfma_f32_16x16x32_bf16 v[92:95], v[144:147], v[124:127], v[92:95]
	v_mfma_f32_16x16x32_bf16 v[56:59], v[148:151], v[124:127], v[56:59]
	v_mfma_f32_16x16x32_bf16 v[46:49], v[136:139], v[128:131], v[48:51]
	v_mfma_f32_16x16x32_bf16 v[96:99], v[140:143], v[128:131], v[96:99]
	v_mfma_f32_16x16x32_bf16 v[100:103], v[144:147], v[128:131], v[100:103]
	v_mfma_f32_16x16x32_bf16 v[60:63], v[148:151], v[128:131], v[60:63]
	v_mfma_f32_16x16x32_bf16 v[38:41], v[136:139], v[132:135], v[38:41]
	v_mfma_f32_16x16x32_bf16 v[32:35], v[140:143], v[132:135], v[34:37]
	v_mfma_f32_16x16x32_bf16 v[26:29], v[144:147], v[132:135], v[28:31]
	v_mfma_f32_16x16x32_bf16 v[18:21], v[148:151], v[132:135], v[18:21]
	s_waitcnt vmcnt(6) lgkmcnt(0)
	s_barrier
	ds_read_b128 v[120:123], v8
	ds_read_b128 v[124:127], v8 offset:2048
	ds_read_b128 v[128:131], v8 offset:4096
	ds_read_b128 v[132:135], v8 offset:6144
	ds_read_b128 v[136:139], v9 offset:16384
	ds_read_b128 v[140:143], v9 offset:18432
	ds_read_b128 v[144:147], v9 offset:20480
	ds_read_b128 v[148:151], v9 offset:22528
	v_mfma_f32_16x16x32_bf16 v[80:83], v[108:111], v[68:71], v[80:83]
	v_mfma_f32_16x16x32_bf16 v[84:87], v[112:115], v[68:71], v[84:87]
	v_mfma_f32_16x16x32_bf16 v[88:91], v[116:119], v[68:71], v[88:91]
	v_mfma_f32_16x16x32_bf16 v[22:25], v[152:155], v[68:71], v[22:25]
	v_mfma_f32_16x16x32_bf16 v[42:45], v[108:111], v[72:75], v[42:45]
	v_mfma_f32_16x16x32_bf16 v[50:53], v[112:115], v[72:75], v[52:55]
	v_mfma_f32_16x16x32_bf16 v[68:71], v[116:119], v[72:75], v[92:95]
	v_mfma_f32_16x16x32_bf16 v[54:57], v[152:155], v[72:75], v[56:59]
	v_mfma_f32_16x16x32_bf16 v[46:49], v[108:111], v[76:79], v[46:49]
	v_mfma_f32_16x16x32_bf16 v[72:75], v[112:115], v[76:79], v[96:99]
	v_mfma_f32_16x16x32_bf16 v[92:95], v[116:119], v[76:79], v[100:103]
	v_mfma_f32_16x16x32_bf16 v[58:61], v[152:155], v[76:79], v[60:63]
	v_mfma_f32_16x16x32_bf16 v[36:39], v[108:111], v[104:107], v[38:41]
	v_mfma_f32_16x16x32_bf16 v[30:33], v[112:115], v[104:107], v[32:35]
	v_mfma_f32_16x16x32_bf16 v[26:29], v[116:119], v[104:107], v[26:29]
	v_mfma_f32_16x16x32_bf16 v[18:21], v[152:155], v[104:107], v[18:21]
	s_mov_b32 m0, s69
	v_lshl_add_u64 v[34:35], v[4:5], 0, s[46:47]
	global_load_lds_dwordx4 v[34:35], off
	v_lshl_add_u64 v[34:35], v[6:7], 0, s[46:47]
	s_mov_b32 m0, s70
	s_mov_b64 s[76:77], 0x4000280
	global_load_lds_dwordx4 v[34:35], off
	v_lshl_add_u64 v[34:35], v[2:3], 0, s[76:77]
	s_mov_b32 m0, s71
	s_mov_b64 s[76:77], 0x4020280
	global_load_lds_dwordx4 v[34:35], off
	v_lshl_add_u64 v[34:35], v[2:3], 0, s[76:77]
	s_mov_b32 m0, s72
	s_mov_b64 s[76:77], 0x4040280
	global_load_lds_dwordx4 v[34:35], off
	v_lshl_add_u64 v[34:35], v[2:3], 0, s[76:77]
	s_mov_b32 m0, s73
	s_mov_b64 s[76:77], 0x4060280
	global_load_lds_dwordx4 v[34:35], off
	v_lshl_add_u64 v[34:35], v[2:3], 0, s[76:77]
	s_mov_b32 m0, s74
	s_nop 0
	global_load_lds_dwordx4 v[34:35], off
	ds_read_b128 v[62:65], v10
	ds_read_b128 v[76:79], v10 offset:2048
	ds_read_b128 v[96:99], v10 offset:4096
	ds_read_b128 v[100:103], v10 offset:6144
	ds_read_b128 v[104:107], v11 offset:16384
	ds_read_b128 v[108:111], v11 offset:18432
	ds_read_b128 v[112:115], v11 offset:20480
	ds_read_b128 v[116:119], v11 offset:22528
	s_waitcnt lgkmcnt(8)
	v_mfma_f32_16x16x32_bf16 v[80:83], v[136:139], v[120:123], v[80:83]
	v_mfma_f32_16x16x32_bf16 v[84:87], v[140:143], v[120:123], v[84:87]
	v_mfma_f32_16x16x32_bf16 v[88:91], v[144:147], v[120:123], v[88:91]
	v_mfma_f32_16x16x32_bf16 v[22:25], v[148:151], v[120:123], v[22:25]
	v_mfma_f32_16x16x32_bf16 v[40:43], v[136:139], v[124:127], v[42:45]
	v_mfma_f32_16x16x32_bf16 v[50:53], v[140:143], v[124:127], v[50:53]
	v_mfma_f32_16x16x32_bf16 v[68:71], v[144:147], v[124:127], v[68:71]
	v_mfma_f32_16x16x32_bf16 v[54:57], v[148:151], v[124:127], v[54:57]
	v_mfma_f32_16x16x32_bf16 v[44:47], v[136:139], v[128:131], v[46:49]
	v_mfma_f32_16x16x32_bf16 v[72:75], v[140:143], v[128:131], v[72:75]
	v_mfma_f32_16x16x32_bf16 v[92:95], v[144:147], v[128:131], v[92:95]
	v_mfma_f32_16x16x32_bf16 v[58:61], v[148:151], v[128:131], v[58:61]
	v_mfma_f32_16x16x32_bf16 v[34:37], v[136:139], v[132:135], v[36:39]
	v_mfma_f32_16x16x32_bf16 v[30:33], v[140:143], v[132:135], v[30:33]
	v_mfma_f32_16x16x32_bf16 v[26:29], v[144:147], v[132:135], v[26:29]
	v_mfma_f32_16x16x32_bf16 v[18:21], v[148:151], v[132:135], v[18:21]
	s_waitcnt vmcnt(6) lgkmcnt(0)
	s_barrier
	ds_read_b128 v[120:123], v8 offset:49152
	ds_read_b128 v[124:127], v8 offset:51200
	ds_read_b128 v[128:131], v8 offset:53248
	ds_read_b128 v[132:135], v8 offset:55296
	ds_read_b128 v[136:139], v12
	ds_read_b128 v[140:143], v12 offset:2048
	ds_read_b128 v[144:147], v12 offset:4096
	ds_read_b128 v[148:151], v12 offset:6144
	v_mfma_f32_16x16x32_bf16 v[80:83], v[104:107], v[62:65], v[80:83]
	v_mfma_f32_16x16x32_bf16 v[84:87], v[108:111], v[62:65], v[84:87]
	v_mfma_f32_16x16x32_bf16 v[88:91], v[112:115], v[62:65], v[88:91]
	v_mfma_f32_16x16x32_bf16 v[22:25], v[116:119], v[62:65], v[22:25]
	v_mfma_f32_16x16x32_bf16 v[38:41], v[104:107], v[76:79], v[40:43]
	v_mfma_f32_16x16x32_bf16 v[48:51], v[108:111], v[76:79], v[50:53]
	v_mfma_f32_16x16x32_bf16 v[62:65], v[112:115], v[76:79], v[68:71]
	v_mfma_f32_16x16x32_bf16 v[52:55], v[116:119], v[76:79], v[54:57]
	v_mfma_f32_16x16x32_bf16 v[42:45], v[104:107], v[96:99], v[44:47]
	v_mfma_f32_16x16x32_bf16 v[68:71], v[108:111], v[96:99], v[72:75]
	v_mfma_f32_16x16x32_bf16 v[72:75], v[112:115], v[96:99], v[92:95]
	v_mfma_f32_16x16x32_bf16 v[56:59], v[116:119], v[96:99], v[58:61]
	v_mfma_f32_16x16x32_bf16 v[34:37], v[104:107], v[100:103], v[34:37]
	v_mfma_f32_16x16x32_bf16 v[30:33], v[108:111], v[100:103], v[30:33]
	v_mfma_f32_16x16x32_bf16 v[26:29], v[112:115], v[100:103], v[26:29]
	v_mfma_f32_16x16x32_bf16 v[18:21], v[116:119], v[100:103], v[18:21]
	s_mov_b32 m0, s64
	v_lshl_add_u64 v[46:47], v[4:5], 0, s[48:49]
	global_load_lds_dwordx4 v[46:47], off
	v_lshl_add_u64 v[46:47], v[6:7], 0, s[48:49]
	s_mov_b32 m0, s2
	s_mov_b64 s[76:77], 0x4000300
	global_load_lds_dwordx4 v[46:47], off
	v_lshl_add_u64 v[46:47], v[2:3], 0, s[76:77]
	s_mov_b32 m0, s33
	s_mov_b64 s[76:77], 0x4020300
	global_load_lds_dwordx4 v[46:47], off
	v_lshl_add_u64 v[46:47], v[2:3], 0, s[76:77]
	s_mov_b32 m0, s61
	s_mov_b64 s[76:77], 0x4040300
	global_load_lds_dwordx4 v[46:47], off
	v_lshl_add_u64 v[46:47], v[2:3], 0, s[76:77]
	s_mov_b32 m0, s62
	s_mov_b64 s[76:77], 0x4060300
	global_load_lds_dwordx4 v[46:47], off
	v_lshl_add_u64 v[46:47], v[2:3], 0, s[76:77]
	s_mov_b32 m0, s63
	s_nop 0
	global_load_lds_dwordx4 v[46:47], off
	ds_read_b128 v[76:79], v10 offset:49152
	ds_read_b128 v[92:95], v10 offset:51200
	ds_read_b128 v[96:99], v10 offset:53248
	ds_read_b128 v[100:103], v10 offset:55296
	ds_read_b128 v[104:107], v13
	ds_read_b128 v[108:111], v13 offset:2048
	ds_read_b128 v[112:115], v13 offset:4096
	ds_read_b128 v[116:119], v13 offset:6144
	s_waitcnt lgkmcnt(8)
	v_mfma_f32_16x16x32_bf16 v[80:83], v[136:139], v[120:123], v[80:83]
	v_mfma_f32_16x16x32_bf16 v[84:87], v[140:143], v[120:123], v[84:87]
	v_mfma_f32_16x16x32_bf16 v[88:91], v[144:147], v[120:123], v[88:91]
	v_mfma_f32_16x16x32_bf16 v[22:25], v[148:151], v[120:123], v[22:25]
	v_mfma_f32_16x16x32_bf16 v[38:41], v[136:139], v[124:127], v[38:41]
	v_mfma_f32_16x16x32_bf16 v[46:49], v[140:143], v[124:127], v[48:51]
	v_mfma_f32_16x16x32_bf16 v[60:63], v[144:147], v[124:127], v[62:65]
	v_mfma_f32_16x16x32_bf16 v[50:53], v[148:151], v[124:127], v[52:55]
	v_mfma_f32_16x16x32_bf16 v[42:45], v[136:139], v[128:131], v[42:45]
	v_mfma_f32_16x16x32_bf16 v[68:71], v[140:143], v[128:131], v[68:71]
	v_mfma_f32_16x16x32_bf16 v[72:75], v[144:147], v[128:131], v[72:75]
	v_mfma_f32_16x16x32_bf16 v[54:57], v[148:151], v[128:131], v[56:59]
	v_mfma_f32_16x16x32_bf16 v[34:37], v[136:139], v[132:135], v[34:37]
	v_mfma_f32_16x16x32_bf16 v[30:33], v[140:143], v[132:135], v[30:33]
	v_mfma_f32_16x16x32_bf16 v[26:29], v[144:147], v[132:135], v[26:29]
	v_mfma_f32_16x16x32_bf16 v[18:21], v[148:151], v[132:135], v[18:21]
	s_waitcnt vmcnt(6) lgkmcnt(0)
	s_barrier
	ds_read_b128 v[120:123], v14
	ds_read_b128 v[124:127], v14 offset:2048
	ds_read_b128 v[128:131], v14 offset:4096
	ds_read_b128 v[132:135], v14 offset:6144
	ds_read_b128 v[136:139], v15
	ds_read_b128 v[140:143], v15 offset:2048
	ds_read_b128 v[144:147], v15 offset:4096
	ds_read_b128 v[148:151], v15 offset:6144
	v_mfma_f32_16x16x32_bf16 v[80:83], v[104:107], v[76:79], v[80:83]
	v_mfma_f32_16x16x32_bf16 v[84:87], v[108:111], v[76:79], v[84:87]
	v_mfma_f32_16x16x32_bf16 v[88:91], v[112:115], v[76:79], v[88:91]
	v_mfma_f32_16x16x32_bf16 v[22:25], v[116:119], v[76:79], v[22:25]
	v_mfma_f32_16x16x32_bf16 v[38:41], v[104:107], v[92:95], v[38:41]
	v_mfma_f32_16x16x32_bf16 v[46:49], v[108:111], v[92:95], v[46:49]
	v_mfma_f32_16x16x32_bf16 v[58:61], v[112:115], v[92:95], v[60:63]
	v_mfma_f32_16x16x32_bf16 v[50:53], v[116:119], v[92:95], v[50:53]
	v_mfma_f32_16x16x32_bf16 v[42:45], v[104:107], v[96:99], v[42:45]
	v_mfma_f32_16x16x32_bf16 v[62:65], v[108:111], v[96:99], v[68:71]
	v_mfma_f32_16x16x32_bf16 v[68:71], v[112:115], v[96:99], v[72:75]
	v_mfma_f32_16x16x32_bf16 v[54:57], v[116:119], v[96:99], v[54:57]
	v_mfma_f32_16x16x32_bf16 v[34:37], v[104:107], v[100:103], v[34:37]
	v_mfma_f32_16x16x32_bf16 v[30:33], v[108:111], v[100:103], v[30:33]
	v_mfma_f32_16x16x32_bf16 v[26:29], v[112:115], v[100:103], v[26:29]
	v_mfma_f32_16x16x32_bf16 v[18:21], v[116:119], v[100:103], v[18:21]
	s_mov_b32 m0, s66
	v_lshl_add_u64 v[72:73], v[4:5], 0, s[96:97]
	global_load_lds_dwordx4 v[72:73], off
	v_lshl_add_u64 v[72:73], v[6:7], 0, s[96:97]
	s_mov_b32 m0, s65
	s_mov_b64 s[76:77], 0x4000380
	global_load_lds_dwordx4 v[72:73], off
	v_lshl_add_u64 v[72:73], v[2:3], 0, s[76:77]
	s_mov_b32 m0, s4
	s_mov_b64 s[76:77], 0x4020380
	global_load_lds_dwordx4 v[72:73], off
	v_lshl_add_u64 v[72:73], v[2:3], 0, s[76:77]
	s_mov_b32 m0, s5
	s_mov_b64 s[76:77], 0x4040380
	global_load_lds_dwordx4 v[72:73], off
	v_lshl_add_u64 v[72:73], v[2:3], 0, s[76:77]
	s_mov_b32 m0, s67
	s_mov_b64 s[76:77], 0x4060380
	global_load_lds_dwordx4 v[72:73], off
	v_lshl_add_u64 v[72:73], v[2:3], 0, s[76:77]
	s_mov_b32 m0, s68
	s_nop 0
	global_load_lds_dwordx4 v[72:73], off
	ds_read_b128 v[72:75], v16
	ds_read_b128 v[76:79], v16 offset:2048
	ds_read_b128 v[92:95], v16 offset:4096
	ds_read_b128 v[96:99], v16 offset:6144
	ds_read_b128 v[100:103], v17
	ds_read_b128 v[104:107], v17 offset:2048
	ds_read_b128 v[108:111], v17 offset:4096
	ds_read_b128 v[112:115], v17 offset:6144
	s_waitcnt lgkmcnt(8)
	v_mfma_f32_16x16x32_bf16 v[80:83], v[136:139], v[120:123], v[80:83]
	v_mfma_f32_16x16x32_bf16 v[84:87], v[140:143], v[120:123], v[84:87]
	v_mfma_f32_16x16x32_bf16 v[88:91], v[144:147], v[120:123], v[88:91]
	v_mfma_f32_16x16x32_bf16 v[22:25], v[148:151], v[120:123], v[22:25]
	v_mfma_f32_16x16x32_bf16 v[38:41], v[136:139], v[124:127], v[38:41]
	v_mfma_f32_16x16x32_bf16 v[46:49], v[140:143], v[124:127], v[46:49]
	v_mfma_f32_16x16x32_bf16 v[58:61], v[144:147], v[124:127], v[58:61]
	v_mfma_f32_16x16x32_bf16 v[50:53], v[148:151], v[124:127], v[50:53]
	v_mfma_f32_16x16x32_bf16 v[42:45], v[136:139], v[128:131], v[42:45]
	v_mfma_f32_16x16x32_bf16 v[62:65], v[140:143], v[128:131], v[62:65]
	v_mfma_f32_16x16x32_bf16 v[68:71], v[144:147], v[128:131], v[68:71]
	v_mfma_f32_16x16x32_bf16 v[54:57], v[148:151], v[128:131], v[54:57]
	v_mfma_f32_16x16x32_bf16 v[34:37], v[136:139], v[132:135], v[34:37]
	v_mfma_f32_16x16x32_bf16 v[30:33], v[140:143], v[132:135], v[30:33]
	v_mfma_f32_16x16x32_bf16 v[26:29], v[144:147], v[132:135], v[26:29]
	v_mfma_f32_16x16x32_bf16 v[18:21], v[148:151], v[132:135], v[18:21]
	s_waitcnt vmcnt(6) lgkmcnt(0)
	s_barrier
	ds_read_b128 v[116:119], v8
	ds_read_b128 v[120:123], v8 offset:2048
	ds_read_b128 v[124:127], v8 offset:4096
	ds_read_b128 v[128:131], v8 offset:6144
	ds_read_b128 v[132:135], v9 offset:16384
	ds_read_b128 v[136:139], v9 offset:18432
	ds_read_b128 v[140:143], v9 offset:20480
	ds_read_b128 v[144:147], v9 offset:22528
	v_mfma_f32_16x16x32_bf16 v[80:83], v[100:103], v[72:75], v[80:83]
	v_mfma_f32_16x16x32_bf16 v[84:87], v[104:107], v[72:75], v[84:87]
	v_mfma_f32_16x16x32_bf16 v[88:91], v[108:111], v[72:75], v[88:91]
	v_mfma_f32_16x16x32_bf16 v[22:25], v[112:115], v[72:75], v[22:25]
	v_mfma_f32_16x16x32_bf16 v[38:41], v[100:103], v[76:79], v[38:41]
	v_mfma_f32_16x16x32_bf16 v[46:49], v[104:107], v[76:79], v[46:49]
	v_mfma_f32_16x16x32_bf16 v[58:61], v[108:111], v[76:79], v[58:61]
	v_mfma_f32_16x16x32_bf16 v[50:53], v[112:115], v[76:79], v[50:53]
	v_mfma_f32_16x16x32_bf16 v[42:45], v[100:103], v[92:95], v[42:45]
	v_mfma_f32_16x16x32_bf16 v[62:65], v[104:107], v[92:95], v[62:65]
	v_mfma_f32_16x16x32_bf16 v[68:71], v[108:111], v[92:95], v[68:71]
	v_mfma_f32_16x16x32_bf16 v[54:57], v[112:115], v[92:95], v[54:57]
	v_mfma_f32_16x16x32_bf16 v[34:37], v[100:103], v[96:99], v[34:37]
	v_mfma_f32_16x16x32_bf16 v[30:33], v[104:107], v[96:99], v[30:33]
	v_mfma_f32_16x16x32_bf16 v[26:29], v[108:111], v[96:99], v[26:29]
	v_mfma_f32_16x16x32_bf16 v[18:21], v[112:115], v[96:99], v[18:21]
	s_mov_b32 m0, s69
	v_lshl_add_u64 v[72:73], v[4:5], 0, s[6:7]
	global_load_lds_dwordx4 v[72:73], off
	v_lshl_add_u64 v[72:73], v[6:7], 0, s[6:7]
	s_mov_b32 m0, s70
	s_mov_b64 s[76:77], 0x4000400
	global_load_lds_dwordx4 v[72:73], off
	v_lshl_add_u64 v[72:73], v[2:3], 0, s[76:77]
	s_mov_b32 m0, s71
	s_mov_b64 s[76:77], 0x4020400
	global_load_lds_dwordx4 v[72:73], off
	v_lshl_add_u64 v[72:73], v[2:3], 0, s[76:77]
	s_mov_b32 m0, s72
	s_mov_b64 s[76:77], 0x4040400
	global_load_lds_dwordx4 v[72:73], off
	v_lshl_add_u64 v[72:73], v[2:3], 0, s[76:77]
	s_mov_b32 m0, s73
	s_mov_b64 s[76:77], 0x4060400
	global_load_lds_dwordx4 v[72:73], off
	v_lshl_add_u64 v[72:73], v[2:3], 0, s[76:77]
	s_mov_b32 m0, s74
	s_nop 0
	global_load_lds_dwordx4 v[72:73], off
	ds_read_b128 v[72:75], v10
	ds_read_b128 v[76:79], v10 offset:2048
	ds_read_b128 v[92:95], v10 offset:4096
	ds_read_b128 v[96:99], v10 offset:6144
	ds_read_b128 v[100:103], v11 offset:16384
	ds_read_b128 v[104:107], v11 offset:18432
	ds_read_b128 v[108:111], v11 offset:20480
	ds_read_b128 v[112:115], v11 offset:22528
	s_waitcnt lgkmcnt(8)
	v_mfma_f32_16x16x32_bf16 v[80:83], v[132:135], v[116:119], v[80:83]
	v_mfma_f32_16x16x32_bf16 v[84:87], v[136:139], v[116:119], v[84:87]
	v_mfma_f32_16x16x32_bf16 v[88:91], v[140:143], v[116:119], v[88:91]
	v_mfma_f32_16x16x32_bf16 v[22:25], v[144:147], v[116:119], v[22:25]
	v_mfma_f32_16x16x32_bf16 v[38:41], v[132:135], v[120:123], v[38:41]
	v_mfma_f32_16x16x32_bf16 v[46:49], v[136:139], v[120:123], v[46:49]
	v_mfma_f32_16x16x32_bf16 v[58:61], v[140:143], v[120:123], v[58:61]
	v_mfma_f32_16x16x32_bf16 v[50:53], v[144:147], v[120:123], v[50:53]
	v_mfma_f32_16x16x32_bf16 v[42:45], v[132:135], v[124:127], v[42:45]
	v_mfma_f32_16x16x32_bf16 v[62:65], v[136:139], v[124:127], v[62:65]
	v_mfma_f32_16x16x32_bf16 v[68:71], v[140:143], v[124:127], v[68:71]
	v_mfma_f32_16x16x32_bf16 v[54:57], v[144:147], v[124:127], v[54:57]
	v_mfma_f32_16x16x32_bf16 v[34:37], v[132:135], v[128:131], v[34:37]
	v_mfma_f32_16x16x32_bf16 v[30:33], v[136:139], v[128:131], v[30:33]
	v_mfma_f32_16x16x32_bf16 v[26:29], v[140:143], v[128:131], v[26:29]
	v_mfma_f32_16x16x32_bf16 v[18:21], v[144:147], v[128:131], v[18:21]
	s_waitcnt vmcnt(6) lgkmcnt(0)
	s_barrier
	ds_read_b128 v[116:119], v8 offset:49152
	ds_read_b128 v[120:123], v8 offset:51200
	ds_read_b128 v[124:127], v8 offset:53248
	ds_read_b128 v[128:131], v8 offset:55296
	ds_read_b128 v[132:135], v12
	ds_read_b128 v[136:139], v12 offset:2048
	ds_read_b128 v[140:143], v12 offset:4096
	ds_read_b128 v[144:147], v12 offset:6144
	v_mfma_f32_16x16x32_bf16 v[80:83], v[100:103], v[72:75], v[80:83]
	v_mfma_f32_16x16x32_bf16 v[84:87], v[104:107], v[72:75], v[84:87]
	v_mfma_f32_16x16x32_bf16 v[88:91], v[108:111], v[72:75], v[88:91]
	v_mfma_f32_16x16x32_bf16 v[22:25], v[112:115], v[72:75], v[22:25]
	v_mfma_f32_16x16x32_bf16 v[38:41], v[100:103], v[76:79], v[38:41]
	v_mfma_f32_16x16x32_bf16 v[46:49], v[104:107], v[76:79], v[46:49]
	v_mfma_f32_16x16x32_bf16 v[58:61], v[108:111], v[76:79], v[58:61]
	v_mfma_f32_16x16x32_bf16 v[50:53], v[112:115], v[76:79], v[50:53]
	v_mfma_f32_16x16x32_bf16 v[42:45], v[100:103], v[92:95], v[42:45]
	v_mfma_f32_16x16x32_bf16 v[62:65], v[104:107], v[92:95], v[62:65]
	v_mfma_f32_16x16x32_bf16 v[68:71], v[108:111], v[92:95], v[68:71]
	v_mfma_f32_16x16x32_bf16 v[54:57], v[112:115], v[92:95], v[54:57]
	v_mfma_f32_16x16x32_bf16 v[34:37], v[100:103], v[96:99], v[34:37]
	v_mfma_f32_16x16x32_bf16 v[30:33], v[104:107], v[96:99], v[30:33]
	v_mfma_f32_16x16x32_bf16 v[26:29], v[108:111], v[96:99], v[26:29]
	v_mfma_f32_16x16x32_bf16 v[18:21], v[112:115], v[96:99], v[18:21]
	s_mov_b32 m0, s64
	v_lshl_add_u64 v[72:73], v[4:5], 0, s[14:15]
	global_load_lds_dwordx4 v[72:73], off
	v_lshl_add_u64 v[72:73], v[6:7], 0, s[14:15]
	s_mov_b32 m0, s2
	s_mov_b64 s[76:77], 0x4000480
	global_load_lds_dwordx4 v[72:73], off
	v_lshl_add_u64 v[72:73], v[2:3], 0, s[76:77]
	s_mov_b32 m0, s33
	s_mov_b64 s[76:77], 0x4020480
	global_load_lds_dwordx4 v[72:73], off
	v_lshl_add_u64 v[72:73], v[2:3], 0, s[76:77]
	s_mov_b32 m0, s61
	s_mov_b64 s[76:77], 0x4040480
	global_load_lds_dwordx4 v[72:73], off
	v_lshl_add_u64 v[72:73], v[2:3], 0, s[76:77]
	s_mov_b32 m0, s62
	s_mov_b64 s[76:77], 0x4060480
	global_load_lds_dwordx4 v[72:73], off
	v_lshl_add_u64 v[72:73], v[2:3], 0, s[76:77]
	s_mov_b32 m0, s63
	s_nop 0
	global_load_lds_dwordx4 v[72:73], off
	ds_read_b128 v[72:75], v10 offset:49152
	ds_read_b128 v[76:79], v10 offset:51200
	ds_read_b128 v[92:95], v10 offset:53248
	ds_read_b128 v[96:99], v10 offset:55296
	ds_read_b128 v[100:103], v13
	ds_read_b128 v[104:107], v13 offset:2048
	ds_read_b128 v[108:111], v13 offset:4096
	ds_read_b128 v[112:115], v13 offset:6144
	s_waitcnt lgkmcnt(8)
	v_mfma_f32_16x16x32_bf16 v[80:83], v[132:135], v[116:119], v[80:83]
	v_mfma_f32_16x16x32_bf16 v[84:87], v[136:139], v[116:119], v[84:87]
	v_mfma_f32_16x16x32_bf16 v[88:91], v[140:143], v[116:119], v[88:91]
	v_mfma_f32_16x16x32_bf16 v[22:25], v[144:147], v[116:119], v[22:25]
	v_mfma_f32_16x16x32_bf16 v[38:41], v[132:135], v[120:123], v[38:41]
	v_mfma_f32_16x16x32_bf16 v[46:49], v[136:139], v[120:123], v[46:49]
	v_mfma_f32_16x16x32_bf16 v[58:61], v[140:143], v[120:123], v[58:61]
	v_mfma_f32_16x16x32_bf16 v[50:53], v[144:147], v[120:123], v[50:53]
	v_mfma_f32_16x16x32_bf16 v[42:45], v[132:135], v[124:127], v[42:45]
	v_mfma_f32_16x16x32_bf16 v[62:65], v[136:139], v[124:127], v[62:65]
	v_mfma_f32_16x16x32_bf16 v[68:71], v[140:143], v[124:127], v[68:71]
	v_mfma_f32_16x16x32_bf16 v[54:57], v[144:147], v[124:127], v[54:57]
	v_mfma_f32_16x16x32_bf16 v[34:37], v[132:135], v[128:131], v[34:37]
	v_mfma_f32_16x16x32_bf16 v[30:33], v[136:139], v[128:131], v[30:33]
	v_mfma_f32_16x16x32_bf16 v[26:29], v[140:143], v[128:131], v[26:29]
	v_mfma_f32_16x16x32_bf16 v[18:21], v[144:147], v[128:131], v[18:21]
	s_waitcnt vmcnt(6) lgkmcnt(0)
	s_barrier
	ds_read_b128 v[116:119], v14
	ds_read_b128 v[120:123], v14 offset:2048
	ds_read_b128 v[124:127], v14 offset:4096
	ds_read_b128 v[128:131], v14 offset:6144
	ds_read_b128 v[132:135], v15
	ds_read_b128 v[136:139], v15 offset:2048
	ds_read_b128 v[140:143], v15 offset:4096
	ds_read_b128 v[144:147], v15 offset:6144
	v_mfma_f32_16x16x32_bf16 v[80:83], v[100:103], v[72:75], v[80:83]
	v_mfma_f32_16x16x32_bf16 v[84:87], v[104:107], v[72:75], v[84:87]
	v_mfma_f32_16x16x32_bf16 v[88:91], v[108:111], v[72:75], v[88:91]
	v_mfma_f32_16x16x32_bf16 v[22:25], v[112:115], v[72:75], v[22:25]
	v_mfma_f32_16x16x32_bf16 v[38:41], v[100:103], v[76:79], v[38:41]
	v_mfma_f32_16x16x32_bf16 v[46:49], v[104:107], v[76:79], v[46:49]
	v_mfma_f32_16x16x32_bf16 v[58:61], v[108:111], v[76:79], v[58:61]
	v_mfma_f32_16x16x32_bf16 v[50:53], v[112:115], v[76:79], v[50:53]
	v_mfma_f32_16x16x32_bf16 v[42:45], v[100:103], v[92:95], v[42:45]
	v_mfma_f32_16x16x32_bf16 v[62:65], v[104:107], v[92:95], v[62:65]
	v_mfma_f32_16x16x32_bf16 v[68:71], v[108:111], v[92:95], v[68:71]
	v_mfma_f32_16x16x32_bf16 v[54:57], v[112:115], v[92:95], v[54:57]
	v_mfma_f32_16x16x32_bf16 v[34:37], v[100:103], v[96:99], v[34:37]
	v_mfma_f32_16x16x32_bf16 v[30:33], v[104:107], v[96:99], v[30:33]
	v_mfma_f32_16x16x32_bf16 v[26:29], v[108:111], v[96:99], v[26:29]
	v_mfma_f32_16x16x32_bf16 v[18:21], v[112:115], v[96:99], v[18:21]
	s_mov_b32 m0, s66
	v_lshl_add_u64 v[72:73], v[4:5], 0, s[24:25]
	global_load_lds_dwordx4 v[72:73], off
	v_lshl_add_u64 v[72:73], v[6:7], 0, s[24:25]
	s_mov_b32 m0, s65
	s_mov_b64 s[76:77], 0x4000500
	global_load_lds_dwordx4 v[72:73], off
	v_lshl_add_u64 v[72:73], v[2:3], 0, s[76:77]
	s_mov_b32 m0, s4
	s_mov_b64 s[76:77], 0x4020500
	global_load_lds_dwordx4 v[72:73], off
	v_lshl_add_u64 v[72:73], v[2:3], 0, s[76:77]
	s_mov_b32 m0, s5
	s_mov_b64 s[76:77], 0x4040500
	global_load_lds_dwordx4 v[72:73], off
	v_lshl_add_u64 v[72:73], v[2:3], 0, s[76:77]
	s_mov_b32 m0, s67
	s_mov_b64 s[76:77], 0x4060500
	global_load_lds_dwordx4 v[72:73], off
	v_lshl_add_u64 v[72:73], v[2:3], 0, s[76:77]
	s_mov_b32 m0, s68
	s_nop 0
	global_load_lds_dwordx4 v[72:73], off
	ds_read_b128 v[72:75], v16
	ds_read_b128 v[76:79], v16 offset:2048
	ds_read_b128 v[92:95], v16 offset:4096
	ds_read_b128 v[96:99], v16 offset:6144
	ds_read_b128 v[100:103], v17
	ds_read_b128 v[104:107], v17 offset:2048
	ds_read_b128 v[108:111], v17 offset:4096
	ds_read_b128 v[112:115], v17 offset:6144
	s_waitcnt lgkmcnt(8)
	v_mfma_f32_16x16x32_bf16 v[80:83], v[132:135], v[116:119], v[80:83]
	v_mfma_f32_16x16x32_bf16 v[84:87], v[136:139], v[116:119], v[84:87]
	v_mfma_f32_16x16x32_bf16 v[88:91], v[140:143], v[116:119], v[88:91]
	v_mfma_f32_16x16x32_bf16 v[22:25], v[144:147], v[116:119], v[22:25]
	v_mfma_f32_16x16x32_bf16 v[38:41], v[132:135], v[120:123], v[38:41]
	v_mfma_f32_16x16x32_bf16 v[46:49], v[136:139], v[120:123], v[46:49]
	v_mfma_f32_16x16x32_bf16 v[58:61], v[140:143], v[120:123], v[58:61]
	v_mfma_f32_16x16x32_bf16 v[50:53], v[144:147], v[120:123], v[50:53]
	v_mfma_f32_16x16x32_bf16 v[42:45], v[132:135], v[124:127], v[42:45]
	v_mfma_f32_16x16x32_bf16 v[62:65], v[136:139], v[124:127], v[62:65]
	v_mfma_f32_16x16x32_bf16 v[68:71], v[140:143], v[124:127], v[68:71]
	v_mfma_f32_16x16x32_bf16 v[54:57], v[144:147], v[124:127], v[54:57]
	v_mfma_f32_16x16x32_bf16 v[34:37], v[132:135], v[128:131], v[34:37]
	v_mfma_f32_16x16x32_bf16 v[30:33], v[136:139], v[128:131], v[30:33]
	v_mfma_f32_16x16x32_bf16 v[26:29], v[140:143], v[128:131], v[26:29]
	v_mfma_f32_16x16x32_bf16 v[18:21], v[144:147], v[128:131], v[18:21]
	s_waitcnt vmcnt(6) lgkmcnt(0)
	s_barrier
	ds_read_b128 v[116:119], v8
	ds_read_b128 v[120:123], v8 offset:2048
	ds_read_b128 v[124:127], v8 offset:4096
	ds_read_b128 v[128:131], v8 offset:6144
	ds_read_b128 v[132:135], v9 offset:16384
	ds_read_b128 v[136:139], v9 offset:18432
	ds_read_b128 v[140:143], v9 offset:20480
	ds_read_b128 v[144:147], v9 offset:22528
	v_mfma_f32_16x16x32_bf16 v[80:83], v[100:103], v[72:75], v[80:83]
	v_mfma_f32_16x16x32_bf16 v[84:87], v[104:107], v[72:75], v[84:87]
	v_mfma_f32_16x16x32_bf16 v[88:91], v[108:111], v[72:75], v[88:91]
	v_mfma_f32_16x16x32_bf16 v[22:25], v[112:115], v[72:75], v[22:25]
	v_mfma_f32_16x16x32_bf16 v[38:41], v[100:103], v[76:79], v[38:41]
	v_mfma_f32_16x16x32_bf16 v[46:49], v[104:107], v[76:79], v[46:49]
	v_mfma_f32_16x16x32_bf16 v[58:61], v[108:111], v[76:79], v[58:61]
	v_mfma_f32_16x16x32_bf16 v[50:53], v[112:115], v[76:79], v[50:53]
	v_mfma_f32_16x16x32_bf16 v[42:45], v[100:103], v[92:95], v[42:45]
	v_mfma_f32_16x16x32_bf16 v[62:65], v[104:107], v[92:95], v[62:65]
	v_mfma_f32_16x16x32_bf16 v[68:71], v[108:111], v[92:95], v[68:71]
	v_mfma_f32_16x16x32_bf16 v[54:57], v[112:115], v[92:95], v[54:57]
	v_mfma_f32_16x16x32_bf16 v[34:37], v[100:103], v[96:99], v[34:37]
	v_mfma_f32_16x16x32_bf16 v[30:33], v[104:107], v[96:99], v[30:33]
	v_mfma_f32_16x16x32_bf16 v[26:29], v[108:111], v[96:99], v[26:29]
	v_mfma_f32_16x16x32_bf16 v[18:21], v[112:115], v[96:99], v[18:21]
	s_mov_b32 m0, s69
	v_lshl_add_u64 v[72:73], v[4:5], 0, s[26:27]
	global_load_lds_dwordx4 v[72:73], off
	v_lshl_add_u64 v[72:73], v[6:7], 0, s[26:27]
	s_mov_b32 m0, s70
	s_mov_b64 s[76:77], 0x4000580
	global_load_lds_dwordx4 v[72:73], off
	v_lshl_add_u64 v[72:73], v[2:3], 0, s[76:77]
	s_mov_b32 m0, s71
	s_mov_b64 s[76:77], 0x4020580
	global_load_lds_dwordx4 v[72:73], off
	v_lshl_add_u64 v[72:73], v[2:3], 0, s[76:77]
	s_mov_b32 m0, s72
	s_mov_b64 s[76:77], 0x4040580
	global_load_lds_dwordx4 v[72:73], off
	v_lshl_add_u64 v[72:73], v[2:3], 0, s[76:77]
	s_mov_b32 m0, s73
	s_mov_b64 s[76:77], 0x4060580
	global_load_lds_dwordx4 v[72:73], off
	v_lshl_add_u64 v[72:73], v[2:3], 0, s[76:77]
	s_mov_b32 m0, s74
	s_nop 0
	global_load_lds_dwordx4 v[72:73], off
	ds_read_b128 v[72:75], v10
	ds_read_b128 v[76:79], v10 offset:2048
	ds_read_b128 v[92:95], v10 offset:4096
	ds_read_b128 v[96:99], v10 offset:6144
	ds_read_b128 v[100:103], v11 offset:16384
	ds_read_b128 v[104:107], v11 offset:18432
	ds_read_b128 v[108:111], v11 offset:20480
	ds_read_b128 v[112:115], v11 offset:22528
	s_waitcnt lgkmcnt(8)
	v_mfma_f32_16x16x32_bf16 v[80:83], v[132:135], v[116:119], v[80:83]
	v_mfma_f32_16x16x32_bf16 v[84:87], v[136:139], v[116:119], v[84:87]
	v_mfma_f32_16x16x32_bf16 v[88:91], v[140:143], v[116:119], v[88:91]
	v_mfma_f32_16x16x32_bf16 v[22:25], v[144:147], v[116:119], v[22:25]
	v_mfma_f32_16x16x32_bf16 v[38:41], v[132:135], v[120:123], v[38:41]
	v_mfma_f32_16x16x32_bf16 v[46:49], v[136:139], v[120:123], v[46:49]
	v_mfma_f32_16x16x32_bf16 v[58:61], v[140:143], v[120:123], v[58:61]
	v_mfma_f32_16x16x32_bf16 v[50:53], v[144:147], v[120:123], v[50:53]
	v_mfma_f32_16x16x32_bf16 v[42:45], v[132:135], v[124:127], v[42:45]
	v_mfma_f32_16x16x32_bf16 v[62:65], v[136:139], v[124:127], v[62:65]
	v_mfma_f32_16x16x32_bf16 v[68:71], v[140:143], v[124:127], v[68:71]
	v_mfma_f32_16x16x32_bf16 v[54:57], v[144:147], v[124:127], v[54:57]
	v_mfma_f32_16x16x32_bf16 v[34:37], v[132:135], v[128:131], v[34:37]
	v_mfma_f32_16x16x32_bf16 v[30:33], v[136:139], v[128:131], v[30:33]
	v_mfma_f32_16x16x32_bf16 v[26:29], v[140:143], v[128:131], v[26:29]
	v_mfma_f32_16x16x32_bf16 v[18:21], v[144:147], v[128:131], v[18:21]
	s_waitcnt vmcnt(6) lgkmcnt(0)
	s_barrier
	ds_read_b128 v[116:119], v8 offset:49152
	ds_read_b128 v[120:123], v8 offset:51200
	ds_read_b128 v[124:127], v8 offset:53248
	ds_read_b128 v[128:131], v8 offset:55296
	ds_read_b128 v[132:135], v12
	ds_read_b128 v[136:139], v12 offset:2048
	ds_read_b128 v[140:143], v12 offset:4096
	ds_read_b128 v[144:147], v12 offset:6144
	v_mfma_f32_16x16x32_bf16 v[80:83], v[100:103], v[72:75], v[80:83]
	v_mfma_f32_16x16x32_bf16 v[84:87], v[104:107], v[72:75], v[84:87]
	v_mfma_f32_16x16x32_bf16 v[88:91], v[108:111], v[72:75], v[88:91]
	v_mfma_f32_16x16x32_bf16 v[22:25], v[112:115], v[72:75], v[22:25]
	v_mfma_f32_16x16x32_bf16 v[38:41], v[100:103], v[76:79], v[38:41]
	v_mfma_f32_16x16x32_bf16 v[46:49], v[104:107], v[76:79], v[46:49]
	v_mfma_f32_16x16x32_bf16 v[58:61], v[108:111], v[76:79], v[58:61]
	v_mfma_f32_16x16x32_bf16 v[50:53], v[112:115], v[76:79], v[50:53]
	v_mfma_f32_16x16x32_bf16 v[42:45], v[100:103], v[92:95], v[42:45]
	v_mfma_f32_16x16x32_bf16 v[62:65], v[104:107], v[92:95], v[62:65]
	v_mfma_f32_16x16x32_bf16 v[68:71], v[108:111], v[92:95], v[68:71]
	v_mfma_f32_16x16x32_bf16 v[54:57], v[112:115], v[92:95], v[54:57]
	v_mfma_f32_16x16x32_bf16 v[34:37], v[100:103], v[96:99], v[34:37]
	v_mfma_f32_16x16x32_bf16 v[30:33], v[104:107], v[96:99], v[30:33]
	v_mfma_f32_16x16x32_bf16 v[26:29], v[108:111], v[96:99], v[26:29]
	v_mfma_f32_16x16x32_bf16 v[18:21], v[112:115], v[96:99], v[18:21]
	s_mov_b32 m0, s64
	v_lshl_add_u64 v[72:73], v[4:5], 0, s[28:29]
	global_load_lds_dwordx4 v[72:73], off
	v_lshl_add_u64 v[72:73], v[6:7], 0, s[28:29]
	s_mov_b32 m0, s2
	s_mov_b64 s[76:77], 0x4000600
	global_load_lds_dwordx4 v[72:73], off
	v_lshl_add_u64 v[72:73], v[2:3], 0, s[76:77]
	s_mov_b32 m0, s33
	s_mov_b64 s[76:77], 0x4020600
	global_load_lds_dwordx4 v[72:73], off
	v_lshl_add_u64 v[72:73], v[2:3], 0, s[76:77]
	s_mov_b32 m0, s61
	s_mov_b64 s[76:77], 0x4040600
	global_load_lds_dwordx4 v[72:73], off
	v_lshl_add_u64 v[72:73], v[2:3], 0, s[76:77]
	s_mov_b32 m0, s62
	s_mov_b64 s[76:77], 0x4060600
	global_load_lds_dwordx4 v[72:73], off
	v_lshl_add_u64 v[72:73], v[2:3], 0, s[76:77]
	s_mov_b32 m0, s63
	s_nop 0
	global_load_lds_dwordx4 v[72:73], off
	ds_read_b128 v[72:75], v10 offset:49152
	ds_read_b128 v[76:79], v10 offset:51200
	ds_read_b128 v[92:95], v10 offset:53248
	ds_read_b128 v[96:99], v10 offset:55296
	ds_read_b128 v[100:103], v13
	ds_read_b128 v[104:107], v13 offset:2048
	ds_read_b128 v[108:111], v13 offset:4096
	ds_read_b128 v[112:115], v13 offset:6144
	s_waitcnt lgkmcnt(8)
	v_mfma_f32_16x16x32_bf16 v[80:83], v[132:135], v[116:119], v[80:83]
	v_mfma_f32_16x16x32_bf16 v[84:87], v[136:139], v[116:119], v[84:87]
	v_mfma_f32_16x16x32_bf16 v[88:91], v[140:143], v[116:119], v[88:91]
	v_mfma_f32_16x16x32_bf16 v[22:25], v[144:147], v[116:119], v[22:25]
	v_mfma_f32_16x16x32_bf16 v[38:41], v[132:135], v[120:123], v[38:41]
	v_mfma_f32_16x16x32_bf16 v[46:49], v[136:139], v[120:123], v[46:49]
	v_mfma_f32_16x16x32_bf16 v[58:61], v[140:143], v[120:123], v[58:61]
	v_mfma_f32_16x16x32_bf16 v[50:53], v[144:147], v[120:123], v[50:53]
	v_mfma_f32_16x16x32_bf16 v[42:45], v[132:135], v[124:127], v[42:45]
	v_mfma_f32_16x16x32_bf16 v[62:65], v[136:139], v[124:127], v[62:65]
	v_mfma_f32_16x16x32_bf16 v[68:71], v[140:143], v[124:127], v[68:71]
	v_mfma_f32_16x16x32_bf16 v[54:57], v[144:147], v[124:127], v[54:57]
	v_mfma_f32_16x16x32_bf16 v[34:37], v[132:135], v[128:131], v[34:37]
	v_mfma_f32_16x16x32_bf16 v[30:33], v[136:139], v[128:131], v[30:33]
	v_mfma_f32_16x16x32_bf16 v[26:29], v[140:143], v[128:131], v[26:29]
	v_mfma_f32_16x16x32_bf16 v[18:21], v[144:147], v[128:131], v[18:21]
	s_waitcnt vmcnt(6) lgkmcnt(0)
	s_barrier
	ds_read_b128 v[116:119], v14
	ds_read_b128 v[120:123], v14 offset:2048
	ds_read_b128 v[124:127], v14 offset:4096
	ds_read_b128 v[128:131], v14 offset:6144
	ds_read_b128 v[132:135], v15
	ds_read_b128 v[136:139], v15 offset:2048
	ds_read_b128 v[140:143], v15 offset:4096
	ds_read_b128 v[144:147], v15 offset:6144
	v_mfma_f32_16x16x32_bf16 v[80:83], v[100:103], v[72:75], v[80:83]
	v_mfma_f32_16x16x32_bf16 v[84:87], v[104:107], v[72:75], v[84:87]
	v_mfma_f32_16x16x32_bf16 v[88:91], v[108:111], v[72:75], v[88:91]
	v_mfma_f32_16x16x32_bf16 v[22:25], v[112:115], v[72:75], v[22:25]
	v_mfma_f32_16x16x32_bf16 v[38:41], v[100:103], v[76:79], v[38:41]
	v_mfma_f32_16x16x32_bf16 v[46:49], v[104:107], v[76:79], v[46:49]
	v_mfma_f32_16x16x32_bf16 v[58:61], v[108:111], v[76:79], v[58:61]
	v_mfma_f32_16x16x32_bf16 v[50:53], v[112:115], v[76:79], v[50:53]
	v_mfma_f32_16x16x32_bf16 v[42:45], v[100:103], v[92:95], v[42:45]
	v_mfma_f32_16x16x32_bf16 v[62:65], v[104:107], v[92:95], v[62:65]
	v_mfma_f32_16x16x32_bf16 v[68:71], v[108:111], v[92:95], v[68:71]
	v_mfma_f32_16x16x32_bf16 v[54:57], v[112:115], v[92:95], v[54:57]
	v_mfma_f32_16x16x32_bf16 v[34:37], v[100:103], v[96:99], v[34:37]
	v_mfma_f32_16x16x32_bf16 v[30:33], v[104:107], v[96:99], v[30:33]
	v_mfma_f32_16x16x32_bf16 v[26:29], v[108:111], v[96:99], v[26:29]
	v_mfma_f32_16x16x32_bf16 v[18:21], v[112:115], v[96:99], v[18:21]
	s_mov_b32 m0, s66
	v_lshl_add_u64 v[72:73], v[4:5], 0, s[30:31]
	global_load_lds_dwordx4 v[72:73], off
	v_lshl_add_u64 v[72:73], v[6:7], 0, s[30:31]
	s_mov_b32 m0, s65
	s_mov_b64 s[76:77], 0x4000680
	global_load_lds_dwordx4 v[72:73], off
	v_lshl_add_u64 v[72:73], v[2:3], 0, s[76:77]
	s_mov_b32 m0, s4
	s_mov_b64 s[76:77], 0x4020680
	global_load_lds_dwordx4 v[72:73], off
	v_lshl_add_u64 v[72:73], v[2:3], 0, s[76:77]
	s_mov_b32 m0, s5
	s_mov_b64 s[4:5], 0x4040680
	global_load_lds_dwordx4 v[72:73], off
	v_lshl_add_u64 v[72:73], v[2:3], 0, s[4:5]
	v_readlane_b32 s4, v196, 22
	v_readlane_b32 s5, v196, 23
	s_mov_b32 m0, s67
	s_mov_b32 s10, s4
	s_mov_b64 s[4:5], 0x4060680
	global_load_lds_dwordx4 v[72:73], off
	v_lshl_add_u64 v[72:73], v[2:3], 0, s[4:5]
	s_mov_b32 m0, s68
	s_nop 0
	global_load_lds_dwordx4 v[72:73], off
	ds_read_b128 v[72:75], v16
	ds_read_b128 v[76:79], v16 offset:2048
	ds_read_b128 v[92:95], v16 offset:4096
	ds_read_b128 v[96:99], v16 offset:6144
	ds_read_b128 v[100:103], v17
	ds_read_b128 v[104:107], v17 offset:2048
	ds_read_b128 v[108:111], v17 offset:4096
	ds_read_b128 v[112:115], v17 offset:6144
	s_waitcnt lgkmcnt(8)
	v_mfma_f32_16x16x32_bf16 v[80:83], v[132:135], v[116:119], v[80:83]
	v_mfma_f32_16x16x32_bf16 v[84:87], v[136:139], v[116:119], v[84:87]
	v_mfma_f32_16x16x32_bf16 v[88:91], v[140:143], v[116:119], v[88:91]
	v_mfma_f32_16x16x32_bf16 v[22:25], v[144:147], v[116:119], v[22:25]
	v_mfma_f32_16x16x32_bf16 v[38:41], v[132:135], v[120:123], v[38:41]
	v_mfma_f32_16x16x32_bf16 v[46:49], v[136:139], v[120:123], v[46:49]
	v_mfma_f32_16x16x32_bf16 v[58:61], v[140:143], v[120:123], v[58:61]
	v_mfma_f32_16x16x32_bf16 v[50:53], v[144:147], v[120:123], v[50:53]
	v_mfma_f32_16x16x32_bf16 v[42:45], v[132:135], v[124:127], v[42:45]
	v_mfma_f32_16x16x32_bf16 v[62:65], v[136:139], v[124:127], v[62:65]
	v_mfma_f32_16x16x32_bf16 v[68:71], v[140:143], v[124:127], v[68:71]
	v_mfma_f32_16x16x32_bf16 v[54:57], v[144:147], v[124:127], v[54:57]
	v_mfma_f32_16x16x32_bf16 v[34:37], v[132:135], v[128:131], v[34:37]
	v_mfma_f32_16x16x32_bf16 v[30:33], v[136:139], v[128:131], v[30:33]
	v_mfma_f32_16x16x32_bf16 v[26:29], v[140:143], v[128:131], v[26:29]
	v_mfma_f32_16x16x32_bf16 v[18:21], v[144:147], v[128:131], v[18:21]
	s_waitcnt vmcnt(6) lgkmcnt(0)
	s_barrier
	ds_read_b128 v[116:119], v8
	ds_read_b128 v[120:123], v8 offset:2048
	ds_read_b128 v[124:127], v8 offset:4096
	ds_read_b128 v[128:131], v8 offset:6144
	ds_read_b128 v[132:135], v9 offset:16384
	ds_read_b128 v[136:139], v9 offset:18432
	ds_read_b128 v[140:143], v9 offset:20480
	ds_read_b128 v[144:147], v9 offset:22528
	v_mfma_f32_16x16x32_bf16 v[80:83], v[100:103], v[72:75], v[80:83]
	v_mfma_f32_16x16x32_bf16 v[84:87], v[104:107], v[72:75], v[84:87]
	v_mfma_f32_16x16x32_bf16 v[88:91], v[108:111], v[72:75], v[88:91]
	v_mfma_f32_16x16x32_bf16 v[22:25], v[112:115], v[72:75], v[22:25]
	v_mfma_f32_16x16x32_bf16 v[38:41], v[100:103], v[76:79], v[38:41]
	v_mfma_f32_16x16x32_bf16 v[46:49], v[104:107], v[76:79], v[46:49]
	v_mfma_f32_16x16x32_bf16 v[58:61], v[108:111], v[76:79], v[58:61]
	v_mfma_f32_16x16x32_bf16 v[50:53], v[112:115], v[76:79], v[50:53]
	v_mfma_f32_16x16x32_bf16 v[42:45], v[100:103], v[92:95], v[42:45]
	v_mfma_f32_16x16x32_bf16 v[62:65], v[104:107], v[92:95], v[62:65]
	v_mfma_f32_16x16x32_bf16 v[68:71], v[108:111], v[92:95], v[68:71]
	v_mfma_f32_16x16x32_bf16 v[54:57], v[112:115], v[92:95], v[54:57]
	v_mfma_f32_16x16x32_bf16 v[34:37], v[100:103], v[96:99], v[34:37]
	v_mfma_f32_16x16x32_bf16 v[30:33], v[104:107], v[96:99], v[30:33]
	v_mfma_f32_16x16x32_bf16 v[26:29], v[108:111], v[96:99], v[26:29]
	v_mfma_f32_16x16x32_bf16 v[18:21], v[112:115], v[96:99], v[18:21]
	s_mov_b32 m0, s69
	v_lshl_add_u64 v[72:73], v[4:5], 0, s[34:35]
	global_load_lds_dwordx4 v[72:73], off
	v_lshl_add_u64 v[72:73], v[6:7], 0, s[34:35]
	s_mov_b32 m0, s70
	s_mov_b64 s[4:5], 0x4000700
	global_load_lds_dwordx4 v[72:73], off
	v_lshl_add_u64 v[72:73], v[2:3], 0, s[4:5]
	s_mov_b32 m0, s71
	s_mov_b64 s[4:5], 0x4020700
	global_load_lds_dwordx4 v[72:73], off
	v_lshl_add_u64 v[72:73], v[2:3], 0, s[4:5]
	s_mov_b32 m0, s72
	s_mov_b64 s[4:5], 0x4040700
	global_load_lds_dwordx4 v[72:73], off
	v_lshl_add_u64 v[72:73], v[2:3], 0, s[4:5]
	s_mov_b32 m0, s73
	s_mov_b64 s[4:5], 0x4060700
	global_load_lds_dwordx4 v[72:73], off
	v_lshl_add_u64 v[72:73], v[2:3], 0, s[4:5]
	s_mov_b32 m0, s74
	v_readlane_b32 s72, v197, 34
	global_load_lds_dwordx4 v[72:73], off
	ds_read_b128 v[72:75], v10
	ds_read_b128 v[76:79], v10 offset:2048
	ds_read_b128 v[92:95], v10 offset:4096
	ds_read_b128 v[96:99], v10 offset:6144
	ds_read_b128 v[100:103], v11 offset:16384
	ds_read_b128 v[104:107], v11 offset:18432
	ds_read_b128 v[108:111], v11 offset:20480
	ds_read_b128 v[112:115], v11 offset:22528
	v_readlane_b32 s73, v197, 35
	v_readlane_b32 s82, v197, 44
	v_readlane_b32 s83, v197, 45
	v_readlane_b32 s84, v197, 46
	v_readlane_b32 s85, v197, 47
	v_readlane_b32 s74, v197, 36
	v_readlane_b32 s75, v197, 37
	v_readlane_b32 s76, v197, 38
	v_readlane_b32 s77, v197, 39
	v_readlane_b32 s78, v197, 40
	v_readlane_b32 s79, v197, 41
	v_readlane_b32 s80, v197, 42
	v_readlane_b32 s81, v197, 43
	v_readlane_b32 s86, v197, 48
	v_readlane_b32 s87, v197, 49
	s_waitcnt lgkmcnt(8)
	v_mfma_f32_16x16x32_bf16 v[80:83], v[132:135], v[116:119], v[80:83]
	v_mfma_f32_16x16x32_bf16 v[84:87], v[136:139], v[116:119], v[84:87]
	v_mfma_f32_16x16x32_bf16 v[88:91], v[140:143], v[116:119], v[88:91]
	v_mfma_f32_16x16x32_bf16 v[22:25], v[144:147], v[116:119], v[22:25]
	v_mfma_f32_16x16x32_bf16 v[38:41], v[132:135], v[120:123], v[38:41]
	v_mfma_f32_16x16x32_bf16 v[46:49], v[136:139], v[120:123], v[46:49]
	v_mfma_f32_16x16x32_bf16 v[58:61], v[140:143], v[120:123], v[58:61]
	v_mfma_f32_16x16x32_bf16 v[50:53], v[144:147], v[120:123], v[50:53]
	v_mfma_f32_16x16x32_bf16 v[42:45], v[132:135], v[124:127], v[42:45]
	v_mfma_f32_16x16x32_bf16 v[62:65], v[136:139], v[124:127], v[62:65]
	v_mfma_f32_16x16x32_bf16 v[68:71], v[140:143], v[124:127], v[68:71]
	v_mfma_f32_16x16x32_bf16 v[54:57], v[144:147], v[124:127], v[54:57]
	v_mfma_f32_16x16x32_bf16 v[34:37], v[132:135], v[128:131], v[34:37]
	v_mfma_f32_16x16x32_bf16 v[30:33], v[136:139], v[128:131], v[30:33]
	v_mfma_f32_16x16x32_bf16 v[26:29], v[140:143], v[128:131], v[26:29]
	v_mfma_f32_16x16x32_bf16 v[18:21], v[144:147], v[128:131], v[18:21]
	s_waitcnt vmcnt(6) lgkmcnt(0)
	s_barrier
	ds_read_b128 v[116:119], v8 offset:49152
	ds_read_b128 v[120:123], v8 offset:51200
	ds_read_b128 v[124:127], v8 offset:53248
	ds_read_b128 v[128:131], v8 offset:55296
	ds_read_b128 v[132:135], v12
	ds_read_b128 v[136:139], v12 offset:2048
	ds_read_b128 v[140:143], v12 offset:4096
	ds_read_b128 v[144:147], v12 offset:6144
	v_mfma_f32_16x16x32_bf16 v[80:83], v[100:103], v[72:75], v[80:83]
	v_mfma_f32_16x16x32_bf16 v[84:87], v[104:107], v[72:75], v[84:87]
	v_mfma_f32_16x16x32_bf16 v[88:91], v[108:111], v[72:75], v[88:91]
	v_mfma_f32_16x16x32_bf16 v[22:25], v[112:115], v[72:75], v[22:25]
	v_mfma_f32_16x16x32_bf16 v[38:41], v[100:103], v[76:79], v[38:41]
	v_mfma_f32_16x16x32_bf16 v[46:49], v[104:107], v[76:79], v[46:49]
	v_mfma_f32_16x16x32_bf16 v[58:61], v[108:111], v[76:79], v[58:61]
	v_mfma_f32_16x16x32_bf16 v[50:53], v[112:115], v[76:79], v[50:53]
	v_mfma_f32_16x16x32_bf16 v[42:45], v[100:103], v[92:95], v[42:45]
	v_mfma_f32_16x16x32_bf16 v[62:65], v[104:107], v[92:95], v[62:65]
	v_mfma_f32_16x16x32_bf16 v[68:71], v[108:111], v[92:95], v[68:71]
	v_mfma_f32_16x16x32_bf16 v[54:57], v[112:115], v[92:95], v[54:57]
	v_mfma_f32_16x16x32_bf16 v[34:37], v[100:103], v[96:99], v[34:37]
	v_mfma_f32_16x16x32_bf16 v[30:33], v[104:107], v[96:99], v[30:33]
	v_mfma_f32_16x16x32_bf16 v[26:29], v[108:111], v[96:99], v[26:29]
	v_mfma_f32_16x16x32_bf16 v[18:21], v[112:115], v[96:99], v[18:21]
	s_mov_b32 m0, s64
	v_lshl_add_u64 v[4:5], v[4:5], 0, s[36:37]
	global_load_lds_dwordx4 v[4:5], off
	v_lshl_add_u64 v[4:5], v[6:7], 0, s[36:37]
	s_mov_b32 m0, s2
	s_mov_b64 s[4:5], 0x4060780
	global_load_lds_dwordx4 v[4:5], off
	v_lshl_add_u64 v[4:5], v[2:3], 0, s[16:17]
	s_mov_b32 m0, s33
	s_nop 0
	global_load_lds_dwordx4 v[4:5], off
	v_lshl_add_u64 v[4:5], v[2:3], 0, s[18:19]
	s_mov_b32 m0, s61
	s_nop 0
	global_load_lds_dwordx4 v[4:5], off
	v_lshl_add_u64 v[4:5], v[2:3], 0, s[20:21]
	s_mov_b32 m0, s62
	v_lshl_add_u64 v[2:3], v[2:3], 0, s[4:5]
	global_load_lds_dwordx4 v[4:5], off
	s_mov_b32 m0, s63
	s_nop 0
	global_load_lds_dwordx4 v[2:3], off
	ds_read_b128 v[2:5], v10 offset:49152
	ds_read_b128 v[72:75], v10 offset:51200
	ds_read_b128 v[76:79], v10 offset:53248
	ds_read_b128 v[92:95], v10 offset:55296
	ds_read_b128 v[96:99], v13
	ds_read_b128 v[100:103], v13 offset:2048
	ds_read_b128 v[104:107], v13 offset:4096
	ds_read_b128 v[108:111], v13 offset:6144
	s_waitcnt lgkmcnt(8)
	v_mfma_f32_16x16x32_bf16 v[80:83], v[132:135], v[116:119], v[80:83]
	v_mfma_f32_16x16x32_bf16 v[84:87], v[136:139], v[116:119], v[84:87]
	v_mfma_f32_16x16x32_bf16 v[88:91], v[140:143], v[116:119], v[88:91]
	v_mfma_f32_16x16x32_bf16 v[22:25], v[144:147], v[116:119], v[22:25]
	v_mfma_f32_16x16x32_bf16 v[38:41], v[132:135], v[120:123], v[38:41]
	v_mfma_f32_16x16x32_bf16 v[46:49], v[136:139], v[120:123], v[46:49]
	v_mfma_f32_16x16x32_bf16 v[58:61], v[140:143], v[120:123], v[58:61]
	v_mfma_f32_16x16x32_bf16 v[50:53], v[144:147], v[120:123], v[50:53]
	v_mfma_f32_16x16x32_bf16 v[42:45], v[132:135], v[124:127], v[42:45]
	v_mfma_f32_16x16x32_bf16 v[62:65], v[136:139], v[124:127], v[62:65]
	v_mfma_f32_16x16x32_bf16 v[68:71], v[140:143], v[124:127], v[68:71]
	v_mfma_f32_16x16x32_bf16 v[54:57], v[144:147], v[124:127], v[54:57]
	v_mfma_f32_16x16x32_bf16 v[34:37], v[132:135], v[128:131], v[34:37]
	v_mfma_f32_16x16x32_bf16 v[30:33], v[136:139], v[128:131], v[30:33]
	v_mfma_f32_16x16x32_bf16 v[26:29], v[140:143], v[128:131], v[26:29]
	v_mfma_f32_16x16x32_bf16 v[18:21], v[144:147], v[128:131], v[18:21]
	s_waitcnt vmcnt(6) lgkmcnt(0)
	s_barrier
	ds_read_b128 v[112:115], v14
	ds_read_b128 v[116:119], v14 offset:2048
	ds_read_b128 v[120:123], v14 offset:4096
	ds_read_b128 v[124:127], v14 offset:6144
	ds_read_b128 v[128:131], v15
	ds_read_b128 v[132:135], v15 offset:2048
	ds_read_b128 v[136:139], v15 offset:4096
	ds_read_b128 v[12:15], v15 offset:6144
	v_mfma_f32_16x16x32_bf16 v[80:83], v[96:99], v[2:5], v[80:83]
	v_mfma_f32_16x16x32_bf16 v[84:87], v[100:103], v[2:5], v[84:87]
	v_mfma_f32_16x16x32_bf16 v[88:91], v[104:107], v[2:5], v[88:91]
	v_mfma_f32_16x16x32_bf16 v[2:5], v[108:111], v[2:5], v[22:25]
	v_mfma_f32_16x16x32_bf16 v[22:25], v[96:99], v[72:75], v[38:41]
	v_mfma_f32_16x16x32_bf16 v[38:41], v[100:103], v[72:75], v[46:49]
	v_mfma_f32_16x16x32_bf16 v[46:49], v[104:107], v[72:75], v[58:61]
	v_mfma_f32_16x16x32_bf16 v[50:53], v[108:111], v[72:75], v[50:53]
	v_mfma_f32_16x16x32_bf16 v[42:45], v[96:99], v[76:79], v[42:45]
	v_mfma_f32_16x16x32_bf16 v[58:61], v[100:103], v[76:79], v[62:65]
	v_mfma_f32_16x16x32_bf16 v[62:65], v[104:107], v[76:79], v[68:71]
	v_mfma_f32_16x16x32_bf16 v[54:57], v[108:111], v[76:79], v[54:57]
	v_mfma_f32_16x16x32_bf16 v[34:37], v[96:99], v[92:95], v[34:37]
	v_mfma_f32_16x16x32_bf16 v[30:33], v[100:103], v[92:95], v[30:33]
	v_mfma_f32_16x16x32_bf16 v[26:29], v[104:107], v[92:95], v[26:29]
	v_mfma_f32_16x16x32_bf16 v[18:21], v[108:111], v[92:95], v[18:21]
	ds_read_b128 v[68:71], v16
	ds_read_b128 v[72:75], v16 offset:2048
	ds_read_b128 v[76:79], v16 offset:4096
	ds_read_b128 v[92:95], v16 offset:6144
	ds_read_b128 v[96:99], v17
	ds_read_b128 v[100:103], v17 offset:2048
	ds_read_b128 v[104:107], v17 offset:4096
	ds_read_b128 v[108:111], v17 offset:6144
	s_waitcnt lgkmcnt(8)
	v_mfma_f32_16x16x32_bf16 v[80:83], v[128:131], v[112:115], v[80:83]
	v_mfma_f32_16x16x32_bf16 v[84:87], v[132:135], v[112:115], v[84:87]
	v_mfma_f32_16x16x32_bf16 v[88:91], v[136:139], v[112:115], v[88:91]
	v_mfma_f32_16x16x32_bf16 v[2:5], v[12:15], v[112:115], v[2:5]
	v_mfma_f32_16x16x32_bf16 v[22:25], v[128:131], v[116:119], v[22:25]
	v_mfma_f32_16x16x32_bf16 v[38:41], v[132:135], v[116:119], v[38:41]
	v_mfma_f32_16x16x32_bf16 v[46:49], v[136:139], v[116:119], v[46:49]
	v_mfma_f32_16x16x32_bf16 v[50:53], v[12:15], v[116:119], v[50:53]
	v_mfma_f32_16x16x32_bf16 v[42:45], v[128:131], v[120:123], v[42:45]
	v_mfma_f32_16x16x32_bf16 v[58:61], v[132:135], v[120:123], v[58:61]
	v_mfma_f32_16x16x32_bf16 v[62:65], v[136:139], v[120:123], v[62:65]
	v_mfma_f32_16x16x32_bf16 v[54:57], v[12:15], v[120:123], v[54:57]
	v_mfma_f32_16x16x32_bf16 v[34:37], v[128:131], v[124:127], v[34:37]
	v_mfma_f32_16x16x32_bf16 v[30:33], v[132:135], v[124:127], v[30:33]
	v_mfma_f32_16x16x32_bf16 v[26:29], v[136:139], v[124:127], v[26:29]
	v_mfma_f32_16x16x32_bf16 v[12:15], v[12:15], v[124:127], v[18:21]
	s_waitcnt vmcnt(0) lgkmcnt(0)
	s_barrier
	s_nop 1
	ds_read_b128 v[16:19], v8
	ds_read_b128 v[112:115], v8 offset:2048
	ds_read_b128 v[116:119], v8 offset:4096
	ds_read_b128 v[120:123], v8 offset:6144
	ds_read_b128 v[124:127], v9 offset:16384
	ds_read_b128 v[128:131], v9 offset:18432
	ds_read_b128 v[132:135], v9 offset:20480
	ds_read_b128 v[6:9], v9 offset:22528
	v_mfma_f32_16x16x32_bf16 v[80:83], v[96:99], v[68:71], v[80:83]
	v_mfma_f32_16x16x32_bf16 v[84:87], v[100:103], v[68:71], v[84:87]
	v_mfma_f32_16x16x32_bf16 v[88:91], v[104:107], v[68:71], v[88:91]
	v_mfma_f32_16x16x32_bf16 v[2:5], v[108:111], v[68:71], v[2:5]
	v_mfma_f32_16x16x32_bf16 v[20:23], v[96:99], v[72:75], v[22:25]
	v_mfma_f32_16x16x32_bf16 v[38:41], v[100:103], v[72:75], v[38:41]
	v_mfma_f32_16x16x32_bf16 v[46:49], v[104:107], v[72:75], v[46:49]
	v_mfma_f32_16x16x32_bf16 v[50:53], v[108:111], v[72:75], v[50:53]
	v_mfma_f32_16x16x32_bf16 v[42:45], v[96:99], v[76:79], v[42:45]
	v_mfma_f32_16x16x32_bf16 v[58:61], v[100:103], v[76:79], v[58:61]
	v_mfma_f32_16x16x32_bf16 v[62:65], v[104:107], v[76:79], v[62:65]
	v_mfma_f32_16x16x32_bf16 v[54:57], v[108:111], v[76:79], v[54:57]
	v_mfma_f32_16x16x32_bf16 v[34:37], v[96:99], v[92:95], v[34:37]
	v_mfma_f32_16x16x32_bf16 v[30:33], v[100:103], v[92:95], v[30:33]
	v_mfma_f32_16x16x32_bf16 v[24:27], v[104:107], v[92:95], v[26:29]
	v_mfma_f32_16x16x32_bf16 v[12:15], v[108:111], v[92:95], v[12:15]
	ds_read_b128 v[68:71], v10
	ds_read_b128 v[72:75], v10 offset:2048
	ds_read_b128 v[76:79], v10 offset:4096
	ds_read_b128 v[92:95], v10 offset:6144
	ds_read_b128 v[96:99], v11 offset:16384
	ds_read_b128 v[100:103], v11 offset:18432
	ds_read_b128 v[104:107], v11 offset:20480
	ds_read_b128 v[108:111], v11 offset:22528
	s_waitcnt lgkmcnt(8)
	v_mfma_f32_16x16x32_bf16 v[80:83], v[124:127], v[16:19], v[80:83]
	v_mfma_f32_16x16x32_bf16 v[84:87], v[128:131], v[16:19], v[84:87]
	v_mfma_f32_16x16x32_bf16 v[88:91], v[132:135], v[16:19], v[88:91]
	v_mfma_f32_16x16x32_bf16 v[2:5], v[6:9], v[16:19], v[2:5]
	v_mfma_f32_16x16x32_bf16 v[16:19], v[124:127], v[112:115], v[20:23]
	v_mfma_f32_16x16x32_bf16 v[20:23], v[128:131], v[112:115], v[38:41]
	v_mfma_f32_16x16x32_bf16 v[38:41], v[132:135], v[112:115], v[46:49]
	v_mfma_f32_16x16x32_bf16 v[112:115], v[6:9], v[112:115], v[50:53]
	v_mfma_f32_16x16x32_bf16 v[136:139], v[124:127], v[116:119], v[42:45]
	v_mfma_f32_16x16x32_bf16 v[140:143], v[128:131], v[116:119], v[58:61]
	v_mfma_f32_16x16x32_bf16 v[144:147], v[132:135], v[116:119], v[62:65]
	v_mfma_f32_16x16x32_bf16 v[116:119], v[6:9], v[116:119], v[54:57]
	v_mfma_f32_16x16x32_bf16 v[124:127], v[124:127], v[120:123], v[34:37]
	v_mfma_f32_16x16x32_bf16 v[128:131], v[128:131], v[120:123], v[30:33]
	v_mfma_f32_16x16x32_bf16 v[132:135], v[132:135], v[120:123], v[24:27]
	v_mfma_f32_16x16x32_bf16 v[120:123], v[6:9], v[120:123], v[12:15]
	s_waitcnt vmcnt(0) lgkmcnt(0)
	s_barrier
	v_mfma_f32_16x16x32_bf16 v[58:61], v[96:99], v[68:71], v[80:83]
	v_mfma_f32_16x16x32_bf16 v[62:65], v[100:103], v[68:71], v[84:87]
	v_mfma_f32_16x16x32_bf16 v[54:57], v[104:107], v[68:71], v[88:91]
	v_mfma_f32_16x16x32_bf16 v[50:53], v[108:111], v[68:71], v[2:5]
	v_mfma_f32_16x16x32_bf16 v[42:45], v[96:99], v[72:75], v[16:19]
	v_mfma_f32_16x16x32_bf16 v[46:49], v[100:103], v[72:75], v[20:23]
	v_mfma_f32_16x16x32_bf16 v[38:41], v[104:107], v[72:75], v[38:41]
	v_mfma_f32_16x16x32_bf16 v[34:37], v[108:111], v[72:75], v[112:115]
	v_mfma_f32_16x16x32_bf16 v[26:29], v[96:99], v[76:79], v[136:139]
	v_mfma_f32_16x16x32_bf16 v[30:33], v[100:103], v[76:79], v[140:143]
	v_mfma_f32_16x16x32_bf16 v[22:25], v[104:107], v[76:79], v[144:147]
	v_mfma_f32_16x16x32_bf16 v[18:21], v[108:111], v[76:79], v[116:119]
	v_mfma_f32_16x16x32_bf16 v[10:13], v[96:99], v[92:95], v[124:127]
	v_mfma_f32_16x16x32_bf16 v[14:17], v[100:103], v[92:95], v[128:131]
	v_mfma_f32_16x16x32_bf16 v[6:9], v[104:107], v[92:95], v[132:135]
	v_mfma_f32_16x16x32_bf16 v[2:5], v[108:111], v[92:95], v[120:123]
	v_ashrrev_i32_e32 v66, 2, v1
	v_and_b32_e32 v66, 0xffffffc0, v66
	v_add_u32_e32 v66, s59, v66
	v_and_or_b32 v68, v1, 15, v66
	v_mul_f32_e32 v66, 0xbfb8aa3b, v58
	v_exp_f32_e32 v72, v66
	v_mul_f32_e32 v66, 0xbfb8aa3b, v59
	v_exp_f32_e32 v73, v66
	s_ashr_i32 s59, s58, 31
	s_lshl_b64 s[4:5], s[58:59], 20
	v_lshrrev_b32_e32 v78, 1, v1
	v_pk_add_f32 v[76:77], v[72:73], 1.0 op_sel_hi:[1,0]
	v_ashrrev_i32_e32 v69, 31, v68
	s_add_u32 s4, s22, s4
	v_and_b32_e32 v66, 0xc0, v1
	v_div_scale_f32 v1, s[58:59], v77, v77, v59
	s_addc_u32 s5, s23, s5
	v_lshlrev_b64 v[70:71], 11, v[68:69]
	v_rcp_f32_e32 v69, v1
	v_lshl_add_u64 v[70:71], s[4:5], 0, v[70:71]
	s_lshl_b32 s2, s60, 8
	v_lshl_add_u64 v[70:71], v[70:71], 0, s[2:3]
	v_lshl_add_u64 v[74:75], v[70:71], 0, v[66:67]
	v_and_b32_e32 v70, 24, v78
	v_mov_b32_e32 v71, v67
	v_lshl_add_u64 v[72:73], v[74:75], 0, v[70:71]
	v_fma_f32 v74, -v1, v69, 1.0
	v_fmac_f32_e32 v69, v74, v69
	v_div_scale_f32 v74, vcc, v59, v77, v59
	v_mul_f32_e32 v75, v74, v69
	v_fma_f32 v78, -v1, v75, v74
	v_fmac_f32_e32 v75, v78, v69
	v_div_scale_f32 v78, s[58:59], v76, v76, v58
	v_rcp_f32_e32 v79, v78
	v_fma_f32 v1, -v1, v75, v74
	v_div_fmas_f32 v1, v1, v69, v75
	v_mul_f32_e32 v74, 0xbfb8aa3b, v60
	v_mul_f32_e32 v75, 0xbfb8aa3b, v61
	v_exp_f32_e32 v74, v74
	v_exp_f32_e32 v75, v75
	v_div_fixup_f32 v59, v1, v77, v59
	v_fma_f32 v1, -v78, v79, 1.0
	v_fmac_f32_e32 v79, v1, v79
	v_div_scale_f32 v1, vcc, v58, v76, v58
	v_mul_f32_e32 v69, v1, v79
	v_fma_f32 v77, -v78, v69, v1
	v_pk_add_f32 v[74:75], v[74:75], 1.0 op_sel_hi:[1,0]
	v_fmac_f32_e32 v69, v77, v79
	v_div_scale_f32 v77, s[58:59], v75, v75, v61
	v_fma_f32 v1, -v78, v69, v1
	v_rcp_f32_e32 v78, v77
	v_div_fmas_f32 v1, v1, v79, v69
	v_div_fixup_f32 v58, v1, v76, v58
	v_pk_mul_f32 v[58:59], v[62:63], v[58:59]
	v_fma_f32 v1, -v77, v78, 1.0
	v_fmac_f32_e32 v78, v1, v78
	v_div_scale_f32 v1, vcc, v61, v75, v61
	v_mul_f32_e32 v62, v1, v78
	v_fma_f32 v63, -v77, v62, v1
	v_fmac_f32_e32 v62, v63, v78
	v_div_scale_f32 v63, s[58:59], v74, v74, v60
	v_rcp_f32_e32 v69, v63
	v_fma_f32 v1, -v77, v62, v1
	v_div_fmas_f32 v1, v1, v78, v62
	v_div_fixup_f32 v61, v1, v75, v61
	v_fma_f32 v1, -v63, v69, 1.0
	v_fmac_f32_e32 v69, v1, v69
	v_div_scale_f32 v1, vcc, v60, v74, v60
	v_mul_f32_e32 v75, v1, v69
	v_fma_f32 v62, -v63, v75, v1
	v_fmac_f32_e32 v75, v62, v69
	v_fma_f32 v1, -v63, v75, v1
	v_mul_f32_e32 v62, 0xbfb8aa3b, v54
	v_mul_f32_e32 v63, 0xbfb8aa3b, v55
	v_exp_f32_e32 v62, v62
	v_exp_f32_e32 v63, v63
	v_div_fmas_f32 v1, v1, v69, v75
	v_div_fixup_f32 v60, v1, v74, v60
	v_pk_mul_f32 v[60:61], v[64:65], v[60:61]
	v_pk_add_f32 v[62:63], v[62:63], 1.0 op_sel_hi:[1,0]
	v_cvt_pk_bf16_f32 v58, v58, v59
	v_div_scale_f32 v1, s[58:59], v63, v63, v55
	v_rcp_f32_e32 v64, v1
	v_cvt_pk_bf16_f32 v59, v60, v61
	s_waitcnt lgkmcnt(0)
	s_barrier
	global_store_dwordx2 v[72:73], v[58:59], off
	v_fma_f32 v58, -v1, v64, 1.0
	v_fmac_f32_e32 v64, v58, v64
	v_div_scale_f32 v58, vcc, v55, v63, v55
	v_mul_f32_e32 v59, v58, v64
	v_fma_f32 v60, -v1, v59, v58
	v_fmac_f32_e32 v59, v60, v64
	v_div_scale_f32 v60, s[58:59], v62, v62, v54
	v_rcp_f32_e32 v61, v60
	v_fma_f32 v1, -v1, v59, v58
	v_div_fmas_f32 v1, v1, v64, v59
	v_mul_f32_e32 v58, 0xbfb8aa3b, v56
	v_mul_f32_e32 v59, 0xbfb8aa3b, v57
	v_div_fixup_f32 v55, v1, v63, v55
	v_fma_f32 v1, -v60, v61, 1.0
	v_exp_f32_e32 v58, v58
	v_exp_f32_e32 v59, v59
	v_fmac_f32_e32 v61, v1, v61
	v_div_scale_f32 v1, vcc, v54, v62, v54
	v_mul_f32_e32 v63, v1, v61
	v_fma_f32 v64, -v60, v63, v1
	v_fmac_f32_e32 v63, v64, v61
	v_pk_add_f32 v[58:59], v[58:59], 1.0 op_sel_hi:[1,0]
	v_fma_f32 v1, -v60, v63, v1
	v_div_scale_f32 v60, s[58:59], v59, v59, v57
	v_rcp_f32_e32 v64, v60
	v_div_fmas_f32 v1, v1, v61, v63
	v_div_fixup_f32 v54, v1, v62, v54
	v_pk_mul_f32 v[50:51], v[50:51], v[54:55]
	v_fma_f32 v1, -v60, v64, 1.0
	v_fmac_f32_e32 v64, v1, v64
	v_div_scale_f32 v1, vcc, v57, v59, v57
	v_mul_f32_e32 v54, v1, v64
	v_fma_f32 v55, -v60, v54, v1
	v_fmac_f32_e32 v54, v55, v64
	v_fma_f32 v1, -v60, v54, v1
	v_div_scale_f32 v60, s[58:59], v58, v58, v56
	v_rcp_f32_e32 v61, v60
	v_div_fmas_f32 v1, v1, v64, v54
	v_div_fixup_f32 v55, v1, v59, v57
	v_cvt_pk_bf16_f32 v50, v50, v51
	v_fma_f32 v1, -v60, v61, 1.0
	v_fmac_f32_e32 v61, v1, v61
	v_div_scale_f32 v1, vcc, v56, v58, v56
	v_mul_f32_e32 v54, v1, v61
	v_fma_f32 v57, -v60, v54, v1
	v_fmac_f32_e32 v54, v57, v61
	v_fma_f32 v1, -v60, v54, v1
	v_div_fmas_f32 v1, v1, v61, v54
	v_div_fixup_f32 v54, v1, v58, v56
	v_pk_mul_f32 v[52:53], v[52:53], v[54:55]
	v_mul_f32_e32 v1, 0xbfb8aa3b, v42
	v_cvt_pk_bf16_f32 v51, v52, v53
	v_exp_f32_e32 v52, v1
	v_mul_f32_e32 v1, 0xbfb8aa3b, v43
	v_exp_f32_e32 v53, v1
	global_store_dwordx2 v[72:73], v[50:51], off offset:32
	v_or_b32_e32 v50, 16, v68
	v_ashrrev_i32_e32 v51, 31, v50
	v_pk_add_f32 v[52:53], v[52:53], 1.0 op_sel_hi:[1,0]
	v_lshlrev_b64 v[50:51], 11, v[50:51]
	v_div_scale_f32 v1, s[58:59], v53, v53, v43
	v_rcp_f32_e32 v54, v1
	v_lshl_add_u64 v[50:51], s[4:5], 0, v[50:51]
	v_lshl_add_u64 v[50:51], v[50:51], 0, s[2:3]
	v_lshl_add_u64 v[50:51], v[50:51], 0, v[66:67]
	v_fma_f32 v55, -v1, v54, 1.0
	v_fmac_f32_e32 v54, v55, v54
	v_div_scale_f32 v55, vcc, v43, v53, v43
	v_mul_f32_e32 v56, v55, v54
	v_fma_f32 v57, -v1, v56, v55
	v_fmac_f32_e32 v56, v57, v54
	v_div_scale_f32 v57, s[58:59], v52, v52, v42
	v_rcp_f32_e32 v58, v57
	v_fma_f32 v1, -v1, v56, v55
	v_div_fmas_f32 v1, v1, v54, v56
	v_mul_f32_e32 v54, 0xbfb8aa3b, v44
	v_mul_f32_e32 v55, 0xbfb8aa3b, v45
	v_exp_f32_e32 v54, v54
	v_exp_f32_e32 v55, v55
	v_div_fixup_f32 v43, v1, v53, v43
	v_fma_f32 v1, -v57, v58, 1.0
	v_fmac_f32_e32 v58, v1, v58
	v_div_scale_f32 v1, vcc, v42, v52, v42
	v_mul_f32_e32 v53, v1, v58
	v_fma_f32 v56, -v57, v53, v1
	v_pk_add_f32 v[54:55], v[54:55], 1.0 op_sel_hi:[1,0]
	v_fmac_f32_e32 v53, v56, v58
	v_div_scale_f32 v56, s[58:59], v55, v55, v45
	v_fma_f32 v1, -v57, v53, v1
	v_rcp_f32_e32 v57, v56
	v_div_fmas_f32 v1, v1, v58, v53
	v_div_fixup_f32 v42, v1, v52, v42
	v_pk_mul_f32 v[42:43], v[46:47], v[42:43]
	v_fma_f32 v1, -v56, v57, 1.0
	v_fmac_f32_e32 v57, v1, v57
	v_div_scale_f32 v1, vcc, v45, v55, v45
	v_mul_f32_e32 v46, v1, v57
	v_fma_f32 v47, -v56, v46, v1
	v_fmac_f32_e32 v46, v47, v57
	v_div_scale_f32 v47, s[58:59], v54, v54, v44
	v_rcp_f32_e32 v52, v47
	v_fma_f32 v1, -v56, v46, v1
	v_div_fmas_f32 v1, v1, v57, v46
	v_div_fixup_f32 v45, v1, v55, v45
	v_fma_f32 v1, -v47, v52, 1.0
	v_fmac_f32_e32 v52, v1, v52
	v_div_scale_f32 v1, vcc, v44, v54, v44
	v_mul_f32_e32 v53, v1, v52
	v_fma_f32 v46, -v47, v53, v1
	v_fmac_f32_e32 v53, v46, v52
	v_fma_f32 v1, -v47, v53, v1
	v_mul_f32_e32 v46, 0xbfb8aa3b, v38
	v_mul_f32_e32 v47, 0xbfb8aa3b, v39
	v_exp_f32_e32 v46, v46
	v_exp_f32_e32 v47, v47
	v_div_fmas_f32 v1, v1, v52, v53
	v_div_fixup_f32 v44, v1, v54, v44
	v_pk_mul_f32 v[44:45], v[48:49], v[44:45]
	v_pk_add_f32 v[46:47], v[46:47], 1.0 op_sel_hi:[1,0]
	v_lshl_add_u64 v[50:51], v[50:51], 0, v[70:71]
	v_div_scale_f32 v1, s[58:59], v47, v47, v39
	v_rcp_f32_e32 v48, v1
	v_cvt_pk_bf16_f32 v42, v42, v43
	v_cvt_pk_bf16_f32 v43, v44, v45
	global_store_dwordx2 v[50:51], v[42:43], off
	v_fma_f32 v42, -v1, v48, 1.0
	v_fmac_f32_e32 v48, v42, v48
	v_div_scale_f32 v42, vcc, v39, v47, v39
	v_mul_f32_e32 v43, v42, v48
	v_fma_f32 v44, -v1, v43, v42
	v_fmac_f32_e32 v43, v44, v48
	v_div_scale_f32 v44, s[58:59], v46, v46, v38
	v_rcp_f32_e32 v45, v44
	v_fma_f32 v1, -v1, v43, v42
	v_div_fmas_f32 v1, v1, v48, v43
	v_mul_f32_e32 v42, 0xbfb8aa3b, v40
	v_mul_f32_e32 v43, 0xbfb8aa3b, v41
	v_div_fixup_f32 v39, v1, v47, v39
	v_fma_f32 v1, -v44, v45, 1.0
	v_exp_f32_e32 v42, v42
	v_exp_f32_e32 v43, v43
	v_fmac_f32_e32 v45, v1, v45
	v_div_scale_f32 v1, vcc, v38, v46, v38
	v_mul_f32_e32 v47, v1, v45
	v_fma_f32 v48, -v44, v47, v1
	v_fmac_f32_e32 v47, v48, v45
	v_pk_add_f32 v[42:43], v[42:43], 1.0 op_sel_hi:[1,0]
	v_fma_f32 v1, -v44, v47, v1
	v_div_scale_f32 v44, s[58:59], v43, v43, v41
	v_rcp_f32_e32 v48, v44
	v_div_fmas_f32 v1, v1, v45, v47
	v_div_fixup_f32 v38, v1, v46, v38
	v_pk_mul_f32 v[34:35], v[34:35], v[38:39]
	v_fma_f32 v1, -v44, v48, 1.0
	v_fmac_f32_e32 v48, v1, v48
	v_div_scale_f32 v1, vcc, v41, v43, v41
	v_mul_f32_e32 v38, v1, v48
	v_fma_f32 v39, -v44, v38, v1
	v_fmac_f32_e32 v38, v39, v48
	v_fma_f32 v1, -v44, v38, v1
	v_div_scale_f32 v44, s[58:59], v42, v42, v40
	v_rcp_f32_e32 v45, v44
	v_div_fmas_f32 v1, v1, v48, v38
	v_div_fixup_f32 v39, v1, v43, v41
	v_cvt_pk_bf16_f32 v34, v34, v35
	v_fma_f32 v1, -v44, v45, 1.0
	v_fmac_f32_e32 v45, v1, v45
	v_div_scale_f32 v1, vcc, v40, v42, v40
	v_mul_f32_e32 v38, v1, v45
	v_fma_f32 v41, -v44, v38, v1
	v_fmac_f32_e32 v38, v41, v45
	v_fma_f32 v1, -v44, v38, v1
	v_div_fmas_f32 v1, v1, v45, v38
	v_div_fixup_f32 v38, v1, v42, v40
	v_pk_mul_f32 v[36:37], v[36:37], v[38:39]
	v_mul_f32_e32 v1, 0xbfb8aa3b, v26
	v_cvt_pk_bf16_f32 v35, v36, v37
	v_exp_f32_e32 v36, v1
	v_mul_f32_e32 v1, 0xbfb8aa3b, v27
	v_exp_f32_e32 v37, v1
	global_store_dwordx2 v[50:51], v[34:35], off offset:32
	v_or_b32_e32 v34, 32, v68
	v_ashrrev_i32_e32 v35, 31, v34
	v_pk_add_f32 v[36:37], v[36:37], 1.0 op_sel_hi:[1,0]
	v_lshlrev_b64 v[34:35], 11, v[34:35]
	v_div_scale_f32 v1, s[58:59], v37, v37, v27
	v_rcp_f32_e32 v38, v1
	v_lshl_add_u64 v[34:35], s[4:5], 0, v[34:35]
	v_lshl_add_u64 v[34:35], v[34:35], 0, s[2:3]
	v_lshl_add_u64 v[34:35], v[34:35], 0, v[66:67]
	v_fma_f32 v39, -v1, v38, 1.0
	v_fmac_f32_e32 v38, v39, v38
	v_div_scale_f32 v39, vcc, v27, v37, v27
	v_mul_f32_e32 v40, v39, v38
	v_fma_f32 v41, -v1, v40, v39
	v_fmac_f32_e32 v40, v41, v38
	v_div_scale_f32 v41, s[58:59], v36, v36, v26
	v_rcp_f32_e32 v42, v41
	v_fma_f32 v1, -v1, v40, v39
	v_div_fmas_f32 v1, v1, v38, v40
	v_mul_f32_e32 v38, 0xbfb8aa3b, v28
	v_mul_f32_e32 v39, 0xbfb8aa3b, v29
	v_exp_f32_e32 v38, v38
	v_exp_f32_e32 v39, v39
	v_div_fixup_f32 v27, v1, v37, v27
	v_fma_f32 v1, -v41, v42, 1.0
	v_fmac_f32_e32 v42, v1, v42
	v_div_scale_f32 v1, vcc, v26, v36, v26
	v_mul_f32_e32 v37, v1, v42
	v_fma_f32 v40, -v41, v37, v1
	v_pk_add_f32 v[38:39], v[38:39], 1.0 op_sel_hi:[1,0]
	v_fmac_f32_e32 v37, v40, v42
	v_div_scale_f32 v40, s[58:59], v39, v39, v29
	v_fma_f32 v1, -v41, v37, v1
	v_rcp_f32_e32 v41, v40
	v_div_fmas_f32 v1, v1, v42, v37
	v_div_fixup_f32 v26, v1, v36, v26
	v_pk_mul_f32 v[26:27], v[30:31], v[26:27]
	v_fma_f32 v1, -v40, v41, 1.0
	v_fmac_f32_e32 v41, v1, v41
	v_div_scale_f32 v1, vcc, v29, v39, v29
	v_mul_f32_e32 v30, v1, v41
	v_fma_f32 v31, -v40, v30, v1
	v_fmac_f32_e32 v30, v31, v41
	v_div_scale_f32 v31, s[58:59], v38, v38, v28
	v_rcp_f32_e32 v36, v31
	v_fma_f32 v1, -v40, v30, v1
	v_div_fmas_f32 v1, v1, v41, v30
	v_div_fixup_f32 v29, v1, v39, v29
	v_fma_f32 v1, -v31, v36, 1.0
	v_fmac_f32_e32 v36, v1, v36
	v_div_scale_f32 v1, vcc, v28, v38, v28
	v_mul_f32_e32 v37, v1, v36
	v_fma_f32 v30, -v31, v37, v1
	v_fmac_f32_e32 v37, v30, v36
	v_fma_f32 v1, -v31, v37, v1
	v_mul_f32_e32 v30, 0xbfb8aa3b, v22
	v_mul_f32_e32 v31, 0xbfb8aa3b, v23
	v_exp_f32_e32 v30, v30
	v_exp_f32_e32 v31, v31
	v_div_fmas_f32 v1, v1, v36, v37
	v_div_fixup_f32 v28, v1, v38, v28
	v_pk_mul_f32 v[28:29], v[32:33], v[28:29]
	v_pk_add_f32 v[30:31], v[30:31], 1.0 op_sel_hi:[1,0]
	v_lshl_add_u64 v[34:35], v[34:35], 0, v[70:71]
	v_div_scale_f32 v1, s[58:59], v31, v31, v23
	v_rcp_f32_e32 v32, v1
	v_cvt_pk_bf16_f32 v26, v26, v27
	v_cvt_pk_bf16_f32 v27, v28, v29
	global_store_dwordx2 v[34:35], v[26:27], off
	v_fma_f32 v26, -v1, v32, 1.0
	v_fmac_f32_e32 v32, v26, v32
	v_div_scale_f32 v26, vcc, v23, v31, v23
	v_mul_f32_e32 v27, v26, v32
	v_fma_f32 v28, -v1, v27, v26
	v_fmac_f32_e32 v27, v28, v32
	v_div_scale_f32 v28, s[58:59], v30, v30, v22
	v_rcp_f32_e32 v29, v28
	v_fma_f32 v1, -v1, v27, v26
	v_div_fmas_f32 v1, v1, v32, v27
	v_mul_f32_e32 v26, 0xbfb8aa3b, v24
	v_mul_f32_e32 v27, 0xbfb8aa3b, v25
	v_div_fixup_f32 v23, v1, v31, v23
	v_fma_f32 v1, -v28, v29, 1.0
	v_exp_f32_e32 v26, v26
	v_exp_f32_e32 v27, v27
	v_fmac_f32_e32 v29, v1, v29
	v_div_scale_f32 v1, vcc, v22, v30, v22
	v_mul_f32_e32 v31, v1, v29
	v_fma_f32 v32, -v28, v31, v1
	v_fmac_f32_e32 v31, v32, v29
	v_pk_add_f32 v[26:27], v[26:27], 1.0 op_sel_hi:[1,0]
	v_fma_f32 v1, -v28, v31, v1
	v_div_scale_f32 v28, s[58:59], v27, v27, v25
	v_rcp_f32_e32 v32, v28
	v_div_fmas_f32 v1, v1, v29, v31
	v_div_fixup_f32 v22, v1, v30, v22
	v_pk_mul_f32 v[18:19], v[18:19], v[22:23]
	v_fma_f32 v1, -v28, v32, 1.0
	v_fmac_f32_e32 v32, v1, v32
	v_div_scale_f32 v1, vcc, v25, v27, v25
	v_mul_f32_e32 v22, v1, v32
	v_fma_f32 v23, -v28, v22, v1
	v_fmac_f32_e32 v22, v23, v32
	v_fma_f32 v1, -v28, v22, v1
	v_div_scale_f32 v28, s[58:59], v26, v26, v24
	v_rcp_f32_e32 v29, v28
	v_div_fmas_f32 v1, v1, v32, v22
	v_div_fixup_f32 v23, v1, v27, v25
	v_cvt_pk_bf16_f32 v18, v18, v19
	v_fma_f32 v1, -v28, v29, 1.0
	v_fmac_f32_e32 v29, v1, v29
	v_div_scale_f32 v1, vcc, v24, v26, v24
	v_mul_f32_e32 v22, v1, v29
	v_fma_f32 v25, -v28, v22, v1
	v_fmac_f32_e32 v22, v25, v29
	v_fma_f32 v1, -v28, v22, v1
	v_div_fmas_f32 v1, v1, v29, v22
	v_div_fixup_f32 v22, v1, v26, v24
	v_pk_mul_f32 v[20:21], v[20:21], v[22:23]
	v_mul_f32_e32 v1, 0xbfb8aa3b, v10
	v_cvt_pk_bf16_f32 v19, v20, v21
	v_exp_f32_e32 v20, v1
	v_mul_f32_e32 v1, 0xbfb8aa3b, v11
	v_exp_f32_e32 v21, v1
	global_store_dwordx2 v[34:35], v[18:19], off offset:32
	v_or_b32_e32 v18, 48, v68
	v_ashrrev_i32_e32 v19, 31, v18
	v_lshlrev_b64 v[18:19], 11, v[18:19]
	v_pk_add_f32 v[20:21], v[20:21], 1.0 op_sel_hi:[1,0]
	v_lshl_add_u64 v[18:19], s[4:5], 0, v[18:19]
	v_div_scale_f32 v1, s[4:5], v21, v21, v11
	v_rcp_f32_e32 v22, v1
	v_lshl_add_u64 v[18:19], v[18:19], 0, s[2:3]
	v_lshl_add_u64 v[18:19], v[18:19], 0, v[66:67]
	v_lshl_add_u64 v[18:19], v[18:19], 0, v[70:71]
	v_fma_f32 v23, -v1, v22, 1.0
	v_fmac_f32_e32 v22, v23, v22
	v_div_scale_f32 v23, vcc, v11, v21, v11
	v_mul_f32_e32 v24, v23, v22
	v_fma_f32 v25, -v1, v24, v23
	v_fmac_f32_e32 v24, v25, v22
	v_div_scale_f32 v25, s[4:5], v20, v20, v10
	v_rcp_f32_e32 v26, v25
	v_fma_f32 v1, -v1, v24, v23
	v_div_fmas_f32 v1, v1, v22, v24
	v_mul_f32_e32 v22, 0xbfb8aa3b, v12
	v_mul_f32_e32 v23, 0xbfb8aa3b, v13
	v_exp_f32_e32 v22, v22
	v_exp_f32_e32 v23, v23
	v_div_fixup_f32 v11, v1, v21, v11
	v_fma_f32 v1, -v25, v26, 1.0
	v_fmac_f32_e32 v26, v1, v26
	v_div_scale_f32 v1, vcc, v10, v20, v10
	v_mul_f32_e32 v21, v1, v26
	v_fma_f32 v24, -v25, v21, v1
	v_pk_add_f32 v[22:23], v[22:23], 1.0 op_sel_hi:[1,0]
	v_fmac_f32_e32 v21, v24, v26
	v_div_scale_f32 v24, s[4:5], v23, v23, v13
	v_fma_f32 v1, -v25, v21, v1
	v_rcp_f32_e32 v25, v24
	v_div_fmas_f32 v1, v1, v26, v21
	v_div_fixup_f32 v10, v1, v20, v10
	v_pk_mul_f32 v[10:11], v[14:15], v[10:11]
	v_fma_f32 v1, -v24, v25, 1.0
	v_fmac_f32_e32 v25, v1, v25
	v_div_scale_f32 v1, vcc, v13, v23, v13
	v_mul_f32_e32 v14, v1, v25
	v_fma_f32 v15, -v24, v14, v1
	v_fmac_f32_e32 v14, v15, v25
	v_div_scale_f32 v15, s[4:5], v22, v22, v12
	v_rcp_f32_e32 v20, v15
	v_fma_f32 v1, -v24, v14, v1
	v_div_fmas_f32 v1, v1, v25, v14
	v_div_fixup_f32 v13, v1, v23, v13
	v_fma_f32 v1, -v15, v20, 1.0
	v_fmac_f32_e32 v20, v1, v20
	v_div_scale_f32 v1, vcc, v12, v22, v12
	v_mul_f32_e32 v21, v1, v20
	v_fma_f32 v14, -v15, v21, v1
	v_fmac_f32_e32 v21, v14, v20
	v_fma_f32 v1, -v15, v21, v1
	v_mul_f32_e32 v14, 0xbfb8aa3b, v6
	v_mul_f32_e32 v15, 0xbfb8aa3b, v7
	v_exp_f32_e32 v14, v14
	v_exp_f32_e32 v15, v15
	v_div_fmas_f32 v1, v1, v20, v21
	v_div_fixup_f32 v12, v1, v22, v12
	v_pk_mul_f32 v[12:13], v[16:17], v[12:13]
	v_pk_add_f32 v[14:15], v[14:15], 1.0 op_sel_hi:[1,0]
	v_cvt_pk_bf16_f32 v10, v10, v11
	v_div_scale_f32 v1, s[4:5], v15, v15, v7
	v_rcp_f32_e32 v16, v1
	v_cvt_pk_bf16_f32 v11, v12, v13
	global_store_dwordx2 v[18:19], v[10:11], off
	s_add_i32 s98, s98, s10
	v_fma_f32 v10, -v1, v16, 1.0
	v_fmac_f32_e32 v16, v10, v16
	v_div_scale_f32 v10, vcc, v7, v15, v7
	v_mul_f32_e32 v11, v10, v16
	v_fma_f32 v12, -v1, v11, v10
	v_fmac_f32_e32 v11, v12, v16
	v_div_scale_f32 v12, s[4:5], v14, v14, v6
	v_rcp_f32_e32 v13, v12
	v_fma_f32 v1, -v1, v11, v10
	v_div_fmas_f32 v1, v1, v16, v11
	v_mul_f32_e32 v10, 0xbfb8aa3b, v8
	v_mul_f32_e32 v11, 0xbfb8aa3b, v9
	v_div_fixup_f32 v7, v1, v15, v7
	v_fma_f32 v1, -v12, v13, 1.0
	v_exp_f32_e32 v10, v10
	v_exp_f32_e32 v11, v11
	v_fmac_f32_e32 v13, v1, v13
	v_div_scale_f32 v1, vcc, v6, v14, v6
	v_mul_f32_e32 v15, v1, v13
	v_fma_f32 v16, -v12, v15, v1
	v_fmac_f32_e32 v15, v16, v13
	v_pk_add_f32 v[10:11], v[10:11], 1.0 op_sel_hi:[1,0]
	v_fma_f32 v1, -v12, v15, v1
	v_div_scale_f32 v12, s[4:5], v11, v11, v9
	v_rcp_f32_e32 v16, v12
	v_div_fmas_f32 v1, v1, v13, v15
	v_div_fixup_f32 v6, v1, v14, v6
	v_pk_mul_f32 v[2:3], v[2:3], v[6:7]
	v_fma_f32 v1, -v12, v16, 1.0
	v_fmac_f32_e32 v16, v1, v16
	v_div_scale_f32 v1, vcc, v9, v11, v9
	v_mul_f32_e32 v6, v1, v16
	v_fma_f32 v7, -v12, v6, v1
	v_fmac_f32_e32 v6, v7, v16
	v_fma_f32 v1, -v12, v6, v1
	v_div_scale_f32 v12, s[4:5], v10, v10, v8
	v_rcp_f32_e32 v13, v12
	v_div_fmas_f32 v1, v1, v16, v6
	v_div_fixup_f32 v7, v1, v11, v9
	s_add_i32 s38, s38, s39
	v_fma_f32 v1, -v12, v13, 1.0
	v_fmac_f32_e32 v13, v1, v13
	v_div_scale_f32 v1, vcc, v8, v10, v8
	v_mul_f32_e32 v6, v1, v13
	v_fma_f32 v9, -v12, v6, v1
	v_fmac_f32_e32 v6, v9, v13
	v_fma_f32 v1, -v12, v6, v1
	v_div_fmas_f32 v1, v1, v13, v6
	v_div_fixup_f32 v6, v1, v10, v8
	v_pk_mul_f32 v[4:5], v[4:5], v[6:7]
	v_cvt_pk_bf16_f32 v2, v2, v3
	v_cvt_pk_bf16_f32 v3, v4, v5
	s_cmpk_lt_i32 s98, 0x800
	global_store_dwordx2 v[18:19], v[2:3], off offset:32
	s_cbranch_scc1 .LBB0_1435
	v_readlane_b32 s0, v197, 18
	v_readlane_b32 s47, v196, 5
	v_readlane_b32 s96, v196, 24
	s_mov_b32 s46, s10
	v_readlane_b32 s1, v197, 19
	v_readlane_b32 s97, v196, 25

.LBB0_1492:
	s_cmpk_gt_i32 s47, 0x3ff
	s_cbranch_scc1 .LBB0_1496
	v_writelane_b32 v197, s2, 18
	v_readlane_b32 s8, v196, 6
	v_readlane_b32 s10, v196, 8
	v_writelane_b32 v197, s3, 19
	v_readlane_b32 s11, v196, 9
	v_readlane_b32 s12, v196, 10
	v_readlane_b32 s13, v196, 11
	v_readlane_b32 s14, v196, 12
	v_readlane_b32 s15, v196, 13
	v_readlane_b32 s16, v196, 14
	v_readlane_b32 s17, v196, 15
	v_readlane_b32 s18, v196, 16
	v_readlane_b32 s19, v196, 17
	v_readlane_b32 s20, v196, 18
	v_readlane_b32 s21, v196, 19
	v_readlane_b32 s72, v197, 34
	s_lshl_b32 s38, s47, 2
	s_lshl_b32 s39, s46, 2
	s_lshl_b32 s56, s47, 4
	s_lshl_b32 s57, s46, 4
	s_lshl_b32 s58, s47, 7
	s_lshl_b32 s59, s46, 7
	v_mov_b32_e32 v3, 0
	s_mov_b64 vcc, 0x2060600
	s_mov_b64 s[2:3], 0x680
	s_mov_b64 s[0:1], 0x20680
	s_mov_b64 s[6:7], 0x2000680
	s_mov_b64 s[24:25], 0x20700
	s_mov_b64 s[26:27], 0x2000700
	s_mov_b64 s[28:29], 0x2020700
	s_mov_b64 s[30:31], 0x2040700
	s_mov_b64 s[34:35], 0x2060700
	s_mov_b64 s[36:37], 0x780
	s_mov_b64 s[40:41], 0x20780
	s_mov_b64 s[42:43], 0x2000780
	s_mov_b32 s97, s47
	s_mov_b64 s[46:47], 0x2020780
	s_mov_b64 s[48:49], 0x2040780
	s_mov_b64 s[52:53], 0x2060780
	v_readlane_b32 s22, v196, 20
	v_readlane_b32 s23, v196, 21
	s_mov_b64 s[20:21], 0x700
	s_mov_b64 s[18:19], 0x2060680
	s_mov_b64 s[16:17], 0x2040680
	s_mov_b64 s[14:15], 0x2020680
	s_mov_b64 s[12:13], 0x2040600
	s_mov_b64 s[10:11], 0x2020600
	v_readlane_b32 s84, v197, 46
	v_readlane_b32 s85, v197, 47
	v_readlane_b32 s9, v196, 7
	v_readlane_b32 s73, v197, 35
	v_readlane_b32 s74, v197, 36
	v_readlane_b32 s75, v197, 37
	v_readlane_b32 s76, v197, 38
	v_readlane_b32 s77, v197, 39
	v_readlane_b32 s78, v197, 40
	v_readlane_b32 s79, v197, 41
	v_readlane_b32 s80, v197, 42
	v_readlane_b32 s81, v197, 43
	v_readlane_b32 s82, v197, 44
	v_readlane_b32 s83, v197, 45
	v_readlane_b32 s86, v197, 48
	v_readlane_b32 s87, v197, 49
	s_mov_b32 s98, s97
.LBB0_1494:
	s_mov_b32 s97, s98
	s_cmp_lg_u32 s39, 0x400
	s_cbranch_scc1 .Lremap_done_16
	s_lshr_b32 s4, s98, 8
	s_bfe_u32 s5, s98, 0x30005
	s_and_b32 s8, s98, 31
	s_lshr_b32 s9, s4, 1
	s_lshl_b32 s9, s9, 3
	s_add_i32 s5, s5, s9
	s_and_b32 s4, s4, 1
	s_lshl_b32 s4, s4, 3
	s_lshr_b32 s60, s8, 2
	s_add_i32 s4, s4, s60
	s_and_b32 s8, s8, 3
	s_lshl_b32 s8, s8, 4
	s_lshl_b32 s5, s5, 6
	s_add_i32 s5, s5, s8
	s_add_i32 s97, s5, s4
.Lremap_done_16:
	s_lshl_b32 s38, s97, 2
	s_lshl_b32 s56, s97, 4
	s_lshl_b32 s58, s97, 7
	s_ashr_i32 s4, s97, 6
	s_and_b32 s5, s38, 48
	s_add_i32 s60, s5, s4
	s_ashr_i32 s5, s4, 31
	s_lshl_b64 s[4:5], s[4:5], 21
	s_and_b32 s33, s56, 0x300
	s_add_u32 s4, s84, s4
	s_addc_u32 s5, s85, s5
	s_lshl_b32 s61, s33, 11
	s_add_u32 s62, s4, s61
	v_mov_b32_e32 v1, v0
	s_addc_u32 s63, s5, 0
	s_ashr_i32 s61, s60, 31
	s_waitcnt vmcnt(0) lgkmcnt(0)
	s_barrier
	s_lshl_b64 s[4:5], s[60:61], 9
	v_ashrrev_i32_e32 v4, 3, v1
	s_and_b32 s60, s58, 0x180
	v_lshrrev_b32_e32 v2, 4, v1
	s_or_b32 s64, s4, s60
	s_mov_b32 s65, s5
	v_ashrrev_i32_e32 v5, 31, v4
	v_xor_b32_e32 v2, v2, v1
	v_lshl_add_u64 v[6:7], s[64:65], 0, v[4:5]
	v_lshlrev_b64 v[6:7], 11, v[6:7]
	v_lshlrev_b32_e32 v2, 4, v2
	v_lshlrev_b64 v[4:5], 11, v[4:5]
	v_lshl_add_u64 v[6:7], s[22:23], 0, v[6:7]
	v_and_b32_e32 v2, 0x70, v2
	v_lshl_add_u64 v[4:5], s[62:63], 0, v[4:5]
	v_lshl_add_u64 v[6:7], v[6:7], 0, v[2:3]
	v_lshl_add_u64 v[4:5], v[4:5], 0, v[2:3]
	v_mov_b32_e32 v2, v0
	s_mov_b64 s[62:63], 0x2000000
	v_readfirstlane_b32 s61, v2
	s_lshl_b32 s61, s61, 4
	v_lshl_add_u64 v[10:11], v[4:5], 0, s[62:63]
	s_mov_b64 s[62:63], 0x2020000
	s_and_b32 s61, s61, 0xfffffc00
	v_lshl_add_u64 v[12:13], v[4:5], 0, s[62:63]
	s_mov_b64 s[62:63], 0x2040000
	s_add_i32 s66, s61, 0
	s_mov_b64 s[64:65], 0x20000
	v_lshl_add_u64 v[14:15], v[4:5], 0, s[62:63]
	s_mov_b64 s[62:63], 0x2060000
	s_mov_b32 m0, s66
	s_add_i32 s61, s66, 0x2000
	v_lshl_add_u64 v[8:9], v[6:7], 0, s[64:65]
	v_lshl_add_u64 v[16:17], v[4:5], 0, s[62:63]
	global_load_lds_dwordx4 v[6:7], off
	s_mov_b32 m0, s61
	s_add_i32 s62, s66, 0x4000
	global_load_lds_dwordx4 v[8:9], off
	s_mov_b32 m0, s62
	s_add_i32 s63, s66, 0x6000
	global_load_lds_dwordx4 v[10:11], off
	s_mov_b32 m0, s63
	s_add_i32 s64, s66, 0x8000
	global_load_lds_dwordx4 v[12:13], off
	s_mov_b32 m0, s64
	s_add_i32 s65, s66, 0xa000
	global_load_lds_dwordx4 v[14:15], off
	s_mov_b32 m0, s65
	s_mov_b64 s[68:69], 0x80
	s_add_i32 s67, s66, 0xc000
	global_load_lds_dwordx4 v[16:17], off
	v_lshl_add_u64 v[8:9], v[6:7], 0, s[68:69]
	s_mov_b32 m0, s67
	s_mov_b64 s[68:69], 0x20080
	global_load_lds_dwordx4 v[8:9], off
	v_lshl_add_u64 v[8:9], v[6:7], 0, s[68:69]
	s_add_i32 s68, s66, 0xe000
	s_mov_b32 m0, s68
	s_mov_b64 s[70:71], 0x2000080
	s_add_i32 s69, s66, 0x10000
	global_load_lds_dwordx4 v[8:9], off
	v_lshl_add_u64 v[8:9], v[4:5], 0, s[70:71]
	s_mov_b32 m0, s69
	s_mov_b64 s[70:71], 0x2020080
	global_load_lds_dwordx4 v[8:9], off
	v_lshl_add_u64 v[8:9], v[4:5], 0, s[70:71]
	s_add_i32 s70, s66, 0x12000
	s_mov_b32 m0, s70
	s_mov_b64 s[72:73], 0x2040080
	s_add_i32 s71, s66, 0x14000
	global_load_lds_dwordx4 v[8:9], off
	v_lshl_add_u64 v[8:9], v[4:5], 0, s[72:73]
	s_mov_b32 m0, s71
	s_mov_b64 s[72:73], 0x2060080
	global_load_lds_dwordx4 v[8:9], off
	v_lshl_add_u64 v[8:9], v[4:5], 0, s[72:73]
	s_add_i32 s72, s66, 0x16000
	s_mov_b32 m0, s72
	v_lshrrev_b32_e32 v18, 4, v2
	v_and_b32_e32 v20, 15, v2
	global_load_lds_dwordx4 v[8:9], off
	v_bfe_u32 v8, v2, 1, 3
	v_lshrrev_b32_e32 v9, 2, v2
	s_mov_b32 s73, 0x1ffffc0
	v_bfe_u32 v19, v2, 4, 2
	v_and_or_b32 v9, v9, s73, v20
	v_lshlrev_b32_e32 v2, 7, v2
	v_bitop3_b32 v10, v18, v8, 3 bitop3:0x6c
	v_lshlrev_b32_e32 v9, 7, v9
	v_and_b32_e32 v60, 0x6780, v2
	v_lshlrev_b32_e32 v10, 4, v10
	v_bitop3_b32 v8, v19, v8, 4 bitop3:0x36
	v_add_u32_e32 v2, 0x4000, v60
	v_or_b32_e32 v144, v10, v9
	v_lshlrev_b32_e32 v61, 4, v8
	v_or_b32_e32 v8, v10, v60
	s_add_i32 s73, s66, 0x18000
	s_mov_b64 s[74:75], 0x100
	s_waitcnt vmcnt(6)
	s_barrier
	v_or_b32_e32 v145, v10, v2
	v_or_b32_e32 v149, v61, v2
	v_add_u32_e32 v2, 0, v144
	v_add_u32_e32 v8, 0, v8
	v_lshl_add_u64 v[10:11], v[6:7], 0, s[74:75]
	s_mov_b32 m0, s73
	s_mov_b64 s[74:75], 0x20100
	ds_read_b128 v[12:15], v2
	ds_read_b128 v[16:19], v2 offset:2048
	ds_read_b128 v[20:23], v2 offset:4096
	ds_read_b128 v[24:27], v2 offset:6144
	ds_read_b128 v[28:31], v8 offset:22528
	ds_read_b128 v[32:35], v8 offset:20480
	ds_read_b128 v[36:39], v8 offset:18432
	ds_read_b128 v[40:43], v8 offset:16384
	global_load_lds_dwordx4 v[10:11], off
	v_lshl_add_u64 v[10:11], v[6:7], 0, s[74:75]
	s_add_i32 s74, s66, 0x1a000
	s_mov_b32 m0, s74
	s_mov_b64 s[76:77], 0x2000100
	s_add_i32 s75, s66, 0x1c000
	global_load_lds_dwordx4 v[10:11], off
	v_lshl_add_u64 v[10:11], v[4:5], 0, s[76:77]
	s_mov_b32 m0, s75
	s_mov_b64 s[76:77], 0x2020100
	global_load_lds_dwordx4 v[10:11], off
	v_lshl_add_u64 v[10:11], v[4:5], 0, s[76:77]
	s_add_i32 s76, s66, 0x1e000
	s_mov_b32 m0, s76
	s_mov_b64 s[78:79], 0x2040100
	s_add_i32 s77, s66, 0x20000
	global_load_lds_dwordx4 v[10:11], off
	v_lshl_add_u64 v[10:11], v[4:5], 0, s[78:79]
	s_mov_b32 m0, s77
	s_mov_b64 s[78:79], 0x2060100
	global_load_lds_dwordx4 v[10:11], off
	v_lshl_add_u64 v[10:11], v[4:5], 0, s[78:79]
	s_add_i32 s78, s66, 0x22000
	s_mov_b32 m0, s78
	v_or_b32_e32 v148, v61, v9
	global_load_lds_dwordx4 v[10:11], off
	v_or_b32_e32 v10, v61, v60
	v_add_u32_e32 v9, 0, v148
	v_add_u32_e32 v10, 0, v10
	ds_read_b128 v[44:47], v9
	ds_read_b128 v[48:51], v9 offset:2048
	ds_read_b128 v[52:55], v9 offset:4096
	ds_read_b128 v[56:59], v9 offset:6144
	ds_read_b128 v[60:63], v10 offset:16384
	ds_read_b128 v[64:67], v10 offset:18432
	ds_read_b128 v[68:71], v10 offset:20480
	ds_read_b128 v[72:75], v10 offset:22528
	s_waitcnt lgkmcnt(8)
	v_mfma_f32_16x16x32_bf16 v[76:79], v[40:43], v[12:15], 0
	v_mfma_f32_16x16x32_bf16 v[80:83], v[36:39], v[12:15], 0
	v_mfma_f32_16x16x32_bf16 v[84:87], v[32:35], v[12:15], 0
	v_mfma_f32_16x16x32_bf16 v[12:15], v[28:31], v[12:15], 0
	v_mfma_f32_16x16x32_bf16 v[88:91], v[40:43], v[16:19], 0
	v_mfma_f32_16x16x32_bf16 v[92:95], v[36:39], v[16:19], 0
	v_mfma_f32_16x16x32_bf16 v[96:99], v[32:35], v[16:19], 0
	v_mfma_f32_16x16x32_bf16 v[16:19], v[28:31], v[16:19], 0
	v_mfma_f32_16x16x32_bf16 v[100:103], v[40:43], v[20:23], 0
	v_mfma_f32_16x16x32_bf16 v[104:107], v[36:39], v[20:23], 0
	v_mfma_f32_16x16x32_bf16 v[108:111], v[32:35], v[20:23], 0
	v_mfma_f32_16x16x32_bf16 v[20:23], v[28:31], v[20:23], 0
	v_mfma_f32_16x16x32_bf16 v[40:43], v[40:43], v[24:27], 0
	v_mfma_f32_16x16x32_bf16 v[36:39], v[36:39], v[24:27], 0
	v_mfma_f32_16x16x32_bf16 v[32:35], v[32:35], v[24:27], 0
	v_mfma_f32_16x16x32_bf16 v[24:27], v[28:31], v[24:27], 0
	s_add_i32 s79, 0, 0xc000
	s_waitcnt vmcnt(6) lgkmcnt(0)
	s_barrier
	v_add_u32_e32 v11, s79, v145
	ds_read_b128 v[28:31], v2 offset:49152
	ds_read_b128 v[112:115], v2 offset:51200
	ds_read_b128 v[116:119], v2 offset:53248
	ds_read_b128 v[120:123], v2 offset:55296
	ds_read_b128 v[124:127], v11
	ds_read_b128 v[128:131], v11 offset:2048
	ds_read_b128 v[132:135], v11 offset:4096
	ds_read_b128 v[136:139], v11 offset:6144
	v_mfma_f32_16x16x32_bf16 v[76:79], v[60:63], v[44:47], v[76:79]
	v_mfma_f32_16x16x32_bf16 v[80:83], v[64:67], v[44:47], v[80:83]
	v_mfma_f32_16x16x32_bf16 v[84:87], v[68:71], v[44:47], v[84:87]
	v_mfma_f32_16x16x32_bf16 v[44:47], v[72:75], v[44:47], v[12:15]
	v_mfma_f32_16x16x32_bf16 v[88:91], v[60:63], v[48:51], v[88:91]
	v_mfma_f32_16x16x32_bf16 v[92:95], v[64:67], v[48:51], v[92:95]
	v_mfma_f32_16x16x32_bf16 v[96:99], v[68:71], v[48:51], v[96:99]
	v_mfma_f32_16x16x32_bf16 v[14:17], v[72:75], v[48:51], v[16:19]
	v_mfma_f32_16x16x32_bf16 v[48:51], v[60:63], v[52:55], v[100:103]
	v_mfma_f32_16x16x32_bf16 v[100:103], v[64:67], v[52:55], v[104:107]
	v_mfma_f32_16x16x32_bf16 v[104:107], v[68:71], v[52:55], v[108:111]
	v_mfma_f32_16x16x32_bf16 v[18:21], v[72:75], v[52:55], v[20:23]
	v_mfma_f32_16x16x32_bf16 v[40:43], v[60:63], v[56:59], v[40:43]
	v_mfma_f32_16x16x32_bf16 v[36:39], v[64:67], v[56:59], v[36:39]
	v_mfma_f32_16x16x32_bf16 v[32:35], v[68:71], v[56:59], v[32:35]
	v_mfma_f32_16x16x32_bf16 v[22:25], v[72:75], v[56:59], v[24:27]
	s_mov_b64 s[80:81], 0x180
	s_mov_b32 m0, s66
	v_lshl_add_u64 v[12:13], v[6:7], 0, s[80:81]
	s_mov_b64 s[80:81], 0x20180
	global_load_lds_dwordx4 v[12:13], off
	v_lshl_add_u64 v[12:13], v[6:7], 0, s[80:81]
	s_mov_b32 m0, s61
	s_mov_b64 s[80:81], 0x2000180
	global_load_lds_dwordx4 v[12:13], off
	v_lshl_add_u64 v[12:13], v[4:5], 0, s[80:81]
	s_mov_b32 m0, s62
	s_mov_b64 s[80:81], 0x2020180
	global_load_lds_dwordx4 v[12:13], off
	v_lshl_add_u64 v[12:13], v[4:5], 0, s[80:81]
	s_mov_b32 m0, s63
	s_mov_b64 s[80:81], 0x2040180
	global_load_lds_dwordx4 v[12:13], off
	v_lshl_add_u64 v[12:13], v[4:5], 0, s[80:81]
	s_mov_b32 m0, s64
	s_mov_b64 s[80:81], 0x2060180
	global_load_lds_dwordx4 v[12:13], off
	v_lshl_add_u64 v[12:13], v[4:5], 0, s[80:81]
	s_mov_b32 m0, s65
	s_nop 0
	global_load_lds_dwordx4 v[12:13], off
	v_add_u32_e32 v12, s79, v149
	ds_read_b128 v[52:55], v9 offset:49152
	ds_read_b128 v[56:59], v9 offset:51200
	ds_read_b128 v[60:63], v9 offset:53248
	ds_read_b128 v[64:67], v9 offset:55296
	ds_read_b128 v[68:71], v12
	ds_read_b128 v[72:75], v12 offset:2048
	ds_read_b128 v[108:111], v12 offset:4096
	ds_read_b128 v[140:143], v12 offset:6144
	s_waitcnt lgkmcnt(8)
	v_mfma_f32_16x16x32_bf16 v[76:79], v[124:127], v[28:31], v[76:79]
	v_mfma_f32_16x16x32_bf16 v[80:83], v[128:131], v[28:31], v[80:83]
	v_mfma_f32_16x16x32_bf16 v[84:87], v[132:135], v[28:31], v[84:87]
	v_mfma_f32_16x16x32_bf16 v[26:29], v[136:139], v[28:31], v[44:47]
	v_mfma_f32_16x16x32_bf16 v[44:47], v[124:127], v[112:115], v[88:91]
	v_mfma_f32_16x16x32_bf16 v[88:91], v[128:131], v[112:115], v[92:95]
	v_mfma_f32_16x16x32_bf16 v[92:95], v[132:135], v[112:115], v[96:99]
	v_mfma_f32_16x16x32_bf16 v[96:99], v[136:139], v[112:115], v[14:17]
	v_mfma_f32_16x16x32_bf16 v[48:51], v[124:127], v[116:119], v[48:51]
	v_mfma_f32_16x16x32_bf16 v[100:103], v[128:131], v[116:119], v[100:103]
	v_mfma_f32_16x16x32_bf16 v[104:107], v[132:135], v[116:119], v[104:107]
	v_mfma_f32_16x16x32_bf16 v[16:19], v[136:139], v[116:119], v[18:21]
	v_mfma_f32_16x16x32_bf16 v[40:43], v[124:127], v[120:123], v[40:43]
	v_mfma_f32_16x16x32_bf16 v[36:39], v[128:131], v[120:123], v[36:39]
	v_mfma_f32_16x16x32_bf16 v[30:33], v[132:135], v[120:123], v[32:35]
	v_mfma_f32_16x16x32_bf16 v[20:23], v[136:139], v[120:123], v[22:25]
	s_add_i32 s79, 0, 0x18000
	s_waitcnt vmcnt(6) lgkmcnt(0)
	s_barrier
	v_add_u32_e32 v13, s79, v144
	v_add_u32_e32 v14, s79, v145
	ds_read_b128 v[112:115], v13
	ds_read_b128 v[116:119], v13 offset:2048
	ds_read_b128 v[120:123], v13 offset:4096
	ds_read_b128 v[124:127], v13 offset:6144
	ds_read_b128 v[128:131], v14
	ds_read_b128 v[132:135], v14 offset:2048
	ds_read_b128 v[136:139], v14 offset:4096
	ds_read_b128 v[144:147], v14 offset:6144
	v_mfma_f32_16x16x32_bf16 v[76:79], v[68:71], v[52:55], v[76:79]
	v_mfma_f32_16x16x32_bf16 v[80:83], v[72:75], v[52:55], v[80:83]
	v_mfma_f32_16x16x32_bf16 v[84:87], v[108:111], v[52:55], v[84:87]
	v_mfma_f32_16x16x32_bf16 v[24:27], v[140:143], v[52:55], v[26:29]
	v_mfma_f32_16x16x32_bf16 v[44:47], v[68:71], v[56:59], v[44:47]
	v_mfma_f32_16x16x32_bf16 v[52:55], v[72:75], v[56:59], v[88:91]
	v_mfma_f32_16x16x32_bf16 v[88:91], v[108:111], v[56:59], v[92:95]
	v_mfma_f32_16x16x32_bf16 v[56:59], v[140:143], v[56:59], v[96:99]
	v_mfma_f32_16x16x32_bf16 v[48:51], v[68:71], v[60:63], v[48:51]
	v_mfma_f32_16x16x32_bf16 v[92:95], v[72:75], v[60:63], v[100:103]
	v_mfma_f32_16x16x32_bf16 v[96:99], v[108:111], v[60:63], v[104:107]
	v_mfma_f32_16x16x32_bf16 v[60:63], v[140:143], v[60:63], v[16:19]
	v_mfma_f32_16x16x32_bf16 v[40:43], v[68:71], v[64:67], v[40:43]
	v_mfma_f32_16x16x32_bf16 v[34:37], v[72:75], v[64:67], v[36:39]
	v_mfma_f32_16x16x32_bf16 v[28:31], v[108:111], v[64:67], v[30:33]
	v_mfma_f32_16x16x32_bf16 v[18:21], v[140:143], v[64:67], v[20:23]
	s_mov_b64 s[80:81], 0x200
	s_mov_b32 m0, s67
	v_lshl_add_u64 v[16:17], v[6:7], 0, s[80:81]
	s_mov_b64 s[80:81], 0x20200
	global_load_lds_dwordx4 v[16:17], off
	v_lshl_add_u64 v[16:17], v[6:7], 0, s[80:81]
	s_mov_b32 m0, s68
	s_mov_b64 s[80:81], 0x2000200
	global_load_lds_dwordx4 v[16:17], off
	v_lshl_add_u64 v[16:17], v[4:5], 0, s[80:81]
	s_mov_b32 m0, s69
	s_mov_b64 s[80:81], 0x2020200
	global_load_lds_dwordx4 v[16:17], off
	v_lshl_add_u64 v[16:17], v[4:5], 0, s[80:81]
	s_mov_b32 m0, s70
	s_mov_b64 s[80:81], 0x2040200
	global_load_lds_dwordx4 v[16:17], off
	v_lshl_add_u64 v[16:17], v[4:5], 0, s[80:81]
	s_mov_b32 m0, s71
	s_mov_b64 s[80:81], 0x2060200
	global_load_lds_dwordx4 v[16:17], off
	v_lshl_add_u64 v[16:17], v[4:5], 0, s[80:81]
	s_mov_b32 m0, s72
	v_add_u32_e32 v15, s79, v148
	global_load_lds_dwordx4 v[16:17], off
	v_add_u32_e32 v16, s79, v149
	ds_read_b128 v[64:67], v15
	ds_read_b128 v[68:71], v15 offset:2048
	ds_read_b128 v[72:75], v15 offset:4096
	ds_read_b128 v[100:103], v15 offset:6144
	ds_read_b128 v[104:107], v16
	ds_read_b128 v[108:111], v16 offset:2048
	ds_read_b128 v[140:143], v16 offset:4096
	ds_read_b128 v[148:151], v16 offset:6144
	s_waitcnt lgkmcnt(8)
	v_mfma_f32_16x16x32_bf16 v[76:79], v[128:131], v[112:115], v[76:79]
	v_mfma_f32_16x16x32_bf16 v[80:83], v[132:135], v[112:115], v[80:83]
	v_mfma_f32_16x16x32_bf16 v[84:87], v[136:139], v[112:115], v[84:87]
	v_mfma_f32_16x16x32_bf16 v[22:25], v[144:147], v[112:115], v[24:27]
	v_mfma_f32_16x16x32_bf16 v[44:47], v[128:131], v[116:119], v[44:47]
	v_mfma_f32_16x16x32_bf16 v[52:55], v[132:135], v[116:119], v[52:55]
	v_mfma_f32_16x16x32_bf16 v[88:91], v[136:139], v[116:119], v[88:91]
	v_mfma_f32_16x16x32_bf16 v[56:59], v[144:147], v[116:119], v[56:59]
	v_mfma_f32_16x16x32_bf16 v[48:51], v[128:131], v[120:123], v[48:51]
	v_mfma_f32_16x16x32_bf16 v[92:95], v[132:135], v[120:123], v[92:95]
	v_mfma_f32_16x16x32_bf16 v[96:99], v[136:139], v[120:123], v[96:99]
	v_mfma_f32_16x16x32_bf16 v[60:63], v[144:147], v[120:123], v[60:63]
	v_mfma_f32_16x16x32_bf16 v[38:41], v[128:131], v[124:127], v[40:43]
	v_mfma_f32_16x16x32_bf16 v[32:35], v[132:135], v[124:127], v[34:37]
	v_mfma_f32_16x16x32_bf16 v[26:29], v[136:139], v[124:127], v[28:31]
	v_mfma_f32_16x16x32_bf16 v[18:21], v[144:147], v[124:127], v[18:21]
	s_waitcnt vmcnt(6) lgkmcnt(0)
	s_barrier
	ds_read_b128 v[112:115], v2
	ds_read_b128 v[116:119], v2 offset:2048
	ds_read_b128 v[120:123], v2 offset:4096
	ds_read_b128 v[124:127], v2 offset:6144
	ds_read_b128 v[128:131], v8 offset:16384
	ds_read_b128 v[132:135], v8 offset:18432
	ds_read_b128 v[136:139], v8 offset:20480
	ds_read_b128 v[144:147], v8 offset:22528
	v_mfma_f32_16x16x32_bf16 v[76:79], v[104:107], v[64:67], v[76:79]
	v_mfma_f32_16x16x32_bf16 v[80:83], v[108:111], v[64:67], v[80:83]
	v_mfma_f32_16x16x32_bf16 v[84:87], v[140:143], v[64:67], v[84:87]
	v_mfma_f32_16x16x32_bf16 v[22:25], v[148:151], v[64:67], v[22:25]
	v_mfma_f32_16x16x32_bf16 v[42:45], v[104:107], v[68:71], v[44:47]
	v_mfma_f32_16x16x32_bf16 v[52:55], v[108:111], v[68:71], v[52:55]
	v_mfma_f32_16x16x32_bf16 v[64:67], v[140:143], v[68:71], v[88:91]
	v_mfma_f32_16x16x32_bf16 v[56:59], v[148:151], v[68:71], v[56:59]
	v_mfma_f32_16x16x32_bf16 v[46:49], v[104:107], v[72:75], v[48:51]
	v_mfma_f32_16x16x32_bf16 v[68:71], v[108:111], v[72:75], v[92:95]
	v_mfma_f32_16x16x32_bf16 v[88:91], v[140:143], v[72:75], v[96:99]
	v_mfma_f32_16x16x32_bf16 v[60:63], v[148:151], v[72:75], v[60:63]
	v_mfma_f32_16x16x32_bf16 v[36:39], v[104:107], v[100:103], v[38:41]
	v_mfma_f32_16x16x32_bf16 v[30:33], v[108:111], v[100:103], v[32:35]
	v_mfma_f32_16x16x32_bf16 v[26:29], v[140:143], v[100:103], v[26:29]
	v_mfma_f32_16x16x32_bf16 v[18:21], v[148:151], v[100:103], v[18:21]
	s_mov_b64 s[80:81], 0x280
	s_mov_b32 m0, s73
	v_lshl_add_u64 v[34:35], v[6:7], 0, s[80:81]
	s_mov_b64 s[80:81], 0x20280
	global_load_lds_dwordx4 v[34:35], off
	v_lshl_add_u64 v[34:35], v[6:7], 0, s[80:81]
	s_mov_b32 m0, s74
	s_mov_b64 s[80:81], 0x2000280
	global_load_lds_dwordx4 v[34:35], off
	v_lshl_add_u64 v[34:35], v[4:5], 0, s[80:81]
	s_mov_b32 m0, s75
	s_mov_b64 s[80:81], 0x2020280
	global_load_lds_dwordx4 v[34:35], off
	v_lshl_add_u64 v[34:35], v[4:5], 0, s[80:81]
	s_mov_b32 m0, s76
	s_mov_b64 s[80:81], 0x2040280
	global_load_lds_dwordx4 v[34:35], off
	v_lshl_add_u64 v[34:35], v[4:5], 0, s[80:81]
	s_mov_b32 m0, s77
	s_mov_b64 s[80:81], 0x2060280
	global_load_lds_dwordx4 v[34:35], off
	v_lshl_add_u64 v[34:35], v[4:5], 0, s[80:81]
	s_mov_b32 m0, s78
	s_nop 0
	global_load_lds_dwordx4 v[34:35], off
	ds_read_b128 v[72:75], v9
	ds_read_b128 v[92:95], v9 offset:2048
	ds_read_b128 v[96:99], v9 offset:4096
	ds_read_b128 v[100:103], v9 offset:6144
	ds_read_b128 v[104:107], v10 offset:16384
	ds_read_b128 v[108:111], v10 offset:18432
	ds_read_b128 v[140:143], v10 offset:20480
	ds_read_b128 v[148:151], v10 offset:22528
	s_waitcnt lgkmcnt(8)
	v_mfma_f32_16x16x32_bf16 v[76:79], v[128:131], v[112:115], v[76:79]
	v_mfma_f32_16x16x32_bf16 v[80:83], v[132:135], v[112:115], v[80:83]
	v_mfma_f32_16x16x32_bf16 v[84:87], v[136:139], v[112:115], v[84:87]
	v_mfma_f32_16x16x32_bf16 v[22:25], v[144:147], v[112:115], v[22:25]
	v_mfma_f32_16x16x32_bf16 v[40:43], v[128:131], v[116:119], v[42:45]
	v_mfma_f32_16x16x32_bf16 v[50:53], v[132:135], v[116:119], v[52:55]
	v_mfma_f32_16x16x32_bf16 v[64:67], v[136:139], v[116:119], v[64:67]
	v_mfma_f32_16x16x32_bf16 v[54:57], v[144:147], v[116:119], v[56:59]
	v_mfma_f32_16x16x32_bf16 v[44:47], v[128:131], v[120:123], v[46:49]
	v_mfma_f32_16x16x32_bf16 v[68:71], v[132:135], v[120:123], v[68:71]
	v_mfma_f32_16x16x32_bf16 v[88:91], v[136:139], v[120:123], v[88:91]
	v_mfma_f32_16x16x32_bf16 v[58:61], v[144:147], v[120:123], v[60:63]
	v_mfma_f32_16x16x32_bf16 v[34:37], v[128:131], v[124:127], v[36:39]
	v_mfma_f32_16x16x32_bf16 v[30:33], v[132:135], v[124:127], v[30:33]
	v_mfma_f32_16x16x32_bf16 v[26:29], v[136:139], v[124:127], v[26:29]
	v_mfma_f32_16x16x32_bf16 v[18:21], v[144:147], v[124:127], v[18:21]
	s_waitcnt vmcnt(6) lgkmcnt(0)
	s_barrier
	ds_read_b128 v[112:115], v2 offset:49152
	ds_read_b128 v[116:119], v2 offset:51200
	ds_read_b128 v[120:123], v2 offset:53248
	ds_read_b128 v[124:127], v2 offset:55296
	ds_read_b128 v[128:131], v11
	ds_read_b128 v[132:135], v11 offset:2048
	ds_read_b128 v[136:139], v11 offset:4096
	ds_read_b128 v[144:147], v11 offset:6144
	v_mfma_f32_16x16x32_bf16 v[76:79], v[104:107], v[72:75], v[76:79]
	v_mfma_f32_16x16x32_bf16 v[80:83], v[108:111], v[72:75], v[80:83]
	v_mfma_f32_16x16x32_bf16 v[84:87], v[140:143], v[72:75], v[84:87]
	v_mfma_f32_16x16x32_bf16 v[22:25], v[148:151], v[72:75], v[22:25]
	v_mfma_f32_16x16x32_bf16 v[38:41], v[104:107], v[92:95], v[40:43]
	v_mfma_f32_16x16x32_bf16 v[48:51], v[108:111], v[92:95], v[50:53]
	v_mfma_f32_16x16x32_bf16 v[62:65], v[140:143], v[92:95], v[64:67]
	v_mfma_f32_16x16x32_bf16 v[52:55], v[148:151], v[92:95], v[54:57]
	v_mfma_f32_16x16x32_bf16 v[42:45], v[104:107], v[96:99], v[44:47]
	v_mfma_f32_16x16x32_bf16 v[66:69], v[108:111], v[96:99], v[68:71]
	v_mfma_f32_16x16x32_bf16 v[70:73], v[140:143], v[96:99], v[88:91]
	v_mfma_f32_16x16x32_bf16 v[56:59], v[148:151], v[96:99], v[58:61]
	v_mfma_f32_16x16x32_bf16 v[34:37], v[104:107], v[100:103], v[34:37]
	v_mfma_f32_16x16x32_bf16 v[30:33], v[108:111], v[100:103], v[30:33]
	v_mfma_f32_16x16x32_bf16 v[26:29], v[140:143], v[100:103], v[26:29]
	v_mfma_f32_16x16x32_bf16 v[18:21], v[148:151], v[100:103], v[18:21]
	s_mov_b64 s[80:81], 0x300
	s_mov_b32 m0, s66
	v_lshl_add_u64 v[46:47], v[6:7], 0, s[80:81]
	s_mov_b64 s[80:81], 0x20300
	global_load_lds_dwordx4 v[46:47], off
	v_lshl_add_u64 v[46:47], v[6:7], 0, s[80:81]
	s_mov_b32 m0, s61
	s_mov_b64 s[80:81], 0x2000300
	global_load_lds_dwordx4 v[46:47], off
	v_lshl_add_u64 v[46:47], v[4:5], 0, s[80:81]
	s_mov_b32 m0, s62
	s_mov_b64 s[80:81], 0x2020300
	global_load_lds_dwordx4 v[46:47], off
	v_lshl_add_u64 v[46:47], v[4:5], 0, s[80:81]
	s_mov_b32 m0, s63
	s_mov_b64 s[80:81], 0x2040300
	global_load_lds_dwordx4 v[46:47], off
	v_lshl_add_u64 v[46:47], v[4:5], 0, s[80:81]
	s_mov_b32 m0, s64
	s_mov_b64 s[80:81], 0x2060300
	global_load_lds_dwordx4 v[46:47], off
	v_lshl_add_u64 v[46:47], v[4:5], 0, s[80:81]
	s_mov_b32 m0, s65
	s_nop 0
	global_load_lds_dwordx4 v[46:47], off
	ds_read_b128 v[88:91], v9 offset:49152
	ds_read_b128 v[92:95], v9 offset:51200
	ds_read_b128 v[96:99], v9 offset:53248
	ds_read_b128 v[100:103], v9 offset:55296
	ds_read_b128 v[104:107], v12
	ds_read_b128 v[108:111], v12 offset:2048
	ds_read_b128 v[140:143], v12 offset:4096
	ds_read_b128 v[148:151], v12 offset:6144
	s_waitcnt lgkmcnt(8)
	v_mfma_f32_16x16x32_bf16 v[74:77], v[128:131], v[112:115], v[76:79]
	v_mfma_f32_16x16x32_bf16 v[78:81], v[132:135], v[112:115], v[80:83]
	v_mfma_f32_16x16x32_bf16 v[82:85], v[136:139], v[112:115], v[84:87]
	v_mfma_f32_16x16x32_bf16 v[22:25], v[144:147], v[112:115], v[22:25]
	v_mfma_f32_16x16x32_bf16 v[38:41], v[128:131], v[116:119], v[38:41]
	v_mfma_f32_16x16x32_bf16 v[46:49], v[132:135], v[116:119], v[48:51]
	v_mfma_f32_16x16x32_bf16 v[60:63], v[136:139], v[116:119], v[62:65]
	v_mfma_f32_16x16x32_bf16 v[50:53], v[144:147], v[116:119], v[52:55]
	v_mfma_f32_16x16x32_bf16 v[42:45], v[128:131], v[120:123], v[42:45]
	v_mfma_f32_16x16x32_bf16 v[64:67], v[132:135], v[120:123], v[66:69]
	v_mfma_f32_16x16x32_bf16 v[68:71], v[136:139], v[120:123], v[70:73]
	v_mfma_f32_16x16x32_bf16 v[54:57], v[144:147], v[120:123], v[56:59]
	v_mfma_f32_16x16x32_bf16 v[34:37], v[128:131], v[124:127], v[34:37]
	v_mfma_f32_16x16x32_bf16 v[30:33], v[132:135], v[124:127], v[30:33]
	v_mfma_f32_16x16x32_bf16 v[26:29], v[136:139], v[124:127], v[26:29]
	v_mfma_f32_16x16x32_bf16 v[18:21], v[144:147], v[124:127], v[18:21]
	s_waitcnt vmcnt(6) lgkmcnt(0)
	s_barrier
	ds_read_b128 v[112:115], v13
	ds_read_b128 v[116:119], v13 offset:2048
	ds_read_b128 v[120:123], v13 offset:4096
	ds_read_b128 v[124:127], v13 offset:6144
	ds_read_b128 v[128:131], v14
	ds_read_b128 v[132:135], v14 offset:2048
	ds_read_b128 v[136:139], v14 offset:4096
	ds_read_b128 v[144:147], v14 offset:6144
	v_mfma_f32_16x16x32_bf16 v[72:75], v[104:107], v[88:91], v[74:77]
	v_mfma_f32_16x16x32_bf16 v[76:79], v[108:111], v[88:91], v[78:81]
	v_mfma_f32_16x16x32_bf16 v[80:83], v[140:143], v[88:91], v[82:85]
	v_mfma_f32_16x16x32_bf16 v[22:25], v[148:151], v[88:91], v[22:25]
	v_mfma_f32_16x16x32_bf16 v[38:41], v[104:107], v[92:95], v[38:41]
	v_mfma_f32_16x16x32_bf16 v[46:49], v[108:111], v[92:95], v[46:49]
	v_mfma_f32_16x16x32_bf16 v[58:61], v[140:143], v[92:95], v[60:63]
	v_mfma_f32_16x16x32_bf16 v[50:53], v[148:151], v[92:95], v[50:53]
	v_mfma_f32_16x16x32_bf16 v[42:45], v[104:107], v[96:99], v[42:45]
	v_mfma_f32_16x16x32_bf16 v[62:65], v[108:111], v[96:99], v[64:67]
	v_mfma_f32_16x16x32_bf16 v[66:69], v[140:143], v[96:99], v[68:71]
	v_mfma_f32_16x16x32_bf16 v[54:57], v[148:151], v[96:99], v[54:57]
	v_mfma_f32_16x16x32_bf16 v[34:37], v[104:107], v[100:103], v[34:37]
	v_mfma_f32_16x16x32_bf16 v[30:33], v[108:111], v[100:103], v[30:33]
	v_mfma_f32_16x16x32_bf16 v[26:29], v[140:143], v[100:103], v[26:29]
	v_mfma_f32_16x16x32_bf16 v[18:21], v[148:151], v[100:103], v[18:21]
	s_mov_b64 s[80:81], 0x380
	s_mov_b32 m0, s67
	v_lshl_add_u64 v[70:71], v[6:7], 0, s[80:81]
	s_mov_b64 s[80:81], 0x20380
	global_load_lds_dwordx4 v[70:71], off
	v_lshl_add_u64 v[70:71], v[6:7], 0, s[80:81]
	s_mov_b32 m0, s68
	s_mov_b64 s[80:81], 0x2000380
	global_load_lds_dwordx4 v[70:71], off
	v_lshl_add_u64 v[70:71], v[4:5], 0, s[80:81]
	s_mov_b32 m0, s69
	s_mov_b64 s[80:81], 0x2020380
	global_load_lds_dwordx4 v[70:71], off
	v_lshl_add_u64 v[70:71], v[4:5], 0, s[80:81]
	s_mov_b32 m0, s70
	s_mov_b64 s[80:81], 0x2040380
	global_load_lds_dwordx4 v[70:71], off
	v_lshl_add_u64 v[70:71], v[4:5], 0, s[80:81]
	s_mov_b32 m0, s71
	s_mov_b64 s[80:81], 0x2060380
	global_load_lds_dwordx4 v[70:71], off
	v_lshl_add_u64 v[70:71], v[4:5], 0, s[80:81]
	s_mov_b32 m0, s72
	s_nop 0
	global_load_lds_dwordx4 v[70:71], off
	ds_read_b128 v[84:87], v15
	ds_read_b128 v[88:91], v15 offset:2048
	ds_read_b128 v[92:95], v15 offset:4096
	ds_read_b128 v[96:99], v15 offset:6144
	ds_read_b128 v[100:103], v16
	ds_read_b128 v[104:107], v16 offset:2048
	ds_read_b128 v[108:111], v16 offset:4096
	ds_read_b128 v[140:143], v16 offset:6144
	s_waitcnt lgkmcnt(8)
	v_mfma_f32_16x16x32_bf16 v[70:73], v[128:131], v[112:115], v[72:75]
	v_mfma_f32_16x16x32_bf16 v[74:77], v[132:135], v[112:115], v[76:79]
	v_mfma_f32_16x16x32_bf16 v[78:81], v[136:139], v[112:115], v[80:83]
	v_mfma_f32_16x16x32_bf16 v[22:25], v[144:147], v[112:115], v[22:25]
	v_mfma_f32_16x16x32_bf16 v[38:41], v[128:131], v[116:119], v[38:41]
	v_mfma_f32_16x16x32_bf16 v[46:49], v[132:135], v[116:119], v[46:49]
	v_mfma_f32_16x16x32_bf16 v[58:61], v[136:139], v[116:119], v[58:61]
	v_mfma_f32_16x16x32_bf16 v[50:53], v[144:147], v[116:119], v[50:53]
	v_mfma_f32_16x16x32_bf16 v[42:45], v[128:131], v[120:123], v[42:45]
	v_mfma_f32_16x16x32_bf16 v[62:65], v[132:135], v[120:123], v[62:65]
	v_mfma_f32_16x16x32_bf16 v[66:69], v[136:139], v[120:123], v[66:69]
	v_mfma_f32_16x16x32_bf16 v[54:57], v[144:147], v[120:123], v[54:57]
	v_mfma_f32_16x16x32_bf16 v[34:37], v[128:131], v[124:127], v[34:37]
	v_mfma_f32_16x16x32_bf16 v[30:33], v[132:135], v[124:127], v[30:33]
	v_mfma_f32_16x16x32_bf16 v[26:29], v[136:139], v[124:127], v[26:29]
	v_mfma_f32_16x16x32_bf16 v[18:21], v[144:147], v[124:127], v[18:21]
	s_waitcnt vmcnt(6) lgkmcnt(0)
	s_barrier
	ds_read_b128 v[112:115], v2
	ds_read_b128 v[116:119], v2 offset:2048
	ds_read_b128 v[120:123], v2 offset:4096
	ds_read_b128 v[124:127], v2 offset:6144
	ds_read_b128 v[128:131], v8 offset:16384
	ds_read_b128 v[132:135], v8 offset:18432
	ds_read_b128 v[136:139], v8 offset:20480
	ds_read_b128 v[144:147], v8 offset:22528
	v_mfma_f32_16x16x32_bf16 v[70:73], v[100:103], v[84:87], v[70:73]
	v_mfma_f32_16x16x32_bf16 v[74:77], v[104:107], v[84:87], v[74:77]
	v_mfma_f32_16x16x32_bf16 v[78:81], v[108:111], v[84:87], v[78:81]
	v_mfma_f32_16x16x32_bf16 v[22:25], v[140:143], v[84:87], v[22:25]
	v_mfma_f32_16x16x32_bf16 v[38:41], v[100:103], v[88:91], v[38:41]
	v_mfma_f32_16x16x32_bf16 v[46:49], v[104:107], v[88:91], v[46:49]
	v_mfma_f32_16x16x32_bf16 v[58:61], v[108:111], v[88:91], v[58:61]
	v_mfma_f32_16x16x32_bf16 v[50:53], v[140:143], v[88:91], v[50:53]
	v_mfma_f32_16x16x32_bf16 v[42:45], v[100:103], v[92:95], v[42:45]
	v_mfma_f32_16x16x32_bf16 v[62:65], v[104:107], v[92:95], v[62:65]
	v_mfma_f32_16x16x32_bf16 v[66:69], v[108:111], v[92:95], v[66:69]
	v_mfma_f32_16x16x32_bf16 v[54:57], v[140:143], v[92:95], v[54:57]
	v_mfma_f32_16x16x32_bf16 v[34:37], v[100:103], v[96:99], v[34:37]
	v_mfma_f32_16x16x32_bf16 v[30:33], v[104:107], v[96:99], v[30:33]
	v_mfma_f32_16x16x32_bf16 v[26:29], v[108:111], v[96:99], v[26:29]
	v_mfma_f32_16x16x32_bf16 v[18:21], v[140:143], v[96:99], v[18:21]
	s_mov_b64 s[80:81], 0x400
	s_mov_b32 m0, s73
	v_lshl_add_u64 v[82:83], v[6:7], 0, s[80:81]
	s_mov_b64 s[80:81], 0x20400
	global_load_lds_dwordx4 v[82:83], off
	v_lshl_add_u64 v[82:83], v[6:7], 0, s[80:81]
	s_mov_b32 m0, s74
	s_mov_b64 s[80:81], 0x2000400
	global_load_lds_dwordx4 v[82:83], off
	v_lshl_add_u64 v[82:83], v[4:5], 0, s[80:81]
	s_mov_b32 m0, s75
	s_mov_b64 s[80:81], 0x2020400
	global_load_lds_dwordx4 v[82:83], off
	v_lshl_add_u64 v[82:83], v[4:5], 0, s[80:81]
	s_mov_b32 m0, s76
	s_mov_b64 s[80:81], 0x2040400
	global_load_lds_dwordx4 v[82:83], off
	v_lshl_add_u64 v[82:83], v[4:5], 0, s[80:81]
	s_mov_b32 m0, s77
	s_mov_b64 s[80:81], 0x2060400
	global_load_lds_dwordx4 v[82:83], off
	v_lshl_add_u64 v[82:83], v[4:5], 0, s[80:81]
	s_mov_b32 m0, s78
	s_nop 0
	global_load_lds_dwordx4 v[82:83], off
	ds_read_b128 v[82:85], v9
	ds_read_b128 v[86:89], v9 offset:2048
	ds_read_b128 v[90:93], v9 offset:4096
	ds_read_b128 v[94:97], v9 offset:6144
	ds_read_b128 v[98:101], v10 offset:16384
	ds_read_b128 v[102:105], v10 offset:18432
	ds_read_b128 v[106:109], v10 offset:20480
	ds_read_b128 v[140:143], v10 offset:22528
	s_waitcnt lgkmcnt(8)
	v_mfma_f32_16x16x32_bf16 v[70:73], v[128:131], v[112:115], v[70:73]
	v_mfma_f32_16x16x32_bf16 v[74:77], v[132:135], v[112:115], v[74:77]
	v_mfma_f32_16x16x32_bf16 v[78:81], v[136:139], v[112:115], v[78:81]
	v_mfma_f32_16x16x32_bf16 v[22:25], v[144:147], v[112:115], v[22:25]
	v_mfma_f32_16x16x32_bf16 v[38:41], v[128:131], v[116:119], v[38:41]
	v_mfma_f32_16x16x32_bf16 v[46:49], v[132:135], v[116:119], v[46:49]
	v_mfma_f32_16x16x32_bf16 v[58:61], v[136:139], v[116:119], v[58:61]
	v_mfma_f32_16x16x32_bf16 v[50:53], v[144:147], v[116:119], v[50:53]
	v_mfma_f32_16x16x32_bf16 v[42:45], v[128:131], v[120:123], v[42:45]
	v_mfma_f32_16x16x32_bf16 v[62:65], v[132:135], v[120:123], v[62:65]
	v_mfma_f32_16x16x32_bf16 v[66:69], v[136:139], v[120:123], v[66:69]
	v_mfma_f32_16x16x32_bf16 v[54:57], v[144:147], v[120:123], v[54:57]
	v_mfma_f32_16x16x32_bf16 v[34:37], v[128:131], v[124:127], v[34:37]
	v_mfma_f32_16x16x32_bf16 v[30:33], v[132:135], v[124:127], v[30:33]
	v_mfma_f32_16x16x32_bf16 v[26:29], v[136:139], v[124:127], v[26:29]
	v_mfma_f32_16x16x32_bf16 v[18:21], v[144:147], v[124:127], v[18:21]
	s_waitcnt vmcnt(6) lgkmcnt(0)
	s_barrier
	ds_read_b128 v[110:113], v2 offset:49152
	ds_read_b128 v[114:117], v2 offset:51200
	ds_read_b128 v[118:121], v2 offset:53248
	ds_read_b128 v[122:125], v2 offset:55296
	ds_read_b128 v[126:129], v11
	ds_read_b128 v[130:133], v11 offset:2048
	ds_read_b128 v[134:137], v11 offset:4096
	ds_read_b128 v[144:147], v11 offset:6144
	v_mfma_f32_16x16x32_bf16 v[70:73], v[98:101], v[82:85], v[70:73]
	v_mfma_f32_16x16x32_bf16 v[74:77], v[102:105], v[82:85], v[74:77]
	v_mfma_f32_16x16x32_bf16 v[78:81], v[106:109], v[82:85], v[78:81]
	v_mfma_f32_16x16x32_bf16 v[22:25], v[140:143], v[82:85], v[22:25]
	v_mfma_f32_16x16x32_bf16 v[38:41], v[98:101], v[86:89], v[38:41]
	v_mfma_f32_16x16x32_bf16 v[46:49], v[102:105], v[86:89], v[46:49]
	v_mfma_f32_16x16x32_bf16 v[58:61], v[106:109], v[86:89], v[58:61]
	v_mfma_f32_16x16x32_bf16 v[50:53], v[140:143], v[86:89], v[50:53]
	v_mfma_f32_16x16x32_bf16 v[42:45], v[98:101], v[90:93], v[42:45]
	v_mfma_f32_16x16x32_bf16 v[62:65], v[102:105], v[90:93], v[62:65]
	v_mfma_f32_16x16x32_bf16 v[66:69], v[106:109], v[90:93], v[66:69]
	v_mfma_f32_16x16x32_bf16 v[54:57], v[140:143], v[90:93], v[54:57]
	v_mfma_f32_16x16x32_bf16 v[34:37], v[98:101], v[94:97], v[34:37]
	v_mfma_f32_16x16x32_bf16 v[30:33], v[102:105], v[94:97], v[30:33]
	v_mfma_f32_16x16x32_bf16 v[26:29], v[106:109], v[94:97], v[26:29]
	v_mfma_f32_16x16x32_bf16 v[18:21], v[140:143], v[94:97], v[18:21]
	s_mov_b64 s[80:81], 0x480
	s_mov_b32 m0, s66
	v_lshl_add_u64 v[82:83], v[6:7], 0, s[80:81]
	s_mov_b64 s[80:81], 0x20480
	global_load_lds_dwordx4 v[82:83], off
	v_lshl_add_u64 v[82:83], v[6:7], 0, s[80:81]
	s_mov_b32 m0, s61
	s_mov_b64 s[80:81], 0x2000480
	global_load_lds_dwordx4 v[82:83], off
	v_lshl_add_u64 v[82:83], v[4:5], 0, s[80:81]
	s_mov_b32 m0, s62
	s_mov_b64 s[80:81], 0x2020480
	global_load_lds_dwordx4 v[82:83], off
	v_lshl_add_u64 v[82:83], v[4:5], 0, s[80:81]
	s_mov_b32 m0, s63
	s_mov_b64 s[80:81], 0x2040480
	global_load_lds_dwordx4 v[82:83], off
	v_lshl_add_u64 v[82:83], v[4:5], 0, s[80:81]
	s_mov_b32 m0, s64
	s_mov_b64 s[80:81], 0x2060480
	global_load_lds_dwordx4 v[82:83], off
	v_lshl_add_u64 v[82:83], v[4:5], 0, s[80:81]
	s_mov_b32 m0, s65
	s_nop 0
	global_load_lds_dwordx4 v[82:83], off
	ds_read_b128 v[82:85], v9 offset:49152
	ds_read_b128 v[86:89], v9 offset:51200
	ds_read_b128 v[90:93], v9 offset:53248
	ds_read_b128 v[94:97], v9 offset:55296
	ds_read_b128 v[98:101], v12
	ds_read_b128 v[102:105], v12 offset:2048
	ds_read_b128 v[106:109], v12 offset:4096
	ds_read_b128 v[138:141], v12 offset:6144
	s_waitcnt lgkmcnt(8)
	v_mfma_f32_16x16x32_bf16 v[70:73], v[126:129], v[110:113], v[70:73]
	v_mfma_f32_16x16x32_bf16 v[74:77], v[130:133], v[110:113], v[74:77]
	v_mfma_f32_16x16x32_bf16 v[78:81], v[134:137], v[110:113], v[78:81]
	v_mfma_f32_16x16x32_bf16 v[22:25], v[144:147], v[110:113], v[22:25]
	v_mfma_f32_16x16x32_bf16 v[38:41], v[126:129], v[114:117], v[38:41]
	v_mfma_f32_16x16x32_bf16 v[46:49], v[130:133], v[114:117], v[46:49]
	v_mfma_f32_16x16x32_bf16 v[58:61], v[134:137], v[114:117], v[58:61]
	v_mfma_f32_16x16x32_bf16 v[50:53], v[144:147], v[114:117], v[50:53]
	v_mfma_f32_16x16x32_bf16 v[42:45], v[126:129], v[118:121], v[42:45]
	v_mfma_f32_16x16x32_bf16 v[62:65], v[130:133], v[118:121], v[62:65]
	v_mfma_f32_16x16x32_bf16 v[66:69], v[134:137], v[118:121], v[66:69]
	v_mfma_f32_16x16x32_bf16 v[54:57], v[144:147], v[118:121], v[54:57]
	v_mfma_f32_16x16x32_bf16 v[34:37], v[126:129], v[122:125], v[34:37]
	v_mfma_f32_16x16x32_bf16 v[30:33], v[130:133], v[122:125], v[30:33]
	v_mfma_f32_16x16x32_bf16 v[26:29], v[134:137], v[122:125], v[26:29]
	v_mfma_f32_16x16x32_bf16 v[18:21], v[144:147], v[122:125], v[18:21]
	s_waitcnt vmcnt(6) lgkmcnt(0)
	s_barrier
	ds_read_b128 v[110:113], v13
	ds_read_b128 v[114:117], v13 offset:2048
	ds_read_b128 v[118:121], v13 offset:4096
	ds_read_b128 v[122:125], v13 offset:6144
	ds_read_b128 v[126:129], v14
	ds_read_b128 v[130:133], v14 offset:2048
	ds_read_b128 v[134:137], v14 offset:4096
	ds_read_b128 v[142:145], v14 offset:6144
	v_mfma_f32_16x16x32_bf16 v[70:73], v[98:101], v[82:85], v[70:73]
	v_mfma_f32_16x16x32_bf16 v[74:77], v[102:105], v[82:85], v[74:77]
	v_mfma_f32_16x16x32_bf16 v[78:81], v[106:109], v[82:85], v[78:81]
	v_mfma_f32_16x16x32_bf16 v[22:25], v[138:141], v[82:85], v[22:25]
	v_mfma_f32_16x16x32_bf16 v[38:41], v[98:101], v[86:89], v[38:41]
	v_mfma_f32_16x16x32_bf16 v[46:49], v[102:105], v[86:89], v[46:49]
	v_mfma_f32_16x16x32_bf16 v[58:61], v[106:109], v[86:89], v[58:61]
	v_mfma_f32_16x16x32_bf16 v[50:53], v[138:141], v[86:89], v[50:53]
	v_mfma_f32_16x16x32_bf16 v[42:45], v[98:101], v[90:93], v[42:45]
	v_mfma_f32_16x16x32_bf16 v[62:65], v[102:105], v[90:93], v[62:65]
	v_mfma_f32_16x16x32_bf16 v[66:69], v[106:109], v[90:93], v[66:69]
	v_mfma_f32_16x16x32_bf16 v[54:57], v[138:141], v[90:93], v[54:57]
	v_mfma_f32_16x16x32_bf16 v[34:37], v[98:101], v[94:97], v[34:37]
	v_mfma_f32_16x16x32_bf16 v[30:33], v[102:105], v[94:97], v[30:33]
	v_mfma_f32_16x16x32_bf16 v[26:29], v[106:109], v[94:97], v[26:29]
	v_mfma_f32_16x16x32_bf16 v[18:21], v[138:141], v[94:97], v[18:21]
	s_mov_b64 s[80:81], 0x500
	s_mov_b32 m0, s67
	v_lshl_add_u64 v[82:83], v[6:7], 0, s[80:81]
	s_mov_b64 s[80:81], 0x20500
	global_load_lds_dwordx4 v[82:83], off
	v_lshl_add_u64 v[82:83], v[6:7], 0, s[80:81]
	s_mov_b32 m0, s68
	s_mov_b64 s[80:81], 0x2000500
	global_load_lds_dwordx4 v[82:83], off
	v_lshl_add_u64 v[82:83], v[4:5], 0, s[80:81]
	s_mov_b32 m0, s69
	s_mov_b64 s[80:81], 0x2020500
	global_load_lds_dwordx4 v[82:83], off
	v_lshl_add_u64 v[82:83], v[4:5], 0, s[80:81]
	s_mov_b32 m0, s70
	s_mov_b64 s[80:81], 0x2040500
	global_load_lds_dwordx4 v[82:83], off
	v_lshl_add_u64 v[82:83], v[4:5], 0, s[80:81]
	s_mov_b32 m0, s71
	s_mov_b64 s[80:81], 0x2060500
	global_load_lds_dwordx4 v[82:83], off
	v_lshl_add_u64 v[82:83], v[4:5], 0, s[80:81]
	s_mov_b32 m0, s72
	s_nop 0
	global_load_lds_dwordx4 v[82:83], off
	ds_read_b128 v[82:85], v15
	ds_read_b128 v[86:89], v15 offset:2048
	ds_read_b128 v[90:93], v15 offset:4096
	ds_read_b128 v[94:97], v15 offset:6144
	ds_read_b128 v[98:101], v16
	ds_read_b128 v[102:105], v16 offset:2048
	ds_read_b128 v[106:109], v16 offset:4096
	ds_read_b128 v[138:141], v16 offset:6144
	s_waitcnt lgkmcnt(8)
	v_mfma_f32_16x16x32_bf16 v[70:73], v[126:129], v[110:113], v[70:73]
	v_mfma_f32_16x16x32_bf16 v[74:77], v[130:133], v[110:113], v[74:77]
	v_mfma_f32_16x16x32_bf16 v[78:81], v[134:137], v[110:113], v[78:81]
	v_mfma_f32_16x16x32_bf16 v[22:25], v[142:145], v[110:113], v[22:25]
	v_mfma_f32_16x16x32_bf16 v[38:41], v[126:129], v[114:117], v[38:41]
	v_mfma_f32_16x16x32_bf16 v[46:49], v[130:133], v[114:117], v[46:49]
	v_mfma_f32_16x16x32_bf16 v[58:61], v[134:137], v[114:117], v[58:61]
	v_mfma_f32_16x16x32_bf16 v[50:53], v[142:145], v[114:117], v[50:53]
	v_mfma_f32_16x16x32_bf16 v[42:45], v[126:129], v[118:121], v[42:45]
	v_mfma_f32_16x16x32_bf16 v[62:65], v[130:133], v[118:121], v[62:65]
	v_mfma_f32_16x16x32_bf16 v[66:69], v[134:137], v[118:121], v[66:69]
	v_mfma_f32_16x16x32_bf16 v[54:57], v[142:145], v[118:121], v[54:57]
	v_mfma_f32_16x16x32_bf16 v[34:37], v[126:129], v[122:125], v[34:37]
	v_mfma_f32_16x16x32_bf16 v[30:33], v[130:133], v[122:125], v[30:33]
	v_mfma_f32_16x16x32_bf16 v[26:29], v[134:137], v[122:125], v[26:29]
	v_mfma_f32_16x16x32_bf16 v[18:21], v[142:145], v[122:125], v[18:21]
	s_waitcnt vmcnt(6) lgkmcnt(0)
	s_barrier
	ds_read_b128 v[110:113], v2
	ds_read_b128 v[114:117], v2 offset:2048
	ds_read_b128 v[118:121], v2 offset:4096
	ds_read_b128 v[122:125], v2 offset:6144
	ds_read_b128 v[126:129], v8 offset:16384
	ds_read_b128 v[130:133], v8 offset:18432
	ds_read_b128 v[134:137], v8 offset:20480
	ds_read_b128 v[142:145], v8 offset:22528
	v_mfma_f32_16x16x32_bf16 v[70:73], v[98:101], v[82:85], v[70:73]
	v_mfma_f32_16x16x32_bf16 v[74:77], v[102:105], v[82:85], v[74:77]
	v_mfma_f32_16x16x32_bf16 v[78:81], v[106:109], v[82:85], v[78:81]
	v_mfma_f32_16x16x32_bf16 v[22:25], v[138:141], v[82:85], v[22:25]
	v_mfma_f32_16x16x32_bf16 v[38:41], v[98:101], v[86:89], v[38:41]
	v_mfma_f32_16x16x32_bf16 v[46:49], v[102:105], v[86:89], v[46:49]
	v_mfma_f32_16x16x32_bf16 v[58:61], v[106:109], v[86:89], v[58:61]
	v_mfma_f32_16x16x32_bf16 v[50:53], v[138:141], v[86:89], v[50:53]
	v_mfma_f32_16x16x32_bf16 v[42:45], v[98:101], v[90:93], v[42:45]
	v_mfma_f32_16x16x32_bf16 v[62:65], v[102:105], v[90:93], v[62:65]
	v_mfma_f32_16x16x32_bf16 v[66:69], v[106:109], v[90:93], v[66:69]
	v_mfma_f32_16x16x32_bf16 v[54:57], v[138:141], v[90:93], v[54:57]
	v_mfma_f32_16x16x32_bf16 v[34:37], v[98:101], v[94:97], v[34:37]
	v_mfma_f32_16x16x32_bf16 v[30:33], v[102:105], v[94:97], v[30:33]
	v_mfma_f32_16x16x32_bf16 v[26:29], v[106:109], v[94:97], v[26:29]
	v_mfma_f32_16x16x32_bf16 v[18:21], v[138:141], v[94:97], v[18:21]
	s_mov_b64 s[80:81], 0x580
	s_mov_b32 m0, s73
	v_lshl_add_u64 v[82:83], v[6:7], 0, s[80:81]
	s_mov_b64 s[80:81], 0x20580
	global_load_lds_dwordx4 v[82:83], off
	v_lshl_add_u64 v[82:83], v[6:7], 0, s[80:81]
	s_mov_b32 m0, s74
	s_mov_b64 s[80:81], 0x2000580
	global_load_lds_dwordx4 v[82:83], off
	v_lshl_add_u64 v[82:83], v[4:5], 0, s[80:81]
	s_mov_b32 m0, s75
	s_mov_b64 s[80:81], 0x2020580
	global_load_lds_dwordx4 v[82:83], off
	v_lshl_add_u64 v[82:83], v[4:5], 0, s[80:81]
	s_mov_b32 m0, s76
	s_mov_b64 s[80:81], 0x2040580
	global_load_lds_dwordx4 v[82:83], off
	v_lshl_add_u64 v[82:83], v[4:5], 0, s[80:81]
	s_mov_b32 m0, s77
	s_mov_b64 s[80:81], 0x2060580
	global_load_lds_dwordx4 v[82:83], off
	v_lshl_add_u64 v[82:83], v[4:5], 0, s[80:81]
	s_mov_b32 m0, s78
	s_nop 0
	global_load_lds_dwordx4 v[82:83], off
	ds_read_b128 v[82:85], v9
	ds_read_b128 v[86:89], v9 offset:2048
	ds_read_b128 v[90:93], v9 offset:4096
	ds_read_b128 v[94:97], v9 offset:6144
	ds_read_b128 v[98:101], v10 offset:16384
	ds_read_b128 v[102:105], v10 offset:18432
	ds_read_b128 v[106:109], v10 offset:20480
	ds_read_b128 v[138:141], v10 offset:22528
	s_waitcnt lgkmcnt(8)
	v_mfma_f32_16x16x32_bf16 v[70:73], v[126:129], v[110:113], v[70:73]
	v_mfma_f32_16x16x32_bf16 v[74:77], v[130:133], v[110:113], v[74:77]
	v_mfma_f32_16x16x32_bf16 v[78:81], v[134:137], v[110:113], v[78:81]
	v_mfma_f32_16x16x32_bf16 v[22:25], v[142:145], v[110:113], v[22:25]
	v_mfma_f32_16x16x32_bf16 v[38:41], v[126:129], v[114:117], v[38:41]
	v_mfma_f32_16x16x32_bf16 v[46:49], v[130:133], v[114:117], v[46:49]
	v_mfma_f32_16x16x32_bf16 v[58:61], v[134:137], v[114:117], v[58:61]
	v_mfma_f32_16x16x32_bf16 v[50:53], v[142:145], v[114:117], v[50:53]
	v_mfma_f32_16x16x32_bf16 v[42:45], v[126:129], v[118:121], v[42:45]
	v_mfma_f32_16x16x32_bf16 v[62:65], v[130:133], v[118:121], v[62:65]
	v_mfma_f32_16x16x32_bf16 v[66:69], v[134:137], v[118:121], v[66:69]
	v_mfma_f32_16x16x32_bf16 v[54:57], v[142:145], v[118:121], v[54:57]
	v_mfma_f32_16x16x32_bf16 v[34:37], v[126:129], v[122:125], v[34:37]
	v_mfma_f32_16x16x32_bf16 v[30:33], v[130:133], v[122:125], v[30:33]
	v_mfma_f32_16x16x32_bf16 v[26:29], v[134:137], v[122:125], v[26:29]
	v_mfma_f32_16x16x32_bf16 v[18:21], v[142:145], v[122:125], v[18:21]
	s_waitcnt vmcnt(6) lgkmcnt(0)
	s_barrier
	ds_read_b128 v[110:113], v2 offset:49152
	ds_read_b128 v[114:117], v2 offset:51200
	ds_read_b128 v[118:121], v2 offset:53248
	ds_read_b128 v[122:125], v2 offset:55296
	ds_read_b128 v[126:129], v11
	ds_read_b128 v[130:133], v11 offset:2048
	ds_read_b128 v[134:137], v11 offset:4096
	ds_read_b128 v[142:145], v11 offset:6144
	v_mfma_f32_16x16x32_bf16 v[70:73], v[98:101], v[82:85], v[70:73]
	v_mfma_f32_16x16x32_bf16 v[74:77], v[102:105], v[82:85], v[74:77]
	v_mfma_f32_16x16x32_bf16 v[78:81], v[106:109], v[82:85], v[78:81]
	v_mfma_f32_16x16x32_bf16 v[22:25], v[138:141], v[82:85], v[22:25]
	v_mfma_f32_16x16x32_bf16 v[38:41], v[98:101], v[86:89], v[38:41]
	v_mfma_f32_16x16x32_bf16 v[46:49], v[102:105], v[86:89], v[46:49]
	v_mfma_f32_16x16x32_bf16 v[58:61], v[106:109], v[86:89], v[58:61]
	v_mfma_f32_16x16x32_bf16 v[50:53], v[138:141], v[86:89], v[50:53]
	v_mfma_f32_16x16x32_bf16 v[42:45], v[98:101], v[90:93], v[42:45]
	v_mfma_f32_16x16x32_bf16 v[62:65], v[102:105], v[90:93], v[62:65]
	v_mfma_f32_16x16x32_bf16 v[66:69], v[106:109], v[90:93], v[66:69]
	v_mfma_f32_16x16x32_bf16 v[54:57], v[138:141], v[90:93], v[54:57]
	v_mfma_f32_16x16x32_bf16 v[34:37], v[98:101], v[94:97], v[34:37]
	v_mfma_f32_16x16x32_bf16 v[30:33], v[102:105], v[94:97], v[30:33]
	v_mfma_f32_16x16x32_bf16 v[26:29], v[106:109], v[94:97], v[26:29]
	v_mfma_f32_16x16x32_bf16 v[18:21], v[138:141], v[94:97], v[18:21]
	s_mov_b64 s[80:81], 0x600
	s_mov_b32 m0, s66
	v_lshl_add_u64 v[82:83], v[6:7], 0, s[80:81]
	s_mov_b64 s[80:81], 0x20600
	global_load_lds_dwordx4 v[82:83], off
	v_lshl_add_u64 v[82:83], v[6:7], 0, s[80:81]
	s_mov_b32 m0, s61
	s_mov_b64 s[80:81], 0x2000600
	global_load_lds_dwordx4 v[82:83], off
	v_lshl_add_u64 v[82:83], v[4:5], 0, s[80:81]
	s_mov_b32 m0, s62
	s_nop 0
	global_load_lds_dwordx4 v[82:83], off
	v_lshl_add_u64 v[82:83], v[4:5], 0, s[10:11]
	s_mov_b32 m0, s63
	s_nop 0
	global_load_lds_dwordx4 v[82:83], off
	v_lshl_add_u64 v[82:83], v[4:5], 0, s[12:13]
	s_mov_b32 m0, s64
	s_nop 0
	global_load_lds_dwordx4 v[82:83], off
	v_lshl_add_u64 v[82:83], v[4:5], 0, vcc
	s_mov_b32 m0, s65
	s_nop 0
	global_load_lds_dwordx4 v[82:83], off
	ds_read_b128 v[82:85], v9 offset:49152
	ds_read_b128 v[86:89], v9 offset:51200
	ds_read_b128 v[90:93], v9 offset:53248
	ds_read_b128 v[94:97], v9 offset:55296
	ds_read_b128 v[98:101], v12
	ds_read_b128 v[102:105], v12 offset:2048
	ds_read_b128 v[106:109], v12 offset:4096
	ds_read_b128 v[138:141], v12 offset:6144
	s_waitcnt lgkmcnt(8)
	v_mfma_f32_16x16x32_bf16 v[70:73], v[126:129], v[110:113], v[70:73]
	v_mfma_f32_16x16x32_bf16 v[74:77], v[130:133], v[110:113], v[74:77]
	v_mfma_f32_16x16x32_bf16 v[78:81], v[134:137], v[110:113], v[78:81]
	v_mfma_f32_16x16x32_bf16 v[22:25], v[142:145], v[110:113], v[22:25]
	v_mfma_f32_16x16x32_bf16 v[38:41], v[126:129], v[114:117], v[38:41]
	v_mfma_f32_16x16x32_bf16 v[46:49], v[130:133], v[114:117], v[46:49]
	v_mfma_f32_16x16x32_bf16 v[58:61], v[134:137], v[114:117], v[58:61]
	v_mfma_f32_16x16x32_bf16 v[50:53], v[142:145], v[114:117], v[50:53]
	v_mfma_f32_16x16x32_bf16 v[42:45], v[126:129], v[118:121], v[42:45]
	v_mfma_f32_16x16x32_bf16 v[62:65], v[130:133], v[118:121], v[62:65]
	v_mfma_f32_16x16x32_bf16 v[66:69], v[134:137], v[118:121], v[66:69]
	v_mfma_f32_16x16x32_bf16 v[54:57], v[142:145], v[118:121], v[54:57]
	v_mfma_f32_16x16x32_bf16 v[34:37], v[126:129], v[122:125], v[34:37]
	v_mfma_f32_16x16x32_bf16 v[30:33], v[130:133], v[122:125], v[30:33]
	v_mfma_f32_16x16x32_bf16 v[26:29], v[134:137], v[122:125], v[26:29]
	v_mfma_f32_16x16x32_bf16 v[18:21], v[142:145], v[122:125], v[18:21]
	s_waitcnt vmcnt(6) lgkmcnt(0)
	s_barrier
	ds_read_b128 v[110:113], v13
	ds_read_b128 v[114:117], v13 offset:2048
	ds_read_b128 v[118:121], v13 offset:4096
	ds_read_b128 v[122:125], v13 offset:6144
	ds_read_b128 v[126:129], v14
	ds_read_b128 v[130:133], v14 offset:2048
	ds_read_b128 v[134:137], v14 offset:4096
	ds_read_b128 v[142:145], v14 offset:6144
	v_mfma_f32_16x16x32_bf16 v[70:73], v[98:101], v[82:85], v[70:73]
	v_mfma_f32_16x16x32_bf16 v[74:77], v[102:105], v[82:85], v[74:77]
	v_mfma_f32_16x16x32_bf16 v[78:81], v[106:109], v[82:85], v[78:81]
	v_mfma_f32_16x16x32_bf16 v[22:25], v[138:141], v[82:85], v[22:25]
	v_mfma_f32_16x16x32_bf16 v[38:41], v[98:101], v[86:89], v[38:41]
	v_mfma_f32_16x16x32_bf16 v[46:49], v[102:105], v[86:89], v[46:49]
	v_mfma_f32_16x16x32_bf16 v[58:61], v[106:109], v[86:89], v[58:61]
	v_mfma_f32_16x16x32_bf16 v[50:53], v[138:141], v[86:89], v[50:53]
	v_mfma_f32_16x16x32_bf16 v[42:45], v[98:101], v[90:93], v[42:45]
	v_mfma_f32_16x16x32_bf16 v[62:65], v[102:105], v[90:93], v[62:65]
	v_mfma_f32_16x16x32_bf16 v[66:69], v[106:109], v[90:93], v[66:69]
	v_mfma_f32_16x16x32_bf16 v[54:57], v[138:141], v[90:93], v[54:57]
	v_mfma_f32_16x16x32_bf16 v[34:37], v[98:101], v[94:97], v[34:37]
	v_mfma_f32_16x16x32_bf16 v[30:33], v[102:105], v[94:97], v[30:33]
	v_mfma_f32_16x16x32_bf16 v[26:29], v[106:109], v[94:97], v[26:29]
	v_mfma_f32_16x16x32_bf16 v[18:21], v[138:141], v[94:97], v[18:21]
	s_mov_b32 m0, s67
	v_lshl_add_u64 v[82:83], v[6:7], 0, s[2:3]
	global_load_lds_dwordx4 v[82:83], off
	v_lshl_add_u64 v[82:83], v[6:7], 0, s[0:1]
	s_mov_b32 m0, s68
	s_nop 0
	global_load_lds_dwordx4 v[82:83], off
	v_lshl_add_u64 v[82:83], v[4:5], 0, s[6:7]
	s_mov_b32 m0, s69
	s_nop 0
	global_load_lds_dwordx4 v[82:83], off
	v_lshl_add_u64 v[82:83], v[4:5], 0, s[14:15]
	s_mov_b32 m0, s70
	s_nop 0
	global_load_lds_dwordx4 v[82:83], off
	v_lshl_add_u64 v[82:83], v[4:5], 0, s[16:17]
	s_mov_b32 m0, s71
	s_nop 0
	global_load_lds_dwordx4 v[82:83], off
	v_lshl_add_u64 v[82:83], v[4:5], 0, s[18:19]
	s_mov_b32 m0, s72
	s_nop 0
	global_load_lds_dwordx4 v[82:83], off
	ds_read_b128 v[82:85], v15
	ds_read_b128 v[86:89], v15 offset:2048
	ds_read_b128 v[90:93], v15 offset:4096
	ds_read_b128 v[94:97], v15 offset:6144
	ds_read_b128 v[98:101], v16
	ds_read_b128 v[102:105], v16 offset:2048
	ds_read_b128 v[106:109], v16 offset:4096
	ds_read_b128 v[138:141], v16 offset:6144
	s_waitcnt lgkmcnt(8)
	v_mfma_f32_16x16x32_bf16 v[70:73], v[126:129], v[110:113], v[70:73]
	v_mfma_f32_16x16x32_bf16 v[74:77], v[130:133], v[110:113], v[74:77]
	v_mfma_f32_16x16x32_bf16 v[78:81], v[134:137], v[110:113], v[78:81]
	v_mfma_f32_16x16x32_bf16 v[22:25], v[142:145], v[110:113], v[22:25]
	v_mfma_f32_16x16x32_bf16 v[38:41], v[126:129], v[114:117], v[38:41]
	v_mfma_f32_16x16x32_bf16 v[46:49], v[130:133], v[114:117], v[46:49]
	v_mfma_f32_16x16x32_bf16 v[58:61], v[134:137], v[114:117], v[58:61]
	v_mfma_f32_16x16x32_bf16 v[50:53], v[142:145], v[114:117], v[50:53]
	v_mfma_f32_16x16x32_bf16 v[42:45], v[126:129], v[118:121], v[42:45]
	v_mfma_f32_16x16x32_bf16 v[62:65], v[130:133], v[118:121], v[62:65]
	v_mfma_f32_16x16x32_bf16 v[66:69], v[134:137], v[118:121], v[66:69]
	v_mfma_f32_16x16x32_bf16 v[54:57], v[142:145], v[118:121], v[54:57]
	v_mfma_f32_16x16x32_bf16 v[34:37], v[126:129], v[122:125], v[34:37]
	v_mfma_f32_16x16x32_bf16 v[30:33], v[130:133], v[122:125], v[30:33]
	v_mfma_f32_16x16x32_bf16 v[26:29], v[134:137], v[122:125], v[26:29]
	v_mfma_f32_16x16x32_bf16 v[18:21], v[142:145], v[122:125], v[18:21]
	s_waitcnt vmcnt(6) lgkmcnt(0)
	s_barrier
	ds_read_b128 v[110:113], v2
	ds_read_b128 v[114:117], v2 offset:2048
	ds_read_b128 v[118:121], v2 offset:4096
	ds_read_b128 v[122:125], v2 offset:6144
	ds_read_b128 v[126:129], v8 offset:16384
	ds_read_b128 v[130:133], v8 offset:18432
	ds_read_b128 v[134:137], v8 offset:20480
	ds_read_b128 v[142:145], v8 offset:22528
	v_mfma_f32_16x16x32_bf16 v[70:73], v[98:101], v[82:85], v[70:73]
	v_mfma_f32_16x16x32_bf16 v[74:77], v[102:105], v[82:85], v[74:77]
	v_mfma_f32_16x16x32_bf16 v[78:81], v[106:109], v[82:85], v[78:81]
	v_mfma_f32_16x16x32_bf16 v[22:25], v[138:141], v[82:85], v[22:25]
	v_mfma_f32_16x16x32_bf16 v[38:41], v[98:101], v[86:89], v[38:41]
	v_mfma_f32_16x16x32_bf16 v[46:49], v[102:105], v[86:89], v[46:49]
	v_mfma_f32_16x16x32_bf16 v[58:61], v[106:109], v[86:89], v[58:61]
	v_mfma_f32_16x16x32_bf16 v[50:53], v[138:141], v[86:89], v[50:53]
	v_mfma_f32_16x16x32_bf16 v[42:45], v[98:101], v[90:93], v[42:45]
	v_mfma_f32_16x16x32_bf16 v[62:65], v[102:105], v[90:93], v[62:65]
	v_mfma_f32_16x16x32_bf16 v[66:69], v[106:109], v[90:93], v[66:69]
	v_mfma_f32_16x16x32_bf16 v[54:57], v[138:141], v[90:93], v[54:57]
	v_mfma_f32_16x16x32_bf16 v[34:37], v[98:101], v[94:97], v[34:37]
	v_mfma_f32_16x16x32_bf16 v[30:33], v[102:105], v[94:97], v[30:33]
	v_mfma_f32_16x16x32_bf16 v[26:29], v[106:109], v[94:97], v[26:29]
	v_mfma_f32_16x16x32_bf16 v[18:21], v[138:141], v[94:97], v[18:21]
	s_mov_b32 m0, s73
	v_lshl_add_u64 v[82:83], v[6:7], 0, s[20:21]
	global_load_lds_dwordx4 v[82:83], off
	v_lshl_add_u64 v[82:83], v[6:7], 0, s[24:25]
	s_mov_b32 m0, s74
	s_nop 0
	global_load_lds_dwordx4 v[82:83], off
	v_lshl_add_u64 v[82:83], v[4:5], 0, s[26:27]
	s_mov_b32 m0, s75
	s_nop 0
	global_load_lds_dwordx4 v[82:83], off
	v_lshl_add_u64 v[82:83], v[4:5], 0, s[28:29]
	s_mov_b32 m0, s76
	s_nop 0
	global_load_lds_dwordx4 v[82:83], off
	v_lshl_add_u64 v[82:83], v[4:5], 0, s[30:31]
	s_mov_b32 m0, s77
	s_nop 0
	global_load_lds_dwordx4 v[82:83], off
	v_lshl_add_u64 v[82:83], v[4:5], 0, s[34:35]
	s_mov_b32 m0, s78
	v_readlane_b32 s72, v197, 34
	global_load_lds_dwordx4 v[82:83], off
	ds_read_b128 v[82:85], v9
	ds_read_b128 v[86:89], v9 offset:2048
	ds_read_b128 v[90:93], v9 offset:4096
	ds_read_b128 v[94:97], v9 offset:6144
	ds_read_b128 v[98:101], v10 offset:16384
	ds_read_b128 v[102:105], v10 offset:18432
	ds_read_b128 v[106:109], v10 offset:20480
	ds_read_b128 v[138:141], v10 offset:22528
	v_readlane_b32 s84, v197, 46
	v_readlane_b32 s85, v197, 47
	v_readlane_b32 s73, v197, 35
	v_readlane_b32 s74, v197, 36
	v_readlane_b32 s75, v197, 37
	v_readlane_b32 s76, v197, 38
	v_readlane_b32 s77, v197, 39
	v_readlane_b32 s78, v197, 40
	v_readlane_b32 s79, v197, 41
	v_readlane_b32 s80, v197, 42
	v_readlane_b32 s81, v197, 43
	v_readlane_b32 s82, v197, 44
	v_readlane_b32 s83, v197, 45
	v_readlane_b32 s86, v197, 48
	v_readlane_b32 s87, v197, 49
	s_waitcnt lgkmcnt(8)
	v_mfma_f32_16x16x32_bf16 v[70:73], v[126:129], v[110:113], v[70:73]
	v_mfma_f32_16x16x32_bf16 v[74:77], v[130:133], v[110:113], v[74:77]
	v_mfma_f32_16x16x32_bf16 v[78:81], v[134:137], v[110:113], v[78:81]
	v_mfma_f32_16x16x32_bf16 v[22:25], v[142:145], v[110:113], v[22:25]
	v_mfma_f32_16x16x32_bf16 v[38:41], v[126:129], v[114:117], v[38:41]
	v_mfma_f32_16x16x32_bf16 v[46:49], v[130:133], v[114:117], v[46:49]
	v_mfma_f32_16x16x32_bf16 v[58:61], v[134:137], v[114:117], v[58:61]
	v_mfma_f32_16x16x32_bf16 v[50:53], v[142:145], v[114:117], v[50:53]
	v_mfma_f32_16x16x32_bf16 v[42:45], v[126:129], v[118:121], v[42:45]
	v_mfma_f32_16x16x32_bf16 v[62:65], v[130:133], v[118:121], v[62:65]
	v_mfma_f32_16x16x32_bf16 v[66:69], v[134:137], v[118:121], v[66:69]
	v_mfma_f32_16x16x32_bf16 v[54:57], v[142:145], v[118:121], v[54:57]
	v_mfma_f32_16x16x32_bf16 v[34:37], v[126:129], v[122:125], v[34:37]
	v_mfma_f32_16x16x32_bf16 v[30:33], v[130:133], v[122:125], v[30:33]
	v_mfma_f32_16x16x32_bf16 v[26:29], v[134:137], v[122:125], v[26:29]
	v_mfma_f32_16x16x32_bf16 v[18:21], v[142:145], v[122:125], v[18:21]
	s_waitcnt vmcnt(6) lgkmcnt(0)
	s_barrier
	ds_read_b128 v[110:113], v2 offset:49152
	ds_read_b128 v[114:117], v2 offset:51200
	ds_read_b128 v[118:121], v2 offset:53248
	ds_read_b128 v[122:125], v2 offset:55296
	ds_read_b128 v[126:129], v11
	ds_read_b128 v[130:133], v11 offset:2048
	ds_read_b128 v[134:137], v11 offset:4096
	ds_read_b128 v[142:145], v11 offset:6144
	v_mfma_f32_16x16x32_bf16 v[70:73], v[98:101], v[82:85], v[70:73]
	v_mfma_f32_16x16x32_bf16 v[74:77], v[102:105], v[82:85], v[74:77]
	v_mfma_f32_16x16x32_bf16 v[78:81], v[106:109], v[82:85], v[78:81]
	v_mfma_f32_16x16x32_bf16 v[22:25], v[138:141], v[82:85], v[22:25]
	v_mfma_f32_16x16x32_bf16 v[38:41], v[98:101], v[86:89], v[38:41]
	v_mfma_f32_16x16x32_bf16 v[46:49], v[102:105], v[86:89], v[46:49]
	v_mfma_f32_16x16x32_bf16 v[58:61], v[106:109], v[86:89], v[58:61]
	v_mfma_f32_16x16x32_bf16 v[50:53], v[138:141], v[86:89], v[50:53]
	v_mfma_f32_16x16x32_bf16 v[42:45], v[98:101], v[90:93], v[42:45]
	v_mfma_f32_16x16x32_bf16 v[62:65], v[102:105], v[90:93], v[62:65]
	v_mfma_f32_16x16x32_bf16 v[66:69], v[106:109], v[90:93], v[66:69]
	v_mfma_f32_16x16x32_bf16 v[54:57], v[138:141], v[90:93], v[54:57]
	v_mfma_f32_16x16x32_bf16 v[34:37], v[98:101], v[94:97], v[34:37]
	v_mfma_f32_16x16x32_bf16 v[30:33], v[102:105], v[94:97], v[30:33]
	v_mfma_f32_16x16x32_bf16 v[26:29], v[106:109], v[94:97], v[26:29]
	v_mfma_f32_16x16x32_bf16 v[18:21], v[138:141], v[94:97], v[18:21]
	s_mov_b32 m0, s66
	v_lshl_add_u64 v[82:83], v[6:7], 0, s[36:37]
	global_load_lds_dwordx4 v[82:83], off
	v_lshl_add_u64 v[6:7], v[6:7], 0, s[40:41]
	s_mov_b32 m0, s61
	v_readlane_b32 s8, v196, 22
	global_load_lds_dwordx4 v[6:7], off
	v_lshl_add_u64 v[6:7], v[4:5], 0, s[42:43]
	s_mov_b32 m0, s62
	v_readlane_b32 s9, v196, 23
	global_load_lds_dwordx4 v[6:7], off
	v_lshl_add_u64 v[6:7], v[4:5], 0, s[46:47]
	s_mov_b32 m0, s63
	s_nop 0
	global_load_lds_dwordx4 v[6:7], off
	v_lshl_add_u64 v[6:7], v[4:5], 0, s[48:49]
	s_mov_b32 m0, s64
	v_lshl_add_u64 v[4:5], v[4:5], 0, s[52:53]
	global_load_lds_dwordx4 v[6:7], off
	s_mov_b32 m0, s65
	s_nop 0
	global_load_lds_dwordx4 v[4:5], off
	ds_read_b128 v[4:7], v9 offset:49152
	ds_read_b128 v[82:85], v9 offset:51200
	ds_read_b128 v[86:89], v9 offset:53248
	ds_read_b128 v[90:93], v9 offset:55296
	ds_read_b128 v[94:97], v12
	ds_read_b128 v[98:101], v12 offset:2048
	ds_read_b128 v[102:105], v12 offset:4096
	ds_read_b128 v[106:109], v12 offset:6144
	s_waitcnt lgkmcnt(8)
	v_mfma_f32_16x16x32_bf16 v[70:73], v[126:129], v[110:113], v[70:73]
	v_mfma_f32_16x16x32_bf16 v[74:77], v[130:133], v[110:113], v[74:77]
	v_mfma_f32_16x16x32_bf16 v[78:81], v[134:137], v[110:113], v[78:81]
	v_mfma_f32_16x16x32_bf16 v[22:25], v[142:145], v[110:113], v[22:25]
	v_mfma_f32_16x16x32_bf16 v[38:41], v[126:129], v[114:117], v[38:41]
	v_mfma_f32_16x16x32_bf16 v[46:49], v[130:133], v[114:117], v[46:49]
	v_mfma_f32_16x16x32_bf16 v[58:61], v[134:137], v[114:117], v[58:61]
	v_mfma_f32_16x16x32_bf16 v[50:53], v[142:145], v[114:117], v[50:53]
	v_mfma_f32_16x16x32_bf16 v[42:45], v[126:129], v[118:121], v[42:45]
	v_mfma_f32_16x16x32_bf16 v[62:65], v[130:133], v[118:121], v[62:65]
	v_mfma_f32_16x16x32_bf16 v[66:69], v[134:137], v[118:121], v[66:69]
	v_mfma_f32_16x16x32_bf16 v[54:57], v[142:145], v[118:121], v[54:57]
	v_mfma_f32_16x16x32_bf16 v[34:37], v[126:129], v[122:125], v[34:37]
	v_mfma_f32_16x16x32_bf16 v[30:33], v[130:133], v[122:125], v[30:33]
	v_mfma_f32_16x16x32_bf16 v[26:29], v[134:137], v[122:125], v[26:29]
	v_mfma_f32_16x16x32_bf16 v[18:21], v[142:145], v[122:125], v[18:21]
	s_waitcnt vmcnt(6) lgkmcnt(0)
	s_barrier
	ds_read_b128 v[110:113], v13
	ds_read_b128 v[114:117], v13 offset:2048
	ds_read_b128 v[118:121], v13 offset:4096
	ds_read_b128 v[122:125], v13 offset:6144
	ds_read_b128 v[126:129], v14
	ds_read_b128 v[130:133], v14 offset:2048
	ds_read_b128 v[134:137], v14 offset:4096
	ds_read_b128 v[138:141], v14 offset:6144
	v_mfma_f32_16x16x32_bf16 v[70:73], v[94:97], v[4:7], v[70:73]
	v_mfma_f32_16x16x32_bf16 v[74:77], v[98:101], v[4:7], v[74:77]
	v_mfma_f32_16x16x32_bf16 v[78:81], v[102:105], v[4:7], v[78:81]
	v_mfma_f32_16x16x32_bf16 v[4:7], v[106:109], v[4:7], v[22:25]
	v_mfma_f32_16x16x32_bf16 v[22:25], v[94:97], v[82:85], v[38:41]
	v_mfma_f32_16x16x32_bf16 v[38:41], v[98:101], v[82:85], v[46:49]
	v_mfma_f32_16x16x32_bf16 v[46:49], v[102:105], v[82:85], v[58:61]
	v_mfma_f32_16x16x32_bf16 v[50:53], v[106:109], v[82:85], v[50:53]
	v_mfma_f32_16x16x32_bf16 v[42:45], v[94:97], v[86:89], v[42:45]
	v_mfma_f32_16x16x32_bf16 v[58:61], v[98:101], v[86:89], v[62:65]
	v_mfma_f32_16x16x32_bf16 v[62:65], v[102:105], v[86:89], v[66:69]
	v_mfma_f32_16x16x32_bf16 v[54:57], v[106:109], v[86:89], v[54:57]
	v_mfma_f32_16x16x32_bf16 v[34:37], v[94:97], v[90:93], v[34:37]
	v_mfma_f32_16x16x32_bf16 v[30:33], v[98:101], v[90:93], v[30:33]
	v_mfma_f32_16x16x32_bf16 v[26:29], v[102:105], v[90:93], v[26:29]
	v_mfma_f32_16x16x32_bf16 v[18:21], v[106:109], v[90:93], v[18:21]
	ds_read_b128 v[66:69], v15
	ds_read_b128 v[82:85], v15 offset:2048
	ds_read_b128 v[86:89], v15 offset:4096
	ds_read_b128 v[12:15], v15 offset:6144
	ds_read_b128 v[90:93], v16
	ds_read_b128 v[94:97], v16 offset:2048
	ds_read_b128 v[98:101], v16 offset:4096
	ds_read_b128 v[102:105], v16 offset:6144
	s_waitcnt lgkmcnt(8)
	v_mfma_f32_16x16x32_bf16 v[70:73], v[126:129], v[110:113], v[70:73]
	v_mfma_f32_16x16x32_bf16 v[74:77], v[130:133], v[110:113], v[74:77]
	v_mfma_f32_16x16x32_bf16 v[78:81], v[134:137], v[110:113], v[78:81]
	v_mfma_f32_16x16x32_bf16 v[4:7], v[138:141], v[110:113], v[4:7]
	v_mfma_f32_16x16x32_bf16 v[22:25], v[126:129], v[114:117], v[22:25]
	v_mfma_f32_16x16x32_bf16 v[38:41], v[130:133], v[114:117], v[38:41]
	v_mfma_f32_16x16x32_bf16 v[46:49], v[134:137], v[114:117], v[46:49]
	v_mfma_f32_16x16x32_bf16 v[50:53], v[138:141], v[114:117], v[50:53]
	v_mfma_f32_16x16x32_bf16 v[42:45], v[126:129], v[118:121], v[42:45]
	v_mfma_f32_16x16x32_bf16 v[58:61], v[130:133], v[118:121], v[58:61]
	v_mfma_f32_16x16x32_bf16 v[62:65], v[134:137], v[118:121], v[62:65]
	v_mfma_f32_16x16x32_bf16 v[54:57], v[138:141], v[118:121], v[54:57]
	v_mfma_f32_16x16x32_bf16 v[34:37], v[126:129], v[122:125], v[34:37]
	v_mfma_f32_16x16x32_bf16 v[30:33], v[130:133], v[122:125], v[30:33]
	v_mfma_f32_16x16x32_bf16 v[26:29], v[134:137], v[122:125], v[26:29]
	v_mfma_f32_16x16x32_bf16 v[16:19], v[138:141], v[122:125], v[18:21]
	s_waitcnt vmcnt(0) lgkmcnt(0)
	s_barrier
	ds_read_b128 v[106:109], v2
	ds_read_b128 v[110:113], v2 offset:2048
	ds_read_b128 v[114:117], v2 offset:4096
	ds_read_b128 v[118:121], v2 offset:6144
	ds_read_b128 v[122:125], v8 offset:16384
	ds_read_b128 v[126:129], v8 offset:18432
	ds_read_b128 v[130:133], v8 offset:20480
	ds_read_b128 v[134:137], v8 offset:22528
	v_and_b32_e32 v2, 0xc0, v1
	v_mfma_f32_16x16x32_bf16 v[70:73], v[90:93], v[66:69], v[70:73]
	v_mfma_f32_16x16x32_bf16 v[74:77], v[94:97], v[66:69], v[74:77]
	v_mfma_f32_16x16x32_bf16 v[78:81], v[98:101], v[66:69], v[78:81]
	v_mfma_f32_16x16x32_bf16 v[4:7], v[102:105], v[66:69], v[4:7]
	v_mfma_f32_16x16x32_bf16 v[20:23], v[90:93], v[82:85], v[22:25]
	v_mfma_f32_16x16x32_bf16 v[38:41], v[94:97], v[82:85], v[38:41]
	v_mfma_f32_16x16x32_bf16 v[46:49], v[98:101], v[82:85], v[46:49]
	v_mfma_f32_16x16x32_bf16 v[50:53], v[102:105], v[82:85], v[50:53]
	v_mfma_f32_16x16x32_bf16 v[42:45], v[90:93], v[86:89], v[42:45]
	v_mfma_f32_16x16x32_bf16 v[58:61], v[94:97], v[86:89], v[58:61]
	v_mfma_f32_16x16x32_bf16 v[62:65], v[98:101], v[86:89], v[62:65]
	v_mfma_f32_16x16x32_bf16 v[54:57], v[102:105], v[86:89], v[54:57]
	v_mfma_f32_16x16x32_bf16 v[34:37], v[90:93], v[12:15], v[34:37]
	v_mfma_f32_16x16x32_bf16 v[30:33], v[94:97], v[12:15], v[30:33]
	v_mfma_f32_16x16x32_bf16 v[24:27], v[98:101], v[12:15], v[26:29]
	v_mfma_f32_16x16x32_bf16 v[12:15], v[102:105], v[12:15], v[16:19]
	s_nop 2
	ds_read_b128 v[16:19], v9
	ds_read_b128 v[66:69], v9 offset:2048
	ds_read_b128 v[82:85], v9 offset:4096
	ds_read_b128 v[86:89], v9 offset:6144
	ds_read_b128 v[90:93], v10 offset:16384
	ds_read_b128 v[94:97], v10 offset:18432
	ds_read_b128 v[98:101], v10 offset:20480
	ds_read_b128 v[8:11], v10 offset:22528
	s_waitcnt lgkmcnt(8)
	v_mfma_f32_16x16x32_bf16 v[70:73], v[122:125], v[106:109], v[70:73]
	v_mfma_f32_16x16x32_bf16 v[74:77], v[126:129], v[106:109], v[74:77]
	v_mfma_f32_16x16x32_bf16 v[78:81], v[130:133], v[106:109], v[78:81]
	v_mfma_f32_16x16x32_bf16 v[4:7], v[134:137], v[106:109], v[4:7]
	v_mfma_f32_16x16x32_bf16 v[20:23], v[122:125], v[110:113], v[20:23]
	v_mfma_f32_16x16x32_bf16 v[38:41], v[126:129], v[110:113], v[38:41]
	v_mfma_f32_16x16x32_bf16 v[46:49], v[130:133], v[110:113], v[46:49]
	v_mfma_f32_16x16x32_bf16 v[50:53], v[134:137], v[110:113], v[50:53]
	v_mfma_f32_16x16x32_bf16 v[42:45], v[122:125], v[114:117], v[42:45]
	v_mfma_f32_16x16x32_bf16 v[58:61], v[126:129], v[114:117], v[58:61]
	v_mfma_f32_16x16x32_bf16 v[62:65], v[130:133], v[114:117], v[62:65]
	v_mfma_f32_16x16x32_bf16 v[54:57], v[134:137], v[114:117], v[54:57]
	v_mfma_f32_16x16x32_bf16 v[34:37], v[122:125], v[118:121], v[34:37]
	v_mfma_f32_16x16x32_bf16 v[28:31], v[126:129], v[118:121], v[30:33]
	v_mfma_f32_16x16x32_bf16 v[24:27], v[130:133], v[118:121], v[24:27]
	v_mfma_f32_16x16x32_bf16 v[12:15], v[134:137], v[118:121], v[12:15]
	s_waitcnt vmcnt(0) lgkmcnt(0)
	s_barrier
	v_mfma_f32_16x16x32_bf16 v[70:73], v[90:93], v[16:19], v[70:73]
	v_mfma_f32_16x16x32_bf16 v[74:77], v[94:97], v[16:19], v[74:77]
	v_mfma_f32_16x16x32_bf16 v[78:81], v[98:101], v[16:19], v[78:81]
	v_mfma_f32_16x16x32_bf16 v[4:7], v[8:11], v[16:19], v[4:7]
	v_mfma_f32_16x16x32_bf16 v[16:19], v[90:93], v[66:69], v[20:23]
	v_mfma_f32_16x16x32_bf16 v[20:23], v[94:97], v[66:69], v[38:41]
	v_mfma_f32_16x16x32_bf16 v[38:41], v[98:101], v[66:69], v[46:49]
	v_mfma_f32_16x16x32_bf16 v[46:49], v[8:11], v[66:69], v[50:53]
	v_mfma_f32_16x16x32_bf16 v[42:45], v[90:93], v[82:85], v[42:45]
	v_mfma_f32_16x16x32_bf16 v[50:53], v[94:97], v[82:85], v[58:61]
	v_mfma_f32_16x16x32_bf16 v[58:61], v[98:101], v[82:85], v[62:65]
	v_mfma_f32_16x16x32_bf16 v[54:57], v[8:11], v[82:85], v[54:57]
	v_mfma_f32_16x16x32_bf16 v[32:35], v[90:93], v[86:89], v[34:37]
	v_mfma_f32_16x16x32_bf16 v[28:31], v[94:97], v[86:89], v[28:31]
	v_mfma_f32_16x16x32_bf16 v[24:27], v[98:101], v[86:89], v[24:27]
	v_mfma_f32_16x16x32_bf16 v[8:11], v[8:11], v[86:89], v[12:15]
	s_nop 2
	v_ashrrev_i32_e32 v12, 2, v1
	v_and_b32_e32 v12, 0xffffffc0, v12
	v_add_u32_e32 v12, s60, v12
	s_add_u32 s60, s88, s33
	v_and_or_b32 v12, v1, 15, v12
	s_addc_u32 s61, s89, 0
	v_lshrrev_b32_e32 v1, 2, v1
	v_lshl_add_u64 v[14:15], s[60:61], 0, v[2:3]
	v_and_b32_e32 v2, 12, v1
	v_mov_b32_e32 v1, v3
	v_lshl_add_u64 v[14:15], v[14:15], 0, v[2:3]
	v_ashrrev_i32_e32 v13, 31, v12
	v_cvt_pk_fp8_f32 v1, v70, v71
	v_mov_b32_e32 v2, v3
	v_lshl_add_u64 v[36:37], s[4:5], 0, v[12:13]
	v_cvt_pk_fp8_f32 v2, v74, v75
	v_mov_b32_e32 v13, v3
	v_cvt_pk_fp8_f32 v13, v78, v79
	v_mov_b32_e32 v62, v3
	v_cvt_pk_fp8_f32 v62, v4, v5
	v_cvt_pk_fp8_f32 v1, v72, v73 op_sel:[0,0,1]
	v_cvt_pk_fp8_f32 v2, v76, v77 op_sel:[0,0,1]
	v_lshlrev_b64 v[36:37], 10, v[36:37]
	v_cvt_pk_fp8_f32 v13, v80, v81 op_sel:[0,0,1]
	v_lshl_add_u64 v[36:37], v[14:15], 0, v[36:37]
	v_cvt_pk_fp8_f32 v62, v6, v7 op_sel:[0,0,1]
	s_waitcnt lgkmcnt(0)
	s_barrier
	global_store_dword v[36:37], v1, off
	global_store_dword v[36:37], v2, off offset:16
	global_store_dword v[36:37], v13, off offset:32
	global_store_dword v[36:37], v62, off offset:48
	v_mov_b32_e32 v1, v3
	v_cvt_pk_fp8_f32 v1, v16, v17
	v_mov_b32_e32 v2, v3
	v_cvt_pk_fp8_f32 v2, v20, v21
	v_mov_b32_e32 v6, v3
	v_cvt_pk_fp8_f32 v6, v38, v39
	v_mov_b32_e32 v7, v3
	v_or_b32_e32 v4, 16, v12
	v_cvt_pk_fp8_f32 v7, v46, v47
	v_ashrrev_i32_e32 v5, 31, v4
	v_cvt_pk_fp8_f32 v1, v18, v19 op_sel:[0,0,1]
	v_lshl_add_u64 v[4:5], s[4:5], 0, v[4:5]
	v_cvt_pk_fp8_f32 v2, v22, v23 op_sel:[0,0,1]
	v_lshlrev_b64 v[4:5], 10, v[4:5]
	v_cvt_pk_fp8_f32 v6, v40, v41 op_sel:[0,0,1]
	v_lshl_add_u64 v[4:5], v[14:15], 0, v[4:5]
	v_cvt_pk_fp8_f32 v7, v48, v49 op_sel:[0,0,1]
	global_store_dword v[4:5], v1, off
	global_store_dword v[4:5], v2, off offset:16
	global_store_dword v[4:5], v6, off offset:32
	global_store_dword v[4:5], v7, off offset:48
	v_mov_b32_e32 v1, v3
	v_cvt_pk_fp8_f32 v1, v42, v43
	v_mov_b32_e32 v2, v3
	v_cvt_pk_fp8_f32 v2, v50, v51
	v_mov_b32_e32 v6, v3
	v_cvt_pk_fp8_f32 v6, v58, v59
	v_mov_b32_e32 v7, v3
	v_or_b32_e32 v4, 32, v12
	v_cvt_pk_fp8_f32 v7, v54, v55
	v_ashrrev_i32_e32 v5, 31, v4
	v_cvt_pk_fp8_f32 v1, v44, v45 op_sel:[0,0,1]
	v_lshl_add_u64 v[4:5], s[4:5], 0, v[4:5]
	v_cvt_pk_fp8_f32 v2, v52, v53 op_sel:[0,0,1]
	v_lshlrev_b64 v[4:5], 10, v[4:5]
	v_cvt_pk_fp8_f32 v6, v60, v61 op_sel:[0,0,1]
	v_lshl_add_u64 v[4:5], v[14:15], 0, v[4:5]
	v_cvt_pk_fp8_f32 v7, v56, v57 op_sel:[0,0,1]
	global_store_dword v[4:5], v1, off
	global_store_dword v[4:5], v2, off offset:16
	global_store_dword v[4:5], v6, off offset:32
	global_store_dword v[4:5], v7, off offset:48
	v_mov_b32_e32 v1, v3
	v_mov_b32_e32 v7, v3
	v_cvt_pk_fp8_f32 v1, v32, v33
	v_mov_b32_e32 v2, v3
	v_cvt_pk_fp8_f32 v7, v8, v9
	v_cvt_pk_fp8_f32 v2, v28, v29
	v_mov_b32_e32 v6, v3
	v_cvt_pk_fp8_f32 v6, v24, v25
	v_or_b32_e32 v4, 48, v12
	v_ashrrev_i32_e32 v5, 31, v4
	v_cvt_pk_fp8_f32 v1, v34, v35 op_sel:[0,0,1]
	v_cvt_pk_fp8_f32 v7, v10, v11 op_sel:[0,0,1]
	v_lshl_add_u64 v[4:5], s[4:5], 0, v[4:5]
	v_cvt_pk_fp8_f32 v2, v30, v31 op_sel:[0,0,1]
	v_lshlrev_b64 v[4:5], 10, v[4:5]
	v_cvt_pk_fp8_f32 v6, v26, v27 op_sel:[0,0,1]
	s_add_i32 s98, s98, s8
	s_add_i32 s38, s38, s39
	s_add_i32 s56, s56, s57
	s_add_i32 s58, s58, s59
	v_lshl_add_u64 v[4:5], v[14:15], 0, v[4:5]
	s_cmpk_lt_i32 s98, 0x400
	global_store_dword v[4:5], v1, off
	global_store_dword v[4:5], v2, off offset:16
	global_store_dword v[4:5], v6, off offset:32
	global_store_dword v[4:5], v7, off offset:48
	s_cbranch_scc1 .LBB0_1494
	v_readlane_b32 s2, v197, 18
	s_mov_b32 s46, s8
	v_readlane_b32 s3, v197, 19

	.amdhsa_kernel _Z14fwd_megakernel6Params
		.amdhsa_group_segment_fixed_size 0
		.amdhsa_private_segment_fixed_size 0
		.amdhsa_kernarg_size 672
		.amdhsa_user_sgpr_count 2
		.amdhsa_user_sgpr_dispatch_ptr 0
		.amdhsa_user_sgpr_queue_ptr 0
		.amdhsa_user_sgpr_kernarg_segment_ptr 1
		.amdhsa_user_sgpr_dispatch_id 0
		.amdhsa_user_sgpr_kernarg_preload_length 0
		.amdhsa_user_sgpr_kernarg_preload_offset 0
		.amdhsa_user_sgpr_private_segment_size 0
		.amdhsa_uses_dynamic_stack 0
		.amdhsa_enable_private_segment 0
		.amdhsa_system_sgpr_workgroup_id_x 1
		.amdhsa_system_sgpr_workgroup_id_y 0
		.amdhsa_system_sgpr_workgroup_id_z 0
		.amdhsa_system_sgpr_workgroup_info 0
		.amdhsa_system_vgpr_workitem_id 0
		.amdhsa_next_free_vgpr 256
		.amdhsa_next_free_sgpr 100
		.amdhsa_accum_offset 256
		.amdhsa_reserve_vcc 1
		.amdhsa_float_round_mode_32 0
		.amdhsa_float_round_mode_16_64 0
		.amdhsa_float_denorm_mode_32 3
		.amdhsa_float_denorm_mode_16_64 3
		.amdhsa_dx10_clamp 1
		.amdhsa_ieee_mode 1
		.amdhsa_fp16_overflow 0
		.amdhsa_tg_split 0
		.amdhsa_exception_fp_ieee_invalid_op 0
		.amdhsa_exception_fp_denorm_src 0
		.amdhsa_exception_fp_ieee_div_zero 0
		.amdhsa_exception_fp_ieee_overflow 0
		.amdhsa_exception_fp_ieee_underflow 0
		.amdhsa_exception_fp_ieee_inexact 0
		.amdhsa_exception_int_div_zero 0
	.end_amdhsa_kernel

amdhsa.kernels:
  - .agpr_count:     0
    .args:
      - .offset:         0
        .size:           416
        .value_kind:     by_value
      - .offset:         416
        .size:           4
        .value_kind:     hidden_block_count_x
      - .offset:         420
        .size:           4
        .value_kind:     hidden_block_count_y
      - .offset:         424
        .size:           4
        .value_kind:     hidden_block_count_z
      - .offset:         428
        .size:           2
        .value_kind:     hidden_group_size_x
      - .offset:         430
        .size:           2
        .value_kind:     hidden_group_size_y
      - .offset:         432
        .size:           2
        .value_kind:     hidden_group_size_z
      - .offset:         434
        .size:           2
        .value_kind:     hidden_remainder_x
      - .offset:         436
        .size:           2
        .value_kind:     hidden_remainder_y
      - .offset:         438
        .size:           2
        .value_kind:     hidden_remainder_z
      - .offset:         456
        .size:           8
        .value_kind:     hidden_global_offset_x
      - .offset:         464
        .size:           8
        .value_kind:     hidden_global_offset_y
      - .offset:         472
        .size:           8
        .value_kind:     hidden_global_offset_z
      - .offset:         480
        .size:           2
        .value_kind:     hidden_grid_dims
      - .offset:         536
        .size:           4
        .value_kind:     hidden_dynamic_lds_size
    .group_segment_fixed_size: 0
    .kernarg_segment_align: 8
    .kernarg_segment_size: 672
    .language:       OpenCL C
    .language_version:
      - 2
      - 0
    .max_flat_workgroup_size: 512
    .name:           _Z14fwd_megakernel6Params
    .private_segment_fixed_size: 0
    .sgpr_count:     106
    .sgpr_spill_count: 104
    .symbol:         _Z14fwd_megakernel6Params.kd
    .uniform_work_group_size: 1
    .uses_dynamic_stack: false
    .vgpr_count:     256
    .vgpr_spill_count: 0
    .wavefront_size: 64
